# 256x128 GEMM mainloops: staging registers re-loaded right behind the ds_write that frees them (global prefetch distance 2 k-steps)
# baseline (speedup 1.0000x reference)
.LBB0_207:
	s_ashr_i32 s0, s64, 3
	s_lshr_b32 s1, s0, 28
	s_add_i32 s1, s0, s1
	s_and_b32 s5, s1, -16
	s_and_b32 s4, s64, 1
	s_sub_i32 s26, s0, s5
	s_lshr_b32 s5, s0, 6
	s_mul_i32 s5, s5, 5
	s_add_i32 s26, s26, s5
	s_and_b32 s26, s26, 15
	s_lshl_b32 s0, s1, 6
	s_lshl_b32 s1, s64, 7
	s_lshl_b32 s26, s26, 1
	s_and_b32 s0, s0, 0xfffffc00
	s_and_b32 s1, s1, 0x300
	s_or_b32 s26, s26, s4
	s_or_b32 s4, s0, s1
	s_ashr_i32 s5, s4, 31
	s_lshl_b32 s0, s26, 7
	s_lshl_b64 s[52:53], s[4:5], 11
	s_add_u32 s52, s3, s52
	s_addc_u32 s53, s34, s53
	s_ashr_i32 s1, s0, 31
	v_mov_b32_e32 v34, v220
	s_lshl_b64 s[54:55], s[0:1], 11
	s_add_u32 s54, s72, s54
	v_ashrrev_i32_e32 v24, 2, v34
	v_ashrrev_i32_e32 v25, 31, v24
	s_addc_u32 s55, s73, s55
	v_lshlrev_b64 v[0:1], 11, v[24:25]
	v_lshlrev_b32_e32 v4, 4, v34
	v_lshl_add_u64 v[2:3], s[54:55], 0, v[0:1]
	v_lshl_add_u64 v[0:1], s[52:53], 0, v[0:1]
	v_and_b32_e32 v152, 48, v4
	v_lshl_add_u64 v[154:155], v[0:1], 0, v[152:153]
	v_add_co_u32_e32 v26, vcc, s35, v154
	v_lshl_add_u64 v[156:157], v[2:3], 0, v[152:153]
	s_nop 0
	v_addc_co_u32_e32 v27, vcc, 0, v155, vcc
	v_add_co_u32_e32 v28, vcc, s36, v154
	global_load_dwordx4 v[0:3], v[154:155], off
	s_nop 0
	v_addc_co_u32_e32 v29, vcc, 0, v155, vcc
	v_add_co_u32_e32 v30, vcc, s37, v154
	global_load_dwordx4 v[4:7], v[26:27], off
	global_load_dwordx4 v[8:11], v[28:29], off
	v_addc_co_u32_e32 v31, vcc, 0, v155, vcc
	v_add_co_u32_e32 v32, vcc, s35, v156
	global_load_dwordx4 v[12:15], v[30:31], off
	global_load_dwordx4 v[16:19], v[156:157], off
	v_addc_co_u32_e32 v33, vcc, 0, v157, vcc
	global_load_dwordx4 v[20:23], v[32:33], off
	global_load_dwordx4 v[128:131], v[154:155], off offset:64
	global_load_dwordx4 v[136:139], v[26:27], off offset:64
	global_load_dwordx4 v[140:143], v[28:29], off offset:64
	global_load_dwordx4 v[144:147], v[30:31], off offset:64
	global_load_dwordx4 v[132:135], v[156:157], off offset:64
	global_load_dwordx4 v[148:151], v[32:33], off offset:64
	v_lshrrev_b32_e32 v35, 4, v34
	v_lshrrev_b32_e32 v36, 2, v34
	v_sub_u32_e32 v39, 0, v35
	v_sub_u32_e32 v36, 0, v36
	v_and_b32_e32 v37, 0x3ffff8f, v34
	v_lshlrev_b32_e32 v38, 6, v34
	v_xor_b32_e32 v34, v34, v39
	v_xor_b32_e32 v35, v35, v36
	v_lshlrev_b32_e32 v34, 4, v34
	v_lshlrev_b32_e32 v35, 4, v35
	v_mov_b32_e32 v25, 0x4000
	v_and_b32_e32 v40, 0x1000, v38
	v_and_b32_e32 v34, 48, v34
	v_and_b32_e32 v35, 48, v35
	v_and_b32_e32 v41, 0x3c0, v38
	v_and_b32_e32 v38, 0xffffe3c0, v38
	v_lshl_add_u32 v25, v37, 6, v25
	v_lshl_or_b32 v152, v24, 6, v34
	v_or_b32_e32 v24, v35, v40
	s_mov_b32 s1, -2
	v_or3_b32 v175, v40, v41, v35
	v_add_u32_e32 v176, v35, v38
	v_add_u32_e32 v177, v35, v25
	v_add_u32_e32 v178, v24, v41
	v_lshl_add_u64 v[158:159], v[154:155], 0, s[22:23]
	v_lshl_add_u64 v[160:161], v[154:155], 0, s[24:25]
	v_lshl_add_u64 v[162:163], v[154:155], 0, s[28:29]
	v_lshl_add_u64 v[164:165], v[156:157], 0, s[22:23]
	s_mov_b32 s5, s31
	v_mov_b32_e32 v64, 0
	v_mov_b32_e32 v65, v153
	v_mov_b32_e32 v66, v153
	v_mov_b32_e32 v67, v153
	v_mov_b32_e32 v68, 0
	v_mov_b32_e32 v69, v153
	v_mov_b32_e32 v70, v153
	v_mov_b32_e32 v71, v153
	v_mov_b32_e32 v72, 0
	v_mov_b32_e32 v73, v153
	v_mov_b32_e32 v74, v153
	v_mov_b32_e32 v75, v153
	v_mov_b32_e32 v76, 0
	v_mov_b32_e32 v77, v153
	v_mov_b32_e32 v78, v153
	v_mov_b32_e32 v79, v153
	v_mov_b32_e32 v80, 0
	s_waitcnt vmcnt(11)
	ds_write_b128 v152, v[0:3]
	s_waitcnt vmcnt(10)
	ds_write_b128 v152, v[4:7] offset:4096
	s_waitcnt vmcnt(9)
	ds_write_b128 v152, v[8:11] offset:8192
	s_waitcnt vmcnt(8)
	ds_write_b128 v152, v[12:15] offset:12288
	s_waitcnt vmcnt(7)
	ds_write_b128 v152, v[16:19] offset:32768
	s_waitcnt vmcnt(6)
	ds_write_b128 v152, v[20:23] offset:36864
	v_mov_b32_e32 v0, 0
	v_mov_b32_e32 v1, v153
	v_mov_b32_e32 v2, v153
	v_mov_b32_e32 v3, v153
	v_mov_b32_e32 v4, 0
	v_mov_b32_e32 v5, v153
	v_mov_b32_e32 v6, v153
	v_mov_b32_e32 v7, v153
	v_mov_b32_e32 v8, 0
	v_mov_b32_e32 v9, v153
	v_mov_b32_e32 v10, v153
	v_mov_b32_e32 v11, v153
	v_mov_b32_e32 v12, 0
	v_mov_b32_e32 v13, v153
	v_mov_b32_e32 v14, v153
	v_mov_b32_e32 v15, v153
	v_mov_b32_e32 v16, 0
	v_mov_b32_e32 v17, v153
	v_mov_b32_e32 v18, v153
	v_mov_b32_e32 v19, v153
	v_mov_b32_e32 v20, 0
	v_mov_b32_e32 v21, v153
	v_mov_b32_e32 v22, v153
	v_mov_b32_e32 v23, v153
	v_mov_b32_e32 v81, v153
	v_mov_b32_e32 v82, v153
	v_mov_b32_e32 v83, v153
	v_mov_b32_e32 v84, 0
	v_mov_b32_e32 v85, v153
	v_mov_b32_e32 v86, v153
	v_mov_b32_e32 v87, v153
	v_mov_b32_e32 v24, 0
	v_mov_b32_e32 v25, v153
	v_mov_b32_e32 v26, v153
	v_mov_b32_e32 v27, v153
	v_mov_b32_e32 v28, 0
	v_mov_b32_e32 v29, v153
	v_mov_b32_e32 v30, v153
	v_mov_b32_e32 v31, v153
	v_mov_b32_e32 v88, 0
	v_mov_b32_e32 v89, v153
	v_mov_b32_e32 v90, v153
	v_mov_b32_e32 v91, v153
	v_mov_b32_e32 v92, 0
	v_mov_b32_e32 v93, v153
	v_mov_b32_e32 v94, v153
	v_mov_b32_e32 v95, v153
	v_mov_b32_e32 v32, 0
	v_mov_b32_e32 v33, v153
	v_mov_b32_e32 v34, v153
	v_mov_b32_e32 v35, v153
	v_mov_b32_e32 v36, 0
	v_mov_b32_e32 v37, v153
	v_mov_b32_e32 v38, v153
	v_mov_b32_e32 v39, v153
	v_mov_b32_e32 v96, 0
	v_mov_b32_e32 v97, v153
	v_mov_b32_e32 v98, v153
	v_mov_b32_e32 v99, v153
	v_mov_b32_e32 v100, 0
	v_mov_b32_e32 v101, v153
	v_mov_b32_e32 v102, v153
	v_mov_b32_e32 v103, v153
	v_mov_b32_e32 v40, 0
	v_mov_b32_e32 v41, v153
	v_mov_b32_e32 v42, v153
	v_mov_b32_e32 v43, v153
	v_mov_b32_e32 v44, 0
	v_mov_b32_e32 v45, v153
	v_mov_b32_e32 v46, v153
	v_mov_b32_e32 v47, v153
	v_mov_b32_e32 v104, 0
	v_mov_b32_e32 v105, v153
	v_mov_b32_e32 v106, v153
	v_mov_b32_e32 v107, v153
	v_mov_b32_e32 v108, 0
	v_mov_b32_e32 v109, v153
	v_mov_b32_e32 v110, v153
	v_mov_b32_e32 v111, v153
	v_mov_b32_e32 v48, 0
	v_mov_b32_e32 v49, v153
	v_mov_b32_e32 v50, v153
	v_mov_b32_e32 v51, v153
	v_mov_b32_e32 v52, 0
	v_mov_b32_e32 v53, v153
	v_mov_b32_e32 v54, v153
	v_mov_b32_e32 v55, v153
	v_mov_b32_e32 v112, 0
	v_mov_b32_e32 v113, v153
	v_mov_b32_e32 v114, v153
	v_mov_b32_e32 v115, v153
	v_mov_b32_e32 v116, 0
	v_mov_b32_e32 v117, v153
	v_mov_b32_e32 v118, v153
	v_mov_b32_e32 v119, v153
	v_mov_b32_e32 v56, 0
	v_mov_b32_e32 v57, v153
	v_mov_b32_e32 v58, v153
	v_mov_b32_e32 v59, v153
	v_mov_b32_e32 v60, 0
	v_mov_b32_e32 v61, v153
	v_mov_b32_e32 v62, v153
	v_mov_b32_e32 v63, v153
	v_mov_b32_e32 v120, 0
	v_mov_b32_e32 v121, v153
	v_mov_b32_e32 v122, v153
	v_mov_b32_e32 v123, v153
	v_mov_b32_e32 v124, 0
	v_mov_b32_e32 v125, v153
	v_mov_b32_e32 v126, v153
	v_mov_b32_e32 v127, v153
	s_waitcnt lgkmcnt(0)
	s_barrier
	global_load_dwordx4 v[180:183], v[154:155], off offset:128
	global_load_dwordx4 v[184:187], v[158:159], off offset:128
	global_load_dwordx4 v[188:191], v[160:161], off offset:128
	global_load_dwordx4 v[192:195], v[162:163], off offset:128
	global_load_dwordx4 v[196:199], v[156:157], off offset:128
	global_load_dwordx4 v[200:203], v[164:165], off offset:128
.LBB0_208:
	s_add_i32 s27, s5, 64
	s_add_i32 s30, s5, 96
	s_min_u32 s30, s30, 0x3e0
	s_lshl_b32 s30, s30, 1
	ds_read_b128 v[204:207], v178 offset:32768
	ds_read_b128 v[208:211], v178 offset:33792
	ds_read_b128 v[212:215], v178 offset:34816
	ds_read_b128 v[216:219], v178 offset:35840
	ds_read_b128 v[222:225], v176
	ds_read_b128 v[226:229], v176 offset:1024
	ds_read_b128 v[230:233], v176 offset:2048
	ds_read_b128 v[234:237], v176 offset:3072
	ds_read_b128 v[238:241], v176 offset:4096
	ds_read_b128 v[242:245], v176 offset:5120
	ds_read_b128 v[246:249], v176 offset:6144
	ds_read_b128 v[250:253], v176 offset:7168
	s_setprio 1
	s_waitcnt lgkmcnt(7)
	v_mfma_f32_16x16x32_bf16 v[124:127], v[222:225], v[204:207], v[124:127]
	v_mfma_f32_16x16x32_bf16 v[120:123], v[222:225], v[208:211], v[120:123]
	v_mfma_f32_16x16x32_bf16 v[60:63], v[222:225], v[212:215], v[60:63]
	v_mfma_f32_16x16x32_bf16 v[56:59], v[222:225], v[216:219], v[56:59]
	s_waitcnt vmcnt(11)
	ds_write_b128 v152, v[128:131] offset:16384
	s_waitcnt lgkmcnt(7)
	v_mfma_f32_16x16x32_bf16 v[116:119], v[226:229], v[204:207], v[116:119]
	v_mfma_f32_16x16x32_bf16 v[112:115], v[226:229], v[208:211], v[112:115]
	v_mfma_f32_16x16x32_bf16 v[52:55], v[226:229], v[212:215], v[52:55]
	v_mfma_f32_16x16x32_bf16 v[48:51], v[226:229], v[216:219], v[48:51]
	s_waitcnt vmcnt(10)
	ds_write_b128 v152, v[136:139] offset:20480
	v_lshl_add_u64 v[128:129], v[154:155], 0, s[30:31]
	global_load_dwordx4 v[128:131], v[128:129], off
	s_waitcnt lgkmcnt(7)
	v_mfma_f32_16x16x32_bf16 v[108:111], v[230:233], v[204:207], v[108:111]
	v_mfma_f32_16x16x32_bf16 v[104:107], v[230:233], v[208:211], v[104:107]
	v_mfma_f32_16x16x32_bf16 v[44:47], v[230:233], v[212:215], v[44:47]
	v_mfma_f32_16x16x32_bf16 v[40:43], v[230:233], v[216:219], v[40:43]
	s_waitcnt vmcnt(10)
	ds_write_b128 v152, v[140:143] offset:24576
	v_lshl_add_u64 v[136:137], v[158:159], 0, s[30:31]
	global_load_dwordx4 v[136:139], v[136:137], off
	s_waitcnt lgkmcnt(7)
	v_mfma_f32_16x16x32_bf16 v[100:103], v[234:237], v[204:207], v[100:103]
	v_mfma_f32_16x16x32_bf16 v[96:99], v[234:237], v[208:211], v[96:99]
	v_mfma_f32_16x16x32_bf16 v[36:39], v[234:237], v[212:215], v[36:39]
	v_mfma_f32_16x16x32_bf16 v[32:35], v[234:237], v[216:219], v[32:35]
	s_waitcnt vmcnt(10)
	ds_write_b128 v152, v[144:147] offset:28672
	v_lshl_add_u64 v[140:141], v[160:161], 0, s[30:31]
	global_load_dwordx4 v[140:143], v[140:141], off
	s_waitcnt lgkmcnt(7)
	v_mfma_f32_16x16x32_bf16 v[92:95], v[238:241], v[204:207], v[92:95]
	v_mfma_f32_16x16x32_bf16 v[88:91], v[238:241], v[208:211], v[88:91]
	v_mfma_f32_16x16x32_bf16 v[28:31], v[238:241], v[212:215], v[28:31]
	v_mfma_f32_16x16x32_bf16 v[24:27], v[238:241], v[216:219], v[24:27]
	s_waitcnt vmcnt(10)
	ds_write_b128 v152, v[132:135] offset:40960
	v_lshl_add_u64 v[144:145], v[162:163], 0, s[30:31]
	global_load_dwordx4 v[144:147], v[144:145], off
	s_waitcnt lgkmcnt(7)
	v_mfma_f32_16x16x32_bf16 v[84:87], v[242:245], v[204:207], v[84:87]
	v_mfma_f32_16x16x32_bf16 v[80:83], v[242:245], v[208:211], v[80:83]
	v_mfma_f32_16x16x32_bf16 v[20:23], v[242:245], v[212:215], v[20:23]
	v_mfma_f32_16x16x32_bf16 v[16:19], v[242:245], v[216:219], v[16:19]
	s_waitcnt vmcnt(10)
	ds_write_b128 v152, v[148:151] offset:45056
	v_lshl_add_u64 v[132:133], v[156:157], 0, s[30:31]
	global_load_dwordx4 v[132:135], v[132:133], off
	s_waitcnt lgkmcnt(7)
	v_mfma_f32_16x16x32_bf16 v[76:79], v[246:249], v[204:207], v[76:79]
	v_mfma_f32_16x16x32_bf16 v[72:75], v[246:249], v[208:211], v[72:75]
	v_mfma_f32_16x16x32_bf16 v[12:15], v[246:249], v[212:215], v[12:15]
	v_mfma_f32_16x16x32_bf16 v[8:11], v[246:249], v[216:219], v[8:11]
	v_lshl_add_u64 v[148:149], v[164:165], 0, s[30:31]
	global_load_dwordx4 v[148:151], v[148:149], off
	s_waitcnt lgkmcnt(6)
	v_mfma_f32_16x16x32_bf16 v[68:71], v[250:253], v[204:207], v[68:71]
	v_mfma_f32_16x16x32_bf16 v[64:67], v[250:253], v[208:211], v[64:67]
	v_mfma_f32_16x16x32_bf16 v[4:7], v[250:253], v[212:215], v[4:7]
	v_mfma_f32_16x16x32_bf16 v[0:3], v[250:253], v[216:219], v[0:3]
	s_setprio 0
	s_waitcnt lgkmcnt(0)
	s_barrier
	s_add_i32 s30, s5, 0x80
	s_min_u32 s30, s30, 0x3e0
	s_lshl_b32 s30, s30, 1
	ds_read_b128 v[204:207], v175 offset:40960
	ds_read_b128 v[208:211], v175 offset:41984
	ds_read_b128 v[212:215], v175 offset:43008
	ds_read_b128 v[216:219], v175 offset:44032
	ds_read_b128 v[222:225], v177
	ds_read_b128 v[226:229], v177 offset:1024
	ds_read_b128 v[230:233], v177 offset:2048
	ds_read_b128 v[234:237], v177 offset:3072
	ds_read_b128 v[238:241], v177 offset:4096
	ds_read_b128 v[242:245], v177 offset:5120
	ds_read_b128 v[246:249], v177 offset:6144
	ds_read_b128 v[250:253], v177 offset:7168
	s_setprio 1
	s_waitcnt lgkmcnt(7)
	v_mfma_f32_16x16x32_bf16 v[124:127], v[222:225], v[204:207], v[124:127]
	v_mfma_f32_16x16x32_bf16 v[120:123], v[222:225], v[208:211], v[120:123]
	v_mfma_f32_16x16x32_bf16 v[60:63], v[222:225], v[212:215], v[60:63]
	v_mfma_f32_16x16x32_bf16 v[56:59], v[222:225], v[216:219], v[56:59]
	s_waitcnt vmcnt(11)
	ds_write_b128 v152, v[180:183]
	s_waitcnt lgkmcnt(7)
	v_mfma_f32_16x16x32_bf16 v[116:119], v[226:229], v[204:207], v[116:119]
	v_mfma_f32_16x16x32_bf16 v[112:115], v[226:229], v[208:211], v[112:115]
	v_mfma_f32_16x16x32_bf16 v[52:55], v[226:229], v[212:215], v[52:55]
	v_mfma_f32_16x16x32_bf16 v[48:51], v[226:229], v[216:219], v[48:51]
	s_waitcnt vmcnt(10)
	ds_write_b128 v152, v[184:187] offset:4096
	v_lshl_add_u64 v[180:181], v[154:155], 0, s[30:31]
	global_load_dwordx4 v[180:183], v[180:181], off
	s_waitcnt lgkmcnt(7)
	v_mfma_f32_16x16x32_bf16 v[108:111], v[230:233], v[204:207], v[108:111]
	v_mfma_f32_16x16x32_bf16 v[104:107], v[230:233], v[208:211], v[104:107]
	v_mfma_f32_16x16x32_bf16 v[44:47], v[230:233], v[212:215], v[44:47]
	v_mfma_f32_16x16x32_bf16 v[40:43], v[230:233], v[216:219], v[40:43]
	s_waitcnt vmcnt(10)
	ds_write_b128 v152, v[188:191] offset:8192
	v_lshl_add_u64 v[184:185], v[158:159], 0, s[30:31]
	global_load_dwordx4 v[184:187], v[184:185], off
	s_waitcnt lgkmcnt(7)
	v_mfma_f32_16x16x32_bf16 v[100:103], v[234:237], v[204:207], v[100:103]
	v_mfma_f32_16x16x32_bf16 v[96:99], v[234:237], v[208:211], v[96:99]
	v_mfma_f32_16x16x32_bf16 v[36:39], v[234:237], v[212:215], v[36:39]
	v_mfma_f32_16x16x32_bf16 v[32:35], v[234:237], v[216:219], v[32:35]
	s_waitcnt vmcnt(10)
	ds_write_b128 v152, v[192:195] offset:12288
	v_lshl_add_u64 v[188:189], v[160:161], 0, s[30:31]
	global_load_dwordx4 v[188:191], v[188:189], off
	s_waitcnt lgkmcnt(7)
	v_mfma_f32_16x16x32_bf16 v[92:95], v[238:241], v[204:207], v[92:95]
	v_mfma_f32_16x16x32_bf16 v[88:91], v[238:241], v[208:211], v[88:91]
	v_mfma_f32_16x16x32_bf16 v[28:31], v[238:241], v[212:215], v[28:31]
	v_mfma_f32_16x16x32_bf16 v[24:27], v[238:241], v[216:219], v[24:27]
	s_waitcnt vmcnt(10)
	ds_write_b128 v152, v[196:199] offset:32768
	v_lshl_add_u64 v[192:193], v[162:163], 0, s[30:31]
	global_load_dwordx4 v[192:195], v[192:193], off
	s_waitcnt lgkmcnt(7)
	v_mfma_f32_16x16x32_bf16 v[84:87], v[242:245], v[204:207], v[84:87]
	v_mfma_f32_16x16x32_bf16 v[80:83], v[242:245], v[208:211], v[80:83]
	v_mfma_f32_16x16x32_bf16 v[20:23], v[242:245], v[212:215], v[20:23]
	v_mfma_f32_16x16x32_bf16 v[16:19], v[242:245], v[216:219], v[16:19]
	s_waitcnt vmcnt(10)
	ds_write_b128 v152, v[200:203] offset:36864
	v_lshl_add_u64 v[196:197], v[156:157], 0, s[30:31]
	global_load_dwordx4 v[196:199], v[196:197], off
	s_waitcnt lgkmcnt(7)
	v_mfma_f32_16x16x32_bf16 v[76:79], v[246:249], v[204:207], v[76:79]
	v_mfma_f32_16x16x32_bf16 v[72:75], v[246:249], v[208:211], v[72:75]
	v_mfma_f32_16x16x32_bf16 v[12:15], v[246:249], v[212:215], v[12:15]
	v_mfma_f32_16x16x32_bf16 v[8:11], v[246:249], v[216:219], v[8:11]
	v_lshl_add_u64 v[200:201], v[164:165], 0, s[30:31]
	global_load_dwordx4 v[200:203], v[200:201], off
	s_waitcnt lgkmcnt(6)
	v_mfma_f32_16x16x32_bf16 v[68:71], v[250:253], v[204:207], v[68:71]
	v_mfma_f32_16x16x32_bf16 v[64:67], v[250:253], v[208:211], v[64:67]
	v_mfma_f32_16x16x32_bf16 v[4:7], v[250:253], v[212:215], v[4:7]
	v_mfma_f32_16x16x32_bf16 v[0:3], v[250:253], v[216:219], v[0:3]
	s_setprio 0
	s_add_i32 s1, s1, 2
	s_cmp_lt_u32 s1, 30
	s_mov_b32 s5, s27
	s_waitcnt lgkmcnt(0)
	s_barrier
	s_cbranch_scc1 .LBB0_208
	s_waitcnt vmcnt(0)
	s_waitcnt vmcnt(5)
	v_mov_b32_e32 v128, v220
	s_cmp_gt_i32 s26, 15
	v_and_b32_e32 v158, 15, v128
	v_and_b32_e32 v160, 64, v128
	v_and_b32_e32 v129, 0xffffff80, v128
	v_lshrrev_b32_e32 v128, 2, v128
	v_add_u32_e32 v130, s4, v129
	v_and_b32_e32 v159, 12, v128
	s_waitcnt vmcnt(3)
	v_or_b32_e32 v136, v130, v159
	v_ashrrev_i32_e32 v128, 14, v130
	s_waitcnt vmcnt(0)
	v_or_b32_e32 v150, 16, v136
	v_or_b32_e32 v148, 32, v136
	v_or_b32_e32 v146, 48, v136
	v_or_b32_e32 v142, 64, v136
	v_or_b32_e32 v140, 0x50, v136
	v_or_b32_e32 v138, 0x60, v136
	v_or_b32_e32 v134, 0x70, v136
	s_mov_b64 s[4:5], -1
	v_ashrrev_i32_e32 v137, 31, v136
	v_lshlrev_b32_e32 v132, 1, v159
	v_mov_b32_e32 v250, s0
	v_and_b32_e32 v250, 0x80, v250
	v_add_u32_e32 v250, v250, v160
	v_mul_u32_u24_e32 v250, 30, v250
	v_lshrrev_b32_e32 v251, 3, v158
	v_mul_u32_u24_e32 v251, 0xf0, v251
	v_add_u32_e32 v250, v250, v251
	v_lshrrev_b32_e32 v251, 2, v159
	v_mul_u32_u24_e32 v251, 0x7c0, v251
	v_sub_u32_e32 v250, v250, v251
	v_ashrrev_i32_e32 v251, 31, v250
	v_and_b32_e32 v252, 8, v159
	v_lshlrev_b32_e32 v252, 5, v252
	v_and_b32_e32 v253, 4, v159
	v_lshl_or_b32 v252, v253, 1, v252
	v_lshl_or_b32 v252, v158, 4, v252
	v_mov_b32_e32 v253, 0
	v_ashrrev_i32_e32 v129, 31, v128
	v_ashrrev_i32_e32 v151, 31, v150
	v_ashrrev_i32_e32 v149, 31, v148
	v_ashrrev_i32_e32 v147, 31, v146
	v_ashrrev_i32_e32 v143, 31, v142
	v_ashrrev_i32_e32 v141, 31, v140
	v_ashrrev_i32_e32 v139, 31, v138
	v_ashrrev_i32_e32 v135, 31, v134
	s_cbranch_scc0 .LBB0_211
	v_lshl_add_u64 v[144:145], v[136:137], 2, s[8:9]
	global_load_dwordx4 v[162:165], v[144:145], off
	s_add_i32 s1, s0, 0xfffff800
	s_and_b32 s5, s0, 0x180
	s_ashr_i32 s4, s1, 9
	v_or_b32_e32 v154, s5, v160
	s_ashr_i32 s5, s4, 31
	v_lshlrev_b64 v[144:145], 9, v[128:129]
	s_lshl_b64 s[4:5], s[4:5], 7
	v_lshrrev_b32_e32 v152, 7, v130
	v_lshl_add_u64 v[130:131], v[144:145], 0, s[4:5]
	v_and_or_b32 v130, v152, s38, v130
	v_lshlrev_b64 v[130:131], 16, v[130:131]
	v_mov_b32_e32 v133, v153
	v_lshl_or_b32 v130, v154, 7, v130
	v_lshl_add_u64 v[178:179], s[12:13], 0, v[252:253]
	v_mov_b32_e32 v145, v131
	v_mov_b32_e32 v181, v131
	v_lshlrev_b64 v[156:157], 1, v[130:131]
	v_or_b32_e32 v144, 0x800, v130
	v_or_b32_e32 v180, 0x1000, v130
	v_or_b32_e32 v130, 0x1800, v130
	v_lshl_add_u64 v[182:183], v[178:179], 0, v[156:157]
	v_lshlrev_b64 v[154:155], 1, v[144:145]
	v_lshlrev_b64 v[144:145], 1, v[180:181]
	v_lshlrev_b64 v[130:131], 1, v[130:131]
	v_lshl_add_u64 v[176:177], v[150:151], 2, s[8:9]
	v_lshl_add_u64 v[180:181], v[178:179], 0, v[154:155]
	v_lshl_add_u64 v[184:185], v[178:179], 0, v[144:145]
	v_lshl_add_u64 v[178:179], v[178:179], 0, v[130:131]
	s_waitcnt vmcnt(0)
	v_mul_f32_e32 v133, v124, v162
	v_mul_f32_e32 v152, v125, v163
	v_mul_f32_e32 v161, v126, v164
	v_mul_f32_e32 v175, v127, v165
	v_mul_f32_e32 v186, v120, v162
	v_mul_f32_e32 v187, v121, v163
	v_mul_f32_e32 v188, v122, v164
	v_mul_f32_e32 v189, v123, v165
	v_mul_f32_e32 v190, v60, v162
	v_mul_f32_e32 v191, v61, v163
	v_mul_f32_e32 v194, v56, v162
	v_mul_f32_e32 v195, v57, v163
	v_cvt_pk_bf16_f32 v162, v133, v152
	v_cvt_pk_bf16_f32 v163, v161, v175
	v_mul_f32_e32 v192, v62, v164
	v_mul_f32_e32 v193, v63, v165
	v_mul_f32_e32 v196, v58, v164
	v_mul_f32_e32 v197, v59, v165
	v_cvt_pk_bf16_f32 v164, v186, v187
	v_cvt_pk_bf16_f32 v165, v188, v189
	v_cvt_pk_bf16_f32 v186, v190, v191
	v_cvt_pk_bf16_f32 v187, v192, v193
	v_cvt_pk_bf16_f32 v188, v194, v195
	v_cvt_pk_bf16_f32 v189, v196, v197
	global_store_dwordx2 v[182:183], v[162:163], off
	global_store_dwordx2 v[180:181], v[164:165], off
	global_store_dwordx2 v[184:185], v[186:187], off
	global_store_dwordx2 v[178:179], v[188:189], off
	global_load_dwordx4 v[162:165], v[176:177], off
	v_bitop3_b32 v133, v136, 28, 16 bitop3:0xc8
	v_lshlrev_b32_e32 v152, 1, v133
	v_lshl_add_u64 v[178:179], s[12:13], 0, v[252:253]
	v_lshl_add_u64 v[180:181], v[178:179], 0, v[156:157]
	v_lshl_add_u64 v[176:177], v[148:149], 2, s[8:9]
	v_lshl_add_u64 v[182:183], v[178:179], 0, v[154:155]
	v_lshl_add_u64 v[184:185], v[178:179], 0, v[144:145]
	v_lshl_add_u64 v[178:179], v[178:179], 0, v[130:131]
	s_waitcnt vmcnt(0)
	v_mul_f32_e32 v133, v116, v162
	v_mul_f32_e32 v152, v117, v163
	v_mul_f32_e32 v161, v118, v164
	v_mul_f32_e32 v175, v119, v165
	v_mul_f32_e32 v186, v112, v162
	v_mul_f32_e32 v187, v113, v163
	v_mul_f32_e32 v188, v114, v164
	v_mul_f32_e32 v189, v115, v165
	v_mul_f32_e32 v190, v52, v162
	v_mul_f32_e32 v191, v53, v163
	v_mul_f32_e32 v194, v48, v162
	v_mul_f32_e32 v195, v49, v163
	v_cvt_pk_bf16_f32 v162, v133, v152
	v_cvt_pk_bf16_f32 v163, v161, v175
	v_mul_f32_e32 v192, v54, v164
	v_mul_f32_e32 v193, v55, v165
	v_mul_f32_e32 v196, v50, v164
	v_mul_f32_e32 v197, v51, v165
	v_cvt_pk_bf16_f32 v164, v186, v187
	v_cvt_pk_bf16_f32 v165, v188, v189
	v_cvt_pk_bf16_f32 v186, v190, v191
	v_cvt_pk_bf16_f32 v187, v192, v193
	v_cvt_pk_bf16_f32 v188, v194, v195
	v_cvt_pk_bf16_f32 v189, v196, v197
	global_store_dwordx2 v[180:181], v[162:163], off offset:512
	global_store_dwordx2 v[182:183], v[164:165], off offset:512
	global_store_dwordx2 v[184:185], v[186:187], off offset:512
	global_store_dwordx2 v[178:179], v[188:189], off offset:512
	global_load_dwordx4 v[162:165], v[176:177], off
	v_bitop3_b32 v133, v136, 44, 32 bitop3:0xc8
	v_lshlrev_b32_e32 v152, 1, v133
	v_lshl_add_u64 v[178:179], s[12:13], 0, v[252:253]
	v_lshl_add_u64 v[180:181], v[178:179], 0, v[156:157]
	v_lshl_add_u64 v[176:177], v[146:147], 2, s[8:9]
	v_lshl_add_u64 v[182:183], v[178:179], 0, v[154:155]
	v_lshl_add_u64 v[184:185], v[178:179], 0, v[144:145]
	v_lshl_add_u64 v[178:179], v[178:179], 0, v[130:131]
	s_waitcnt vmcnt(0)
	v_mul_f32_e32 v133, v108, v162
	v_mul_f32_e32 v152, v109, v163
	v_mul_f32_e32 v161, v110, v164
	v_mul_f32_e32 v175, v111, v165
	v_mul_f32_e32 v186, v104, v162
	v_mul_f32_e32 v187, v105, v163
	v_mul_f32_e32 v188, v106, v164
	v_mul_f32_e32 v189, v107, v165
	v_mul_f32_e32 v190, v44, v162
	v_mul_f32_e32 v191, v45, v163
	v_mul_f32_e32 v194, v40, v162
	v_mul_f32_e32 v195, v41, v163
	v_cvt_pk_bf16_f32 v162, v133, v152
	v_cvt_pk_bf16_f32 v163, v161, v175
	v_mul_f32_e32 v192, v46, v164
	v_mul_f32_e32 v193, v47, v165
	v_mul_f32_e32 v196, v42, v164
	v_mul_f32_e32 v197, v43, v165
	v_cvt_pk_bf16_f32 v164, v186, v187
	v_cvt_pk_bf16_f32 v165, v188, v189
	v_cvt_pk_bf16_f32 v186, v190, v191
	v_cvt_pk_bf16_f32 v187, v192, v193
	v_cvt_pk_bf16_f32 v188, v194, v195
	v_cvt_pk_bf16_f32 v189, v196, v197
	global_store_dwordx2 v[180:181], v[162:163], off offset:1024
	global_store_dwordx2 v[182:183], v[164:165], off offset:1024
	global_store_dwordx2 v[184:185], v[186:187], off offset:1024
	global_store_dwordx2 v[178:179], v[188:189], off offset:1024
	global_load_dwordx4 v[162:165], v[176:177], off
	v_bitop3_b32 v133, v136, 60, 48 bitop3:0xc8
	v_lshlrev_b32_e32 v152, 1, v133
	v_lshl_add_u64 v[178:179], s[12:13], 0, v[252:253]
	v_lshl_add_u64 v[180:181], v[178:179], 0, v[156:157]
	v_lshl_add_u64 v[176:177], v[142:143], 2, s[8:9]
	v_lshl_add_u64 v[182:183], v[178:179], 0, v[154:155]
	v_lshl_add_u64 v[184:185], v[178:179], 0, v[144:145]
	v_lshl_add_u64 v[178:179], v[178:179], 0, v[130:131]
	s_waitcnt vmcnt(0)
	v_mul_f32_e32 v133, v100, v162
	v_mul_f32_e32 v152, v101, v163
	v_mul_f32_e32 v161, v102, v164
	v_mul_f32_e32 v175, v103, v165
	v_mul_f32_e32 v186, v96, v162
	v_mul_f32_e32 v187, v97, v163
	v_mul_f32_e32 v188, v98, v164
	v_mul_f32_e32 v189, v99, v165
	v_mul_f32_e32 v190, v36, v162
	v_mul_f32_e32 v191, v37, v163
	v_mul_f32_e32 v194, v32, v162
	v_mul_f32_e32 v195, v33, v163
	v_cvt_pk_bf16_f32 v162, v133, v152
	v_cvt_pk_bf16_f32 v163, v161, v175
	v_mul_f32_e32 v192, v38, v164
	v_mul_f32_e32 v193, v39, v165
	v_mul_f32_e32 v196, v34, v164
	v_mul_f32_e32 v197, v35, v165
	v_cvt_pk_bf16_f32 v164, v186, v187
	v_cvt_pk_bf16_f32 v165, v188, v189
	v_cvt_pk_bf16_f32 v186, v190, v191
	v_cvt_pk_bf16_f32 v187, v192, v193
	v_cvt_pk_bf16_f32 v188, v194, v195
	v_cvt_pk_bf16_f32 v189, v196, v197
	global_store_dwordx2 v[180:181], v[162:163], off offset:1536
	global_store_dwordx2 v[182:183], v[164:165], off offset:1536
	global_store_dwordx2 v[184:185], v[186:187], off offset:1536
	global_store_dwordx2 v[178:179], v[188:189], off offset:1536
	global_load_dwordx4 v[162:165], v[176:177], off
	v_bitop3_b32 v133, v136, s39, 64 bitop3:0xc8
	v_lshlrev_b32_e32 v152, 1, v133
	v_lshl_add_u64 v[178:179], s[12:13], 0, v[252:253]
	v_lshl_add_u64 v[180:181], v[178:179], 0, v[156:157]
	v_lshl_add_u64 v[176:177], v[140:141], 2, s[8:9]
	v_lshl_add_u64 v[182:183], v[178:179], 0, v[154:155]
	v_lshl_add_u64 v[184:185], v[178:179], 0, v[144:145]
	v_lshl_add_u64 v[178:179], v[178:179], 0, v[130:131]
	s_waitcnt vmcnt(0)
	v_mul_f32_e32 v133, v92, v162
	v_mul_f32_e32 v152, v93, v163
	v_mul_f32_e32 v161, v94, v164
	v_mul_f32_e32 v175, v95, v165
	v_mul_f32_e32 v186, v88, v162
	v_mul_f32_e32 v187, v89, v163
	v_mul_f32_e32 v188, v90, v164
	v_mul_f32_e32 v189, v91, v165
	v_mul_f32_e32 v190, v28, v162
	v_mul_f32_e32 v191, v29, v163
	v_mul_f32_e32 v194, v24, v162
	v_mul_f32_e32 v195, v25, v163
	v_cvt_pk_bf16_f32 v162, v133, v152
	v_cvt_pk_bf16_f32 v163, v161, v175
	v_mul_f32_e32 v192, v30, v164
	v_mul_f32_e32 v193, v31, v165
	v_mul_f32_e32 v196, v26, v164
	v_mul_f32_e32 v197, v27, v165
	v_cvt_pk_bf16_f32 v164, v186, v187
	v_cvt_pk_bf16_f32 v165, v188, v189
	v_cvt_pk_bf16_f32 v186, v190, v191
	v_cvt_pk_bf16_f32 v187, v192, v193
	v_cvt_pk_bf16_f32 v188, v194, v195
	v_cvt_pk_bf16_f32 v189, v196, v197
	global_store_dwordx2 v[180:181], v[162:163], off offset:2048
	global_store_dwordx2 v[182:183], v[164:165], off offset:2048
	global_store_dwordx2 v[184:185], v[186:187], off offset:2048
	global_store_dwordx2 v[178:179], v[188:189], off offset:2048
	global_load_dwordx4 v[162:165], v[176:177], off
	v_bitop3_b32 v133, v136, s40, v166 bitop3:0xc8
	v_lshlrev_b32_e32 v152, 1, v133
	v_lshl_add_u64 v[178:179], s[12:13], 0, v[252:253]
	v_lshl_add_u64 v[180:181], v[178:179], 0, v[156:157]
	v_lshl_add_u64 v[176:177], v[138:139], 2, s[8:9]
	v_lshl_add_u64 v[182:183], v[178:179], 0, v[154:155]
	v_lshl_add_u64 v[184:185], v[178:179], 0, v[144:145]
	v_lshl_add_u64 v[178:179], v[178:179], 0, v[130:131]
	s_waitcnt vmcnt(0)
	v_mul_f32_e32 v133, v84, v162
	v_mul_f32_e32 v152, v85, v163
	v_mul_f32_e32 v161, v86, v164
	v_mul_f32_e32 v175, v87, v165
	v_mul_f32_e32 v186, v80, v162
	v_mul_f32_e32 v187, v81, v163
	v_mul_f32_e32 v188, v82, v164
	v_mul_f32_e32 v189, v83, v165
	v_mul_f32_e32 v190, v20, v162
	v_mul_f32_e32 v191, v21, v163
	v_mul_f32_e32 v194, v16, v162
	v_mul_f32_e32 v195, v17, v163
	v_cvt_pk_bf16_f32 v162, v133, v152
	v_cvt_pk_bf16_f32 v163, v161, v175
	v_mul_f32_e32 v192, v22, v164
	v_mul_f32_e32 v193, v23, v165
	v_mul_f32_e32 v196, v18, v164
	v_mul_f32_e32 v197, v19, v165
	v_cvt_pk_bf16_f32 v164, v186, v187
	v_cvt_pk_bf16_f32 v165, v188, v189
	v_cvt_pk_bf16_f32 v186, v190, v191
	v_cvt_pk_bf16_f32 v187, v192, v193
	v_cvt_pk_bf16_f32 v188, v194, v195
	v_cvt_pk_bf16_f32 v189, v196, v197
	global_store_dwordx2 v[180:181], v[162:163], off offset:2560
	global_store_dwordx2 v[182:183], v[164:165], off offset:2560
	global_store_dwordx2 v[184:185], v[186:187], off offset:2560
	global_store_dwordx2 v[178:179], v[188:189], off offset:2560
	global_load_dwordx4 v[162:165], v[176:177], off
	v_bitop3_b32 v133, v136, s41, v167 bitop3:0xc8
	v_lshlrev_b32_e32 v152, 1, v133
	v_lshl_add_u64 v[178:179], s[12:13], 0, v[252:253]
	v_lshl_add_u64 v[180:181], v[178:179], 0, v[156:157]
	v_lshl_add_u64 v[176:177], v[134:135], 2, s[8:9]
	v_lshl_add_u64 v[182:183], v[178:179], 0, v[154:155]
	v_lshl_add_u64 v[184:185], v[178:179], 0, v[144:145]
	v_lshl_add_u64 v[178:179], v[178:179], 0, v[130:131]
	s_waitcnt vmcnt(0)
	v_mul_f32_e32 v133, v76, v162
	v_mul_f32_e32 v152, v77, v163
	v_mul_f32_e32 v161, v78, v164
	v_mul_f32_e32 v175, v79, v165
	v_mul_f32_e32 v186, v72, v162
	v_mul_f32_e32 v187, v73, v163
	v_mul_f32_e32 v188, v74, v164
	v_mul_f32_e32 v189, v75, v165
	v_mul_f32_e32 v190, v12, v162
	v_mul_f32_e32 v191, v13, v163
	v_mul_f32_e32 v194, v8, v162
	v_mul_f32_e32 v195, v9, v163
	v_cvt_pk_bf16_f32 v162, v133, v152
	v_cvt_pk_bf16_f32 v163, v161, v175
	v_mul_f32_e32 v192, v14, v164
	v_mul_f32_e32 v193, v15, v165
	v_mul_f32_e32 v196, v10, v164
	v_mul_f32_e32 v197, v11, v165
	v_cvt_pk_bf16_f32 v164, v186, v187
	v_cvt_pk_bf16_f32 v165, v188, v189
	v_cvt_pk_bf16_f32 v186, v190, v191
	v_cvt_pk_bf16_f32 v187, v192, v193
	v_cvt_pk_bf16_f32 v188, v194, v195
	v_cvt_pk_bf16_f32 v189, v196, v197
	global_store_dwordx2 v[180:181], v[162:163], off offset:3072
	global_store_dwordx2 v[182:183], v[164:165], off offset:3072
	global_store_dwordx2 v[184:185], v[186:187], off offset:3072
	global_store_dwordx2 v[178:179], v[188:189], off offset:3072
	global_load_dwordx4 v[162:165], v[176:177], off
	v_bitop3_b32 v133, v136, s42, v168 bitop3:0xc8
	v_lshlrev_b32_e32 v152, 1, v133
	v_lshl_add_u64 v[176:177], s[12:13], 0, v[252:253]
	v_lshl_add_u64 v[156:157], v[176:177], 0, v[156:157]
	v_lshl_add_u64 v[154:155], v[176:177], 0, v[154:155]
	v_lshl_add_u64 v[144:145], v[176:177], 0, v[144:145]
	v_lshl_add_u64 v[130:131], v[176:177], 0, v[130:131]
	s_waitcnt vmcnt(0)
	v_mul_f32_e32 v133, v68, v162
	v_mul_f32_e32 v152, v69, v163
	v_mul_f32_e32 v161, v70, v164
	v_mul_f32_e32 v175, v71, v165
	v_mul_f32_e32 v176, v64, v162
	v_mul_f32_e32 v177, v65, v163
	v_mul_f32_e32 v178, v66, v164
	v_mul_f32_e32 v179, v67, v165
	v_mul_f32_e32 v180, v4, v162
	v_mul_f32_e32 v181, v5, v163
	v_mul_f32_e32 v184, v0, v162
	v_mul_f32_e32 v185, v1, v163
	v_cvt_pk_bf16_f32 v162, v133, v152
	v_cvt_pk_bf16_f32 v163, v161, v175
	v_mul_f32_e32 v182, v6, v164
	v_mul_f32_e32 v183, v7, v165
	v_mul_f32_e32 v186, v2, v164
	v_mul_f32_e32 v187, v3, v165
	v_cvt_pk_bf16_f32 v164, v176, v177
	v_cvt_pk_bf16_f32 v165, v178, v179
	v_cvt_pk_bf16_f32 v176, v180, v181
	v_cvt_pk_bf16_f32 v177, v182, v183
	v_cvt_pk_bf16_f32 v178, v184, v185
	v_cvt_pk_bf16_f32 v179, v186, v187
	global_store_dwordx2 v[156:157], v[162:163], off offset:3584
	global_store_dwordx2 v[154:155], v[164:165], off offset:3584
	global_store_dwordx2 v[144:145], v[176:177], off offset:3584
	global_store_dwordx2 v[130:131], v[178:179], off offset:3584
	s_cbranch_execnz .LBB0_206
	s_branch .LBB0_212

.LBB0_502:
	s_ashr_i32 s14, s34, 3
	s_lshr_b32 s28, s14, 28
	s_add_i32 s28, s14, s28
	s_and_b32 s29, s28, -16
	s_sub_i32 s33, s14, s29
	s_lshl_b32 s14, s28, 7
	s_lshl_b32 s28, s34, 8
	s_and_b32 s14, s14, 0xfffff800
	s_and_b32 s28, s28, 0x700
	s_or_b32 s28, s14, s28
	s_ashr_i32 s29, s28, 31
	s_lshl_b32 s35, s33, 7
	s_lshl_b64 s[36:37], s[28:29], 11
	s_add_u32 s36, s3, s36
	s_addc_u32 s37, s4, s37
	s_add_i32 s14, s35, 0x1000
	v_mov_b32_e32 v36, v220
	s_lshl_b64 s[38:39], s[14:15], 11
	s_add_u32 s38, s72, s38
	v_ashrrev_i32_e32 v26, 2, v36
	v_ashrrev_i32_e32 v27, 31, v26
	s_addc_u32 s39, s73, s39
	v_lshlrev_b64 v[0:1], 11, v[26:27]
	v_lshlrev_b32_e32 v4, 4, v36
	v_lshl_add_u64 v[2:3], s[38:39], 0, v[0:1]
	v_lshl_add_u64 v[0:1], s[36:37], 0, v[0:1]
	v_and_b32_e32 v152, 48, v4
	v_lshl_add_u64 v[154:155], v[0:1], 0, v[152:153]
	v_add_co_u32_e32 v28, vcc, s27, v154
	v_lshl_add_u64 v[156:157], v[2:3], 0, v[152:153]
	s_nop 0
	v_addc_co_u32_e32 v29, vcc, 0, v155, vcc
	v_add_co_u32_e32 v30, vcc, s30, v154
	global_load_dwordx4 v[2:5], v[154:155], off
	s_nop 0
	v_addc_co_u32_e32 v31, vcc, 0, v155, vcc
	v_add_co_u32_e32 v32, vcc, s31, v154
	global_load_dwordx4 v[6:9], v[28:29], off
	s_nop 0
	v_addc_co_u32_e32 v33, vcc, 0, v155, vcc
	v_add_co_u32_e32 v34, vcc, s27, v156
	global_load_dwordx4 v[10:13], v[30:31], off
	s_nop 0
	v_addc_co_u32_e32 v35, vcc, 0, v157, vcc
	global_load_dwordx4 v[14:17], v[32:33], off
	global_load_dwordx4 v[18:21], v[156:157], off
	global_load_dwordx4 v[22:25], v[34:35], off
	global_load_dwordx4 v[44:47], v[154:155], off offset:64
	global_load_dwordx4 v[60:63], v[28:29], off offset:64
	global_load_dwordx4 v[68:71], v[30:31], off offset:64
	global_load_dwordx4 v[140:143], v[32:33], off offset:64
	global_load_dwordx4 v[52:55], v[156:157], off offset:64
	global_load_dwordx4 v[144:147], v[34:35], off offset:64
	v_lshrrev_b32_e32 v27, 4, v36
	v_lshrrev_b32_e32 v37, 2, v36
	v_sub_u32_e32 v40, 0, v27
	v_sub_u32_e32 v37, 0, v37
	v_and_b32_e32 v38, 0x3ffff8f, v36
	v_lshlrev_b32_e32 v39, 6, v36
	v_xor_b32_e32 v36, v36, v40
	v_xor_b32_e32 v27, v27, v37
	v_lshlrev_b32_e32 v36, 4, v36
	v_lshlrev_b32_e32 v27, 4, v27
	v_and_b32_e32 v41, 0x1000, v39
	v_and_b32_e32 v36, 48, v36
	v_and_b32_e32 v27, 48, v27
	v_and_b32_e32 v42, 0x3c0, v39
	v_and_b32_e32 v39, 0xffffe3c0, v39
	v_lshl_add_u32 v38, v38, 6, v194
	v_lshl_or_b32 v152, v26, 6, v36
	v_or_b32_e32 v26, v27, v41
	s_mov_b32 s29, -2
	s_mov_b32 s36, s15
	v_mov_b32_e32 v0, 0
	v_mov_b32_e32 v1, v153
	v_or3_b32 v166, v41, v42, v27
	v_add_u32_e32 v167, v27, v39
	v_add_u32_e32 v168, v27, v38
	v_add_u32_e32 v169, v26, v42
	v_lshl_add_u64 v[158:159], v[154:155], 0, s[16:17]
	v_lshl_add_u64 v[160:161], v[154:155], 0, s[22:23]
	v_lshl_add_u64 v[162:163], v[154:155], 0, s[24:25]
	v_lshl_add_u64 v[164:165], v[156:157], 0, s[16:17]
	v_mov_b32_e32 v26, v153
	v_mov_b32_e32 v27, v153
	v_mov_b32_e32 v28, 0
	v_mov_b32_e32 v29, v153
	v_mov_b32_e32 v30, v153
	v_mov_b32_e32 v31, v153
	v_mov_b32_e32 v32, 0
	v_mov_b32_e32 v33, v153
	v_mov_b32_e32 v34, v153
	v_mov_b32_e32 v35, v153
	v_mov_b32_e32 v36, 0
	v_mov_b32_e32 v37, v153
	v_mov_b32_e32 v38, v153
	v_mov_b32_e32 v39, v153
	v_mov_b32_e32 v40, 0
	v_mov_b32_e32 v41, v153
	v_mov_b32_e32 v42, v153
	v_mov_b32_e32 v43, v153
	v_mov_b32_e32 v48, 0
	s_waitcnt vmcnt(11)
	ds_write_b128 v152, v[2:5]
	s_waitcnt vmcnt(10)
	ds_write_b128 v152, v[6:9] offset:4096
	s_waitcnt vmcnt(9)
	ds_write_b128 v152, v[10:13] offset:8192
	s_waitcnt vmcnt(8)
	ds_write_b128 v152, v[14:17] offset:12288
	s_waitcnt vmcnt(7)
	ds_write_b128 v152, v[18:21] offset:32768
	s_waitcnt vmcnt(6)
	ds_write_b128 v152, v[22:25] offset:36864
	v_mov_b32_e32 v2, v153
	v_mov_b32_e32 v3, v153
	v_mov_b32_e32 v4, 0
	v_mov_b32_e32 v5, v153
	v_mov_b32_e32 v6, v153
	v_mov_b32_e32 v7, v153
	v_mov_b32_e32 v8, 0
	v_mov_b32_e32 v9, v153
	v_mov_b32_e32 v10, v153
	v_mov_b32_e32 v11, v153
	v_mov_b32_e32 v12, 0
	v_mov_b32_e32 v13, v153
	v_mov_b32_e32 v14, v153
	v_mov_b32_e32 v15, v153
	v_mov_b32_e32 v16, 0
	v_mov_b32_e32 v17, v153
	v_mov_b32_e32 v18, v153
	v_mov_b32_e32 v19, v153
	v_mov_b32_e32 v20, 0
	v_mov_b32_e32 v21, v153
	v_mov_b32_e32 v22, v153
	v_mov_b32_e32 v23, v153
	v_mov_b32_e32 v24, 0
	v_mov_b32_e32 v25, v153
	v_mov_b32_e32 v49, v153
	v_mov_b32_e32 v50, v153
	v_mov_b32_e32 v51, v153
	v_mov_b32_e32 v56, 0
	v_mov_b32_e32 v57, v153
	v_mov_b32_e32 v58, v153
	v_mov_b32_e32 v59, v153
	v_mov_b32_e32 v64, 0
	v_mov_b32_e32 v65, v153
	v_mov_b32_e32 v66, v153
	v_mov_b32_e32 v67, v153
	v_mov_b32_e32 v72, 0
	v_mov_b32_e32 v73, v153
	v_mov_b32_e32 v74, v153
	v_mov_b32_e32 v75, v153
	v_mov_b32_e32 v76, 0
	v_mov_b32_e32 v77, v153
	v_mov_b32_e32 v78, v153
	v_mov_b32_e32 v79, v153
	v_mov_b32_e32 v80, 0
	v_mov_b32_e32 v81, v153
	v_mov_b32_e32 v82, v153
	v_mov_b32_e32 v83, v153
	v_mov_b32_e32 v84, 0
	v_mov_b32_e32 v85, v153
	v_mov_b32_e32 v86, v153
	v_mov_b32_e32 v87, v153
	v_mov_b32_e32 v88, 0
	v_mov_b32_e32 v89, v153
	v_mov_b32_e32 v90, v153
	v_mov_b32_e32 v91, v153
	v_mov_b32_e32 v92, 0
	v_mov_b32_e32 v93, v153
	v_mov_b32_e32 v94, v153
	v_mov_b32_e32 v95, v153
	v_mov_b32_e32 v96, 0
	v_mov_b32_e32 v97, v153
	v_mov_b32_e32 v98, v153
	v_mov_b32_e32 v99, v153
	v_mov_b32_e32 v100, 0
	v_mov_b32_e32 v101, v153
	v_mov_b32_e32 v102, v153
	v_mov_b32_e32 v103, v153
	v_mov_b32_e32 v104, 0
	v_mov_b32_e32 v105, v153
	v_mov_b32_e32 v106, v153
	v_mov_b32_e32 v107, v153
	v_mov_b32_e32 v108, 0
	v_mov_b32_e32 v109, v153
	v_mov_b32_e32 v110, v153
	v_mov_b32_e32 v111, v153
	v_mov_b32_e32 v112, 0
	v_mov_b32_e32 v113, v153
	v_mov_b32_e32 v114, v153
	v_mov_b32_e32 v115, v153
	v_mov_b32_e32 v116, 0
	v_mov_b32_e32 v117, v153
	v_mov_b32_e32 v118, v153
	v_mov_b32_e32 v119, v153
	v_mov_b32_e32 v120, 0
	v_mov_b32_e32 v121, v153
	v_mov_b32_e32 v122, v153
	v_mov_b32_e32 v123, v153
	v_mov_b32_e32 v124, 0
	v_mov_b32_e32 v125, v153
	v_mov_b32_e32 v126, v153
	v_mov_b32_e32 v127, v153
	v_mov_b32_e32 v128, 0
	v_mov_b32_e32 v129, v153
	v_mov_b32_e32 v130, v153
	v_mov_b32_e32 v131, v153
	v_mov_b32_e32 v132, 0
	v_mov_b32_e32 v133, v153
	v_mov_b32_e32 v134, v153
	v_mov_b32_e32 v135, v153
	v_mov_b32_e32 v136, 0
	v_mov_b32_e32 v137, v153
	v_mov_b32_e32 v138, v153
	v_mov_b32_e32 v139, v153
	v_mov_b32_e32 v148, 0
	v_mov_b32_e32 v149, v153
	v_mov_b32_e32 v150, v153
	v_mov_b32_e32 v151, v153
	s_waitcnt lgkmcnt(0)
	s_barrier
	global_load_dwordx4 v[170:173], v[154:155], off offset:128
	global_load_dwordx4 v[174:177], v[158:159], off offset:128
	global_load_dwordx4 v[178:181], v[160:161], off offset:128
	global_load_dwordx4 v[182:185], v[162:163], off offset:128
	global_load_dwordx4 v[186:189], v[156:157], off offset:128
	global_load_dwordx4 v[190:193], v[164:165], off offset:128
.LBB0_503:
	s_add_i32 s37, s36, 64
	s_add_i32 s14, s36, 96
	s_min_u32 s14, s14, 0x3e0
	s_lshl_b32 s14, s14, 1
	ds_read_b128 v[196:199], v169 offset:32768
	ds_read_b128 v[200:203], v169 offset:33792
	ds_read_b128 v[204:207], v169 offset:34816
	ds_read_b128 v[208:211], v169 offset:35840
	ds_read_b128 v[212:215], v167
	ds_read_b128 v[216:219], v167 offset:1024
	ds_read_b128 v[222:225], v167 offset:2048
	ds_read_b128 v[226:229], v167 offset:3072
	ds_read_b128 v[230:233], v167 offset:4096
	ds_read_b128 v[234:237], v167 offset:5120
	ds_read_b128 v[238:241], v167 offset:6144
	ds_read_b128 v[242:245], v167 offset:7168
	s_setprio 1
	s_waitcnt lgkmcnt(7)
	v_mfma_f32_16x16x32_bf16 v[148:151], v[196:199], v[212:215], v[148:151]
	v_mfma_f32_16x16x32_bf16 v[136:139], v[200:203], v[212:215], v[136:139]
	v_mfma_f32_16x16x32_bf16 v[132:135], v[204:207], v[212:215], v[132:135]
	v_mfma_f32_16x16x32_bf16 v[128:131], v[208:211], v[212:215], v[128:131]
	s_waitcnt vmcnt(11)
	ds_write_b128 v152, v[44:47] offset:16384
	s_waitcnt lgkmcnt(7)
	v_mfma_f32_16x16x32_bf16 v[124:127], v[196:199], v[216:219], v[124:127]
	v_mfma_f32_16x16x32_bf16 v[120:123], v[200:203], v[216:219], v[120:123]
	v_mfma_f32_16x16x32_bf16 v[116:119], v[204:207], v[216:219], v[116:119]
	v_mfma_f32_16x16x32_bf16 v[112:115], v[208:211], v[216:219], v[112:115]
	s_waitcnt vmcnt(10)
	ds_write_b128 v152, v[60:63] offset:20480
	v_lshl_add_u64 v[44:45], v[154:155], 0, s[14:15]
	global_load_dwordx4 v[44:47], v[44:45], off
	s_waitcnt lgkmcnt(7)
	v_mfma_f32_16x16x32_bf16 v[108:111], v[196:199], v[222:225], v[108:111]
	v_mfma_f32_16x16x32_bf16 v[104:107], v[200:203], v[222:225], v[104:107]
	v_mfma_f32_16x16x32_bf16 v[100:103], v[204:207], v[222:225], v[100:103]
	v_mfma_f32_16x16x32_bf16 v[96:99], v[208:211], v[222:225], v[96:99]
	s_waitcnt vmcnt(10)
	ds_write_b128 v152, v[68:71] offset:24576
	v_lshl_add_u64 v[60:61], v[158:159], 0, s[14:15]
	global_load_dwordx4 v[60:63], v[60:61], off
	s_waitcnt lgkmcnt(7)
	v_mfma_f32_16x16x32_bf16 v[92:95], v[196:199], v[226:229], v[92:95]
	v_mfma_f32_16x16x32_bf16 v[88:91], v[200:203], v[226:229], v[88:91]
	v_mfma_f32_16x16x32_bf16 v[84:87], v[204:207], v[226:229], v[84:87]
	v_mfma_f32_16x16x32_bf16 v[80:83], v[208:211], v[226:229], v[80:83]
	s_waitcnt vmcnt(10)
	ds_write_b128 v152, v[140:143] offset:28672
	v_lshl_add_u64 v[68:69], v[160:161], 0, s[14:15]
	global_load_dwordx4 v[68:71], v[68:69], off
	s_waitcnt lgkmcnt(7)
	v_mfma_f32_16x16x32_bf16 v[76:79], v[196:199], v[230:233], v[76:79]
	v_mfma_f32_16x16x32_bf16 v[72:75], v[200:203], v[230:233], v[72:75]
	v_mfma_f32_16x16x32_bf16 v[64:67], v[204:207], v[230:233], v[64:67]
	v_mfma_f32_16x16x32_bf16 v[56:59], v[208:211], v[230:233], v[56:59]
	s_waitcnt vmcnt(10)
	ds_write_b128 v152, v[52:55] offset:40960
	v_lshl_add_u64 v[140:141], v[162:163], 0, s[14:15]
	global_load_dwordx4 v[140:143], v[140:141], off
	s_waitcnt lgkmcnt(7)
	v_mfma_f32_16x16x32_bf16 v[48:51], v[196:199], v[234:237], v[48:51]
	v_mfma_f32_16x16x32_bf16 v[40:43], v[200:203], v[234:237], v[40:43]
	v_mfma_f32_16x16x32_bf16 v[36:39], v[204:207], v[234:237], v[36:39]
	v_mfma_f32_16x16x32_bf16 v[32:35], v[208:211], v[234:237], v[32:35]
	s_waitcnt vmcnt(10)
	ds_write_b128 v152, v[144:147] offset:45056
	v_lshl_add_u64 v[52:53], v[156:157], 0, s[14:15]
	global_load_dwordx4 v[52:55], v[52:53], off
	s_waitcnt lgkmcnt(7)
	v_mfma_f32_16x16x32_bf16 v[28:31], v[196:199], v[238:241], v[28:31]
	v_mfma_f32_16x16x32_bf16 v[24:27], v[200:203], v[238:241], v[24:27]
	v_mfma_f32_16x16x32_bf16 v[20:23], v[204:207], v[238:241], v[20:23]
	v_mfma_f32_16x16x32_bf16 v[16:19], v[208:211], v[238:241], v[16:19]
	v_lshl_add_u64 v[144:145], v[164:165], 0, s[14:15]
	global_load_dwordx4 v[144:147], v[144:145], off
	s_waitcnt lgkmcnt(6)
	v_mfma_f32_16x16x32_bf16 v[12:15], v[196:199], v[242:245], v[12:15]
	v_mfma_f32_16x16x32_bf16 v[8:11], v[200:203], v[242:245], v[8:11]
	v_mfma_f32_16x16x32_bf16 v[4:7], v[204:207], v[242:245], v[4:7]
	v_mfma_f32_16x16x32_bf16 v[0:3], v[208:211], v[242:245], v[0:3]
	s_setprio 0
	s_waitcnt lgkmcnt(0)
	s_barrier
	s_add_i32 s14, s36, 0x80
	s_min_u32 s14, s14, 0x3e0
	s_lshl_b32 s14, s14, 1
	ds_read_b128 v[196:199], v166 offset:40960
	ds_read_b128 v[200:203], v166 offset:41984
	ds_read_b128 v[204:207], v166 offset:43008
	ds_read_b128 v[208:211], v166 offset:44032
	ds_read_b128 v[212:215], v168
	ds_read_b128 v[216:219], v168 offset:1024
	ds_read_b128 v[222:225], v168 offset:2048
	ds_read_b128 v[226:229], v168 offset:3072
	ds_read_b128 v[230:233], v168 offset:4096
	ds_read_b128 v[234:237], v168 offset:5120
	ds_read_b128 v[238:241], v168 offset:6144
	ds_read_b128 v[242:245], v168 offset:7168
	s_setprio 1
	s_waitcnt lgkmcnt(7)
	v_mfma_f32_16x16x32_bf16 v[148:151], v[196:199], v[212:215], v[148:151]
	v_mfma_f32_16x16x32_bf16 v[136:139], v[200:203], v[212:215], v[136:139]
	v_mfma_f32_16x16x32_bf16 v[132:135], v[204:207], v[212:215], v[132:135]
	v_mfma_f32_16x16x32_bf16 v[128:131], v[208:211], v[212:215], v[128:131]
	s_waitcnt vmcnt(11)
	ds_write_b128 v152, v[170:173]
	s_waitcnt lgkmcnt(7)
	v_mfma_f32_16x16x32_bf16 v[124:127], v[196:199], v[216:219], v[124:127]
	v_mfma_f32_16x16x32_bf16 v[120:123], v[200:203], v[216:219], v[120:123]
	v_mfma_f32_16x16x32_bf16 v[116:119], v[204:207], v[216:219], v[116:119]
	v_mfma_f32_16x16x32_bf16 v[112:115], v[208:211], v[216:219], v[112:115]
	s_waitcnt vmcnt(10)
	ds_write_b128 v152, v[174:177] offset:4096
	v_lshl_add_u64 v[170:171], v[154:155], 0, s[14:15]
	global_load_dwordx4 v[170:173], v[170:171], off
	s_waitcnt lgkmcnt(7)
	v_mfma_f32_16x16x32_bf16 v[108:111], v[196:199], v[222:225], v[108:111]
	v_mfma_f32_16x16x32_bf16 v[104:107], v[200:203], v[222:225], v[104:107]
	v_mfma_f32_16x16x32_bf16 v[100:103], v[204:207], v[222:225], v[100:103]
	v_mfma_f32_16x16x32_bf16 v[96:99], v[208:211], v[222:225], v[96:99]
	s_waitcnt vmcnt(10)
	ds_write_b128 v152, v[178:181] offset:8192
	v_lshl_add_u64 v[174:175], v[158:159], 0, s[14:15]
	global_load_dwordx4 v[174:177], v[174:175], off
	s_waitcnt lgkmcnt(7)
	v_mfma_f32_16x16x32_bf16 v[92:95], v[196:199], v[226:229], v[92:95]
	v_mfma_f32_16x16x32_bf16 v[88:91], v[200:203], v[226:229], v[88:91]
	v_mfma_f32_16x16x32_bf16 v[84:87], v[204:207], v[226:229], v[84:87]
	v_mfma_f32_16x16x32_bf16 v[80:83], v[208:211], v[226:229], v[80:83]
	s_waitcnt vmcnt(10)
	ds_write_b128 v152, v[182:185] offset:12288
	v_lshl_add_u64 v[178:179], v[160:161], 0, s[14:15]
	global_load_dwordx4 v[178:181], v[178:179], off
	s_waitcnt lgkmcnt(7)
	v_mfma_f32_16x16x32_bf16 v[76:79], v[196:199], v[230:233], v[76:79]
	v_mfma_f32_16x16x32_bf16 v[72:75], v[200:203], v[230:233], v[72:75]
	v_mfma_f32_16x16x32_bf16 v[64:67], v[204:207], v[230:233], v[64:67]
	v_mfma_f32_16x16x32_bf16 v[56:59], v[208:211], v[230:233], v[56:59]
	s_waitcnt vmcnt(10)
	ds_write_b128 v152, v[186:189] offset:32768
	v_lshl_add_u64 v[182:183], v[162:163], 0, s[14:15]
	global_load_dwordx4 v[182:185], v[182:183], off
	s_waitcnt lgkmcnt(7)
	v_mfma_f32_16x16x32_bf16 v[48:51], v[196:199], v[234:237], v[48:51]
	v_mfma_f32_16x16x32_bf16 v[40:43], v[200:203], v[234:237], v[40:43]
	v_mfma_f32_16x16x32_bf16 v[36:39], v[204:207], v[234:237], v[36:39]
	v_mfma_f32_16x16x32_bf16 v[32:35], v[208:211], v[234:237], v[32:35]
	s_waitcnt vmcnt(10)
	ds_write_b128 v152, v[190:193] offset:36864
	v_lshl_add_u64 v[186:187], v[156:157], 0, s[14:15]
	global_load_dwordx4 v[186:189], v[186:187], off
	s_waitcnt lgkmcnt(7)
	v_mfma_f32_16x16x32_bf16 v[28:31], v[196:199], v[238:241], v[28:31]
	v_mfma_f32_16x16x32_bf16 v[24:27], v[200:203], v[238:241], v[24:27]
	v_mfma_f32_16x16x32_bf16 v[20:23], v[204:207], v[238:241], v[20:23]
	v_mfma_f32_16x16x32_bf16 v[16:19], v[208:211], v[238:241], v[16:19]
	v_lshl_add_u64 v[190:191], v[164:165], 0, s[14:15]
	global_load_dwordx4 v[190:193], v[190:191], off
	s_waitcnt lgkmcnt(6)
	v_mfma_f32_16x16x32_bf16 v[12:15], v[196:199], v[242:245], v[12:15]
	v_mfma_f32_16x16x32_bf16 v[8:11], v[200:203], v[242:245], v[8:11]
	v_mfma_f32_16x16x32_bf16 v[4:7], v[204:207], v[242:245], v[4:7]
	v_mfma_f32_16x16x32_bf16 v[0:3], v[208:211], v[242:245], v[0:3]
	s_setprio 0
	s_add_i32 s29, s29, 2
	s_cmp_lt_u32 s29, 30
	s_mov_b32 s36, s37
	s_waitcnt lgkmcnt(0)
	s_barrier
	s_cbranch_scc1 .LBB0_503
	s_waitcnt vmcnt(0)
	s_waitcnt vmcnt(1)
	v_mov_b32_e32 v142, v220
	v_readlane_b32 s36, v254, 6
	v_and_b32_e32 v45, 0xffffff80, v142
	v_add_u32_e32 v143, s28, v45
	v_lshrrev_b32_e32 v45, 2, v142
	v_and_b32_e32 v44, 64, v142
	v_and_b32_e32 v45, 12, v45
	s_ashr_i32 s28, s33, 2
	v_or3_b32 v140, v44, v45, s35
	s_ashr_i32 s29, s28, 31
	v_ashrrev_i32_e32 v141, 31, v140
	v_readlane_b32 s44, v254, 14
	v_readlane_b32 s45, v254, 15
	s_waitcnt vmcnt(0)
	v_and_or_b32 v144, v142, 15, v143
	s_lshl_b64 s[28:29], s[28:29], 3
	v_lshl_add_u64 v[44:45], v[140:141], 2, s[44:45]
	s_add_u32 s28, s5, s28
	v_lshlrev_b64 v[140:141], 1, v[140:141]
	v_ashrrev_i32_e32 v145, 31, v144
	s_addc_u32 s29, s26, s29
	v_lshl_add_u64 v[142:143], s[70:71], 0, v[140:141]
	v_lshl_add_u64 v[146:147], v[144:145], 2, s[6:7]
	v_lshlrev_b64 v[154:155], 5, v[144:145]
	v_lshlrev_b64 v[190:191], 12, v[144:145]
	global_load_dwordx4 v[68:71], v[44:45], off
	global_load_dwordx4 v[60:63], v[44:45], off offset:64
	global_load_dwordx4 v[52:55], v[44:45], off offset:128
	s_nop 0
	global_load_dwordx4 v[44:47], v[44:45], off offset:192
	v_lshl_add_u64 v[154:155], s[28:29], 0, v[154:155]
	global_load_dword v202, v[146:147], off
	global_load_dwordx2 v[184:185], v[154:155], off
	v_lshl_add_u64 v[146:147], v[142:143], 0, v[190:191]
	global_load_dwordx2 v[196:197], v[146:147], off
	global_load_dwordx2 v[198:199], v[146:147], off offset:32
	global_load_dwordx2 v[200:201], v[146:147], off offset:64
	global_load_dwordx2 v[192:193], v[146:147], off offset:96
	v_or_b32_e32 v146, 16, v144
	v_ashrrev_i32_e32 v147, 31, v146
	v_lshlrev_b64 v[188:189], 12, v[146:147]
	v_lshl_add_u64 v[154:155], v[146:147], 2, s[6:7]
	v_lshlrev_b64 v[156:157], 5, v[146:147]
	v_lshl_add_u64 v[146:147], v[142:143], 0, v[188:189]
	v_lshl_add_u64 v[156:157], s[28:29], 0, v[156:157]
	global_load_dword v195, v[154:155], off
	global_load_dwordx2 v[172:173], v[156:157], off
	global_load_dwordx2 v[186:187], v[146:147], off
	global_load_dwordx2 v[182:183], v[146:147], off offset:32
	global_load_dwordx2 v[180:181], v[146:147], off offset:64
	global_load_dwordx2 v[178:179], v[146:147], off offset:96
	v_or_b32_e32 v146, 32, v144
	v_ashrrev_i32_e32 v147, 31, v146
	v_lshl_add_u64 v[154:155], v[146:147], 2, s[6:7]
	v_lshlrev_b64 v[156:157], 5, v[146:147]
	v_lshl_add_u64 v[156:157], s[28:29], 0, v[156:157]
	global_load_dword v152, v[154:155], off
	global_load_dwordx2 v[160:161], v[156:157], off
	v_or_b32_e32 v154, 48, v144
	v_lshlrev_b64 v[176:177], 12, v[146:147]
	v_ashrrev_i32_e32 v155, 31, v154
	v_lshl_add_u64 v[146:147], v[142:143], 0, v[176:177]
	v_lshlrev_b64 v[156:157], 5, v[154:155]
	v_lshlrev_b64 v[164:165], 12, v[154:155]
	global_load_dwordx2 v[174:175], v[146:147], off
	global_load_dwordx2 v[170:171], v[146:147], off offset:32
	global_load_dwordx2 v[168:169], v[146:147], off offset:64
	global_load_dwordx2 v[166:167], v[146:147], off offset:96
	v_lshl_add_u64 v[146:147], v[154:155], 2, s[6:7]
	v_lshl_add_u64 v[156:157], s[28:29], 0, v[156:157]
	v_lshl_add_u64 v[154:155], v[142:143], 0, v[164:165]
	global_load_dword v145, v[146:147], off
	s_nop 0
	global_load_dwordx2 v[146:147], v[156:157], off
	global_load_dwordx2 v[162:163], v[154:155], off
	global_load_dwordx2 v[158:159], v[154:155], off offset:32
	s_nop 0
	global_load_dwordx2 v[156:157], v[154:155], off offset:64
	s_nop 0
	global_load_dwordx2 v[154:155], v[154:155], off offset:96
	v_readlane_b32 s37, v254, 7
	v_readlane_b32 s38, v254, 8
	v_readlane_b32 s39, v254, 9
	v_readlane_b32 s40, v254, 10
	v_readlane_b32 s41, v254, 11
	v_readlane_b32 s42, v254, 12
	v_readlane_b32 s43, v254, 13
	v_readlane_b32 s46, v254, 16
	v_readlane_b32 s47, v254, 17
	v_readlane_b32 s48, v254, 18
	v_readlane_b32 s49, v254, 19
	v_readlane_b32 s50, v254, 20
	v_readlane_b32 s51, v254, 21
	v_lshl_add_u64 v[140:141], s[8:9], 0, v[140:141]
	s_waitcnt vmcnt(23)
	v_mul_f32_e32 v148, v148, v202
	v_mul_f32_e32 v205, 0xbfb8aa3b, v148
	v_exp_f32_e32 v205, v205
	v_mul_f32_e32 v149, v149, v202
	v_mul_f32_e32 v206, 0xbfb8aa3b, v149
	v_exp_f32_e32 v206, v206
	v_add_f32_e32 v205, 1.0, v205
	v_rcp_f32_e32 v205, v205
	s_waitcnt vmcnt(21)
	v_lshlrev_b32_e32 v203, 16, v196
	v_mul_f32_e32 v150, v150, v202
	v_sub_f32_e32 v203, v203, v184
	v_mul_f32_e32 v148, v148, v205
	v_add_f32_e32 v205, 1.0, v206
	v_rcp_f32_e32 v205, v205
	v_mul_f32_e32 v148, v148, v203
	v_mul_f32_e32 v203, 0xbfb8aa3b, v150
	v_exp_f32_e32 v203, v203
	v_and_b32_e32 v196, 0xffff0000, v196
	v_mul_f32_e32 v151, v151, v202
	v_mul_f32_e32 v149, v149, v205
	v_sub_f32_e32 v196, v196, v184
	v_mul_f32_e32 v149, v149, v196
	v_add_f32_e32 v196, 1.0, v203
	v_mul_f32_e32 v203, 0xbfb8aa3b, v151
	v_exp_f32_e32 v203, v203
	v_rcp_f32_e32 v196, v196
	v_lshlrev_b32_e32 v204, 16, v197
	v_and_b32_e32 v197, 0xffff0000, v197
	v_add_f32_e32 v203, 1.0, v203
	v_rcp_f32_e32 v203, v203
	v_mul_f32_e32 v150, v150, v196
	v_sub_f32_e32 v196, v204, v184
	v_mul_f32_e32 v150, v150, v196
	v_mul_f32_e32 v151, v151, v203
	v_sub_f32_e32 v196, v197, v184
	v_mul_f32_e32 v151, v151, v196
	v_mul_f32_e32 v148, v185, v148
	v_mul_f32_e32 v149, v185, v149
	v_mul_f32_e32 v151, v185, v151
	v_mul_f32_e32 v148, v68, v148
	v_mul_f32_e32 v149, v69, v149
	v_mul_f32_e32 v150, v185, v150
	v_mul_f32_e32 v151, v71, v151
	v_mul_f32_e32 v136, v136, v202
	v_mul_f32_e32 v150, v70, v150
	v_cvt_pk_bf16_f32 v148, v148, v149
	v_cvt_pk_bf16_f32 v149, v150, v151
	v_mul_f32_e32 v151, 0xbfb8aa3b, v136
	v_exp_f32_e32 v151, v151
	v_mul_f32_e32 v137, v137, v202
	v_mul_f32_e32 v197, 0xbfb8aa3b, v137
	v_exp_f32_e32 v197, v197
	v_add_f32_e32 v151, 1.0, v151
	v_rcp_f32_e32 v151, v151
	v_lshl_add_u64 v[190:191], v[140:141], 0, v[190:191]
	global_store_dwordx2 v[190:191], v[148:149], off
	s_waitcnt vmcnt(21)
	v_lshlrev_b32_e32 v148, 16, v198
	v_mul_f32_e32 v136, v136, v151
	v_add_f32_e32 v151, 1.0, v197
	v_rcp_f32_e32 v151, v151
	v_and_b32_e32 v149, 0xffff0000, v198
	v_mul_f32_e32 v138, v138, v202
	v_sub_f32_e32 v148, v148, v184
	v_mul_f32_e32 v139, v139, v202
	v_mul_f32_e32 v136, v136, v148
	v_mul_f32_e32 v137, v137, v151
	v_mul_f32_e32 v148, 0xbfb8aa3b, v138
	v_sub_f32_e32 v149, v149, v184
	v_exp_f32_e32 v148, v148
	v_mul_f32_e32 v137, v137, v149
	v_mul_f32_e32 v149, 0xbfb8aa3b, v139
	v_exp_f32_e32 v149, v149
	v_add_f32_e32 v148, 1.0, v148
	v_rcp_f32_e32 v148, v148
	v_lshlrev_b32_e32 v150, 16, v199
	v_add_f32_e32 v149, 1.0, v149
	v_rcp_f32_e32 v149, v149
	v_and_b32_e32 v196, 0xffff0000, v199
	v_mul_f32_e32 v138, v138, v148
	v_sub_f32_e32 v148, v150, v184
	v_mul_f32_e32 v138, v138, v148
	v_mul_f32_e32 v139, v139, v149
	v_sub_f32_e32 v148, v196, v184
	v_mul_f32_e32 v139, v139, v148
	v_mul_f32_e32 v136, v185, v136
	v_mul_f32_e32 v137, v185, v137
	v_mul_f32_e32 v139, v185, v139
	v_mul_f32_e32 v136, v60, v136
	v_mul_f32_e32 v137, v61, v137
	v_mul_f32_e32 v138, v185, v138
	v_mul_f32_e32 v139, v63, v139
	v_mul_f32_e32 v132, v132, v202
	v_mul_f32_e32 v138, v62, v138
	v_cvt_pk_bf16_f32 v136, v136, v137
	v_cvt_pk_bf16_f32 v137, v138, v139
	v_mul_f32_e32 v139, 0xbfb8aa3b, v132
	v_exp_f32_e32 v139, v139
	v_mul_f32_e32 v133, v133, v202
	v_mul_f32_e32 v149, 0xbfb8aa3b, v133
	v_exp_f32_e32 v149, v149
	v_add_f32_e32 v139, 1.0, v139
	v_rcp_f32_e32 v139, v139
	global_store_dwordx2 v[190:191], v[136:137], off offset:32
	s_waitcnt vmcnt(21)
	v_lshlrev_b32_e32 v136, 16, v200
	v_and_b32_e32 v137, 0xffff0000, v200
	v_mul_f32_e32 v132, v132, v139
	v_add_f32_e32 v139, 1.0, v149
	v_rcp_f32_e32 v139, v139
	v_mul_f32_e32 v134, v134, v202
	v_sub_f32_e32 v136, v136, v184
	v_mul_f32_e32 v135, v135, v202
	v_mul_f32_e32 v132, v132, v136
	v_mul_f32_e32 v133, v133, v139
	v_mul_f32_e32 v136, 0xbfb8aa3b, v134
	v_sub_f32_e32 v137, v137, v184
	v_exp_f32_e32 v136, v136
	v_mul_f32_e32 v133, v133, v137
	v_mul_f32_e32 v137, 0xbfb8aa3b, v135
	v_exp_f32_e32 v137, v137
	v_add_f32_e32 v136, 1.0, v136
	v_rcp_f32_e32 v136, v136
	v_lshlrev_b32_e32 v138, 16, v201
	v_add_f32_e32 v137, 1.0, v137
	v_rcp_f32_e32 v137, v137
	v_and_b32_e32 v148, 0xffff0000, v201
	v_mul_f32_e32 v134, v134, v136
	v_sub_f32_e32 v136, v138, v184
	v_mul_f32_e32 v134, v134, v136
	v_mul_f32_e32 v135, v135, v137
	v_sub_f32_e32 v136, v148, v184
	v_mul_f32_e32 v135, v135, v136
	v_mul_f32_e32 v132, v185, v132
	v_mul_f32_e32 v133, v185, v133
	v_mul_f32_e32 v135, v185, v135
	v_mul_f32_e32 v132, v52, v132
	v_mul_f32_e32 v133, v53, v133
	v_mul_f32_e32 v134, v185, v134
	v_mul_f32_e32 v135, v55, v135
	v_mul_f32_e32 v128, v128, v202
	v_mul_f32_e32 v134, v54, v134
	v_cvt_pk_bf16_f32 v132, v132, v133
	v_cvt_pk_bf16_f32 v133, v134, v135
	v_mul_f32_e32 v135, 0xbfb8aa3b, v128
	v_exp_f32_e32 v135, v135
	v_mul_f32_e32 v129, v129, v202
	v_mul_f32_e32 v137, 0xbfb8aa3b, v129
	v_exp_f32_e32 v137, v137
	v_add_f32_e32 v135, 1.0, v135
	v_rcp_f32_e32 v135, v135
	global_store_dwordx2 v[190:191], v[132:133], off offset:64
	s_waitcnt vmcnt(21)
	v_and_b32_e32 v133, 0xffff0000, v192
	v_mul_f32_e32 v131, v131, v202
	v_mul_f32_e32 v128, v128, v135
	v_add_f32_e32 v135, 1.0, v137
	v_rcp_f32_e32 v135, v135
	v_sub_f32_e32 v133, v133, v184
	v_lshlrev_b32_e32 v132, 16, v192
	v_mul_f32_e32 v130, v130, v202
	v_mul_f32_e32 v129, v129, v135
	v_mul_f32_e32 v129, v129, v133
	v_mul_f32_e32 v133, 0xbfb8aa3b, v131
	v_exp_f32_e32 v133, v133
	v_sub_f32_e32 v132, v132, v184
	v_mul_f32_e32 v128, v128, v132
	v_mul_f32_e32 v132, 0xbfb8aa3b, v130
	v_add_f32_e32 v133, 1.0, v133
	v_rcp_f32_e32 v133, v133
	s_waitcnt vmcnt(20)
	v_mul_f32_e32 v124, v124, v195
	v_exp_f32_e32 v132, v132
	v_mul_f32_e32 v125, v125, v195
	v_mul_f32_e32 v131, v131, v133
	v_mul_f32_e32 v133, 0xbfb8aa3b, v124
	v_exp_f32_e32 v133, v133
	v_add_f32_e32 v132, 1.0, v132
	v_rcp_f32_e32 v132, v132
	v_mul_f32_e32 v135, 0xbfb8aa3b, v125
	v_add_f32_e32 v133, 1.0, v133
	v_rcp_f32_e32 v133, v133
	v_exp_f32_e32 v135, v135
	v_lshlrev_b32_e32 v134, 16, v193
	v_and_b32_e32 v136, 0xffff0000, v193
	v_mul_f32_e32 v130, v130, v132
	v_sub_f32_e32 v132, v134, v184
	v_mul_f32_e32 v130, v130, v132
	v_sub_f32_e32 v132, v136, v184
	v_mul_f32_e32 v124, v124, v133
	v_add_f32_e32 v133, 1.0, v135
	v_mul_f32_e32 v128, v185, v128
	v_mul_f32_e32 v129, v185, v129
	v_mul_f32_e32 v130, v185, v130
	v_mul_f32_e32 v131, v131, v132
	v_rcp_f32_e32 v133, v133
	v_mul_f32_e32 v128, v44, v128
	v_mul_f32_e32 v129, v45, v129
	v_mul_f32_e32 v130, v46, v130
	v_mul_f32_e32 v131, v185, v131
	v_mul_f32_e32 v131, v47, v131
	v_cvt_pk_bf16_f32 v128, v128, v129
	v_cvt_pk_bf16_f32 v129, v130, v131
	s_waitcnt vmcnt(18)
	v_lshlrev_b32_e32 v130, 16, v186
	v_and_b32_e32 v131, 0xffff0000, v186
	v_mul_f32_e32 v126, v126, v195
	v_sub_f32_e32 v130, v130, v172
	v_mul_f32_e32 v127, v127, v195
	v_mul_f32_e32 v124, v124, v130
	v_mul_f32_e32 v125, v125, v133
	v_mul_f32_e32 v130, 0xbfb8aa3b, v126
	v_sub_f32_e32 v131, v131, v172
	v_exp_f32_e32 v130, v130
	v_mul_f32_e32 v125, v125, v131
	v_mul_f32_e32 v131, 0xbfb8aa3b, v127
	v_exp_f32_e32 v131, v131
	v_add_f32_e32 v130, 1.0, v130
	v_rcp_f32_e32 v130, v130
	v_lshlrev_b32_e32 v132, 16, v187
	v_add_f32_e32 v131, 1.0, v131
	v_rcp_f32_e32 v131, v131
	v_and_b32_e32 v134, 0xffff0000, v187
	v_mul_f32_e32 v126, v126, v130
	v_sub_f32_e32 v130, v132, v172
	v_mul_f32_e32 v126, v126, v130
	v_mul_f32_e32 v127, v127, v131
	v_sub_f32_e32 v130, v134, v172
	v_mul_f32_e32 v127, v127, v130
	v_mul_f32_e32 v124, v173, v124
	v_mul_f32_e32 v125, v173, v125
	v_mul_f32_e32 v127, v173, v127
	v_mul_f32_e32 v124, v68, v124
	v_mul_f32_e32 v125, v69, v125
	v_mul_f32_e32 v126, v173, v126
	v_mul_f32_e32 v127, v71, v127
	v_mul_f32_e32 v120, v120, v195
	v_mul_f32_e32 v126, v70, v126
	v_cvt_pk_bf16_f32 v124, v124, v125
	v_cvt_pk_bf16_f32 v125, v126, v127
	v_mul_f32_e32 v127, 0xbfb8aa3b, v120
	v_exp_f32_e32 v127, v127
	v_mul_f32_e32 v121, v121, v195
	v_mul_f32_e32 v131, 0xbfb8aa3b, v121
	v_exp_f32_e32 v131, v131
	v_add_f32_e32 v127, 1.0, v127
	v_rcp_f32_e32 v127, v127
	global_store_dwordx2 v[190:191], v[128:129], off offset:96
	v_lshl_add_u64 v[128:129], v[140:141], 0, v[188:189]
	global_store_dwordx2 v[128:129], v[124:125], off
	v_mul_f32_e32 v120, v120, v127
	v_add_f32_e32 v127, 1.0, v131
	v_rcp_f32_e32 v127, v127
	s_waitcnt vmcnt(19)
	v_lshlrev_b32_e32 v124, 16, v182
	v_and_b32_e32 v125, 0xffff0000, v182
	v_mul_f32_e32 v122, v122, v195
	v_sub_f32_e32 v124, v124, v172
	v_mul_f32_e32 v123, v123, v195
	v_mul_f32_e32 v120, v120, v124
	v_mul_f32_e32 v121, v121, v127
	v_mul_f32_e32 v124, 0xbfb8aa3b, v122
	v_sub_f32_e32 v125, v125, v172
	v_exp_f32_e32 v124, v124
	v_mul_f32_e32 v121, v121, v125
	v_mul_f32_e32 v125, 0xbfb8aa3b, v123
	v_exp_f32_e32 v125, v125
	v_add_f32_e32 v124, 1.0, v124
	v_rcp_f32_e32 v124, v124
	v_lshlrev_b32_e32 v126, 16, v183
	v_add_f32_e32 v125, 1.0, v125
	v_rcp_f32_e32 v125, v125
	v_and_b32_e32 v130, 0xffff0000, v183
	v_mul_f32_e32 v122, v122, v124
	v_sub_f32_e32 v124, v126, v172
	v_mul_f32_e32 v122, v122, v124
	v_mul_f32_e32 v123, v123, v125
	v_sub_f32_e32 v124, v130, v172
	v_mul_f32_e32 v123, v123, v124
	v_mul_f32_e32 v120, v173, v120
	v_mul_f32_e32 v121, v173, v121
	v_mul_f32_e32 v123, v173, v123
	v_mul_f32_e32 v120, v60, v120
	v_mul_f32_e32 v121, v61, v121
	v_mul_f32_e32 v122, v173, v122
	v_mul_f32_e32 v123, v63, v123
	v_mul_f32_e32 v116, v116, v195
	v_mul_f32_e32 v122, v62, v122
	v_cvt_pk_bf16_f32 v120, v120, v121
	v_cvt_pk_bf16_f32 v121, v122, v123
	v_mul_f32_e32 v123, 0xbfb8aa3b, v116
	v_exp_f32_e32 v123, v123
	v_mul_f32_e32 v117, v117, v195
	v_mul_f32_e32 v125, 0xbfb8aa3b, v117
	v_exp_f32_e32 v125, v125
	v_add_f32_e32 v123, 1.0, v123
	v_rcp_f32_e32 v123, v123
	global_store_dwordx2 v[128:129], v[120:121], off offset:32
	s_waitcnt vmcnt(19)
	v_lshlrev_b32_e32 v120, 16, v180
	v_and_b32_e32 v121, 0xffff0000, v180
	v_mul_f32_e32 v116, v116, v123
	v_add_f32_e32 v123, 1.0, v125
	v_rcp_f32_e32 v123, v123
	v_mul_f32_e32 v118, v118, v195
	v_sub_f32_e32 v120, v120, v172
	v_mul_f32_e32 v119, v119, v195
	v_mul_f32_e32 v116, v116, v120
	v_mul_f32_e32 v117, v117, v123
	v_mul_f32_e32 v120, 0xbfb8aa3b, v118
	v_sub_f32_e32 v121, v121, v172
	v_exp_f32_e32 v120, v120
	v_mul_f32_e32 v117, v117, v121
	v_mul_f32_e32 v121, 0xbfb8aa3b, v119
	v_exp_f32_e32 v121, v121
	v_add_f32_e32 v120, 1.0, v120
	v_rcp_f32_e32 v120, v120
	v_lshlrev_b32_e32 v122, 16, v181
	v_add_f32_e32 v121, 1.0, v121
	v_rcp_f32_e32 v121, v121
	v_and_b32_e32 v124, 0xffff0000, v181
	v_mul_f32_e32 v118, v118, v120
	v_sub_f32_e32 v120, v122, v172
	v_mul_f32_e32 v118, v118, v120
	v_mul_f32_e32 v119, v119, v121
	v_sub_f32_e32 v120, v124, v172
	v_mul_f32_e32 v119, v119, v120
	v_mul_f32_e32 v116, v173, v116
	v_mul_f32_e32 v117, v173, v117
	v_mul_f32_e32 v119, v173, v119
	v_mul_f32_e32 v116, v52, v116
	v_mul_f32_e32 v117, v53, v117
	v_mul_f32_e32 v118, v173, v118
	v_mul_f32_e32 v119, v55, v119
	v_mul_f32_e32 v112, v112, v195
	v_mul_f32_e32 v118, v54, v118
	v_cvt_pk_bf16_f32 v116, v116, v117
	v_cvt_pk_bf16_f32 v117, v118, v119
	v_mul_f32_e32 v119, 0xbfb8aa3b, v112
	v_exp_f32_e32 v119, v119
	v_mul_f32_e32 v113, v113, v195
	v_mul_f32_e32 v121, 0xbfb8aa3b, v113
	v_exp_f32_e32 v121, v121
	v_add_f32_e32 v119, 1.0, v119
	v_rcp_f32_e32 v119, v119
	global_store_dwordx2 v[128:129], v[116:117], off offset:64
	s_waitcnt vmcnt(19)
	v_and_b32_e32 v117, 0xffff0000, v178
	v_mul_f32_e32 v115, v115, v195
	v_mul_f32_e32 v112, v112, v119
	v_add_f32_e32 v119, 1.0, v121
	v_rcp_f32_e32 v119, v119
	v_sub_f32_e32 v117, v117, v172
	v_lshlrev_b32_e32 v116, 16, v178
	v_mul_f32_e32 v114, v114, v195
	v_mul_f32_e32 v113, v113, v119
	v_mul_f32_e32 v113, v113, v117
	v_mul_f32_e32 v117, 0xbfb8aa3b, v115
	v_exp_f32_e32 v117, v117
	v_sub_f32_e32 v116, v116, v172
	v_mul_f32_e32 v112, v112, v116
	v_mul_f32_e32 v116, 0xbfb8aa3b, v114
	v_add_f32_e32 v117, 1.0, v117
	v_rcp_f32_e32 v117, v117
	s_waitcnt vmcnt(18)
	v_mul_f32_e32 v108, v108, v152
	v_exp_f32_e32 v116, v116
	v_mul_f32_e32 v109, v109, v152
	v_mul_f32_e32 v115, v115, v117
	v_mul_f32_e32 v117, 0xbfb8aa3b, v108
	v_exp_f32_e32 v117, v117
	v_add_f32_e32 v116, 1.0, v116
	v_rcp_f32_e32 v116, v116
	v_mul_f32_e32 v119, 0xbfb8aa3b, v109
	v_add_f32_e32 v117, 1.0, v117
	v_rcp_f32_e32 v117, v117
	v_exp_f32_e32 v119, v119
	v_lshlrev_b32_e32 v118, 16, v179
	v_and_b32_e32 v120, 0xffff0000, v179
	v_mul_f32_e32 v114, v114, v116
	v_sub_f32_e32 v116, v118, v172
	v_mul_f32_e32 v114, v114, v116
	v_sub_f32_e32 v116, v120, v172
	v_mul_f32_e32 v108, v108, v117
	v_add_f32_e32 v117, 1.0, v119
	v_mul_f32_e32 v112, v173, v112
	v_mul_f32_e32 v113, v173, v113
	v_mul_f32_e32 v114, v173, v114
	v_mul_f32_e32 v115, v115, v116
	v_rcp_f32_e32 v117, v117
	v_mul_f32_e32 v112, v44, v112
	v_mul_f32_e32 v113, v45, v113
	v_mul_f32_e32 v114, v46, v114
	v_mul_f32_e32 v115, v173, v115
	v_mul_f32_e32 v115, v47, v115
	v_cvt_pk_bf16_f32 v112, v112, v113
	v_cvt_pk_bf16_f32 v113, v114, v115
	s_waitcnt vmcnt(16)
	v_lshlrev_b32_e32 v114, 16, v174
	v_and_b32_e32 v115, 0xffff0000, v174
	v_mul_f32_e32 v110, v110, v152
	v_sub_f32_e32 v114, v114, v160
	v_mul_f32_e32 v111, v111, v152
	v_mul_f32_e32 v108, v108, v114
	v_mul_f32_e32 v109, v109, v117
	v_mul_f32_e32 v114, 0xbfb8aa3b, v110
	v_sub_f32_e32 v115, v115, v160
	v_exp_f32_e32 v114, v114
	v_mul_f32_e32 v109, v109, v115
	v_mul_f32_e32 v115, 0xbfb8aa3b, v111
	v_exp_f32_e32 v115, v115
	v_add_f32_e32 v114, 1.0, v114
	v_rcp_f32_e32 v114, v114
	v_lshlrev_b32_e32 v116, 16, v175
	v_add_f32_e32 v115, 1.0, v115
	v_rcp_f32_e32 v115, v115
	v_and_b32_e32 v118, 0xffff0000, v175
	v_mul_f32_e32 v110, v110, v114
	v_sub_f32_e32 v114, v116, v160
	v_mul_f32_e32 v110, v110, v114
	v_mul_f32_e32 v111, v111, v115
	v_sub_f32_e32 v114, v118, v160
	v_mul_f32_e32 v111, v111, v114
	v_mul_f32_e32 v108, v161, v108
	v_mul_f32_e32 v109, v161, v109
	v_mul_f32_e32 v111, v161, v111
	v_mul_f32_e32 v108, v68, v108
	v_mul_f32_e32 v109, v69, v109
	v_mul_f32_e32 v110, v161, v110
	v_mul_f32_e32 v111, v71, v111
	v_mul_f32_e32 v104, v104, v152
	v_mul_f32_e32 v110, v70, v110
	v_cvt_pk_bf16_f32 v108, v108, v109
	v_cvt_pk_bf16_f32 v109, v110, v111
	v_mul_f32_e32 v111, 0xbfb8aa3b, v104
	v_exp_f32_e32 v111, v111
	v_mul_f32_e32 v105, v105, v152
	v_mul_f32_e32 v115, 0xbfb8aa3b, v105
	v_exp_f32_e32 v115, v115
	v_add_f32_e32 v111, 1.0, v111
	v_rcp_f32_e32 v111, v111
	global_store_dwordx2 v[128:129], v[112:113], off offset:96
	v_lshl_add_u64 v[112:113], v[140:141], 0, v[176:177]
	global_store_dwordx2 v[112:113], v[108:109], off
	v_mul_f32_e32 v104, v104, v111
	v_add_f32_e32 v111, 1.0, v115
	v_rcp_f32_e32 v111, v111
	s_waitcnt vmcnt(17)
	v_lshlrev_b32_e32 v108, 16, v170
	v_and_b32_e32 v109, 0xffff0000, v170
	v_mul_f32_e32 v106, v106, v152
	v_sub_f32_e32 v108, v108, v160
	v_mul_f32_e32 v107, v107, v152
	v_mul_f32_e32 v104, v104, v108
	v_mul_f32_e32 v105, v105, v111
	v_mul_f32_e32 v108, 0xbfb8aa3b, v106
	v_sub_f32_e32 v109, v109, v160
	v_exp_f32_e32 v108, v108
	v_mul_f32_e32 v105, v105, v109
	v_mul_f32_e32 v109, 0xbfb8aa3b, v107
	v_exp_f32_e32 v109, v109
	v_add_f32_e32 v108, 1.0, v108
	v_rcp_f32_e32 v108, v108
	v_lshlrev_b32_e32 v110, 16, v171
	v_add_f32_e32 v109, 1.0, v109
	v_rcp_f32_e32 v109, v109
	v_and_b32_e32 v114, 0xffff0000, v171
	v_mul_f32_e32 v106, v106, v108
	v_sub_f32_e32 v108, v110, v160
	v_mul_f32_e32 v106, v106, v108
	v_mul_f32_e32 v107, v107, v109
	v_sub_f32_e32 v108, v114, v160
	v_mul_f32_e32 v107, v107, v108
	v_mul_f32_e32 v104, v161, v104
	v_mul_f32_e32 v105, v161, v105
	v_mul_f32_e32 v107, v161, v107
	v_mul_f32_e32 v104, v60, v104
	v_mul_f32_e32 v105, v61, v105
	v_mul_f32_e32 v106, v161, v106
	v_mul_f32_e32 v107, v63, v107
	v_mul_f32_e32 v100, v100, v152
	v_mul_f32_e32 v106, v62, v106
	v_cvt_pk_bf16_f32 v104, v104, v105
	v_cvt_pk_bf16_f32 v105, v106, v107
	v_mul_f32_e32 v107, 0xbfb8aa3b, v100
	v_exp_f32_e32 v107, v107
	v_mul_f32_e32 v101, v101, v152
	v_mul_f32_e32 v109, 0xbfb8aa3b, v101
	v_exp_f32_e32 v109, v109
	v_add_f32_e32 v107, 1.0, v107
	v_rcp_f32_e32 v107, v107
	global_store_dwordx2 v[112:113], v[104:105], off offset:32
	s_waitcnt vmcnt(17)
	v_lshlrev_b32_e32 v104, 16, v168
	v_and_b32_e32 v105, 0xffff0000, v168
	v_mul_f32_e32 v100, v100, v107
	v_add_f32_e32 v107, 1.0, v109
	v_rcp_f32_e32 v107, v107
	v_mul_f32_e32 v102, v102, v152
	v_sub_f32_e32 v104, v104, v160
	v_mul_f32_e32 v103, v103, v152
	v_mul_f32_e32 v100, v100, v104
	v_mul_f32_e32 v101, v101, v107
	v_mul_f32_e32 v104, 0xbfb8aa3b, v102
	v_sub_f32_e32 v105, v105, v160
	v_exp_f32_e32 v104, v104
	v_mul_f32_e32 v101, v101, v105
	v_mul_f32_e32 v105, 0xbfb8aa3b, v103
	v_exp_f32_e32 v105, v105
	v_add_f32_e32 v104, 1.0, v104
	v_rcp_f32_e32 v104, v104
	v_lshlrev_b32_e32 v106, 16, v169
	v_add_f32_e32 v105, 1.0, v105
	v_rcp_f32_e32 v105, v105
	v_and_b32_e32 v108, 0xffff0000, v169
	v_mul_f32_e32 v102, v102, v104
	v_sub_f32_e32 v104, v106, v160
	v_mul_f32_e32 v102, v102, v104
	v_mul_f32_e32 v103, v103, v105
	v_sub_f32_e32 v104, v108, v160
	v_mul_f32_e32 v103, v103, v104
	v_mul_f32_e32 v100, v161, v100
	v_mul_f32_e32 v101, v161, v101
	v_mul_f32_e32 v103, v161, v103
	v_mul_f32_e32 v100, v52, v100
	v_mul_f32_e32 v101, v53, v101
	v_mul_f32_e32 v102, v161, v102
	v_mul_f32_e32 v103, v55, v103
	v_mul_f32_e32 v96, v96, v152
	v_mul_f32_e32 v102, v54, v102
	v_cvt_pk_bf16_f32 v100, v100, v101
	v_cvt_pk_bf16_f32 v101, v102, v103
	v_mul_f32_e32 v103, 0xbfb8aa3b, v96
	v_exp_f32_e32 v103, v103
	v_mul_f32_e32 v97, v97, v152
	v_mul_f32_e32 v105, 0xbfb8aa3b, v97
	v_exp_f32_e32 v105, v105
	v_add_f32_e32 v103, 1.0, v103
	v_rcp_f32_e32 v103, v103
	global_store_dwordx2 v[112:113], v[100:101], off offset:64
	s_waitcnt vmcnt(17)
	v_and_b32_e32 v101, 0xffff0000, v166
	v_mul_f32_e32 v99, v99, v152
	v_mul_f32_e32 v96, v96, v103
	v_add_f32_e32 v103, 1.0, v105
	v_rcp_f32_e32 v103, v103
	v_sub_f32_e32 v101, v101, v160
	v_lshlrev_b32_e32 v100, 16, v166
	v_mul_f32_e32 v98, v98, v152
	v_mul_f32_e32 v97, v97, v103
	v_mul_f32_e32 v97, v97, v101
	v_mul_f32_e32 v101, 0xbfb8aa3b, v99
	v_exp_f32_e32 v101, v101
	v_sub_f32_e32 v100, v100, v160
	v_mul_f32_e32 v96, v96, v100
	v_mul_f32_e32 v100, 0xbfb8aa3b, v98
	v_add_f32_e32 v101, 1.0, v101
	v_rcp_f32_e32 v101, v101
	s_waitcnt vmcnt(16)
	v_mul_f32_e32 v92, v92, v145
	v_exp_f32_e32 v100, v100
	v_mul_f32_e32 v93, v93, v145
	v_mul_f32_e32 v99, v99, v101
	v_mul_f32_e32 v101, 0xbfb8aa3b, v92
	v_exp_f32_e32 v101, v101
	v_add_f32_e32 v100, 1.0, v100
	v_rcp_f32_e32 v100, v100
	v_mul_f32_e32 v103, 0xbfb8aa3b, v93
	v_add_f32_e32 v101, 1.0, v101
	v_rcp_f32_e32 v101, v101
	v_exp_f32_e32 v103, v103
	v_lshlrev_b32_e32 v102, 16, v167
	v_and_b32_e32 v104, 0xffff0000, v167
	v_mul_f32_e32 v98, v98, v100
	v_sub_f32_e32 v100, v102, v160
	v_mul_f32_e32 v98, v98, v100
	v_sub_f32_e32 v100, v104, v160
	v_mul_f32_e32 v92, v92, v101
	v_add_f32_e32 v101, 1.0, v103
	v_mul_f32_e32 v96, v161, v96
	v_mul_f32_e32 v97, v161, v97
	v_mul_f32_e32 v98, v161, v98
	v_mul_f32_e32 v99, v99, v100
	v_rcp_f32_e32 v101, v101
	v_mul_f32_e32 v96, v44, v96
	v_mul_f32_e32 v97, v45, v97
	v_mul_f32_e32 v98, v46, v98
	v_mul_f32_e32 v99, v161, v99
	v_mul_f32_e32 v99, v47, v99
	v_cvt_pk_bf16_f32 v96, v96, v97
	v_cvt_pk_bf16_f32 v97, v98, v99
	s_waitcnt vmcnt(14)
	v_lshlrev_b32_e32 v98, 16, v162
	v_and_b32_e32 v99, 0xffff0000, v162
	v_mul_f32_e32 v94, v94, v145
	v_sub_f32_e32 v98, v98, v146
	v_mul_f32_e32 v95, v95, v145
	v_mul_f32_e32 v92, v92, v98
	v_mul_f32_e32 v93, v93, v101
	v_mul_f32_e32 v98, 0xbfb8aa3b, v94
	v_sub_f32_e32 v99, v99, v146
	v_exp_f32_e32 v98, v98
	v_mul_f32_e32 v93, v93, v99
	v_mul_f32_e32 v99, 0xbfb8aa3b, v95
	v_exp_f32_e32 v99, v99
	v_add_f32_e32 v98, 1.0, v98
	v_rcp_f32_e32 v98, v98
	v_lshlrev_b32_e32 v100, 16, v163
	v_add_f32_e32 v99, 1.0, v99
	v_rcp_f32_e32 v99, v99
	v_and_b32_e32 v102, 0xffff0000, v163
	v_mul_f32_e32 v94, v94, v98
	v_sub_f32_e32 v98, v100, v146
	v_mul_f32_e32 v94, v94, v98
	v_mul_f32_e32 v95, v95, v99
	v_sub_f32_e32 v98, v102, v146
	v_mul_f32_e32 v95, v95, v98
	v_mul_f32_e32 v92, v147, v92
	v_mul_f32_e32 v93, v147, v93
	v_mul_f32_e32 v95, v147, v95
	v_mul_f32_e32 v92, v68, v92
	v_mul_f32_e32 v93, v69, v93
	v_mul_f32_e32 v94, v147, v94
	v_mul_f32_e32 v95, v71, v95
	v_mul_f32_e32 v88, v88, v145
	v_mul_f32_e32 v94, v70, v94
	v_cvt_pk_bf16_f32 v92, v92, v93
	v_cvt_pk_bf16_f32 v93, v94, v95
	v_mul_f32_e32 v95, 0xbfb8aa3b, v88
	v_exp_f32_e32 v95, v95
	v_mul_f32_e32 v89, v89, v145
	v_mul_f32_e32 v99, 0xbfb8aa3b, v89
	v_exp_f32_e32 v99, v99
	v_add_f32_e32 v95, 1.0, v95
	v_rcp_f32_e32 v95, v95
	global_store_dwordx2 v[112:113], v[96:97], off offset:96
	v_lshl_add_u64 v[96:97], v[140:141], 0, v[164:165]
	global_store_dwordx2 v[96:97], v[92:93], off
	v_mul_f32_e32 v88, v88, v95
	v_add_f32_e32 v95, 1.0, v99
	v_rcp_f32_e32 v95, v95
	s_waitcnt vmcnt(15)
	v_lshlrev_b32_e32 v92, 16, v158
	v_and_b32_e32 v93, 0xffff0000, v158
	v_mul_f32_e32 v90, v90, v145
	v_sub_f32_e32 v92, v92, v146
	v_mul_f32_e32 v91, v91, v145
	v_mul_f32_e32 v88, v88, v92
	v_mul_f32_e32 v89, v89, v95
	v_mul_f32_e32 v92, 0xbfb8aa3b, v90
	v_sub_f32_e32 v93, v93, v146
	v_exp_f32_e32 v92, v92
	v_mul_f32_e32 v89, v89, v93
	v_mul_f32_e32 v93, 0xbfb8aa3b, v91
	v_exp_f32_e32 v93, v93
	v_add_f32_e32 v92, 1.0, v92
	v_rcp_f32_e32 v92, v92
	v_lshlrev_b32_e32 v94, 16, v159
	v_add_f32_e32 v93, 1.0, v93
	v_rcp_f32_e32 v93, v93
	v_and_b32_e32 v98, 0xffff0000, v159
	v_mul_f32_e32 v90, v90, v92
	v_sub_f32_e32 v92, v94, v146
	v_mul_f32_e32 v90, v90, v92
	v_mul_f32_e32 v91, v91, v93
	v_sub_f32_e32 v92, v98, v146
	v_mul_f32_e32 v91, v91, v92
	v_mul_f32_e32 v88, v147, v88
	v_mul_f32_e32 v89, v147, v89
	v_mul_f32_e32 v91, v147, v91
	v_mul_f32_e32 v88, v60, v88
	v_mul_f32_e32 v89, v61, v89
	v_mul_f32_e32 v90, v147, v90
	v_mul_f32_e32 v91, v63, v91
	v_mul_f32_e32 v84, v84, v145
	v_mul_f32_e32 v90, v62, v90
	v_cvt_pk_bf16_f32 v88, v88, v89
	v_cvt_pk_bf16_f32 v89, v90, v91
	v_mul_f32_e32 v91, 0xbfb8aa3b, v84
	v_exp_f32_e32 v91, v91
	v_mul_f32_e32 v85, v85, v145
	v_mul_f32_e32 v93, 0xbfb8aa3b, v85
	v_exp_f32_e32 v93, v93
	v_add_f32_e32 v91, 1.0, v91
	v_rcp_f32_e32 v91, v91
	global_store_dwordx2 v[96:97], v[88:89], off offset:32
	s_waitcnt vmcnt(15)
	v_lshlrev_b32_e32 v88, 16, v156
	v_and_b32_e32 v89, 0xffff0000, v156
	v_mul_f32_e32 v84, v84, v91
	v_add_f32_e32 v91, 1.0, v93
	v_rcp_f32_e32 v91, v91
	v_mul_f32_e32 v86, v86, v145
	v_sub_f32_e32 v88, v88, v146
	v_mul_f32_e32 v87, v87, v145
	v_mul_f32_e32 v84, v84, v88
	v_mul_f32_e32 v85, v85, v91
	v_mul_f32_e32 v88, 0xbfb8aa3b, v86
	v_sub_f32_e32 v89, v89, v146
	v_exp_f32_e32 v88, v88
	v_mul_f32_e32 v85, v85, v89
	v_mul_f32_e32 v89, 0xbfb8aa3b, v87
	v_exp_f32_e32 v89, v89
	v_add_f32_e32 v88, 1.0, v88
	v_rcp_f32_e32 v88, v88
	v_lshlrev_b32_e32 v90, 16, v157
	v_add_f32_e32 v89, 1.0, v89
	v_rcp_f32_e32 v89, v89
	v_and_b32_e32 v92, 0xffff0000, v157
	v_mul_f32_e32 v86, v86, v88
	v_sub_f32_e32 v88, v90, v146
	v_mul_f32_e32 v86, v86, v88
	v_mul_f32_e32 v87, v87, v89
	v_sub_f32_e32 v88, v92, v146
	v_mul_f32_e32 v87, v87, v88
	v_mul_f32_e32 v84, v147, v84
	v_mul_f32_e32 v85, v147, v85
	v_mul_f32_e32 v87, v147, v87
	v_mul_f32_e32 v84, v52, v84
	v_mul_f32_e32 v85, v53, v85
	v_mul_f32_e32 v86, v147, v86
	v_mul_f32_e32 v87, v55, v87
	v_mul_f32_e32 v80, v80, v145
	v_mul_f32_e32 v86, v54, v86
	v_cvt_pk_bf16_f32 v84, v84, v85
	v_cvt_pk_bf16_f32 v85, v86, v87
	v_mul_f32_e32 v87, 0xbfb8aa3b, v80
	v_exp_f32_e32 v87, v87
	v_mul_f32_e32 v81, v81, v145
	v_mul_f32_e32 v89, 0xbfb8aa3b, v81
	v_exp_f32_e32 v89, v89
	v_add_f32_e32 v87, 1.0, v87
	v_rcp_f32_e32 v87, v87
	global_store_dwordx2 v[96:97], v[84:85], off offset:64
	s_waitcnt vmcnt(15)
	v_lshlrev_b32_e32 v84, 16, v154
	v_and_b32_e32 v85, 0xffff0000, v154
	v_mul_f32_e32 v80, v80, v87
	v_add_f32_e32 v87, 1.0, v89
	v_rcp_f32_e32 v87, v87
	v_mul_f32_e32 v82, v82, v145
	v_sub_f32_e32 v84, v84, v146
	v_mul_f32_e32 v83, v83, v145
	v_mul_f32_e32 v80, v80, v84
	v_mul_f32_e32 v81, v81, v87
	v_mul_f32_e32 v84, 0xbfb8aa3b, v82
	v_sub_f32_e32 v85, v85, v146
	v_exp_f32_e32 v84, v84
	v_mul_f32_e32 v81, v81, v85
	v_mul_f32_e32 v85, 0xbfb8aa3b, v83
	v_exp_f32_e32 v85, v85
	v_add_f32_e32 v84, 1.0, v84
	v_rcp_f32_e32 v84, v84
	v_lshlrev_b32_e32 v86, 16, v155
	v_add_f32_e32 v85, 1.0, v85
	v_rcp_f32_e32 v85, v85
	v_and_b32_e32 v88, 0xffff0000, v155
	v_mul_f32_e32 v82, v82, v84
	v_sub_f32_e32 v84, v86, v146
	v_mul_f32_e32 v82, v82, v84
	v_mul_f32_e32 v83, v83, v85
	v_sub_f32_e32 v84, v88, v146
	v_mul_f32_e32 v80, v147, v80
	v_mul_f32_e32 v81, v147, v81
	v_mul_f32_e32 v83, v83, v84
	v_mul_f32_e32 v80, v44, v80
	v_mul_f32_e32 v81, v45, v81
	v_mul_f32_e32 v82, v147, v82
	v_mul_f32_e32 v83, v147, v83
	v_mul_f32_e32 v82, v46, v82
	v_mul_f32_e32 v83, v47, v83
	v_cvt_pk_bf16_f32 v80, v80, v81
	v_cvt_pk_bf16_f32 v81, v82, v83
	global_store_dwordx2 v[96:97], v[80:81], off offset:96
	v_or_b32_e32 v80, 64, v144
	v_ashrrev_i32_e32 v81, 31, v80
	v_lshlrev_b64 v[118:119], 12, v[80:81]
	v_lshl_add_u64 v[82:83], v[80:81], 2, s[6:7]
	v_lshlrev_b64 v[84:85], 5, v[80:81]
	v_lshl_add_u64 v[80:81], v[142:143], 0, v[118:119]
	v_lshl_add_u64 v[84:85], s[28:29], 0, v[84:85]
	global_load_dword v125, v[82:83], off
	global_load_dwordx2 v[112:113], v[84:85], off
	global_load_dwordx2 v[126:127], v[80:81], off
	global_load_dwordx2 v[128:129], v[80:81], off offset:32
	global_load_dwordx2 v[130:131], v[80:81], off offset:64
	global_load_dwordx2 v[120:121], v[80:81], off offset:96
	v_or_b32_e32 v80, 0x50, v144
	v_ashrrev_i32_e32 v81, 31, v80
	v_lshlrev_b64 v[116:117], 12, v[80:81]
	v_lshl_add_u64 v[82:83], v[80:81], 2, s[6:7]
	v_lshlrev_b64 v[84:85], 5, v[80:81]
	v_lshl_add_u64 v[80:81], v[142:143], 0, v[116:117]
	v_lshl_add_u64 v[84:85], s[28:29], 0, v[84:85]
	global_load_dword v124, v[82:83], off
	global_load_dwordx2 v[100:101], v[84:85], off
	global_load_dwordx2 v[114:115], v[80:81], off
	global_load_dwordx2 v[110:111], v[80:81], off offset:32
	global_load_dwordx2 v[108:109], v[80:81], off offset:64
	global_load_dwordx2 v[106:107], v[80:81], off offset:96
	v_or_b32_e32 v80, 0x60, v144
	v_ashrrev_i32_e32 v81, 31, v80
	v_lshl_add_u64 v[82:83], v[80:81], 2, s[6:7]
	v_lshlrev_b64 v[84:85], 5, v[80:81]
	v_lshl_add_u64 v[84:85], s[28:29], 0, v[84:85]
	global_load_dword v123, v[82:83], off
	global_load_dwordx2 v[88:89], v[84:85], off
	v_or_b32_e32 v82, 0x70, v144
	v_lshlrev_b64 v[104:105], 12, v[80:81]
	v_ashrrev_i32_e32 v83, 31, v82
	v_lshl_add_u64 v[80:81], v[142:143], 0, v[104:105]
	v_lshlrev_b64 v[84:85], 5, v[82:83]
	v_lshlrev_b64 v[92:93], 12, v[82:83]
	global_load_dwordx2 v[102:103], v[80:81], off
	global_load_dwordx2 v[98:99], v[80:81], off offset:32
	global_load_dwordx2 v[96:97], v[80:81], off offset:64
	global_load_dwordx2 v[94:95], v[80:81], off offset:96
	v_lshl_add_u64 v[80:81], v[82:83], 2, s[6:7]
	v_lshl_add_u64 v[84:85], s[28:29], 0, v[84:85]
	v_lshl_add_u64 v[82:83], v[142:143], 0, v[92:93]
	global_load_dword v122, v[80:81], off
	s_nop 0
	global_load_dwordx2 v[80:81], v[84:85], off
	global_load_dwordx2 v[90:91], v[82:83], off
	global_load_dwordx2 v[86:87], v[82:83], off offset:32
	s_nop 0
	global_load_dwordx2 v[84:85], v[82:83], off offset:64
	s_nop 0
	global_load_dwordx2 v[82:83], v[82:83], off offset:96
	s_waitcnt vmcnt(23)
	v_mul_f32_e32 v76, v76, v125
	v_mul_f32_e32 v134, 0xbfb8aa3b, v76
	v_exp_f32_e32 v134, v134
	v_mul_f32_e32 v77, v77, v125
	v_mul_f32_e32 v135, 0xbfb8aa3b, v77
	v_exp_f32_e32 v135, v135
	v_add_f32_e32 v134, 1.0, v134
	v_rcp_f32_e32 v134, v134
	s_waitcnt vmcnt(21)
	v_lshlrev_b32_e32 v132, 16, v126
	v_mul_f32_e32 v78, v78, v125
	v_sub_f32_e32 v132, v132, v112
	v_mul_f32_e32 v76, v76, v134
	v_add_f32_e32 v134, 1.0, v135
	v_rcp_f32_e32 v134, v134
	v_mul_f32_e32 v76, v76, v132
	v_mul_f32_e32 v132, 0xbfb8aa3b, v78
	v_exp_f32_e32 v132, v132
	v_and_b32_e32 v126, 0xffff0000, v126
	v_mul_f32_e32 v79, v79, v125
	v_mul_f32_e32 v77, v77, v134
	v_sub_f32_e32 v126, v126, v112
	v_mul_f32_e32 v77, v77, v126
	v_add_f32_e32 v126, 1.0, v132
	v_mul_f32_e32 v132, 0xbfb8aa3b, v79
	v_exp_f32_e32 v132, v132
	v_rcp_f32_e32 v126, v126
	v_lshlrev_b32_e32 v133, 16, v127
	v_and_b32_e32 v127, 0xffff0000, v127
	v_add_f32_e32 v132, 1.0, v132
	v_rcp_f32_e32 v132, v132
	v_mul_f32_e32 v78, v78, v126
	v_sub_f32_e32 v126, v133, v112
	v_mul_f32_e32 v78, v78, v126
	v_mul_f32_e32 v79, v79, v132
	v_sub_f32_e32 v126, v127, v112
	v_mul_f32_e32 v79, v79, v126
	v_mul_f32_e32 v76, v113, v76
	v_mul_f32_e32 v77, v113, v77
	v_mul_f32_e32 v79, v113, v79
	v_mul_f32_e32 v76, v68, v76
	v_mul_f32_e32 v77, v69, v77
	v_mul_f32_e32 v78, v113, v78
	v_mul_f32_e32 v79, v71, v79
	v_mul_f32_e32 v72, v72, v125
	v_mul_f32_e32 v78, v70, v78
	v_cvt_pk_bf16_f32 v76, v76, v77
	v_cvt_pk_bf16_f32 v77, v78, v79
	v_mul_f32_e32 v79, 0xbfb8aa3b, v72
	v_exp_f32_e32 v79, v79
	v_mul_f32_e32 v73, v73, v125
	v_mul_f32_e32 v127, 0xbfb8aa3b, v73
	v_exp_f32_e32 v127, v127
	v_add_f32_e32 v79, 1.0, v79
	v_rcp_f32_e32 v79, v79
	v_lshl_add_u64 v[118:119], v[140:141], 0, v[118:119]
	global_store_dwordx2 v[118:119], v[76:77], off
	s_waitcnt vmcnt(21)
	v_lshlrev_b32_e32 v76, 16, v128
	v_mul_f32_e32 v72, v72, v79
	v_add_f32_e32 v79, 1.0, v127
	v_rcp_f32_e32 v79, v79
	v_and_b32_e32 v77, 0xffff0000, v128
	v_mul_f32_e32 v74, v74, v125
	v_sub_f32_e32 v76, v76, v112
	v_mul_f32_e32 v75, v75, v125
	v_mul_f32_e32 v72, v72, v76
	v_mul_f32_e32 v73, v73, v79
	v_mul_f32_e32 v76, 0xbfb8aa3b, v74
	v_sub_f32_e32 v77, v77, v112
	v_exp_f32_e32 v76, v76
	v_mul_f32_e32 v73, v73, v77
	v_mul_f32_e32 v77, 0xbfb8aa3b, v75
	v_exp_f32_e32 v77, v77
	v_add_f32_e32 v76, 1.0, v76
	v_rcp_f32_e32 v76, v76
	v_lshlrev_b32_e32 v78, 16, v129
	v_add_f32_e32 v77, 1.0, v77
	v_rcp_f32_e32 v77, v77
	v_and_b32_e32 v126, 0xffff0000, v129
	v_mul_f32_e32 v74, v74, v76
	v_sub_f32_e32 v76, v78, v112
	v_mul_f32_e32 v74, v74, v76
	v_mul_f32_e32 v75, v75, v77
	v_sub_f32_e32 v76, v126, v112
	v_mul_f32_e32 v75, v75, v76
	v_mul_f32_e32 v72, v113, v72
	v_mul_f32_e32 v73, v113, v73
	v_mul_f32_e32 v75, v113, v75
	v_mul_f32_e32 v72, v60, v72
	v_mul_f32_e32 v73, v61, v73
	v_mul_f32_e32 v74, v113, v74
	v_mul_f32_e32 v75, v63, v75
	v_mul_f32_e32 v64, v64, v125
	v_mul_f32_e32 v74, v62, v74
	v_cvt_pk_bf16_f32 v72, v72, v73
	v_cvt_pk_bf16_f32 v73, v74, v75
	v_mul_f32_e32 v75, 0xbfb8aa3b, v64
	v_exp_f32_e32 v75, v75
	v_mul_f32_e32 v65, v65, v125
	v_mul_f32_e32 v77, 0xbfb8aa3b, v65
	v_exp_f32_e32 v77, v77
	v_add_f32_e32 v75, 1.0, v75
	v_rcp_f32_e32 v75, v75
	global_store_dwordx2 v[118:119], v[72:73], off offset:32
	s_waitcnt vmcnt(21)
	v_lshlrev_b32_e32 v72, 16, v130
	v_and_b32_e32 v73, 0xffff0000, v130
	v_mul_f32_e32 v64, v64, v75
	v_add_f32_e32 v75, 1.0, v77
	v_rcp_f32_e32 v75, v75
	v_mul_f32_e32 v66, v66, v125
	v_sub_f32_e32 v72, v72, v112
	v_mul_f32_e32 v67, v67, v125
	v_mul_f32_e32 v64, v64, v72
	v_mul_f32_e32 v65, v65, v75
	v_mul_f32_e32 v72, 0xbfb8aa3b, v66
	v_sub_f32_e32 v73, v73, v112
	v_exp_f32_e32 v72, v72
	v_mul_f32_e32 v65, v65, v73
	v_mul_f32_e32 v73, 0xbfb8aa3b, v67
	v_exp_f32_e32 v73, v73
	v_add_f32_e32 v72, 1.0, v72
	v_rcp_f32_e32 v72, v72
	v_lshlrev_b32_e32 v74, 16, v131
	v_add_f32_e32 v73, 1.0, v73
	v_rcp_f32_e32 v73, v73
	v_and_b32_e32 v76, 0xffff0000, v131
	v_mul_f32_e32 v66, v66, v72
	v_sub_f32_e32 v72, v74, v112
	v_mul_f32_e32 v66, v66, v72
	v_mul_f32_e32 v67, v67, v73
	v_sub_f32_e32 v72, v76, v112
	v_mul_f32_e32 v67, v67, v72
	v_mul_f32_e32 v64, v113, v64
	v_mul_f32_e32 v65, v113, v65
	v_mul_f32_e32 v67, v113, v67
	v_mul_f32_e32 v64, v52, v64
	v_mul_f32_e32 v65, v53, v65
	v_mul_f32_e32 v66, v113, v66
	v_mul_f32_e32 v67, v55, v67
	v_mul_f32_e32 v56, v56, v125
	v_mul_f32_e32 v66, v54, v66
	v_cvt_pk_bf16_f32 v64, v64, v65
	v_cvt_pk_bf16_f32 v65, v66, v67
	v_mul_f32_e32 v67, 0xbfb8aa3b, v56
	v_exp_f32_e32 v67, v67
	v_mul_f32_e32 v57, v57, v125
	v_mul_f32_e32 v73, 0xbfb8aa3b, v57
	v_exp_f32_e32 v73, v73
	v_add_f32_e32 v67, 1.0, v67
	v_rcp_f32_e32 v67, v67
	global_store_dwordx2 v[118:119], v[64:65], off offset:64
	s_waitcnt vmcnt(21)
	v_and_b32_e32 v65, 0xffff0000, v120
	v_mul_f32_e32 v59, v59, v125
	v_mul_f32_e32 v56, v56, v67
	v_add_f32_e32 v67, 1.0, v73
	v_rcp_f32_e32 v67, v67
	v_sub_f32_e32 v65, v65, v112
	v_lshlrev_b32_e32 v64, 16, v120
	v_mul_f32_e32 v58, v58, v125
	v_mul_f32_e32 v57, v57, v67
	v_mul_f32_e32 v57, v57, v65
	v_mul_f32_e32 v65, 0xbfb8aa3b, v59
	v_exp_f32_e32 v65, v65
	v_sub_f32_e32 v64, v64, v112
	v_mul_f32_e32 v56, v56, v64
	v_mul_f32_e32 v64, 0xbfb8aa3b, v58
	v_add_f32_e32 v65, 1.0, v65
	v_rcp_f32_e32 v65, v65
	s_waitcnt vmcnt(20)
	v_mul_f32_e32 v48, v48, v124
	v_exp_f32_e32 v64, v64
	v_mul_f32_e32 v49, v49, v124
	v_mul_f32_e32 v59, v59, v65
	v_mul_f32_e32 v65, 0xbfb8aa3b, v48
	v_exp_f32_e32 v65, v65
	v_add_f32_e32 v64, 1.0, v64
	v_rcp_f32_e32 v64, v64
	v_mul_f32_e32 v67, 0xbfb8aa3b, v49
	v_add_f32_e32 v65, 1.0, v65
	v_rcp_f32_e32 v65, v65
	v_exp_f32_e32 v67, v67
	v_lshlrev_b32_e32 v66, 16, v121
	v_and_b32_e32 v72, 0xffff0000, v121
	v_mul_f32_e32 v58, v58, v64
	v_sub_f32_e32 v64, v66, v112
	v_mul_f32_e32 v58, v58, v64
	v_sub_f32_e32 v64, v72, v112
	v_mul_f32_e32 v48, v48, v65
	v_add_f32_e32 v65, 1.0, v67
	v_mul_f32_e32 v56, v113, v56
	v_mul_f32_e32 v57, v113, v57
	v_mul_f32_e32 v58, v113, v58
	v_mul_f32_e32 v59, v59, v64
	v_rcp_f32_e32 v65, v65
	v_mul_f32_e32 v56, v44, v56
	v_mul_f32_e32 v57, v45, v57
	v_mul_f32_e32 v58, v46, v58
	v_mul_f32_e32 v59, v113, v59
	v_mul_f32_e32 v59, v47, v59
	v_cvt_pk_bf16_f32 v56, v56, v57
	v_cvt_pk_bf16_f32 v57, v58, v59
	s_waitcnt vmcnt(18)
	v_lshlrev_b32_e32 v58, 16, v114
	v_and_b32_e32 v59, 0xffff0000, v114
	v_mul_f32_e32 v50, v50, v124
	v_sub_f32_e32 v58, v58, v100
	v_mul_f32_e32 v51, v51, v124
	v_mul_f32_e32 v48, v48, v58
	v_mul_f32_e32 v49, v49, v65
	v_mul_f32_e32 v58, 0xbfb8aa3b, v50
	v_sub_f32_e32 v59, v59, v100
	v_exp_f32_e32 v58, v58
	v_mul_f32_e32 v49, v49, v59
	v_mul_f32_e32 v59, 0xbfb8aa3b, v51
	v_exp_f32_e32 v59, v59
	v_add_f32_e32 v58, 1.0, v58
	v_rcp_f32_e32 v58, v58
	v_lshlrev_b32_e32 v64, 16, v115
	v_add_f32_e32 v59, 1.0, v59
	v_rcp_f32_e32 v59, v59
	v_and_b32_e32 v66, 0xffff0000, v115
	v_mul_f32_e32 v50, v50, v58
	v_sub_f32_e32 v58, v64, v100
	v_mul_f32_e32 v50, v50, v58
	v_mul_f32_e32 v51, v51, v59
	v_sub_f32_e32 v58, v66, v100
	v_mul_f32_e32 v51, v51, v58
	v_mul_f32_e32 v48, v101, v48
	v_mul_f32_e32 v49, v101, v49
	v_mul_f32_e32 v51, v101, v51
	v_mul_f32_e32 v48, v68, v48
	v_mul_f32_e32 v49, v69, v49
	v_mul_f32_e32 v50, v101, v50
	v_mul_f32_e32 v51, v71, v51
	v_mul_f32_e32 v40, v40, v124
	v_mul_f32_e32 v50, v70, v50
	v_cvt_pk_bf16_f32 v48, v48, v49
	v_cvt_pk_bf16_f32 v49, v50, v51
	v_mul_f32_e32 v51, 0xbfb8aa3b, v40
	v_exp_f32_e32 v51, v51
	v_mul_f32_e32 v41, v41, v124
	v_mul_f32_e32 v59, 0xbfb8aa3b, v41
	v_exp_f32_e32 v59, v59
	v_add_f32_e32 v51, 1.0, v51
	v_rcp_f32_e32 v51, v51
	global_store_dwordx2 v[118:119], v[56:57], off offset:96
	v_lshl_add_u64 v[56:57], v[140:141], 0, v[116:117]
	global_store_dwordx2 v[56:57], v[48:49], off
	v_mul_f32_e32 v40, v40, v51
	v_add_f32_e32 v51, 1.0, v59
	v_rcp_f32_e32 v51, v51
	s_waitcnt vmcnt(19)
	v_lshlrev_b32_e32 v48, 16, v110
	v_and_b32_e32 v49, 0xffff0000, v110
	v_mul_f32_e32 v42, v42, v124
	v_sub_f32_e32 v48, v48, v100
	v_mul_f32_e32 v43, v43, v124
	v_mul_f32_e32 v40, v40, v48
	v_mul_f32_e32 v41, v41, v51
	v_mul_f32_e32 v48, 0xbfb8aa3b, v42
	v_sub_f32_e32 v49, v49, v100
	v_exp_f32_e32 v48, v48
	v_mul_f32_e32 v41, v41, v49
	v_mul_f32_e32 v49, 0xbfb8aa3b, v43
	v_exp_f32_e32 v49, v49
	v_add_f32_e32 v48, 1.0, v48
	v_rcp_f32_e32 v48, v48
	v_lshlrev_b32_e32 v50, 16, v111
	v_add_f32_e32 v49, 1.0, v49
	v_rcp_f32_e32 v49, v49
	v_and_b32_e32 v58, 0xffff0000, v111
	v_mul_f32_e32 v42, v42, v48
	v_sub_f32_e32 v48, v50, v100
	v_mul_f32_e32 v42, v42, v48
	v_mul_f32_e32 v43, v43, v49
	v_sub_f32_e32 v48, v58, v100
	v_mul_f32_e32 v43, v43, v48
	v_mul_f32_e32 v40, v101, v40
	v_mul_f32_e32 v41, v101, v41
	v_mul_f32_e32 v43, v101, v43
	v_mul_f32_e32 v40, v60, v40
	v_mul_f32_e32 v41, v61, v41
	v_mul_f32_e32 v42, v101, v42
	v_mul_f32_e32 v43, v63, v43
	v_mul_f32_e32 v36, v36, v124
	v_mul_f32_e32 v42, v62, v42
	v_cvt_pk_bf16_f32 v40, v40, v41
	v_cvt_pk_bf16_f32 v41, v42, v43
	v_mul_f32_e32 v43, 0xbfb8aa3b, v36
	v_exp_f32_e32 v43, v43
	v_mul_f32_e32 v37, v37, v124
	v_mul_f32_e32 v49, 0xbfb8aa3b, v37
	v_exp_f32_e32 v49, v49
	v_add_f32_e32 v43, 1.0, v43
	v_rcp_f32_e32 v43, v43
	global_store_dwordx2 v[56:57], v[40:41], off offset:32
	s_waitcnt vmcnt(19)
	v_lshlrev_b32_e32 v40, 16, v108
	v_and_b32_e32 v41, 0xffff0000, v108
	v_mul_f32_e32 v36, v36, v43
	v_add_f32_e32 v43, 1.0, v49
	v_rcp_f32_e32 v43, v43
	v_mul_f32_e32 v38, v38, v124
	v_sub_f32_e32 v40, v40, v100
	v_mul_f32_e32 v39, v39, v124
	v_mul_f32_e32 v36, v36, v40
	v_mul_f32_e32 v37, v37, v43
	v_mul_f32_e32 v40, 0xbfb8aa3b, v38
	v_sub_f32_e32 v41, v41, v100
	v_exp_f32_e32 v40, v40
	v_mul_f32_e32 v37, v37, v41
	v_mul_f32_e32 v41, 0xbfb8aa3b, v39
	v_exp_f32_e32 v41, v41
	v_add_f32_e32 v40, 1.0, v40
	v_rcp_f32_e32 v40, v40
	v_lshlrev_b32_e32 v42, 16, v109
	v_add_f32_e32 v41, 1.0, v41
	v_rcp_f32_e32 v41, v41
	v_and_b32_e32 v48, 0xffff0000, v109
	v_mul_f32_e32 v38, v38, v40
	v_sub_f32_e32 v40, v42, v100
	v_mul_f32_e32 v38, v38, v40
	v_mul_f32_e32 v39, v39, v41
	v_sub_f32_e32 v40, v48, v100
	v_mul_f32_e32 v39, v39, v40
	v_mul_f32_e32 v36, v101, v36
	v_mul_f32_e32 v37, v101, v37
	v_mul_f32_e32 v39, v101, v39
	v_mul_f32_e32 v36, v52, v36
	v_mul_f32_e32 v37, v53, v37
	v_mul_f32_e32 v38, v101, v38
	v_mul_f32_e32 v39, v55, v39
	v_mul_f32_e32 v32, v32, v124
	v_mul_f32_e32 v38, v54, v38
	v_cvt_pk_bf16_f32 v36, v36, v37
	v_cvt_pk_bf16_f32 v37, v38, v39
	v_mul_f32_e32 v39, 0xbfb8aa3b, v32
	v_exp_f32_e32 v39, v39
	v_mul_f32_e32 v33, v33, v124
	v_mul_f32_e32 v41, 0xbfb8aa3b, v33
	v_exp_f32_e32 v41, v41
	v_add_f32_e32 v39, 1.0, v39
	v_rcp_f32_e32 v39, v39
	global_store_dwordx2 v[56:57], v[36:37], off offset:64
	s_waitcnt vmcnt(19)
	v_and_b32_e32 v37, 0xffff0000, v106
	v_mul_f32_e32 v35, v35, v124
	v_mul_f32_e32 v32, v32, v39
	v_add_f32_e32 v39, 1.0, v41
	v_rcp_f32_e32 v39, v39
	v_sub_f32_e32 v37, v37, v100
	v_lshlrev_b32_e32 v36, 16, v106
	v_mul_f32_e32 v34, v34, v124
	v_mul_f32_e32 v33, v33, v39
	v_mul_f32_e32 v33, v33, v37
	v_mul_f32_e32 v37, 0xbfb8aa3b, v35
	v_exp_f32_e32 v37, v37
	v_sub_f32_e32 v36, v36, v100
	v_mul_f32_e32 v32, v32, v36
	v_mul_f32_e32 v36, 0xbfb8aa3b, v34
	v_add_f32_e32 v37, 1.0, v37
	v_rcp_f32_e32 v37, v37
	s_waitcnt vmcnt(18)
	v_mul_f32_e32 v28, v28, v123
	v_exp_f32_e32 v36, v36
	v_mul_f32_e32 v29, v29, v123
	v_mul_f32_e32 v35, v35, v37
	v_mul_f32_e32 v37, 0xbfb8aa3b, v28
	v_exp_f32_e32 v37, v37
	v_add_f32_e32 v36, 1.0, v36
	v_rcp_f32_e32 v36, v36
	v_mul_f32_e32 v39, 0xbfb8aa3b, v29
	v_add_f32_e32 v37, 1.0, v37
	v_rcp_f32_e32 v37, v37
	v_exp_f32_e32 v39, v39
	v_lshlrev_b32_e32 v38, 16, v107
	v_and_b32_e32 v40, 0xffff0000, v107
	v_mul_f32_e32 v34, v34, v36
	v_sub_f32_e32 v36, v38, v100
	v_mul_f32_e32 v34, v34, v36
	v_sub_f32_e32 v36, v40, v100
	v_mul_f32_e32 v28, v28, v37
	v_add_f32_e32 v37, 1.0, v39
	v_mul_f32_e32 v32, v101, v32
	v_mul_f32_e32 v33, v101, v33
	v_mul_f32_e32 v34, v101, v34
	v_mul_f32_e32 v35, v35, v36
	v_rcp_f32_e32 v37, v37
	v_mul_f32_e32 v32, v44, v32
	v_mul_f32_e32 v33, v45, v33
	v_mul_f32_e32 v34, v46, v34
	v_mul_f32_e32 v35, v101, v35
	v_mul_f32_e32 v35, v47, v35
	v_cvt_pk_bf16_f32 v32, v32, v33
	v_cvt_pk_bf16_f32 v33, v34, v35
	s_waitcnt vmcnt(16)
	v_lshlrev_b32_e32 v34, 16, v102
	v_and_b32_e32 v35, 0xffff0000, v102
	v_mul_f32_e32 v30, v30, v123
	v_sub_f32_e32 v34, v34, v88
	v_mul_f32_e32 v31, v31, v123
	v_mul_f32_e32 v28, v28, v34
	v_mul_f32_e32 v29, v29, v37
	v_mul_f32_e32 v34, 0xbfb8aa3b, v30
	v_sub_f32_e32 v35, v35, v88
	v_exp_f32_e32 v34, v34
	v_mul_f32_e32 v29, v29, v35
	v_mul_f32_e32 v35, 0xbfb8aa3b, v31
	v_exp_f32_e32 v35, v35
	v_add_f32_e32 v34, 1.0, v34
	v_rcp_f32_e32 v34, v34
	v_lshlrev_b32_e32 v36, 16, v103
	v_add_f32_e32 v35, 1.0, v35
	v_rcp_f32_e32 v35, v35
	v_and_b32_e32 v38, 0xffff0000, v103
	v_mul_f32_e32 v30, v30, v34
	v_sub_f32_e32 v34, v36, v88
	v_mul_f32_e32 v30, v30, v34
	v_mul_f32_e32 v31, v31, v35
	v_sub_f32_e32 v34, v38, v88
	v_mul_f32_e32 v31, v31, v34
	v_mul_f32_e32 v28, v89, v28
	v_mul_f32_e32 v29, v89, v29
	v_mul_f32_e32 v31, v89, v31
	v_mul_f32_e32 v28, v68, v28
	v_mul_f32_e32 v29, v69, v29
	v_mul_f32_e32 v30, v89, v30
	v_mul_f32_e32 v31, v71, v31
	v_mul_f32_e32 v24, v24, v123
	v_mul_f32_e32 v30, v70, v30
	v_cvt_pk_bf16_f32 v28, v28, v29
	v_cvt_pk_bf16_f32 v29, v30, v31
	v_mul_f32_e32 v31, 0xbfb8aa3b, v24
	v_exp_f32_e32 v31, v31
	v_mul_f32_e32 v25, v25, v123
	v_mul_f32_e32 v35, 0xbfb8aa3b, v25
	v_exp_f32_e32 v35, v35
	v_add_f32_e32 v31, 1.0, v31
	v_rcp_f32_e32 v31, v31
	global_store_dwordx2 v[56:57], v[32:33], off offset:96
	v_lshl_add_u64 v[32:33], v[140:141], 0, v[104:105]
	global_store_dwordx2 v[32:33], v[28:29], off
	v_mul_f32_e32 v24, v24, v31
	v_add_f32_e32 v31, 1.0, v35
	v_rcp_f32_e32 v31, v31
	s_waitcnt vmcnt(17)
	v_lshlrev_b32_e32 v28, 16, v98
	v_and_b32_e32 v29, 0xffff0000, v98
	v_mul_f32_e32 v26, v26, v123
	v_sub_f32_e32 v28, v28, v88
	v_mul_f32_e32 v27, v27, v123
	v_mul_f32_e32 v24, v24, v28
	v_mul_f32_e32 v25, v25, v31
	v_mul_f32_e32 v28, 0xbfb8aa3b, v26
	v_sub_f32_e32 v29, v29, v88
	v_exp_f32_e32 v28, v28
	v_mul_f32_e32 v25, v25, v29
	v_mul_f32_e32 v29, 0xbfb8aa3b, v27
	v_exp_f32_e32 v29, v29
	v_add_f32_e32 v28, 1.0, v28
	v_rcp_f32_e32 v28, v28
	v_lshlrev_b32_e32 v30, 16, v99
	v_add_f32_e32 v29, 1.0, v29
	v_rcp_f32_e32 v29, v29
	v_and_b32_e32 v34, 0xffff0000, v99
	v_mul_f32_e32 v26, v26, v28
	v_sub_f32_e32 v28, v30, v88
	v_mul_f32_e32 v26, v26, v28
	v_mul_f32_e32 v27, v27, v29
	v_sub_f32_e32 v28, v34, v88
	v_mul_f32_e32 v27, v27, v28
	v_mul_f32_e32 v24, v89, v24
	v_mul_f32_e32 v25, v89, v25
	v_mul_f32_e32 v27, v89, v27
	v_mul_f32_e32 v24, v60, v24
	v_mul_f32_e32 v25, v61, v25
	v_mul_f32_e32 v26, v89, v26
	v_mul_f32_e32 v27, v63, v27
	v_mul_f32_e32 v20, v20, v123
	v_mul_f32_e32 v26, v62, v26
	v_cvt_pk_bf16_f32 v24, v24, v25
	v_cvt_pk_bf16_f32 v25, v26, v27
	v_mul_f32_e32 v27, 0xbfb8aa3b, v20
	v_exp_f32_e32 v27, v27
	v_mul_f32_e32 v21, v21, v123
	v_mul_f32_e32 v29, 0xbfb8aa3b, v21
	v_exp_f32_e32 v29, v29
	v_add_f32_e32 v27, 1.0, v27
	v_rcp_f32_e32 v27, v27
	global_store_dwordx2 v[32:33], v[24:25], off offset:32
	s_waitcnt vmcnt(17)
	v_lshlrev_b32_e32 v24, 16, v96
	v_and_b32_e32 v25, 0xffff0000, v96
	v_mul_f32_e32 v20, v20, v27
	v_add_f32_e32 v27, 1.0, v29
	v_rcp_f32_e32 v27, v27
	v_mul_f32_e32 v22, v22, v123
	v_sub_f32_e32 v24, v24, v88
	v_mul_f32_e32 v23, v23, v123
	v_mul_f32_e32 v20, v20, v24
	v_mul_f32_e32 v21, v21, v27
	v_mul_f32_e32 v24, 0xbfb8aa3b, v22
	v_sub_f32_e32 v25, v25, v88
	v_exp_f32_e32 v24, v24
	v_mul_f32_e32 v21, v21, v25
	v_mul_f32_e32 v25, 0xbfb8aa3b, v23
	v_exp_f32_e32 v25, v25
	v_add_f32_e32 v24, 1.0, v24
	v_rcp_f32_e32 v24, v24
	v_lshlrev_b32_e32 v26, 16, v97
	v_add_f32_e32 v25, 1.0, v25
	v_rcp_f32_e32 v25, v25
	v_and_b32_e32 v28, 0xffff0000, v97
	v_mul_f32_e32 v22, v22, v24
	v_sub_f32_e32 v24, v26, v88
	v_mul_f32_e32 v22, v22, v24
	v_mul_f32_e32 v23, v23, v25
	v_sub_f32_e32 v24, v28, v88
	v_mul_f32_e32 v23, v23, v24
	v_mul_f32_e32 v20, v89, v20
	v_mul_f32_e32 v21, v89, v21
	v_mul_f32_e32 v23, v89, v23
	v_mul_f32_e32 v20, v52, v20
	v_mul_f32_e32 v21, v53, v21
	v_mul_f32_e32 v22, v89, v22
	v_mul_f32_e32 v23, v55, v23
	v_mul_f32_e32 v16, v16, v123
	v_mul_f32_e32 v22, v54, v22
	v_cvt_pk_bf16_f32 v20, v20, v21
	v_cvt_pk_bf16_f32 v21, v22, v23
	v_mul_f32_e32 v23, 0xbfb8aa3b, v16
	v_exp_f32_e32 v23, v23
	v_mul_f32_e32 v17, v17, v123
	v_mul_f32_e32 v25, 0xbfb8aa3b, v17
	v_exp_f32_e32 v25, v25
	v_add_f32_e32 v23, 1.0, v23
	v_rcp_f32_e32 v23, v23
	global_store_dwordx2 v[32:33], v[20:21], off offset:64
	s_waitcnt vmcnt(17)
	v_and_b32_e32 v21, 0xffff0000, v94
	v_mul_f32_e32 v19, v19, v123
	v_mul_f32_e32 v16, v16, v23
	v_add_f32_e32 v23, 1.0, v25
	v_rcp_f32_e32 v23, v23
	v_sub_f32_e32 v21, v21, v88
	v_lshlrev_b32_e32 v20, 16, v94
	v_mul_f32_e32 v18, v18, v123
	v_mul_f32_e32 v17, v17, v23
	v_mul_f32_e32 v17, v17, v21
	v_mul_f32_e32 v21, 0xbfb8aa3b, v19
	v_exp_f32_e32 v21, v21
	v_sub_f32_e32 v20, v20, v88
	v_mul_f32_e32 v16, v16, v20
	v_mul_f32_e32 v20, 0xbfb8aa3b, v18
	v_add_f32_e32 v21, 1.0, v21
	v_rcp_f32_e32 v21, v21
	s_waitcnt vmcnt(16)
	v_mul_f32_e32 v12, v12, v122
	v_exp_f32_e32 v20, v20
	v_mul_f32_e32 v13, v13, v122
	v_mul_f32_e32 v19, v19, v21
	v_mul_f32_e32 v21, 0xbfb8aa3b, v12
	v_exp_f32_e32 v21, v21
	v_add_f32_e32 v20, 1.0, v20
	v_rcp_f32_e32 v20, v20
	v_mul_f32_e32 v23, 0xbfb8aa3b, v13
	v_add_f32_e32 v21, 1.0, v21
	v_rcp_f32_e32 v21, v21
	v_exp_f32_e32 v23, v23
	v_lshlrev_b32_e32 v22, 16, v95
	v_and_b32_e32 v24, 0xffff0000, v95
	v_mul_f32_e32 v18, v18, v20
	v_sub_f32_e32 v20, v22, v88
	v_mul_f32_e32 v18, v18, v20
	v_sub_f32_e32 v20, v24, v88
	v_mul_f32_e32 v12, v12, v21
	v_add_f32_e32 v21, 1.0, v23
	v_mul_f32_e32 v16, v89, v16
	v_mul_f32_e32 v17, v89, v17
	v_mul_f32_e32 v18, v89, v18
	v_mul_f32_e32 v19, v19, v20
	v_rcp_f32_e32 v21, v21
	v_mul_f32_e32 v16, v44, v16
	v_mul_f32_e32 v17, v45, v17
	v_mul_f32_e32 v18, v46, v18
	v_mul_f32_e32 v19, v89, v19
	v_mul_f32_e32 v19, v47, v19
	v_cvt_pk_bf16_f32 v16, v16, v17
	v_cvt_pk_bf16_f32 v17, v18, v19
	s_waitcnt vmcnt(14)
	v_lshlrev_b32_e32 v18, 16, v90
	v_and_b32_e32 v19, 0xffff0000, v90
	v_mul_f32_e32 v14, v14, v122
	v_sub_f32_e32 v18, v18, v80
	v_mul_f32_e32 v15, v15, v122
	v_mul_f32_e32 v12, v12, v18
	v_mul_f32_e32 v13, v13, v21
	v_mul_f32_e32 v18, 0xbfb8aa3b, v14
	v_sub_f32_e32 v19, v19, v80
	v_exp_f32_e32 v18, v18
	v_mul_f32_e32 v13, v13, v19
	v_mul_f32_e32 v19, 0xbfb8aa3b, v15
	v_exp_f32_e32 v19, v19
	v_add_f32_e32 v18, 1.0, v18
	v_rcp_f32_e32 v18, v18
	v_lshlrev_b32_e32 v20, 16, v91
	v_add_f32_e32 v19, 1.0, v19
	v_rcp_f32_e32 v19, v19
	v_and_b32_e32 v22, 0xffff0000, v91
	v_mul_f32_e32 v14, v14, v18
	v_sub_f32_e32 v18, v20, v80
	v_mul_f32_e32 v14, v14, v18
	v_mul_f32_e32 v15, v15, v19
	v_sub_f32_e32 v18, v22, v80
	v_mul_f32_e32 v15, v15, v18
	v_mul_f32_e32 v12, v81, v12
	v_mul_f32_e32 v13, v81, v13
	v_mul_f32_e32 v15, v81, v15
	v_mul_f32_e32 v12, v68, v12
	v_mul_f32_e32 v13, v69, v13
	v_mul_f32_e32 v14, v81, v14
	v_mul_f32_e32 v15, v71, v15
	v_mul_f32_e32 v8, v8, v122
	v_mul_f32_e32 v14, v70, v14
	v_cvt_pk_bf16_f32 v12, v12, v13
	v_cvt_pk_bf16_f32 v13, v14, v15
	v_mul_f32_e32 v15, 0xbfb8aa3b, v8
	v_exp_f32_e32 v15, v15
	v_mul_f32_e32 v9, v9, v122
	v_mul_f32_e32 v19, 0xbfb8aa3b, v9
	v_exp_f32_e32 v19, v19
	v_add_f32_e32 v15, 1.0, v15
	v_rcp_f32_e32 v15, v15
	global_store_dwordx2 v[32:33], v[16:17], off offset:96
	v_lshl_add_u64 v[16:17], v[140:141], 0, v[92:93]
	global_store_dwordx2 v[16:17], v[12:13], off
	v_mul_f32_e32 v8, v8, v15
	v_add_f32_e32 v15, 1.0, v19
	v_rcp_f32_e32 v15, v15
	s_waitcnt vmcnt(15)
	v_lshlrev_b32_e32 v12, 16, v86
	v_and_b32_e32 v13, 0xffff0000, v86
	v_mul_f32_e32 v10, v10, v122
	v_sub_f32_e32 v12, v12, v80
	v_mul_f32_e32 v11, v11, v122
	v_mul_f32_e32 v8, v8, v12
	v_mul_f32_e32 v9, v9, v15
	v_mul_f32_e32 v12, 0xbfb8aa3b, v10
	v_sub_f32_e32 v13, v13, v80
	v_exp_f32_e32 v12, v12
	v_mul_f32_e32 v9, v9, v13
	v_mul_f32_e32 v13, 0xbfb8aa3b, v11
	v_exp_f32_e32 v13, v13
	v_add_f32_e32 v12, 1.0, v12
	v_rcp_f32_e32 v12, v12
	v_lshlrev_b32_e32 v14, 16, v87
	v_add_f32_e32 v13, 1.0, v13
	v_rcp_f32_e32 v13, v13
	v_and_b32_e32 v18, 0xffff0000, v87
	v_mul_f32_e32 v10, v10, v12
	v_sub_f32_e32 v12, v14, v80
	v_mul_f32_e32 v10, v10, v12
	v_mul_f32_e32 v11, v11, v13
	v_sub_f32_e32 v12, v18, v80
	v_mul_f32_e32 v11, v11, v12
	v_mul_f32_e32 v8, v81, v8
	v_mul_f32_e32 v9, v81, v9
	v_mul_f32_e32 v11, v81, v11
	v_mul_f32_e32 v8, v60, v8
	v_mul_f32_e32 v9, v61, v9
	v_mul_f32_e32 v10, v81, v10
	v_mul_f32_e32 v11, v63, v11
	v_mul_f32_e32 v4, v4, v122
	v_mul_f32_e32 v10, v62, v10
	v_cvt_pk_bf16_f32 v8, v8, v9
	v_cvt_pk_bf16_f32 v9, v10, v11
	v_mul_f32_e32 v11, 0xbfb8aa3b, v4
	v_exp_f32_e32 v11, v11
	v_mul_f32_e32 v5, v5, v122
	v_mul_f32_e32 v13, 0xbfb8aa3b, v5
	v_exp_f32_e32 v13, v13
	v_add_f32_e32 v11, 1.0, v11
	v_rcp_f32_e32 v11, v11
	global_store_dwordx2 v[16:17], v[8:9], off offset:32
	s_waitcnt vmcnt(15)
	v_lshlrev_b32_e32 v8, 16, v84
	v_and_b32_e32 v9, 0xffff0000, v84
	v_mul_f32_e32 v4, v4, v11
	v_add_f32_e32 v11, 1.0, v13
	v_rcp_f32_e32 v11, v11
	v_mul_f32_e32 v6, v6, v122
	v_sub_f32_e32 v8, v8, v80
	v_mul_f32_e32 v7, v7, v122
	v_mul_f32_e32 v4, v4, v8
	v_mul_f32_e32 v5, v5, v11
	v_mul_f32_e32 v8, 0xbfb8aa3b, v6
	v_sub_f32_e32 v9, v9, v80
	v_exp_f32_e32 v8, v8
	v_mul_f32_e32 v5, v5, v9
	v_mul_f32_e32 v9, 0xbfb8aa3b, v7
	v_exp_f32_e32 v9, v9
	v_add_f32_e32 v8, 1.0, v8
	v_rcp_f32_e32 v8, v8
	v_lshlrev_b32_e32 v10, 16, v85
	v_add_f32_e32 v9, 1.0, v9
	v_rcp_f32_e32 v9, v9
	v_and_b32_e32 v12, 0xffff0000, v85
	v_mul_f32_e32 v6, v6, v8
	v_sub_f32_e32 v8, v10, v80
	v_mul_f32_e32 v6, v6, v8
	v_mul_f32_e32 v7, v7, v9
	v_sub_f32_e32 v8, v12, v80
	v_mul_f32_e32 v7, v7, v8
	v_mul_f32_e32 v4, v81, v4
	v_mul_f32_e32 v5, v81, v5
	v_mul_f32_e32 v7, v81, v7
	v_mul_f32_e32 v4, v52, v4
	v_mul_f32_e32 v5, v53, v5
	v_mul_f32_e32 v6, v81, v6
	v_mul_f32_e32 v7, v55, v7
	v_mul_f32_e32 v0, v0, v122
	v_mul_f32_e32 v6, v54, v6
	v_cvt_pk_bf16_f32 v4, v4, v5
	v_cvt_pk_bf16_f32 v5, v6, v7
	v_mul_f32_e32 v7, 0xbfb8aa3b, v0
	v_exp_f32_e32 v7, v7
	v_mul_f32_e32 v1, v1, v122
	v_mul_f32_e32 v9, 0xbfb8aa3b, v1
	v_exp_f32_e32 v9, v9
	v_add_f32_e32 v7, 1.0, v7
	v_rcp_f32_e32 v7, v7
	global_store_dwordx2 v[16:17], v[4:5], off offset:64
	s_waitcnt vmcnt(15)
	v_lshlrev_b32_e32 v4, 16, v82
	v_and_b32_e32 v5, 0xffff0000, v82
	v_mul_f32_e32 v0, v0, v7
	v_add_f32_e32 v7, 1.0, v9
	v_rcp_f32_e32 v7, v7
	v_mul_f32_e32 v2, v2, v122
	v_sub_f32_e32 v4, v4, v80
	v_mul_f32_e32 v3, v3, v122
	v_mul_f32_e32 v0, v0, v4
	v_mul_f32_e32 v1, v1, v7
	v_mul_f32_e32 v4, 0xbfb8aa3b, v2
	v_sub_f32_e32 v5, v5, v80
	v_exp_f32_e32 v4, v4
	v_mul_f32_e32 v1, v1, v5
	v_mul_f32_e32 v5, 0xbfb8aa3b, v3
	v_exp_f32_e32 v5, v5
	v_add_f32_e32 v4, 1.0, v4
	v_rcp_f32_e32 v4, v4
	v_lshlrev_b32_e32 v6, 16, v83
	v_add_f32_e32 v5, 1.0, v5
	v_rcp_f32_e32 v5, v5
	v_and_b32_e32 v8, 0xffff0000, v83
	v_mul_f32_e32 v2, v2, v4
	v_sub_f32_e32 v4, v6, v80
	v_mul_f32_e32 v2, v2, v4
	v_mul_f32_e32 v3, v3, v5
	v_sub_f32_e32 v4, v8, v80
	v_mul_f32_e32 v0, v81, v0
	v_mul_f32_e32 v1, v81, v1
	v_mul_f32_e32 v3, v3, v4
	v_mul_f32_e32 v0, v44, v0
	v_mul_f32_e32 v1, v45, v1
	v_mul_f32_e32 v2, v81, v2
	v_mul_f32_e32 v3, v81, v3
	v_mul_f32_e32 v2, v46, v2
	v_mul_f32_e32 v3, v47, v3
	v_cvt_pk_bf16_f32 v0, v0, v1
	v_cvt_pk_bf16_f32 v1, v2, v3
	global_store_dwordx2 v[16:17], v[0:1], off offset:96
	s_add_i32 s34, s34, s74
	s_cmpk_lt_i32 s34, 0x800
	s_cbranch_scc1 .LBB0_502

.LBB0_560:
	s_ashr_i32 s22, s30, 3
	s_lshr_b32 s24, s22, 29
	s_add_i32 s24, s22, s24
	s_and_b32 s25, s24, 0x1fffff8
	s_sub_i32 s22, s22, s25
	s_lshl_b32 s24, s24, 8
	s_lshl_b32 s25, s30, 8
	s_and_b32 s24, s24, 0xfffff800
	s_and_b32 s25, s25, 0x700
	s_or_b32 s28, s24, s25
	s_ashr_i32 s29, s28, 31
	s_lshl_b32 s24, s22, 7
	s_lshl_b64 s[34:35], s[28:29], 12
	s_add_u32 s34, s3, s34
	s_addc_u32 s35, s4, s35
	s_ashr_i32 s25, s24, 31
	v_mov_b32_e32 v36, v220
	s_lshl_b64 s[36:37], s[24:25], 12
	s_add_u32 s36, s5, s36
	v_ashrrev_i32_e32 v26, 2, v36
	v_ashrrev_i32_e32 v27, 31, v26
	s_addc_u32 s37, s8, s37
	v_lshlrev_b64 v[0:1], 12, v[26:27]
	v_lshlrev_b32_e32 v4, 4, v36
	v_lshl_add_u64 v[2:3], s[36:37], 0, v[0:1]
	v_lshl_add_u64 v[0:1], s[34:35], 0, v[0:1]
	v_and_b32_e32 v176, 48, v4
	s_waitcnt vmcnt(9)
	v_lshl_add_u64 v[152:153], v[0:1], 0, v[176:177]
	v_add_co_u32_e32 v28, vcc, s9, v152
	v_lshl_add_u64 v[154:155], v[2:3], 0, v[176:177]
	s_nop 0
	v_addc_co_u32_e32 v29, vcc, 0, v153, vcc
	v_add_co_u32_e32 v30, vcc, s26, v152
	global_load_dwordx4 v[2:5], v[152:153], off
	s_nop 0
	v_addc_co_u32_e32 v31, vcc, 0, v153, vcc
	v_add_co_u32_e32 v32, vcc, s27, v152
	global_load_dwordx4 v[6:9], v[28:29], off
	s_nop 0
	v_addc_co_u32_e32 v33, vcc, 0, v153, vcc
	v_add_co_u32_e32 v34, vcc, s9, v154
	global_load_dwordx4 v[10:13], v[30:31], off
	s_nop 0
	v_addc_co_u32_e32 v35, vcc, 0, v155, vcc
	global_load_dwordx4 v[14:17], v[32:33], off
	global_load_dwordx4 v[18:21], v[154:155], off
	global_load_dwordx4 v[22:25], v[34:35], off
	global_load_dwordx4 v[112:115], v[152:153], off offset:64
	global_load_dwordx4 v[120:123], v[28:29], off offset:64
	global_load_dwordx4 v[124:127], v[30:31], off offset:64
	global_load_dwordx4 v[128:131], v[32:33], off offset:64
	global_load_dwordx4 v[116:119], v[154:155], off offset:64
	global_load_dwordx4 v[132:135], v[34:35], off offset:64
	v_lshrrev_b32_e32 v27, 4, v36
	v_lshrrev_b32_e32 v37, 2, v36
	v_sub_u32_e32 v40, 0, v27
	v_sub_u32_e32 v37, 0, v37
	v_and_b32_e32 v38, 0x3ffff8f, v36
	v_lshlrev_b32_e32 v39, 6, v36
	v_xor_b32_e32 v36, v36, v40
	v_xor_b32_e32 v27, v27, v37
	v_lshlrev_b32_e32 v36, 4, v36
	v_lshlrev_b32_e32 v27, 4, v27
	v_and_b32_e32 v41, 0x1000, v39
	v_and_b32_e32 v36, 48, v36
	v_and_b32_e32 v27, 48, v27
	v_and_b32_e32 v42, 0x3c0, v39
	v_and_b32_e32 v39, 0xffffe3c0, v39
	v_lshl_add_u32 v38, v38, 6, v196
	v_lshl_or_b32 v164, v26, 6, v36
	v_or_b32_e32 v26, v27, v41
	s_mov_b32 s25, -2
	s_mov_b32 s29, s23
	v_mov_b32_e32 v0, 0
	v_mov_b32_e32 v1, v177
	v_or3_b32 v165, v41, v42, v27
	v_add_u32_e32 v166, v27, v39
	v_add_u32_e32 v167, v27, v38
	v_add_u32_e32 v168, v26, v42
	v_lshl_add_u64 v[156:157], v[152:153], 0, s[12:13]
	v_lshl_add_u64 v[158:159], v[152:153], 0, s[14:15]
	v_lshl_add_u64 v[160:161], v[152:153], 0, s[16:17]
	v_lshl_add_u64 v[162:163], v[154:155], 0, s[12:13]
	v_mov_b32_e32 v26, v177
	v_mov_b32_e32 v27, v177
	v_mov_b32_e32 v28, 0
	v_mov_b32_e32 v29, v177
	v_mov_b32_e32 v30, v177
	v_mov_b32_e32 v31, v177
	v_mov_b32_e32 v32, 0
	v_mov_b32_e32 v33, v177
	v_mov_b32_e32 v34, v177
	v_mov_b32_e32 v35, v177
	v_mov_b32_e32 v36, 0
	v_mov_b32_e32 v37, v177
	v_mov_b32_e32 v38, v177
	v_mov_b32_e32 v39, v177
	v_mov_b32_e32 v40, 0
	v_mov_b32_e32 v41, v177
	v_mov_b32_e32 v42, v177
	v_mov_b32_e32 v43, v177
	v_mov_b32_e32 v44, 0
	s_waitcnt vmcnt(11)
	ds_write_b128 v164, v[2:5]
	s_waitcnt vmcnt(10)
	ds_write_b128 v164, v[6:9] offset:4096
	s_waitcnt vmcnt(9)
	ds_write_b128 v164, v[10:13] offset:8192
	s_waitcnt vmcnt(8)
	ds_write_b128 v164, v[14:17] offset:12288
	s_waitcnt vmcnt(7)
	ds_write_b128 v164, v[18:21] offset:32768
	s_waitcnt vmcnt(6)
	ds_write_b128 v164, v[22:25] offset:36864
	v_mov_b32_e32 v2, v177
	v_mov_b32_e32 v3, v177
	v_mov_b32_e32 v4, 0
	v_mov_b32_e32 v5, v177
	v_mov_b32_e32 v6, v177
	v_mov_b32_e32 v7, v177
	v_mov_b32_e32 v8, 0
	v_mov_b32_e32 v9, v177
	v_mov_b32_e32 v10, v177
	v_mov_b32_e32 v11, v177
	v_mov_b32_e32 v12, 0
	v_mov_b32_e32 v13, v177
	v_mov_b32_e32 v14, v177
	v_mov_b32_e32 v15, v177
	v_mov_b32_e32 v16, 0
	v_mov_b32_e32 v17, v177
	v_mov_b32_e32 v18, v177
	v_mov_b32_e32 v19, v177
	v_mov_b32_e32 v20, 0
	v_mov_b32_e32 v21, v177
	v_mov_b32_e32 v22, v177
	v_mov_b32_e32 v23, v177
	v_mov_b32_e32 v24, 0
	v_mov_b32_e32 v25, v177
	v_mov_b32_e32 v45, v177
	v_mov_b32_e32 v46, v177
	v_mov_b32_e32 v47, v177
	v_mov_b32_e32 v48, 0
	v_mov_b32_e32 v49, v177
	v_mov_b32_e32 v50, v177
	v_mov_b32_e32 v51, v177
	v_mov_b32_e32 v52, 0
	v_mov_b32_e32 v53, v177
	v_mov_b32_e32 v54, v177
	v_mov_b32_e32 v55, v177
	v_mov_b32_e32 v56, 0
	v_mov_b32_e32 v57, v177
	v_mov_b32_e32 v58, v177
	v_mov_b32_e32 v59, v177
	v_mov_b32_e32 v60, 0
	v_mov_b32_e32 v61, v177
	v_mov_b32_e32 v62, v177
	v_mov_b32_e32 v63, v177
	v_mov_b32_e32 v64, 0
	v_mov_b32_e32 v65, v177
	v_mov_b32_e32 v66, v177
	v_mov_b32_e32 v67, v177
	v_mov_b32_e32 v68, 0
	v_mov_b32_e32 v69, v177
	v_mov_b32_e32 v70, v177
	v_mov_b32_e32 v71, v177
	v_mov_b32_e32 v72, 0
	v_mov_b32_e32 v73, v177
	v_mov_b32_e32 v74, v177
	v_mov_b32_e32 v75, v177
	v_mov_b32_e32 v76, 0
	v_mov_b32_e32 v77, v177
	v_mov_b32_e32 v78, v177
	v_mov_b32_e32 v79, v177
	v_mov_b32_e32 v80, 0
	v_mov_b32_e32 v81, v177
	v_mov_b32_e32 v82, v177
	v_mov_b32_e32 v83, v177
	v_mov_b32_e32 v84, 0
	v_mov_b32_e32 v85, v177
	v_mov_b32_e32 v86, v177
	v_mov_b32_e32 v87, v177
	v_mov_b32_e32 v88, 0
	v_mov_b32_e32 v89, v177
	v_mov_b32_e32 v90, v177
	v_mov_b32_e32 v91, v177
	v_mov_b32_e32 v92, 0
	v_mov_b32_e32 v93, v177
	v_mov_b32_e32 v94, v177
	v_mov_b32_e32 v95, v177
	v_mov_b32_e32 v96, 0
	v_mov_b32_e32 v97, v177
	v_mov_b32_e32 v98, v177
	v_mov_b32_e32 v99, v177
	v_mov_b32_e32 v100, 0
	v_mov_b32_e32 v101, v177
	v_mov_b32_e32 v102, v177
	v_mov_b32_e32 v103, v177
	v_mov_b32_e32 v104, 0
	v_mov_b32_e32 v105, v177
	v_mov_b32_e32 v106, v177
	v_mov_b32_e32 v107, v177
	v_mov_b32_e32 v108, 0
	v_mov_b32_e32 v109, v177
	v_mov_b32_e32 v110, v177
	v_mov_b32_e32 v111, v177
	v_mov_b32_e32 v136, 0
	v_mov_b32_e32 v137, v177
	v_mov_b32_e32 v138, v177
	v_mov_b32_e32 v139, v177
	v_mov_b32_e32 v140, 0
	v_mov_b32_e32 v141, v177
	v_mov_b32_e32 v142, v177
	v_mov_b32_e32 v143, v177
	v_mov_b32_e32 v144, 0
	v_mov_b32_e32 v145, v177
	v_mov_b32_e32 v146, v177
	v_mov_b32_e32 v147, v177
	v_mov_b32_e32 v148, 0
	v_mov_b32_e32 v149, v177
	v_mov_b32_e32 v150, v177
	v_mov_b32_e32 v151, v177
	s_waitcnt lgkmcnt(0)
	s_barrier
	global_load_dwordx4 v[170:173], v[152:153], off offset:128
	global_load_dwordx4 v[178:181], v[156:157], off offset:128
	global_load_dwordx4 v[182:185], v[158:159], off offset:128
	global_load_dwordx4 v[186:189], v[160:161], off offset:128
	global_load_dwordx4 v[190:193], v[154:155], off offset:128
	global_load_dwordx4 v[198:201], v[162:163], off offset:128
.LBB0_561:
	s_add_i32 s31, s29, 64
	s_add_i32 s22, s29, 96
	s_min_u32 s22, s22, 0x7e0
	s_lshl_b32 s22, s22, 1
	ds_read_b128 v[202:205], v168 offset:32768
	ds_read_b128 v[206:209], v168 offset:33792
	ds_read_b128 v[210:213], v168 offset:34816
	ds_read_b128 v[214:217], v168 offset:35840
	ds_read_b128 v[222:225], v166
	ds_read_b128 v[226:229], v166 offset:1024
	ds_read_b128 v[230:233], v166 offset:2048
	ds_read_b128 v[234:237], v166 offset:3072
	ds_read_b128 v[238:241], v166 offset:4096
	ds_read_b128 v[242:245], v166 offset:5120
	ds_read_b128 v[246:249], v166 offset:6144
	ds_read_b128 v[250:253], v166 offset:7168
	s_setprio 1
	s_waitcnt lgkmcnt(7)
	v_mfma_f32_16x16x32_bf16 v[148:151], v[202:205], v[222:225], v[148:151]
	v_mfma_f32_16x16x32_bf16 v[144:147], v[206:209], v[222:225], v[144:147]
	v_mfma_f32_16x16x32_bf16 v[140:143], v[210:213], v[222:225], v[140:143]
	v_mfma_f32_16x16x32_bf16 v[136:139], v[214:217], v[222:225], v[136:139]
	s_waitcnt vmcnt(11)
	ds_write_b128 v164, v[112:115] offset:16384
	s_waitcnt lgkmcnt(7)
	v_mfma_f32_16x16x32_bf16 v[108:111], v[202:205], v[226:229], v[108:111]
	v_mfma_f32_16x16x32_bf16 v[104:107], v[206:209], v[226:229], v[104:107]
	v_mfma_f32_16x16x32_bf16 v[100:103], v[210:213], v[226:229], v[100:103]
	v_mfma_f32_16x16x32_bf16 v[96:99], v[214:217], v[226:229], v[96:99]
	s_waitcnt vmcnt(10)
	ds_write_b128 v164, v[120:123] offset:20480
	v_lshl_add_u64 v[112:113], v[152:153], 0, s[22:23]
	global_load_dwordx4 v[112:115], v[112:113], off
	s_waitcnt lgkmcnt(7)
	v_mfma_f32_16x16x32_bf16 v[92:95], v[202:205], v[230:233], v[92:95]
	v_mfma_f32_16x16x32_bf16 v[88:91], v[206:209], v[230:233], v[88:91]
	v_mfma_f32_16x16x32_bf16 v[84:87], v[210:213], v[230:233], v[84:87]
	v_mfma_f32_16x16x32_bf16 v[80:83], v[214:217], v[230:233], v[80:83]
	s_waitcnt vmcnt(10)
	ds_write_b128 v164, v[124:127] offset:24576
	v_lshl_add_u64 v[120:121], v[156:157], 0, s[22:23]
	global_load_dwordx4 v[120:123], v[120:121], off
	s_waitcnt lgkmcnt(7)
	v_mfma_f32_16x16x32_bf16 v[76:79], v[202:205], v[234:237], v[76:79]
	v_mfma_f32_16x16x32_bf16 v[72:75], v[206:209], v[234:237], v[72:75]
	v_mfma_f32_16x16x32_bf16 v[68:71], v[210:213], v[234:237], v[68:71]
	v_mfma_f32_16x16x32_bf16 v[64:67], v[214:217], v[234:237], v[64:67]
	s_waitcnt vmcnt(10)
	ds_write_b128 v164, v[128:131] offset:28672
	v_lshl_add_u64 v[124:125], v[158:159], 0, s[22:23]
	global_load_dwordx4 v[124:127], v[124:125], off
	s_waitcnt lgkmcnt(7)
	v_mfma_f32_16x16x32_bf16 v[60:63], v[202:205], v[238:241], v[60:63]
	v_mfma_f32_16x16x32_bf16 v[56:59], v[206:209], v[238:241], v[56:59]
	v_mfma_f32_16x16x32_bf16 v[52:55], v[210:213], v[238:241], v[52:55]
	v_mfma_f32_16x16x32_bf16 v[48:51], v[214:217], v[238:241], v[48:51]
	s_waitcnt vmcnt(10)
	ds_write_b128 v164, v[116:119] offset:40960
	v_lshl_add_u64 v[128:129], v[160:161], 0, s[22:23]
	global_load_dwordx4 v[128:131], v[128:129], off
	s_waitcnt lgkmcnt(7)
	v_mfma_f32_16x16x32_bf16 v[44:47], v[202:205], v[242:245], v[44:47]
	v_mfma_f32_16x16x32_bf16 v[40:43], v[206:209], v[242:245], v[40:43]
	v_mfma_f32_16x16x32_bf16 v[36:39], v[210:213], v[242:245], v[36:39]
	v_mfma_f32_16x16x32_bf16 v[32:35], v[214:217], v[242:245], v[32:35]
	s_waitcnt vmcnt(10)
	ds_write_b128 v164, v[132:135] offset:45056
	v_lshl_add_u64 v[116:117], v[154:155], 0, s[22:23]
	global_load_dwordx4 v[116:119], v[116:117], off
	s_waitcnt lgkmcnt(7)
	v_mfma_f32_16x16x32_bf16 v[28:31], v[202:205], v[246:249], v[28:31]
	v_mfma_f32_16x16x32_bf16 v[24:27], v[206:209], v[246:249], v[24:27]
	v_mfma_f32_16x16x32_bf16 v[20:23], v[210:213], v[246:249], v[20:23]
	v_mfma_f32_16x16x32_bf16 v[16:19], v[214:217], v[246:249], v[16:19]
	v_lshl_add_u64 v[132:133], v[162:163], 0, s[22:23]
	global_load_dwordx4 v[132:135], v[132:133], off
	s_waitcnt lgkmcnt(6)
	v_mfma_f32_16x16x32_bf16 v[12:15], v[202:205], v[250:253], v[12:15]
	v_mfma_f32_16x16x32_bf16 v[8:11], v[206:209], v[250:253], v[8:11]
	v_mfma_f32_16x16x32_bf16 v[4:7], v[210:213], v[250:253], v[4:7]
	v_mfma_f32_16x16x32_bf16 v[0:3], v[214:217], v[250:253], v[0:3]
	s_setprio 0
	s_waitcnt lgkmcnt(0)
	s_barrier
	s_add_i32 s22, s29, 0x80
	s_min_u32 s22, s22, 0x7e0
	s_lshl_b32 s22, s22, 1
	ds_read_b128 v[202:205], v165 offset:40960
	ds_read_b128 v[206:209], v165 offset:41984
	ds_read_b128 v[210:213], v165 offset:43008
	ds_read_b128 v[214:217], v165 offset:44032
	ds_read_b128 v[222:225], v167
	ds_read_b128 v[226:229], v167 offset:1024
	ds_read_b128 v[230:233], v167 offset:2048
	ds_read_b128 v[234:237], v167 offset:3072
	ds_read_b128 v[238:241], v167 offset:4096
	ds_read_b128 v[242:245], v167 offset:5120
	ds_read_b128 v[246:249], v167 offset:6144
	ds_read_b128 v[250:253], v167 offset:7168
	s_setprio 1
	s_waitcnt lgkmcnt(7)
	v_mfma_f32_16x16x32_bf16 v[148:151], v[202:205], v[222:225], v[148:151]
	v_mfma_f32_16x16x32_bf16 v[144:147], v[206:209], v[222:225], v[144:147]
	v_mfma_f32_16x16x32_bf16 v[140:143], v[210:213], v[222:225], v[140:143]
	v_mfma_f32_16x16x32_bf16 v[136:139], v[214:217], v[222:225], v[136:139]
	s_waitcnt vmcnt(11)
	ds_write_b128 v164, v[170:173]
	s_waitcnt lgkmcnt(7)
	v_mfma_f32_16x16x32_bf16 v[108:111], v[202:205], v[226:229], v[108:111]
	v_mfma_f32_16x16x32_bf16 v[104:107], v[206:209], v[226:229], v[104:107]
	v_mfma_f32_16x16x32_bf16 v[100:103], v[210:213], v[226:229], v[100:103]
	v_mfma_f32_16x16x32_bf16 v[96:99], v[214:217], v[226:229], v[96:99]
	s_waitcnt vmcnt(10)
	ds_write_b128 v164, v[178:181] offset:4096
	v_lshl_add_u64 v[170:171], v[152:153], 0, s[22:23]
	global_load_dwordx4 v[170:173], v[170:171], off
	s_waitcnt lgkmcnt(7)
	v_mfma_f32_16x16x32_bf16 v[92:95], v[202:205], v[230:233], v[92:95]
	v_mfma_f32_16x16x32_bf16 v[88:91], v[206:209], v[230:233], v[88:91]
	v_mfma_f32_16x16x32_bf16 v[84:87], v[210:213], v[230:233], v[84:87]
	v_mfma_f32_16x16x32_bf16 v[80:83], v[214:217], v[230:233], v[80:83]
	s_waitcnt vmcnt(10)
	ds_write_b128 v164, v[182:185] offset:8192
	v_lshl_add_u64 v[178:179], v[156:157], 0, s[22:23]
	global_load_dwordx4 v[178:181], v[178:179], off
	s_waitcnt lgkmcnt(7)
	v_mfma_f32_16x16x32_bf16 v[76:79], v[202:205], v[234:237], v[76:79]
	v_mfma_f32_16x16x32_bf16 v[72:75], v[206:209], v[234:237], v[72:75]
	v_mfma_f32_16x16x32_bf16 v[68:71], v[210:213], v[234:237], v[68:71]
	v_mfma_f32_16x16x32_bf16 v[64:67], v[214:217], v[234:237], v[64:67]
	s_waitcnt vmcnt(10)
	ds_write_b128 v164, v[186:189] offset:12288
	v_lshl_add_u64 v[182:183], v[158:159], 0, s[22:23]
	global_load_dwordx4 v[182:185], v[182:183], off
	s_waitcnt lgkmcnt(7)
	v_mfma_f32_16x16x32_bf16 v[60:63], v[202:205], v[238:241], v[60:63]
	v_mfma_f32_16x16x32_bf16 v[56:59], v[206:209], v[238:241], v[56:59]
	v_mfma_f32_16x16x32_bf16 v[52:55], v[210:213], v[238:241], v[52:55]
	v_mfma_f32_16x16x32_bf16 v[48:51], v[214:217], v[238:241], v[48:51]
	s_waitcnt vmcnt(10)
	ds_write_b128 v164, v[190:193] offset:32768
	v_lshl_add_u64 v[186:187], v[160:161], 0, s[22:23]
	global_load_dwordx4 v[186:189], v[186:187], off
	s_waitcnt lgkmcnt(7)
	v_mfma_f32_16x16x32_bf16 v[44:47], v[202:205], v[242:245], v[44:47]
	v_mfma_f32_16x16x32_bf16 v[40:43], v[206:209], v[242:245], v[40:43]
	v_mfma_f32_16x16x32_bf16 v[36:39], v[210:213], v[242:245], v[36:39]
	v_mfma_f32_16x16x32_bf16 v[32:35], v[214:217], v[242:245], v[32:35]
	s_waitcnt vmcnt(10)
	ds_write_b128 v164, v[198:201] offset:36864
	v_lshl_add_u64 v[190:191], v[154:155], 0, s[22:23]
	global_load_dwordx4 v[190:193], v[190:191], off
	s_waitcnt lgkmcnt(7)
	v_mfma_f32_16x16x32_bf16 v[28:31], v[202:205], v[246:249], v[28:31]
	v_mfma_f32_16x16x32_bf16 v[24:27], v[206:209], v[246:249], v[24:27]
	v_mfma_f32_16x16x32_bf16 v[20:23], v[210:213], v[246:249], v[20:23]
	v_mfma_f32_16x16x32_bf16 v[16:19], v[214:217], v[246:249], v[16:19]
	v_lshl_add_u64 v[198:199], v[162:163], 0, s[22:23]
	global_load_dwordx4 v[198:201], v[198:199], off
	s_waitcnt lgkmcnt(6)
	v_mfma_f32_16x16x32_bf16 v[12:15], v[202:205], v[250:253], v[12:15]
	v_mfma_f32_16x16x32_bf16 v[8:11], v[206:209], v[250:253], v[8:11]
	v_mfma_f32_16x16x32_bf16 v[4:7], v[210:213], v[250:253], v[4:7]
	v_mfma_f32_16x16x32_bf16 v[0:3], v[214:217], v[250:253], v[0:3]
	s_setprio 0
	s_add_i32 s25, s25, 2
	s_cmp_lt_u32 s25, 62
	s_mov_b32 s29, s31
	s_waitcnt lgkmcnt(0)
	s_barrier
	s_cbranch_scc1 .LBB0_561
	s_waitcnt vmcnt(0)
	s_waitcnt vmcnt(5)
	v_mov_b32_e32 v112, v220
	v_readlane_b32 s36, v254, 6
	v_and_b32_e32 v114, 0xffffff80, v112
	v_bfe_u32 v176, v112, 4, 2
	v_add_u32_e32 v114, s28, v114
	v_and_b32_e32 v113, 64, v112
	v_and_or_b32 v180, v112, 15, v114
	v_lshlrev_b32_e32 v112, 2, v176
	v_or3_b32 v178, v112, v113, s24
	v_ashrrev_i32_e32 v179, 31, v178
	v_lshlrev_b64 v[214:215], 2, v[178:179]
	v_readlane_b32 s37, v254, 7
	v_ashrrev_i32_e32 v181, 31, v180
	v_or_b32_e32 v190, 16, v180
	v_lshl_add_u64 v[182:183], s[36:37], 0, v[214:215]
	v_lshlrev_b64 v[216:217], 12, v[180:181]
	v_ashrrev_i32_e32 v191, 31, v190
	v_or_b32_e32 v186, 32, v180
	v_lshl_add_u64 v[112:113], v[182:183], 0, v[216:217]
	v_lshlrev_b64 v[194:195], 12, v[190:191]
	v_ashrrev_i32_e32 v187, 31, v186
	v_or_b32_e32 v184, 48, v180
	global_load_dwordx4 v[198:201], v[112:113], off nt
	global_load_dwordx4 v[202:205], v[112:113], off offset:64 nt
	global_load_dwordx4 v[206:209], v[112:113], off offset:128 nt
	global_load_dwordx4 v[210:213], v[112:113], off offset:192 nt
	v_lshl_add_u64 v[112:113], v[182:183], 0, v[194:195]
	v_lshlrev_b64 v[192:193], 12, v[186:187]
	v_ashrrev_i32_e32 v185, 31, v184
	global_load_dwordx4 v[172:175], v[112:113], off nt
	global_load_dwordx4 v[168:171], v[112:113], off offset:64 nt
	global_load_dwordx4 v[164:167], v[112:113], off offset:128 nt
	global_load_dwordx4 v[160:163], v[112:113], off offset:192 nt
	v_lshl_add_u64 v[112:113], v[182:183], 0, v[192:193]
	v_lshlrev_b64 v[188:189], 12, v[184:185]
	global_load_dwordx4 v[156:159], v[112:113], off nt
	global_load_dwordx4 v[152:155], v[112:113], off offset:64 nt
	global_load_dwordx4 v[132:135], v[112:113], off offset:128 nt
	global_load_dwordx4 v[128:131], v[112:113], off offset:192 nt
	v_lshl_add_u64 v[112:113], v[182:183], 0, v[188:189]
	global_load_dwordx4 v[124:127], v[112:113], off nt
	global_load_dwordx4 v[120:123], v[112:113], off offset:64 nt
	global_load_dwordx4 v[116:119], v[112:113], off offset:128 nt
	s_nop 0
	global_load_dwordx4 v[112:115], v[112:113], off offset:192 nt
	v_cmp_eq_u32_e32 vcc, 0, v176
	v_readlane_b32 s38, v254, 8
	v_readlane_b32 s39, v254, 9
	v_readlane_b32 s40, v254, 10
	v_readlane_b32 s41, v254, 11
	v_readlane_b32 s42, v254, 12
	v_readlane_b32 s43, v254, 13
	v_readlane_b32 s44, v254, 14
	v_readlane_b32 s45, v254, 15
	v_readlane_b32 s46, v254, 16
	v_readlane_b32 s47, v254, 17
	v_readlane_b32 s48, v254, 18
	v_readlane_b32 s49, v254, 19
	v_readlane_b32 s50, v254, 20
	v_readlane_b32 s51, v254, 21
	v_lshl_add_u64 v[216:217], s[70:71], 0, v[216:217]
	s_waitcnt vmcnt(15)
	v_pk_add_f32 v[148:149], v[148:149], v[198:199]
	v_lshl_add_u64 v[214:215], v[216:217], 0, v[214:215]
	v_pk_add_f32 v[150:151], v[150:151], v[200:201]
	v_mul_f32_e32 v176, v149, v149
	global_store_dwordx4 v[214:215], v[148:151], off
	v_cvt_pk_bf16_f32 v198, v148, v149
	v_lshlrev_b64 v[200:201], 11, v[180:181]
	v_cvt_pk_bf16_f32 v199, v150, v151
	v_lshl_add_u64 v[200:201], s[6:7], 0, v[200:201]
	v_pk_fma_f32 v[148:149], v[148:149], v[148:149], v[176:177] op_sel_hi:[1,1,0]
	v_lshl_add_u64 v[200:201], v[178:179], 1, v[200:201]
	v_pk_fma_f32 v[148:149], v[150:151], v[150:151], v[148:149]
	v_mul_f32_e32 v150, v151, v151
	v_pk_add_f32 v[148:149], v[150:151], v[148:149] op_sel_hi:[0,1]
	s_waitcnt vmcnt(15)
	v_pk_add_f32 v[146:147], v[146:147], v[204:205]
	v_pk_add_f32 v[144:145], v[144:145], v[202:203]
	global_store_dwordx2 v[200:201], v[198:199], off
	v_cvt_pk_bf16_f32 v150, v144, v145
	global_store_dwordx4 v[214:215], v[144:147], off offset:64
	v_cvt_pk_bf16_f32 v151, v146, v147
	global_store_dwordx2 v[200:201], v[150:151], off offset:32
	v_mul_f32_e32 v150, v145, v145
	v_pk_fma_f32 v[144:145], v[144:145], v[144:145], v[150:151] op_sel_hi:[1,1,0]
	s_waitcnt vmcnt(17)
	v_pk_add_f32 v[142:143], v[142:143], v[208:209]
	v_pk_fma_f32 v[144:145], v[146:147], v[146:147], v[144:145]
	v_mul_f32_e32 v146, v147, v147
	v_pk_add_f32 v[144:145], v[146:147], v[144:145] op_sel_hi:[0,1]
	v_pk_add_f32 v[140:141], v[140:141], v[206:207]
	global_store_dwordx4 v[214:215], v[140:143], off offset:128
	v_cvt_pk_bf16_f32 v146, v140, v141
	v_cvt_pk_bf16_f32 v147, v142, v143
	global_store_dwordx2 v[200:201], v[146:147], off offset:64
	v_mul_f32_e32 v146, v141, v141
	v_pk_fma_f32 v[140:141], v[140:141], v[140:141], v[146:147] op_sel_hi:[1,1,0]
	s_waitcnt vmcnt(18)
	v_pk_add_f32 v[138:139], v[138:139], v[212:213]
	v_pk_fma_f32 v[140:141], v[142:143], v[142:143], v[140:141]
	v_mul_f32_e32 v142, v143, v143
	v_pk_add_f32 v[140:141], v[142:143], v[140:141] op_sel_hi:[0,1]
	v_pk_add_f32 v[136:137], v[136:137], v[210:211]
	global_store_dwordx4 v[214:215], v[136:139], off offset:192
	v_cvt_pk_bf16_f32 v142, v136, v137
	v_cvt_pk_bf16_f32 v143, v138, v139
	global_store_dwordx2 v[200:201], v[142:143], off offset:96
	v_mul_f32_e32 v142, v137, v137
	v_pk_fma_f32 v[136:137], v[136:137], v[136:137], v[142:143] op_sel_hi:[1,1,0]
	v_pk_add_f32 v[144:145], v[148:149], v[144:145]
	v_pk_fma_f32 v[136:137], v[138:139], v[138:139], v[136:137]
	v_mul_f32_e32 v138, v139, v139
	v_pk_add_f32 v[140:141], v[144:145], v[140:141]
	v_pk_add_f32 v[136:137], v[138:139], v[136:137] op_sel_hi:[0,1]
	v_pk_add_f32 v[136:137], v[140:141], v[136:137]
	s_nop 0
	v_mov_b32_e32 v137, v136
	s_nop 1
	v_permlane32_swap_b32_e32 v136, v137
	v_add_f32_e32 v136, v136, v137
	v_mov_b32_e32 v137, v136
	s_nop 1
	v_permlane16_swap_b32_e32 v136, v137
	s_and_saveexec_b64 s[24:25], vcc
	s_cbranch_execz .LBB0_564
	v_lshl_add_u64 v[138:139], v[180:181], 2, s[10:11]
	v_add_f32_e32 v136, v136, v137
	global_atomic_add_f32 v[138:139], v136, off

.LBB0_704:
	s_lshl_b32 s1, s51, 7
	s_lshl_b32 s0, s33, 10
	s_and_b32 s1, s1, 0x300
	s_or_b32 s0, s0, s1
	s_andn2_b64 vcc, exec, s[12:13]
	s_and_b32 s12, s16, 3
	s_cbranch_vccnz .LBB0_708
	s_ashr_i32 s1, s0, 31
	s_lshl_b32 s10, s52, 7
	s_lshl_b64 s[26:27], s[0:1], 11
	s_add_u32 s26, s5, s26
	s_addc_u32 s27, s6, s27
	s_ashr_i32 s11, s10, 31
	v_mov_b32_e32 v40, v220
	s_lshl_b64 s[10:11], s[10:11], 11
	s_add_u32 s10, s7, s10
	v_ashrrev_i32_e32 v30, 2, v40
	v_ashrrev_i32_e32 v31, 31, v30
	s_addc_u32 s11, s8, s11
	v_lshlrev_b64 v[0:1], 11, v[30:31]
	v_lshlrev_b32_e32 v4, 4, v40
	v_lshl_add_u64 v[2:3], s[10:11], 0, v[0:1]
	v_lshl_add_u64 v[0:1], s[26:27], 0, v[0:1]
	v_and_b32_e32 v152, 48, v4
	v_lshl_add_u64 v[154:155], v[0:1], 0, v[152:153]
	v_add_co_u32_e32 v32, vcc, s9, v154
	v_lshl_add_u64 v[156:157], v[2:3], 0, v[152:153]
	s_nop 0
	v_addc_co_u32_e32 v33, vcc, 0, v155, vcc
	v_add_co_u32_e32 v34, vcc, s31, v154
	global_load_dwordx4 v[6:9], v[154:155], off
	s_nop 0
	v_addc_co_u32_e32 v35, vcc, 0, v155, vcc
	v_add_co_u32_e32 v36, vcc, s35, v154
	global_load_dwordx4 v[10:13], v[32:33], off
	s_nop 0
	v_addc_co_u32_e32 v37, vcc, 0, v155, vcc
	v_add_co_u32_e32 v38, vcc, s9, v156
	global_load_dwordx4 v[14:17], v[34:35], off
	s_nop 0
	v_addc_co_u32_e32 v39, vcc, 0, v157, vcc
	global_load_dwordx4 v[18:21], v[36:37], off
	global_load_dwordx4 v[22:25], v[156:157], off
	global_load_dwordx4 v[26:29], v[38:39], off
	global_load_dwordx4 v[112:115], v[154:155], off offset:64
	global_load_dwordx4 v[120:123], v[32:33], off offset:64
	global_load_dwordx4 v[124:127], v[34:35], off offset:64
	global_load_dwordx4 v[128:131], v[36:37], off offset:64
	global_load_dwordx4 v[116:119], v[156:157], off offset:64
	global_load_dwordx4 v[132:135], v[38:39], off offset:64
	v_lshrrev_b32_e32 v31, 4, v40
	v_lshrrev_b32_e32 v41, 2, v40
	v_sub_u32_e32 v44, 0, v31
	v_sub_u32_e32 v41, 0, v41
	v_and_b32_e32 v42, 0x3ffff8f, v40
	v_lshlrev_b32_e32 v43, 6, v40
	v_xor_b32_e32 v40, v40, v44
	v_xor_b32_e32 v31, v31, v41
	v_lshlrev_b32_e32 v40, 4, v40
	v_lshlrev_b32_e32 v31, 4, v31
	v_and_b32_e32 v45, 0x1000, v43
	v_and_b32_e32 v40, 48, v40
	v_and_b32_e32 v31, 48, v31
	v_mov_b32_e32 v0, 0
	v_and_b32_e32 v46, 0x3c0, v43
	v_and_b32_e32 v43, 0xffffe3c0, v43
	v_lshl_add_u32 v42, v42, 6, v167
	v_lshl_or_b32 v152, v30, 6, v40
	v_or_b32_e32 v30, v31, v45
	s_mov_b32 s10, 0
	s_mov_b32 s1, -2
	v_mov_b32_e32 v1, v0
	v_mov_b32_e32 v2, v0
	v_mov_b32_e32 v3, v0
	v_mov_b32_e32 v4, v0
	v_mov_b32_e32 v5, v0
	v_lshl_add_u64 v[158:159], v[154:155], 0, s[22:23]
	v_lshl_add_u64 v[160:161], v[154:155], 0, s[24:25]
	v_lshl_add_u64 v[162:163], v[154:155], 0, s[28:29]
	v_or3_b32 v168, v45, v46, v31
	v_add_u32_e32 v169, v31, v43
	v_add_u32_e32 v170, v31, v42
	v_add_u32_e32 v171, v30, v46
	v_lshl_add_u64 v[164:165], v[156:157], 0, s[22:23]
	v_mov_b32_e32 v30, v0
	v_mov_b32_e32 v31, v0
	v_mov_b32_e32 v32, v0
	v_mov_b32_e32 v33, v0
	v_mov_b32_e32 v34, v0
	v_mov_b32_e32 v35, v0
	v_mov_b32_e32 v36, v0
	v_mov_b32_e32 v37, v0
	v_mov_b32_e32 v38, v0
	v_mov_b32_e32 v39, v0
	v_mov_b32_e32 v40, v0
	v_mov_b32_e32 v41, v0
	v_mov_b32_e32 v42, v0
	v_mov_b32_e32 v43, v0
	v_mov_b32_e32 v44, v0
	v_mov_b32_e32 v45, v0
	v_mov_b32_e32 v46, v0
	s_waitcnt vmcnt(11)
	ds_write_b128 v152, v[6:9]
	s_waitcnt vmcnt(10)
	ds_write_b128 v152, v[10:13] offset:4096
	s_waitcnt vmcnt(9)
	ds_write_b128 v152, v[14:17] offset:8192
	s_waitcnt vmcnt(8)
	ds_write_b128 v152, v[18:21] offset:12288
	s_waitcnt vmcnt(7)
	ds_write_b128 v152, v[22:25] offset:32768
	s_waitcnt vmcnt(6)
	ds_write_b128 v152, v[26:29] offset:36864
	v_mov_b32_e32 v6, v0
	v_mov_b32_e32 v7, v0
	v_mov_b32_e32 v8, v0
	v_mov_b32_e32 v9, v0
	v_mov_b32_e32 v10, v0
	v_mov_b32_e32 v11, v0
	v_mov_b32_e32 v12, v0
	v_mov_b32_e32 v13, v0
	v_mov_b32_e32 v14, v0
	v_mov_b32_e32 v15, v0
	v_mov_b32_e32 v16, v0
	v_mov_b32_e32 v17, v0
	v_mov_b32_e32 v18, v0
	v_mov_b32_e32 v19, v0
	v_mov_b32_e32 v20, v0
	v_mov_b32_e32 v21, v0
	v_mov_b32_e32 v22, v0
	v_mov_b32_e32 v23, v0
	v_mov_b32_e32 v24, v0
	v_mov_b32_e32 v25, v0
	v_mov_b32_e32 v26, v0
	v_mov_b32_e32 v27, v0
	v_mov_b32_e32 v28, v0
	v_mov_b32_e32 v29, v0
	v_mov_b32_e32 v47, v0
	v_mov_b32_e32 v48, v0
	v_mov_b32_e32 v49, v0
	v_mov_b32_e32 v50, v0
	v_mov_b32_e32 v51, v0
	v_mov_b32_e32 v52, v0
	v_mov_b32_e32 v53, v0
	v_mov_b32_e32 v54, v0
	v_mov_b32_e32 v55, v0
	v_mov_b32_e32 v56, v0
	v_mov_b32_e32 v57, v0
	v_mov_b32_e32 v58, v0
	v_mov_b32_e32 v59, v0
	v_mov_b32_e32 v60, v0
	v_mov_b32_e32 v61, v0
	v_mov_b32_e32 v62, v0
	v_mov_b32_e32 v63, v0
	v_mov_b32_e32 v64, v0
	v_mov_b32_e32 v65, v0
	v_mov_b32_e32 v66, v0
	v_mov_b32_e32 v67, v0
	v_mov_b32_e32 v68, v0
	v_mov_b32_e32 v69, v0
	v_mov_b32_e32 v70, v0
	v_mov_b32_e32 v71, v0
	v_mov_b32_e32 v72, v0
	v_mov_b32_e32 v73, v0
	v_mov_b32_e32 v74, v0
	v_mov_b32_e32 v75, v0
	v_mov_b32_e32 v76, v0
	v_mov_b32_e32 v77, v0
	v_mov_b32_e32 v78, v0
	v_mov_b32_e32 v79, v0
	v_mov_b32_e32 v80, v0
	v_mov_b32_e32 v81, v0
	v_mov_b32_e32 v82, v0
	v_mov_b32_e32 v83, v0
	v_mov_b32_e32 v84, v0
	v_mov_b32_e32 v85, v0
	v_mov_b32_e32 v86, v0
	v_mov_b32_e32 v87, v0
	v_mov_b32_e32 v88, v0
	v_mov_b32_e32 v89, v0
	v_mov_b32_e32 v90, v0
	v_mov_b32_e32 v91, v0
	v_mov_b32_e32 v92, v0
	v_mov_b32_e32 v93, v0
	v_mov_b32_e32 v94, v0
	v_mov_b32_e32 v95, v0
	v_mov_b32_e32 v96, v0
	v_mov_b32_e32 v97, v0
	v_mov_b32_e32 v98, v0
	v_mov_b32_e32 v99, v0
	v_mov_b32_e32 v100, v0
	v_mov_b32_e32 v101, v0
	v_mov_b32_e32 v102, v0
	v_mov_b32_e32 v103, v0
	v_mov_b32_e32 v104, v0
	v_mov_b32_e32 v105, v0
	v_mov_b32_e32 v106, v0
	v_mov_b32_e32 v107, v0
	v_mov_b32_e32 v108, v0
	v_mov_b32_e32 v109, v0
	v_mov_b32_e32 v110, v0
	v_mov_b32_e32 v111, v0
	v_mov_b32_e32 v136, v0
	v_mov_b32_e32 v137, v0
	v_mov_b32_e32 v138, v0
	v_mov_b32_e32 v139, v0
	v_mov_b32_e32 v140, v0
	v_mov_b32_e32 v141, v0
	v_mov_b32_e32 v142, v0
	v_mov_b32_e32 v143, v0
	v_mov_b32_e32 v144, v0
	v_mov_b32_e32 v145, v0
	v_mov_b32_e32 v146, v0
	v_mov_b32_e32 v147, v0
	v_mov_b32_e32 v148, v0
	v_mov_b32_e32 v149, v0
	v_mov_b32_e32 v150, v0
	v_mov_b32_e32 v151, v0
	s_waitcnt lgkmcnt(0)
	s_barrier
	global_load_dwordx4 v[172:175], v[154:155], off offset:128
	global_load_dwordx4 v[176:179], v[158:159], off offset:128
	global_load_dwordx4 v[180:183], v[160:161], off offset:128
	global_load_dwordx4 v[184:187], v[162:163], off offset:128
	global_load_dwordx4 v[188:191], v[156:157], off offset:128
	global_load_dwordx4 v[192:195], v[164:165], off offset:128
.LBB0_706:
	s_add_i32 s11, s10, 64
	s_add_i32 s16, s10, 96
	s_min_u32 s16, s16, 0x3e0
	s_lshl_b32 s16, s16, 1
	ds_read_b128 v[196:199], v171 offset:32768
	ds_read_b128 v[200:203], v171 offset:33792
	ds_read_b128 v[204:207], v171 offset:34816
	ds_read_b128 v[208:211], v171 offset:35840
	ds_read_b128 v[212:215], v169
	ds_read_b128 v[216:219], v169 offset:1024
	ds_read_b128 v[222:225], v169 offset:2048
	ds_read_b128 v[226:229], v169 offset:3072
	ds_read_b128 v[230:233], v169 offset:4096
	ds_read_b128 v[234:237], v169 offset:5120
	ds_read_b128 v[238:241], v169 offset:6144
	ds_read_b128 v[242:245], v169 offset:7168
	s_setprio 1
	s_waitcnt lgkmcnt(7)
	v_mfma_f32_16x16x32_bf16 v[148:151], v[196:199], v[212:215], v[148:151]
	v_mfma_f32_16x16x32_bf16 v[144:147], v[200:203], v[212:215], v[144:147]
	v_mfma_f32_16x16x32_bf16 v[140:143], v[204:207], v[212:215], v[140:143]
	v_mfma_f32_16x16x32_bf16 v[136:139], v[208:211], v[212:215], v[136:139]
	s_waitcnt vmcnt(11)
	ds_write_b128 v152, v[112:115] offset:16384
	s_waitcnt lgkmcnt(7)
	v_mfma_f32_16x16x32_bf16 v[108:111], v[196:199], v[216:219], v[108:111]
	v_mfma_f32_16x16x32_bf16 v[104:107], v[200:203], v[216:219], v[104:107]
	v_mfma_f32_16x16x32_bf16 v[100:103], v[204:207], v[216:219], v[100:103]
	v_mfma_f32_16x16x32_bf16 v[96:99], v[208:211], v[216:219], v[96:99]
	s_waitcnt vmcnt(10)
	ds_write_b128 v152, v[120:123] offset:20480
	v_lshl_add_u64 v[112:113], v[154:155], 0, s[16:17]
	global_load_dwordx4 v[112:115], v[112:113], off
	s_waitcnt lgkmcnt(7)
	v_mfma_f32_16x16x32_bf16 v[92:95], v[196:199], v[222:225], v[92:95]
	v_mfma_f32_16x16x32_bf16 v[88:91], v[200:203], v[222:225], v[88:91]
	v_mfma_f32_16x16x32_bf16 v[84:87], v[204:207], v[222:225], v[84:87]
	v_mfma_f32_16x16x32_bf16 v[80:83], v[208:211], v[222:225], v[80:83]
	s_waitcnt vmcnt(10)
	ds_write_b128 v152, v[124:127] offset:24576
	v_lshl_add_u64 v[120:121], v[158:159], 0, s[16:17]
	global_load_dwordx4 v[120:123], v[120:121], off
	s_waitcnt lgkmcnt(7)
	v_mfma_f32_16x16x32_bf16 v[76:79], v[196:199], v[226:229], v[76:79]
	v_mfma_f32_16x16x32_bf16 v[72:75], v[200:203], v[226:229], v[72:75]
	v_mfma_f32_16x16x32_bf16 v[68:71], v[204:207], v[226:229], v[68:71]
	v_mfma_f32_16x16x32_bf16 v[64:67], v[208:211], v[226:229], v[64:67]
	s_waitcnt vmcnt(10)
	ds_write_b128 v152, v[128:131] offset:28672
	v_lshl_add_u64 v[124:125], v[160:161], 0, s[16:17]
	global_load_dwordx4 v[124:127], v[124:125], off
	s_waitcnt lgkmcnt(7)
	v_mfma_f32_16x16x32_bf16 v[60:63], v[196:199], v[230:233], v[60:63]
	v_mfma_f32_16x16x32_bf16 v[56:59], v[200:203], v[230:233], v[56:59]
	v_mfma_f32_16x16x32_bf16 v[52:55], v[204:207], v[230:233], v[52:55]
	v_mfma_f32_16x16x32_bf16 v[48:51], v[208:211], v[230:233], v[48:51]
	s_waitcnt vmcnt(10)
	ds_write_b128 v152, v[116:119] offset:40960
	v_lshl_add_u64 v[128:129], v[162:163], 0, s[16:17]
	global_load_dwordx4 v[128:131], v[128:129], off
	s_waitcnt lgkmcnt(7)
	v_mfma_f32_16x16x32_bf16 v[44:47], v[196:199], v[234:237], v[44:47]
	v_mfma_f32_16x16x32_bf16 v[40:43], v[200:203], v[234:237], v[40:43]
	v_mfma_f32_16x16x32_bf16 v[36:39], v[204:207], v[234:237], v[36:39]
	v_mfma_f32_16x16x32_bf16 v[32:35], v[208:211], v[234:237], v[32:35]
	s_waitcnt vmcnt(10)
	ds_write_b128 v152, v[132:135] offset:45056
	v_lshl_add_u64 v[116:117], v[156:157], 0, s[16:17]
	global_load_dwordx4 v[116:119], v[116:117], off
	s_waitcnt lgkmcnt(7)
	v_mfma_f32_16x16x32_bf16 v[28:31], v[196:199], v[238:241], v[28:31]
	v_mfma_f32_16x16x32_bf16 v[24:27], v[200:203], v[238:241], v[24:27]
	v_mfma_f32_16x16x32_bf16 v[20:23], v[204:207], v[238:241], v[20:23]
	v_mfma_f32_16x16x32_bf16 v[16:19], v[208:211], v[238:241], v[16:19]
	v_lshl_add_u64 v[132:133], v[164:165], 0, s[16:17]
	global_load_dwordx4 v[132:135], v[132:133], off
	s_waitcnt lgkmcnt(6)
	v_mfma_f32_16x16x32_bf16 v[12:15], v[196:199], v[242:245], v[12:15]
	v_mfma_f32_16x16x32_bf16 v[8:11], v[200:203], v[242:245], v[8:11]
	v_mfma_f32_16x16x32_bf16 v[4:7], v[204:207], v[242:245], v[4:7]
	v_mfma_f32_16x16x32_bf16 v[0:3], v[208:211], v[242:245], v[0:3]
	s_setprio 0
	s_waitcnt lgkmcnt(0)
	s_barrier
	s_add_i32 s16, s10, 0x80
	s_min_u32 s16, s16, 0x3e0
	s_lshl_b32 s16, s16, 1
	ds_read_b128 v[196:199], v168 offset:40960
	ds_read_b128 v[200:203], v168 offset:41984
	ds_read_b128 v[204:207], v168 offset:43008
	ds_read_b128 v[208:211], v168 offset:44032
	ds_read_b128 v[212:215], v170
	ds_read_b128 v[216:219], v170 offset:1024
	ds_read_b128 v[222:225], v170 offset:2048
	ds_read_b128 v[226:229], v170 offset:3072
	ds_read_b128 v[230:233], v170 offset:4096
	ds_read_b128 v[234:237], v170 offset:5120
	ds_read_b128 v[238:241], v170 offset:6144
	ds_read_b128 v[242:245], v170 offset:7168
	s_setprio 1
	s_waitcnt lgkmcnt(7)
	v_mfma_f32_16x16x32_bf16 v[148:151], v[196:199], v[212:215], v[148:151]
	v_mfma_f32_16x16x32_bf16 v[144:147], v[200:203], v[212:215], v[144:147]
	v_mfma_f32_16x16x32_bf16 v[140:143], v[204:207], v[212:215], v[140:143]
	v_mfma_f32_16x16x32_bf16 v[136:139], v[208:211], v[212:215], v[136:139]
	s_waitcnt vmcnt(11)
	ds_write_b128 v152, v[172:175]
	s_waitcnt lgkmcnt(7)
	v_mfma_f32_16x16x32_bf16 v[108:111], v[196:199], v[216:219], v[108:111]
	v_mfma_f32_16x16x32_bf16 v[104:107], v[200:203], v[216:219], v[104:107]
	v_mfma_f32_16x16x32_bf16 v[100:103], v[204:207], v[216:219], v[100:103]
	v_mfma_f32_16x16x32_bf16 v[96:99], v[208:211], v[216:219], v[96:99]
	s_waitcnt vmcnt(10)
	ds_write_b128 v152, v[176:179] offset:4096
	v_lshl_add_u64 v[172:173], v[154:155], 0, s[16:17]
	global_load_dwordx4 v[172:175], v[172:173], off
	s_waitcnt lgkmcnt(7)
	v_mfma_f32_16x16x32_bf16 v[92:95], v[196:199], v[222:225], v[92:95]
	v_mfma_f32_16x16x32_bf16 v[88:91], v[200:203], v[222:225], v[88:91]
	v_mfma_f32_16x16x32_bf16 v[84:87], v[204:207], v[222:225], v[84:87]
	v_mfma_f32_16x16x32_bf16 v[80:83], v[208:211], v[222:225], v[80:83]
	s_waitcnt vmcnt(10)
	ds_write_b128 v152, v[180:183] offset:8192
	v_lshl_add_u64 v[176:177], v[158:159], 0, s[16:17]
	global_load_dwordx4 v[176:179], v[176:177], off
	s_waitcnt lgkmcnt(7)
	v_mfma_f32_16x16x32_bf16 v[76:79], v[196:199], v[226:229], v[76:79]
	v_mfma_f32_16x16x32_bf16 v[72:75], v[200:203], v[226:229], v[72:75]
	v_mfma_f32_16x16x32_bf16 v[68:71], v[204:207], v[226:229], v[68:71]
	v_mfma_f32_16x16x32_bf16 v[64:67], v[208:211], v[226:229], v[64:67]
	s_waitcnt vmcnt(10)
	ds_write_b128 v152, v[184:187] offset:12288
	v_lshl_add_u64 v[180:181], v[160:161], 0, s[16:17]
	global_load_dwordx4 v[180:183], v[180:181], off
	s_waitcnt lgkmcnt(7)
	v_mfma_f32_16x16x32_bf16 v[60:63], v[196:199], v[230:233], v[60:63]
	v_mfma_f32_16x16x32_bf16 v[56:59], v[200:203], v[230:233], v[56:59]
	v_mfma_f32_16x16x32_bf16 v[52:55], v[204:207], v[230:233], v[52:55]
	v_mfma_f32_16x16x32_bf16 v[48:51], v[208:211], v[230:233], v[48:51]
	s_waitcnt vmcnt(10)
	ds_write_b128 v152, v[188:191] offset:32768
	v_lshl_add_u64 v[184:185], v[162:163], 0, s[16:17]
	global_load_dwordx4 v[184:187], v[184:185], off
	s_waitcnt lgkmcnt(7)
	v_mfma_f32_16x16x32_bf16 v[44:47], v[196:199], v[234:237], v[44:47]
	v_mfma_f32_16x16x32_bf16 v[40:43], v[200:203], v[234:237], v[40:43]
	v_mfma_f32_16x16x32_bf16 v[36:39], v[204:207], v[234:237], v[36:39]
	v_mfma_f32_16x16x32_bf16 v[32:35], v[208:211], v[234:237], v[32:35]
	s_waitcnt vmcnt(10)
	ds_write_b128 v152, v[192:195] offset:36864
	v_lshl_add_u64 v[188:189], v[156:157], 0, s[16:17]
	global_load_dwordx4 v[188:191], v[188:189], off
	s_waitcnt lgkmcnt(7)
	v_mfma_f32_16x16x32_bf16 v[28:31], v[196:199], v[238:241], v[28:31]
	v_mfma_f32_16x16x32_bf16 v[24:27], v[200:203], v[238:241], v[24:27]
	v_mfma_f32_16x16x32_bf16 v[20:23], v[204:207], v[238:241], v[20:23]
	v_mfma_f32_16x16x32_bf16 v[16:19], v[208:211], v[238:241], v[16:19]
	v_lshl_add_u64 v[192:193], v[164:165], 0, s[16:17]
	global_load_dwordx4 v[192:195], v[192:193], off
	s_waitcnt lgkmcnt(6)
	v_mfma_f32_16x16x32_bf16 v[12:15], v[196:199], v[242:245], v[12:15]
	v_mfma_f32_16x16x32_bf16 v[8:11], v[200:203], v[242:245], v[8:11]
	v_mfma_f32_16x16x32_bf16 v[4:7], v[204:207], v[242:245], v[4:7]
	v_mfma_f32_16x16x32_bf16 v[0:3], v[208:211], v[242:245], v[0:3]
	s_setprio 0
	s_add_i32 s1, s1, 2
	s_cmp_lt_u32 s1, 30
	s_mov_b32 s10, s11
	s_waitcnt lgkmcnt(0)
	s_barrier
	s_cbranch_scc1 .LBB0_706
	s_waitcnt vmcnt(0)
	s_waitcnt vmcnt(4)
	v_mov_b32_e32 v116, v220
	s_nop 0
	v_and_b32_e32 v112, 0xffffff80, v116
	v_add_u32_e32 v117, s0, v112
	v_and_or_b32 v114, v116, 15, v117
	v_ashrrev_i32_e32 v115, 31, v114
	v_lshl_add_u64 v[112:113], v[114:115], 2, s[14:15]
	global_load_dword v122, v[112:113], off
	v_and_b32_e32 v112, 64, v116
	v_lshrrev_b32_e32 v115, 1, v116
	v_ashrrev_i32_e32 v116, 14, v117
	v_ashrrev_i32_e32 v117, 31, v116
	v_lshlrev_b32_e32 v152, 1, v112
	v_or_b32_e32 v118, 16, v114
	v_lshlrev_b64 v[116:117], 16, v[116:117]
	v_lshl_add_u64 v[112:113], s[38:39], 0, v[152:153]
	v_and_b32_e32 v152, 24, v115
	v_ashrrev_i32_e32 v119, 31, v118
	v_lshl_or_b32 v115, s12, 14, v116
	s_waitcnt vmcnt(4)
	v_lshl_add_u64 v[120:121], v[118:119], 2, s[14:15]
	v_lshl_add_u64 v[112:113], v[112:113], 0, v[152:153]
	s_waitcnt vmcnt(0)
	v_fmamk_f32 v116, v122, 0x3a800000, v166
	v_mul_f32_e32 v119, 0x4b800000, v116
	v_cmp_gt_f32_e32 vcc, s40, v116
	s_nop 1
	v_cndmask_b32_e32 v116, v116, v119, vcc
	v_rsq_f32_e32 v119, v116
	v_and_or_b32 v116, v114, s41, v115
	v_lshlrev_b64 v[122:123], 8, v[116:117]
	v_lshl_add_u64 v[122:123], v[112:113], 0, v[122:123]
	v_mul_f32_e32 v116, 0x45800000, v119
	v_cndmask_b32_e32 v116, v119, v116, vcc
	v_mul_f32_e32 v124, v149, v116
	v_mul_f32_e32 v125, v150, v116
	v_mul_f32_e32 v119, v148, v116
	v_mul_f32_e32 v126, v151, v116
	v_mul_f32_e32 v127, v144, v116
	v_mul_f32_e32 v128, v145, v116
	v_mul_f32_e32 v129, v146, v116
	v_mul_f32_e32 v130, v147, v116
	v_mul_f32_e32 v131, v140, v116
	v_cvt_pk_bf16_f32 v124, v119, v124
	v_cvt_pk_bf16_f32 v125, v125, v126
	v_mul_f32_e32 v132, v141, v116
	v_mul_f32_e32 v133, v142, v116
	v_mul_f32_e32 v134, v143, v116
	v_mul_f32_e32 v135, v136, v116
	v_mul_f32_e32 v136, v137, v116
	v_mul_f32_e32 v137, v138, v116
	v_mul_f32_e32 v116, v139, v116
	v_cvt_pk_bf16_f32 v126, v127, v128
	v_cvt_pk_bf16_f32 v127, v129, v130
	v_cvt_pk_bf16_f32 v128, v131, v132
	v_cvt_pk_bf16_f32 v129, v133, v134
	v_cvt_pk_bf16_f32 v130, v135, v136
	v_cvt_pk_bf16_f32 v131, v137, v116
	global_store_dwordx2 v[122:123], v[124:125], off
	global_store_dwordx2 v[122:123], v[126:127], off offset:32
	global_store_dwordx2 v[122:123], v[128:129], off offset:64
	global_store_dwordx2 v[122:123], v[130:131], off offset:96
	global_load_dword v116, v[120:121], off
	v_or_b32_e32 v120, 32, v114
	v_ashrrev_i32_e32 v121, 31, v120
	v_lshl_add_u64 v[122:123], v[120:121], 2, s[14:15]
	s_waitcnt vmcnt(0)
	v_fmamk_f32 v116, v116, 0x3a800000, v166
	v_mul_f32_e32 v119, 0x4b800000, v116
	v_cmp_gt_f32_e32 vcc, s40, v116
	s_nop 1
	v_cndmask_b32_e32 v116, v116, v119, vcc
	v_rsq_f32_e32 v121, v116
	v_and_or_b32 v116, v118, s42, v115
	v_lshlrev_b64 v[118:119], 8, v[116:117]
	v_lshl_add_u64 v[118:119], v[112:113], 0, v[118:119]
	v_mul_f32_e32 v116, 0x45800000, v121
	v_cndmask_b32_e32 v116, v121, v116, vcc
	v_mul_f32_e32 v108, v108, v116
	v_mul_f32_e32 v109, v109, v116
	v_mul_f32_e32 v110, v110, v116
	v_mul_f32_e32 v111, v111, v116
	v_mul_f32_e32 v100, v100, v116
	v_mul_f32_e32 v101, v101, v116
	v_mul_f32_e32 v102, v102, v116
	v_mul_f32_e32 v103, v103, v116
	v_mul_f32_e32 v121, v96, v116
	v_mul_f32_e32 v124, v97, v116
	v_cvt_pk_bf16_f32 v96, v108, v109
	v_cvt_pk_bf16_f32 v97, v110, v111
	v_mul_f32_e32 v104, v104, v116
	v_mul_f32_e32 v105, v105, v116
	v_mul_f32_e32 v106, v106, v116
	v_mul_f32_e32 v107, v107, v116
	v_mul_f32_e32 v125, v98, v116
	v_mul_f32_e32 v116, v99, v116
	v_cvt_pk_bf16_f32 v98, v104, v105
	v_cvt_pk_bf16_f32 v99, v106, v107
	v_cvt_pk_bf16_f32 v100, v100, v101
	v_cvt_pk_bf16_f32 v101, v102, v103
	v_cvt_pk_bf16_f32 v102, v121, v124
	v_cvt_pk_bf16_f32 v103, v125, v116
	global_store_dwordx2 v[118:119], v[96:97], off
	global_store_dwordx2 v[118:119], v[98:99], off offset:32
	global_store_dwordx2 v[118:119], v[100:101], off offset:64
	global_store_dwordx2 v[118:119], v[102:103], off offset:96
	global_load_dword v100, v[122:123], off
	v_or_b32_e32 v96, 48, v114
	v_ashrrev_i32_e32 v97, 31, v96
	v_lshl_add_u64 v[98:99], v[96:97], 2, s[14:15]
	v_and_or_b32 v116, v120, s43, v115
	s_waitcnt vmcnt(0)
	v_fmamk_f32 v97, v100, 0x3a800000, v166
	v_mul_f32_e32 v100, 0x4b800000, v97
	v_cmp_gt_f32_e32 vcc, s40, v97
	s_nop 1
	v_cndmask_b32_e32 v97, v97, v100, vcc
	v_rsq_f32_e32 v97, v97
	v_lshlrev_b64 v[100:101], 8, v[116:117]
	v_lshl_add_u64 v[100:101], v[112:113], 0, v[100:101]
	v_and_or_b32 v116, v96, s44, v115
	v_mul_f32_e32 v102, 0x45800000, v97
	v_cndmask_b32_e32 v97, v97, v102, vcc
	v_mul_f32_e32 v92, v92, v97
	v_mul_f32_e32 v93, v93, v97
	v_mul_f32_e32 v94, v94, v97
	v_mul_f32_e32 v95, v95, v97
	v_mul_f32_e32 v84, v84, v97
	v_mul_f32_e32 v85, v85, v97
	v_mul_f32_e32 v86, v86, v97
	v_mul_f32_e32 v87, v87, v97
	v_mul_f32_e32 v102, v80, v97
	v_mul_f32_e32 v103, v81, v97
	v_cvt_pk_bf16_f32 v80, v92, v93
	v_cvt_pk_bf16_f32 v81, v94, v95
	v_mul_f32_e32 v88, v88, v97
	v_mul_f32_e32 v89, v89, v97
	v_mul_f32_e32 v90, v90, v97
	v_mul_f32_e32 v91, v91, v97
	v_mul_f32_e32 v104, v82, v97
	v_mul_f32_e32 v97, v83, v97
	v_cvt_pk_bf16_f32 v82, v88, v89
	v_cvt_pk_bf16_f32 v83, v90, v91
	v_cvt_pk_bf16_f32 v84, v84, v85
	v_cvt_pk_bf16_f32 v85, v86, v87
	v_cvt_pk_bf16_f32 v86, v102, v103
	v_cvt_pk_bf16_f32 v87, v104, v97
	global_store_dwordx2 v[100:101], v[80:81], off
	global_store_dwordx2 v[100:101], v[82:83], off offset:32
	global_store_dwordx2 v[100:101], v[84:85], off offset:64
	global_store_dwordx2 v[100:101], v[86:87], off offset:96
	global_load_dword v84, v[98:99], off
	v_or_b32_e32 v80, 64, v114
	v_ashrrev_i32_e32 v81, 31, v80
	v_lshl_add_u64 v[82:83], v[80:81], 2, s[14:15]
	s_waitcnt vmcnt(0)
	v_fmamk_f32 v81, v84, 0x3a800000, v166
	v_mul_f32_e32 v84, 0x4b800000, v81
	v_cmp_gt_f32_e32 vcc, s40, v81
	s_nop 1
	v_cndmask_b32_e32 v81, v81, v84, vcc
	v_rsq_f32_e32 v81, v81
	v_lshlrev_b64 v[84:85], 8, v[116:117]
	v_lshl_add_u64 v[84:85], v[112:113], 0, v[84:85]
	v_and_or_b32 v116, v80, s45, v115
	v_mul_f32_e32 v86, 0x45800000, v81
	v_cndmask_b32_e32 v81, v81, v86, vcc
	v_mul_f32_e32 v76, v76, v81
	v_mul_f32_e32 v77, v77, v81
	v_mul_f32_e32 v78, v78, v81
	v_mul_f32_e32 v79, v79, v81
	v_mul_f32_e32 v68, v68, v81
	v_mul_f32_e32 v69, v69, v81
	v_mul_f32_e32 v70, v70, v81
	v_mul_f32_e32 v71, v71, v81
	v_mul_f32_e32 v86, v64, v81
	v_mul_f32_e32 v87, v65, v81
	v_cvt_pk_bf16_f32 v64, v76, v77
	v_cvt_pk_bf16_f32 v65, v78, v79
	v_mul_f32_e32 v72, v72, v81
	v_mul_f32_e32 v73, v73, v81
	v_mul_f32_e32 v74, v74, v81
	v_mul_f32_e32 v75, v75, v81
	v_mul_f32_e32 v88, v66, v81
	v_mul_f32_e32 v81, v67, v81
	v_cvt_pk_bf16_f32 v66, v72, v73
	v_cvt_pk_bf16_f32 v67, v74, v75
	v_cvt_pk_bf16_f32 v68, v68, v69
	v_cvt_pk_bf16_f32 v69, v70, v71
	v_cvt_pk_bf16_f32 v70, v86, v87
	v_cvt_pk_bf16_f32 v71, v88, v81
	global_store_dwordx2 v[84:85], v[64:65], off
	global_store_dwordx2 v[84:85], v[66:67], off offset:32
	global_store_dwordx2 v[84:85], v[68:69], off offset:64
	global_store_dwordx2 v[84:85], v[70:71], off offset:96
	global_load_dword v68, v[82:83], off
	v_or_b32_e32 v64, 0x50, v114
	v_ashrrev_i32_e32 v65, 31, v64
	v_lshl_add_u64 v[66:67], v[64:65], 2, s[14:15]
	s_waitcnt vmcnt(0)
	v_fmamk_f32 v65, v68, 0x3a800000, v166
	v_mul_f32_e32 v68, 0x4b800000, v65
	v_cmp_gt_f32_e32 vcc, s40, v65
	s_nop 1
	v_cndmask_b32_e32 v65, v65, v68, vcc
	v_rsq_f32_e32 v65, v65
	v_lshlrev_b64 v[68:69], 8, v[116:117]
	v_lshl_add_u64 v[68:69], v[112:113], 0, v[68:69]
	v_and_or_b32 v116, v64, s46, v115
	v_mul_f32_e32 v70, 0x45800000, v65
	v_cndmask_b32_e32 v65, v65, v70, vcc
	v_mul_f32_e32 v60, v60, v65
	v_mul_f32_e32 v61, v61, v65
	v_mul_f32_e32 v62, v62, v65
	v_mul_f32_e32 v63, v63, v65
	v_mul_f32_e32 v52, v52, v65
	v_mul_f32_e32 v53, v53, v65
	v_mul_f32_e32 v54, v54, v65
	v_mul_f32_e32 v55, v55, v65
	v_mul_f32_e32 v70, v48, v65
	v_mul_f32_e32 v71, v49, v65
	v_cvt_pk_bf16_f32 v48, v60, v61
	v_cvt_pk_bf16_f32 v49, v62, v63
	v_mul_f32_e32 v56, v56, v65
	v_mul_f32_e32 v57, v57, v65
	v_mul_f32_e32 v58, v58, v65
	v_mul_f32_e32 v59, v59, v65
	v_mul_f32_e32 v72, v50, v65
	v_mul_f32_e32 v65, v51, v65
	v_cvt_pk_bf16_f32 v50, v56, v57
	v_cvt_pk_bf16_f32 v51, v58, v59
	v_cvt_pk_bf16_f32 v52, v52, v53
	v_cvt_pk_bf16_f32 v53, v54, v55
	v_cvt_pk_bf16_f32 v54, v70, v71
	v_cvt_pk_bf16_f32 v55, v72, v65
	global_store_dwordx2 v[68:69], v[48:49], off
	global_store_dwordx2 v[68:69], v[50:51], off offset:32
	global_store_dwordx2 v[68:69], v[52:53], off offset:64
	global_store_dwordx2 v[68:69], v[54:55], off offset:96
	global_load_dword v52, v[66:67], off
	v_or_b32_e32 v48, 0x60, v114
	v_ashrrev_i32_e32 v49, 31, v48
	v_lshl_add_u64 v[50:51], v[48:49], 2, s[14:15]
	s_waitcnt vmcnt(0)
	v_fmamk_f32 v49, v52, 0x3a800000, v166
	v_mul_f32_e32 v52, 0x4b800000, v49
	v_cmp_gt_f32_e32 vcc, s40, v49
	s_nop 1
	v_cndmask_b32_e32 v49, v49, v52, vcc
	v_rsq_f32_e32 v49, v49
	v_lshlrev_b64 v[52:53], 8, v[116:117]
	v_lshl_add_u64 v[52:53], v[112:113], 0, v[52:53]
	v_and_or_b32 v116, v48, s47, v115
	v_mul_f32_e32 v54, 0x45800000, v49
	v_cndmask_b32_e32 v49, v49, v54, vcc
	v_mul_f32_e32 v44, v44, v49
	v_mul_f32_e32 v45, v45, v49
	v_mul_f32_e32 v46, v46, v49
	v_mul_f32_e32 v47, v47, v49
	v_mul_f32_e32 v36, v36, v49
	v_mul_f32_e32 v37, v37, v49
	v_mul_f32_e32 v38, v38, v49
	v_mul_f32_e32 v39, v39, v49
	v_mul_f32_e32 v54, v32, v49
	v_mul_f32_e32 v55, v33, v49
	v_cvt_pk_bf16_f32 v32, v44, v45
	v_cvt_pk_bf16_f32 v33, v46, v47
	v_mul_f32_e32 v40, v40, v49
	v_mul_f32_e32 v41, v41, v49
	v_mul_f32_e32 v42, v42, v49
	v_mul_f32_e32 v43, v43, v49
	v_mul_f32_e32 v56, v34, v49
	v_mul_f32_e32 v49, v35, v49
	v_cvt_pk_bf16_f32 v34, v40, v41
	v_cvt_pk_bf16_f32 v35, v42, v43
	v_cvt_pk_bf16_f32 v36, v36, v37
	v_cvt_pk_bf16_f32 v37, v38, v39
	v_cvt_pk_bf16_f32 v38, v54, v55
	v_cvt_pk_bf16_f32 v39, v56, v49
	global_store_dwordx2 v[52:53], v[32:33], off
	global_store_dwordx2 v[52:53], v[34:35], off offset:32
	global_store_dwordx2 v[52:53], v[36:37], off offset:64
	global_store_dwordx2 v[52:53], v[38:39], off offset:96
	global_load_dword v36, v[50:51], off
	v_or_b32_e32 v32, 0x70, v114
	v_ashrrev_i32_e32 v33, 31, v32
	v_lshl_add_u64 v[34:35], v[32:33], 2, s[14:15]
	s_waitcnt vmcnt(0)
	v_fmamk_f32 v33, v36, 0x3a800000, v166
	v_mul_f32_e32 v36, 0x4b800000, v33
	v_cmp_gt_f32_e32 vcc, s40, v33
	s_nop 1
	v_cndmask_b32_e32 v33, v33, v36, vcc
	v_rsq_f32_e32 v33, v33
	v_lshlrev_b64 v[36:37], 8, v[116:117]
	v_lshl_add_u64 v[36:37], v[112:113], 0, v[36:37]
	v_and_or_b32 v116, v32, s48, v115
	v_mul_f32_e32 v38, 0x45800000, v33
	v_cndmask_b32_e32 v33, v33, v38, vcc
	v_mul_f32_e32 v28, v28, v33
	v_mul_f32_e32 v29, v29, v33
	v_mul_f32_e32 v30, v30, v33
	v_mul_f32_e32 v31, v31, v33
	v_mul_f32_e32 v20, v20, v33
	v_mul_f32_e32 v21, v21, v33
	v_mul_f32_e32 v22, v22, v33
	v_mul_f32_e32 v23, v23, v33
	v_mul_f32_e32 v38, v16, v33
	v_mul_f32_e32 v39, v17, v33
	v_cvt_pk_bf16_f32 v16, v28, v29
	v_cvt_pk_bf16_f32 v17, v30, v31
	v_mul_f32_e32 v24, v24, v33
	v_mul_f32_e32 v25, v25, v33
	v_mul_f32_e32 v26, v26, v33
	v_mul_f32_e32 v27, v27, v33
	v_mul_f32_e32 v40, v18, v33
	v_mul_f32_e32 v33, v19, v33
	v_cvt_pk_bf16_f32 v18, v24, v25
	v_cvt_pk_bf16_f32 v19, v26, v27
	v_cvt_pk_bf16_f32 v20, v20, v21
	v_cvt_pk_bf16_f32 v21, v22, v23
	v_cvt_pk_bf16_f32 v22, v38, v39
	v_cvt_pk_bf16_f32 v23, v40, v33
	global_store_dwordx2 v[36:37], v[16:17], off
	global_store_dwordx2 v[36:37], v[18:19], off offset:32
	global_store_dwordx2 v[36:37], v[20:21], off offset:64
	global_store_dwordx2 v[36:37], v[22:23], off offset:96
	global_load_dword v16, v[34:35], off
	s_waitcnt vmcnt(0)
	v_fmamk_f32 v16, v16, 0x3a800000, v166
	v_mul_f32_e32 v17, 0x4b800000, v16
	v_cmp_gt_f32_e32 vcc, s40, v16
	s_nop 1
	v_cndmask_b32_e32 v16, v16, v17, vcc
	v_rsq_f32_e32 v18, v16
	v_lshlrev_b64 v[16:17], 8, v[116:117]
	v_lshl_add_u64 v[16:17], v[112:113], 0, v[16:17]
	v_mul_f32_e32 v19, 0x45800000, v18
	v_cndmask_b32_e32 v18, v18, v19, vcc
	v_mul_f32_e32 v12, v12, v18
	v_mul_f32_e32 v13, v13, v18
	v_mul_f32_e32 v14, v14, v18
	v_mul_f32_e32 v15, v15, v18
	v_mul_f32_e32 v4, v4, v18
	v_mul_f32_e32 v5, v5, v18
	v_mul_f32_e32 v6, v6, v18
	v_mul_f32_e32 v7, v7, v18
	v_mul_f32_e32 v19, v0, v18
	v_mul_f32_e32 v20, v1, v18
	v_cvt_pk_bf16_f32 v0, v12, v13
	v_cvt_pk_bf16_f32 v1, v14, v15
	v_mul_f32_e32 v8, v8, v18
	v_mul_f32_e32 v9, v9, v18
	v_mul_f32_e32 v10, v10, v18
	v_mul_f32_e32 v11, v11, v18
	v_mul_f32_e32 v21, v2, v18
	v_mul_f32_e32 v18, v3, v18
	v_cvt_pk_bf16_f32 v2, v8, v9
	v_cvt_pk_bf16_f32 v3, v10, v11
	v_cvt_pk_bf16_f32 v4, v4, v5
	v_cvt_pk_bf16_f32 v5, v6, v7
	v_cvt_pk_bf16_f32 v6, v19, v20
	v_cvt_pk_bf16_f32 v7, v21, v18
	global_store_dwordx2 v[16:17], v[0:1], off
	global_store_dwordx2 v[16:17], v[2:3], off offset:32
	global_store_dwordx2 v[16:17], v[4:5], off offset:64
	global_store_dwordx2 v[16:17], v[6:7], off offset:96
	s_branch .LBB0_699
.LBB0_708:
	s_and_b64 vcc, exec, s[10:11]
	s_cbranch_vccz .LBB0_699
	s_ashr_i32 s1, s0, 31
	s_lshl_b64 s[10:11], s[0:1], 11
	s_add_u32 s10, s5, s10
	v_mov_b32_e32 v7, v220
	s_addc_u32 s11, s6, s11
	s_lshl_b32 s1, s52, 18
	s_add_u32 s26, s7, s1
	v_ashrrev_i32_e32 v32, 2, v7
	v_ashrrev_i32_e32 v33, 31, v32
	s_addc_u32 s27, s8, 0
	v_lshlrev_b64 v[0:1], 11, v[32:33]
	v_lshlrev_b32_e32 v4, 4, v7
	v_lshl_add_u64 v[2:3], s[26:27], 0, v[0:1]
	v_lshl_add_u64 v[0:1], s[10:11], 0, v[0:1]
	v_and_b32_e32 v152, 48, v4
	v_lshl_add_u64 v[154:155], v[0:1], 0, v[152:153]
	v_add_co_u32_e32 v34, vcc, s9, v154
	v_lshl_add_u64 v[156:157], v[2:3], 0, v[152:153]
	s_nop 0
	v_addc_co_u32_e32 v35, vcc, 0, v155, vcc
	v_add_co_u32_e32 v36, vcc, s31, v154
	global_load_dwordx4 v[8:11], v[154:155], off
	s_nop 0
	v_addc_co_u32_e32 v37, vcc, 0, v155, vcc
	v_add_co_u32_e32 v38, vcc, s35, v154
	global_load_dwordx4 v[12:15], v[34:35], off
	s_nop 0
	v_addc_co_u32_e32 v39, vcc, 0, v155, vcc
	v_add_co_u32_e32 v40, vcc, s9, v156
	global_load_dwordx4 v[16:19], v[36:37], off
	s_nop 0
	v_addc_co_u32_e32 v41, vcc, 0, v157, vcc
	global_load_dwordx4 v[20:23], v[38:39], off
	global_load_dwordx4 v[24:27], v[156:157], off
	global_load_dwordx4 v[28:31], v[40:41], off
	global_load_dwordx4 v[112:115], v[154:155], off offset:64
	global_load_dwordx4 v[120:123], v[34:35], off offset:64
	global_load_dwordx4 v[124:127], v[36:37], off offset:64
	global_load_dwordx4 v[132:135], v[38:39], off offset:64
	global_load_dwordx4 v[116:119], v[156:157], off offset:64
	global_load_dwordx4 v[136:139], v[40:41], off offset:64
	v_lshrrev_b32_e32 v33, 4, v7
	v_lshrrev_b32_e32 v42, 2, v7
	v_sub_u32_e32 v45, 0, v33
	v_sub_u32_e32 v42, 0, v42
	v_and_b32_e32 v43, 0x3ffff8f, v7
	v_lshlrev_b32_e32 v44, 6, v7
	v_xor_b32_e32 v7, v7, v45
	v_xor_b32_e32 v33, v33, v42
	v_lshlrev_b32_e32 v7, 4, v7
	v_lshlrev_b32_e32 v33, 4, v33
	v_and_b32_e32 v46, 0x1000, v44
	v_and_b32_e32 v7, 48, v7
	v_and_b32_e32 v33, 48, v33
	v_mov_b32_e32 v0, 0
	v_and_b32_e32 v47, 0x3c0, v44
	v_and_b32_e32 v44, 0xffffe3c0, v44
	v_lshl_add_u32 v43, v43, 6, v167
	v_lshl_or_b32 v152, v32, 6, v7
	v_or_b32_e32 v7, v33, v46
	s_mov_b32 s10, 0
	s_mov_b32 s1, -2
	v_mov_b32_e32 v1, v0
	v_mov_b32_e32 v2, v0
	v_mov_b32_e32 v3, v0
	v_mov_b32_e32 v4, v0
	v_mov_b32_e32 v5, v0
	v_mov_b32_e32 v6, v0
	v_lshl_add_u64 v[158:159], v[154:155], 0, s[22:23]
	v_lshl_add_u64 v[160:161], v[154:155], 0, s[24:25]
	v_lshl_add_u64 v[162:163], v[154:155], 0, s[28:29]
	v_or3_b32 v168, v46, v47, v33
	v_add_u32_e32 v169, v33, v44
	v_add_u32_e32 v170, v33, v43
	v_lshl_add_u64 v[164:165], v[156:157], 0, s[22:23]
	v_add_u32_e32 v171, v7, v47
	v_mov_b32_e32 v7, v0
	v_mov_b32_e32 v32, v0
	v_mov_b32_e32 v33, v0
	v_mov_b32_e32 v34, v0
	v_mov_b32_e32 v35, v0
	v_mov_b32_e32 v36, v0
	v_mov_b32_e32 v37, v0
	v_mov_b32_e32 v38, v0
	v_mov_b32_e32 v39, v0
	v_mov_b32_e32 v40, v0
	v_mov_b32_e32 v41, v0
	v_mov_b32_e32 v42, v0
	v_mov_b32_e32 v43, v0
	v_mov_b32_e32 v44, v0
	v_mov_b32_e32 v45, v0
	v_mov_b32_e32 v46, v0
	v_mov_b32_e32 v47, v0
	s_waitcnt vmcnt(11)
	ds_write_b128 v152, v[8:11]
	s_waitcnt vmcnt(10)
	ds_write_b128 v152, v[12:15] offset:4096
	s_waitcnt vmcnt(9)
	ds_write_b128 v152, v[16:19] offset:8192
	s_waitcnt vmcnt(8)
	ds_write_b128 v152, v[20:23] offset:12288
	s_waitcnt vmcnt(7)
	ds_write_b128 v152, v[24:27] offset:32768
	s_waitcnt vmcnt(6)
	ds_write_b128 v152, v[28:31] offset:36864
	v_mov_b32_e32 v8, v0
	v_mov_b32_e32 v9, v0
	v_mov_b32_e32 v10, v0
	v_mov_b32_e32 v11, v0
	v_mov_b32_e32 v12, v0
	v_mov_b32_e32 v13, v0
	v_mov_b32_e32 v14, v0
	v_mov_b32_e32 v15, v0
	v_mov_b32_e32 v16, v0
	v_mov_b32_e32 v17, v0
	v_mov_b32_e32 v18, v0
	v_mov_b32_e32 v19, v0
	v_mov_b32_e32 v20, v0
	v_mov_b32_e32 v21, v0
	v_mov_b32_e32 v22, v0
	v_mov_b32_e32 v23, v0
	v_mov_b32_e32 v24, v0
	v_mov_b32_e32 v25, v0
	v_mov_b32_e32 v26, v0
	v_mov_b32_e32 v27, v0
	v_mov_b32_e32 v28, v0
	v_mov_b32_e32 v29, v0
	v_mov_b32_e32 v30, v0
	v_mov_b32_e32 v31, v0
	v_mov_b32_e32 v48, v0
	v_mov_b32_e32 v49, v0
	v_mov_b32_e32 v50, v0
	v_mov_b32_e32 v51, v0
	v_mov_b32_e32 v52, v0
	v_mov_b32_e32 v53, v0
	v_mov_b32_e32 v54, v0
	v_mov_b32_e32 v55, v0
	v_mov_b32_e32 v56, v0
	v_mov_b32_e32 v57, v0
	v_mov_b32_e32 v58, v0
	v_mov_b32_e32 v59, v0
	v_mov_b32_e32 v60, v0
	v_mov_b32_e32 v61, v0
	v_mov_b32_e32 v62, v0
	v_mov_b32_e32 v63, v0
	v_mov_b32_e32 v64, v0
	v_mov_b32_e32 v65, v0
	v_mov_b32_e32 v66, v0
	v_mov_b32_e32 v67, v0
	v_mov_b32_e32 v68, v0
	v_mov_b32_e32 v69, v0
	v_mov_b32_e32 v70, v0
	v_mov_b32_e32 v71, v0
	v_mov_b32_e32 v72, v0
	v_mov_b32_e32 v73, v0
	v_mov_b32_e32 v74, v0
	v_mov_b32_e32 v75, v0
	v_mov_b32_e32 v76, v0
	v_mov_b32_e32 v77, v0
	v_mov_b32_e32 v78, v0
	v_mov_b32_e32 v79, v0
	v_mov_b32_e32 v80, v0
	v_mov_b32_e32 v81, v0
	v_mov_b32_e32 v82, v0
	v_mov_b32_e32 v83, v0
	v_mov_b32_e32 v84, v0
	v_mov_b32_e32 v85, v0
	v_mov_b32_e32 v86, v0
	v_mov_b32_e32 v87, v0
	v_mov_b32_e32 v88, v0
	v_mov_b32_e32 v89, v0
	v_mov_b32_e32 v90, v0
	v_mov_b32_e32 v91, v0
	v_mov_b32_e32 v92, v0
	v_mov_b32_e32 v93, v0
	v_mov_b32_e32 v94, v0
	v_mov_b32_e32 v95, v0
	v_mov_b32_e32 v96, v0
	v_mov_b32_e32 v97, v0
	v_mov_b32_e32 v98, v0
	v_mov_b32_e32 v99, v0
	v_mov_b32_e32 v100, v0
	v_mov_b32_e32 v101, v0
	v_mov_b32_e32 v102, v0
	v_mov_b32_e32 v103, v0
	v_mov_b32_e32 v104, v0
	v_mov_b32_e32 v105, v0
	v_mov_b32_e32 v106, v0
	v_mov_b32_e32 v107, v0
	v_mov_b32_e32 v108, v0
	v_mov_b32_e32 v109, v0
	v_mov_b32_e32 v110, v0
	v_mov_b32_e32 v111, v0
	v_mov_b32_e32 v128, v0
	v_mov_b32_e32 v129, v0
	v_mov_b32_e32 v130, v0
	v_mov_b32_e32 v131, v0
	v_mov_b32_e32 v140, v0
	v_mov_b32_e32 v141, v0
	v_mov_b32_e32 v142, v0
	v_mov_b32_e32 v143, v0
	v_mov_b32_e32 v144, v0
	v_mov_b32_e32 v145, v0
	v_mov_b32_e32 v146, v0
	v_mov_b32_e32 v147, v0
	v_mov_b32_e32 v148, v0
	v_mov_b32_e32 v149, v0
	v_mov_b32_e32 v150, v0
	v_mov_b32_e32 v151, v0
	s_waitcnt lgkmcnt(0)
	s_barrier
	global_load_dwordx4 v[172:175], v[154:155], off offset:128
	global_load_dwordx4 v[176:179], v[158:159], off offset:128
	global_load_dwordx4 v[180:183], v[160:161], off offset:128
	global_load_dwordx4 v[184:187], v[162:163], off offset:128
	global_load_dwordx4 v[188:191], v[156:157], off offset:128
	global_load_dwordx4 v[192:195], v[164:165], off offset:128
.LBB0_710:
	s_add_i32 s11, s10, 64
	s_add_i32 s16, s10, 96
	s_min_u32 s16, s16, 0x3e0
	s_lshl_b32 s16, s16, 1
	ds_read_b128 v[196:199], v171 offset:32768
	ds_read_b128 v[200:203], v171 offset:33792
	ds_read_b128 v[204:207], v171 offset:34816
	ds_read_b128 v[208:211], v171 offset:35840
	ds_read_b128 v[212:215], v169
	ds_read_b128 v[216:219], v169 offset:1024
	ds_read_b128 v[222:225], v169 offset:2048
	ds_read_b128 v[226:229], v169 offset:3072
	ds_read_b128 v[230:233], v169 offset:4096
	ds_read_b128 v[234:237], v169 offset:5120
	ds_read_b128 v[238:241], v169 offset:6144
	ds_read_b128 v[242:245], v169 offset:7168
	s_setprio 1
	s_waitcnt lgkmcnt(7)
	v_mfma_f32_16x16x32_bf16 v[148:151], v[212:215], v[196:199], v[148:151]
	v_mfma_f32_16x16x32_bf16 v[144:147], v[212:215], v[200:203], v[144:147]
	v_mfma_f32_16x16x32_bf16 v[140:143], v[212:215], v[204:207], v[140:143]
	v_mfma_f32_16x16x32_bf16 v[128:131], v[212:215], v[208:211], v[128:131]
	s_waitcnt vmcnt(11)
	ds_write_b128 v152, v[112:115] offset:16384
	s_waitcnt lgkmcnt(7)
	v_mfma_f32_16x16x32_bf16 v[108:111], v[216:219], v[196:199], v[108:111]
	v_mfma_f32_16x16x32_bf16 v[104:107], v[216:219], v[200:203], v[104:107]
	v_mfma_f32_16x16x32_bf16 v[100:103], v[216:219], v[204:207], v[100:103]
	v_mfma_f32_16x16x32_bf16 v[96:99], v[216:219], v[208:211], v[96:99]
	s_waitcnt vmcnt(10)
	ds_write_b128 v152, v[120:123] offset:20480
	v_lshl_add_u64 v[112:113], v[154:155], 0, s[16:17]
	global_load_dwordx4 v[112:115], v[112:113], off
	s_waitcnt lgkmcnt(7)
	v_mfma_f32_16x16x32_bf16 v[92:95], v[222:225], v[196:199], v[92:95]
	v_mfma_f32_16x16x32_bf16 v[88:91], v[222:225], v[200:203], v[88:91]
	v_mfma_f32_16x16x32_bf16 v[84:87], v[222:225], v[204:207], v[84:87]
	v_mfma_f32_16x16x32_bf16 v[80:83], v[222:225], v[208:211], v[80:83]
	s_waitcnt vmcnt(10)
	ds_write_b128 v152, v[124:127] offset:24576
	v_lshl_add_u64 v[120:121], v[158:159], 0, s[16:17]
	global_load_dwordx4 v[120:123], v[120:121], off
	s_waitcnt lgkmcnt(7)
	v_mfma_f32_16x16x32_bf16 v[76:79], v[226:229], v[196:199], v[76:79]
	v_mfma_f32_16x16x32_bf16 v[72:75], v[226:229], v[200:203], v[72:75]
	v_mfma_f32_16x16x32_bf16 v[68:71], v[226:229], v[204:207], v[68:71]
	v_mfma_f32_16x16x32_bf16 v[64:67], v[226:229], v[208:211], v[64:67]
	s_waitcnt vmcnt(10)
	ds_write_b128 v152, v[132:135] offset:28672
	v_lshl_add_u64 v[124:125], v[160:161], 0, s[16:17]
	global_load_dwordx4 v[124:127], v[124:125], off
	s_waitcnt lgkmcnt(7)
	v_mfma_f32_16x16x32_bf16 v[60:63], v[230:233], v[196:199], v[60:63]
	v_mfma_f32_16x16x32_bf16 v[56:59], v[230:233], v[200:203], v[56:59]
	v_mfma_f32_16x16x32_bf16 v[52:55], v[230:233], v[204:207], v[52:55]
	v_mfma_f32_16x16x32_bf16 v[48:51], v[230:233], v[208:211], v[48:51]
	s_waitcnt vmcnt(10)
	ds_write_b128 v152, v[116:119] offset:40960
	v_lshl_add_u64 v[132:133], v[162:163], 0, s[16:17]
	global_load_dwordx4 v[132:135], v[132:133], off
	s_waitcnt lgkmcnt(7)
	v_mfma_f32_16x16x32_bf16 v[44:47], v[234:237], v[196:199], v[44:47]
	v_mfma_f32_16x16x32_bf16 v[40:43], v[234:237], v[200:203], v[40:43]
	v_mfma_f32_16x16x32_bf16 v[36:39], v[234:237], v[204:207], v[36:39]
	v_mfma_f32_16x16x32_bf16 v[32:35], v[234:237], v[208:211], v[32:35]
	s_waitcnt vmcnt(10)
	ds_write_b128 v152, v[136:139] offset:45056
	v_lshl_add_u64 v[116:117], v[156:157], 0, s[16:17]
	global_load_dwordx4 v[116:119], v[116:117], off
	s_waitcnt lgkmcnt(7)
	v_mfma_f32_16x16x32_bf16 v[28:31], v[238:241], v[196:199], v[28:31]
	v_mfma_f32_16x16x32_bf16 v[24:27], v[238:241], v[200:203], v[24:27]
	v_mfma_f32_16x16x32_bf16 v[20:23], v[238:241], v[204:207], v[20:23]
	v_mfma_f32_16x16x32_bf16 v[16:19], v[238:241], v[208:211], v[16:19]
	v_lshl_add_u64 v[136:137], v[164:165], 0, s[16:17]
	global_load_dwordx4 v[136:139], v[136:137], off
	s_waitcnt lgkmcnt(6)
	v_mfma_f32_16x16x32_bf16 v[12:15], v[242:245], v[196:199], v[12:15]
	v_mfma_f32_16x16x32_bf16 v[8:11], v[242:245], v[200:203], v[8:11]
	v_mfma_f32_16x16x32_bf16 v[4:7], v[242:245], v[204:207], v[4:7]
	v_mfma_f32_16x16x32_bf16 v[0:3], v[242:245], v[208:211], v[0:3]
	s_setprio 0
	s_waitcnt lgkmcnt(0)
	s_barrier
	s_add_i32 s16, s10, 0x80
	s_min_u32 s16, s16, 0x3e0
	s_lshl_b32 s16, s16, 1
	ds_read_b128 v[196:199], v168 offset:40960
	ds_read_b128 v[200:203], v168 offset:41984
	ds_read_b128 v[204:207], v168 offset:43008
	ds_read_b128 v[208:211], v168 offset:44032
	ds_read_b128 v[212:215], v170
	ds_read_b128 v[216:219], v170 offset:1024
	ds_read_b128 v[222:225], v170 offset:2048
	ds_read_b128 v[226:229], v170 offset:3072
	ds_read_b128 v[230:233], v170 offset:4096
	ds_read_b128 v[234:237], v170 offset:5120
	ds_read_b128 v[238:241], v170 offset:6144
	ds_read_b128 v[242:245], v170 offset:7168
	s_setprio 1
	s_waitcnt lgkmcnt(7)
	v_mfma_f32_16x16x32_bf16 v[148:151], v[212:215], v[196:199], v[148:151]
	v_mfma_f32_16x16x32_bf16 v[144:147], v[212:215], v[200:203], v[144:147]
	v_mfma_f32_16x16x32_bf16 v[140:143], v[212:215], v[204:207], v[140:143]
	v_mfma_f32_16x16x32_bf16 v[128:131], v[212:215], v[208:211], v[128:131]
	s_waitcnt vmcnt(11)
	ds_write_b128 v152, v[172:175]
	s_waitcnt lgkmcnt(7)
	v_mfma_f32_16x16x32_bf16 v[108:111], v[216:219], v[196:199], v[108:111]
	v_mfma_f32_16x16x32_bf16 v[104:107], v[216:219], v[200:203], v[104:107]
	v_mfma_f32_16x16x32_bf16 v[100:103], v[216:219], v[204:207], v[100:103]
	v_mfma_f32_16x16x32_bf16 v[96:99], v[216:219], v[208:211], v[96:99]
	s_waitcnt vmcnt(10)
	ds_write_b128 v152, v[176:179] offset:4096
	v_lshl_add_u64 v[172:173], v[154:155], 0, s[16:17]
	global_load_dwordx4 v[172:175], v[172:173], off
	s_waitcnt lgkmcnt(7)
	v_mfma_f32_16x16x32_bf16 v[92:95], v[222:225], v[196:199], v[92:95]
	v_mfma_f32_16x16x32_bf16 v[88:91], v[222:225], v[200:203], v[88:91]
	v_mfma_f32_16x16x32_bf16 v[84:87], v[222:225], v[204:207], v[84:87]
	v_mfma_f32_16x16x32_bf16 v[80:83], v[222:225], v[208:211], v[80:83]
	s_waitcnt vmcnt(10)
	ds_write_b128 v152, v[180:183] offset:8192
	v_lshl_add_u64 v[176:177], v[158:159], 0, s[16:17]
	global_load_dwordx4 v[176:179], v[176:177], off
	s_waitcnt lgkmcnt(7)
	v_mfma_f32_16x16x32_bf16 v[76:79], v[226:229], v[196:199], v[76:79]
	v_mfma_f32_16x16x32_bf16 v[72:75], v[226:229], v[200:203], v[72:75]
	v_mfma_f32_16x16x32_bf16 v[68:71], v[226:229], v[204:207], v[68:71]
	v_mfma_f32_16x16x32_bf16 v[64:67], v[226:229], v[208:211], v[64:67]
	s_waitcnt vmcnt(10)
	ds_write_b128 v152, v[184:187] offset:12288
	v_lshl_add_u64 v[180:181], v[160:161], 0, s[16:17]
	global_load_dwordx4 v[180:183], v[180:181], off
	s_waitcnt lgkmcnt(7)
	v_mfma_f32_16x16x32_bf16 v[60:63], v[230:233], v[196:199], v[60:63]
	v_mfma_f32_16x16x32_bf16 v[56:59], v[230:233], v[200:203], v[56:59]
	v_mfma_f32_16x16x32_bf16 v[52:55], v[230:233], v[204:207], v[52:55]
	v_mfma_f32_16x16x32_bf16 v[48:51], v[230:233], v[208:211], v[48:51]
	s_waitcnt vmcnt(10)
	ds_write_b128 v152, v[188:191] offset:32768
	v_lshl_add_u64 v[184:185], v[162:163], 0, s[16:17]
	global_load_dwordx4 v[184:187], v[184:185], off
	s_waitcnt lgkmcnt(7)
	v_mfma_f32_16x16x32_bf16 v[44:47], v[234:237], v[196:199], v[44:47]
	v_mfma_f32_16x16x32_bf16 v[40:43], v[234:237], v[200:203], v[40:43]
	v_mfma_f32_16x16x32_bf16 v[36:39], v[234:237], v[204:207], v[36:39]
	v_mfma_f32_16x16x32_bf16 v[32:35], v[234:237], v[208:211], v[32:35]
	s_waitcnt vmcnt(10)
	ds_write_b128 v152, v[192:195] offset:36864
	v_lshl_add_u64 v[188:189], v[156:157], 0, s[16:17]
	global_load_dwordx4 v[188:191], v[188:189], off
	s_waitcnt lgkmcnt(7)
	v_mfma_f32_16x16x32_bf16 v[28:31], v[238:241], v[196:199], v[28:31]
	v_mfma_f32_16x16x32_bf16 v[24:27], v[238:241], v[200:203], v[24:27]
	v_mfma_f32_16x16x32_bf16 v[20:23], v[238:241], v[204:207], v[20:23]
	v_mfma_f32_16x16x32_bf16 v[16:19], v[238:241], v[208:211], v[16:19]
	v_lshl_add_u64 v[192:193], v[164:165], 0, s[16:17]
	global_load_dwordx4 v[192:195], v[192:193], off
	s_waitcnt lgkmcnt(6)
	v_mfma_f32_16x16x32_bf16 v[12:15], v[242:245], v[196:199], v[12:15]
	v_mfma_f32_16x16x32_bf16 v[8:11], v[242:245], v[200:203], v[8:11]
	v_mfma_f32_16x16x32_bf16 v[4:7], v[242:245], v[204:207], v[4:7]
	v_mfma_f32_16x16x32_bf16 v[0:3], v[242:245], v[208:211], v[0:3]
	s_setprio 0
	s_add_i32 s1, s1, 2
	s_cmp_lt_u32 s1, 30
	s_mov_b32 s10, s11
	s_waitcnt lgkmcnt(0)
	s_barrier
	s_cbranch_scc1 .LBB0_710
	s_waitcnt vmcnt(0)
	s_waitcnt vmcnt(5)
	v_mov_b32_e32 v114, v220
	v_mov_b32_e32 v115, v153
	v_and_b32_e32 v112, 0xffffff80, v114
	s_waitcnt vmcnt(4)
	v_add_u32_e32 v116, s0, v112
	v_lshrrev_b32_e32 v112, 2, v114
	v_and_b32_e32 v118, 12, v112
	s_waitcnt vmcnt(3)
	v_or_b32_e32 v120, v118, v116
	v_ashrrev_i32_e32 v121, 31, v120
	v_lshl_add_u64 v[112:113], v[120:121], 2, s[14:15]
	global_load_dwordx4 v[132:135], v[112:113], off
	v_ashrrev_i32_e32 v122, 14, v116
	v_ashrrev_i32_e32 v123, 31, v122
	v_lshlrev_b64 v[122:123], 10, v[122:123]
	v_mov_b64_e32 v[112:113], s[34:35]
	s_waitcnt vmcnt(3)
	v_lshrrev_b32_e32 v126, 6, v116
	v_or_b32_e32 v124, 16, v120
	v_lshl_or_b32 v121, s12, 8, v122
	v_ashrrev_i32_e32 v125, 31, v124
	v_and_or_b32 v122, v126, s49, v121
	s_waitcnt vmcnt(1)
	v_lshl_add_u64 v[136:137], v[124:125], 2, s[14:15]
	v_lshlrev_b64 v[124:125], 14, v[122:123]
	v_lshlrev_b32_e32 v114, 7, v114
	v_lshlrev_b32_e32 v152, 1, v118
	v_lshl_add_u64 v[124:125], s[38:39], 0, v[124:125]
	v_and_b32_e32 v114, 0x2780, v114
	v_lshl_add_u64 v[126:127], v[124:125], 0, v[152:153]
	v_mov_b32_e32 v117, v153
	v_mov_b32_e32 v119, v153
	v_or_b32_e32 v116, 0x1000, v114
	v_or_b32_e32 v118, 0x1800, v114
	v_lshl_add_u64 v[124:125], v[126:127], 0, v[114:115]
	v_lshl_add_u64 v[138:139], v[126:127], 0, v[116:117]
	v_lshl_add_u64 v[154:155], v[126:127], 0, v[118:119]
	s_waitcnt vmcnt(0)
	v_pk_fma_f32 v[132:133], v[132:133], s[30:31], v[112:113] op_sel_hi:[1,0,0]
	v_pk_fma_f32 v[134:135], v[134:135], s[30:31], v[112:113] op_sel_hi:[1,0,0]
	v_mul_f32_e32 v122, 0x4b800000, v132
	v_mul_f32_e32 v156, 0x4b800000, v133
	v_mul_f32_e32 v157, 0x4b800000, v134
	v_mul_f32_e32 v158, 0x4b800000, v135
	v_cmp_gt_f32_e32 vcc, s40, v132
	v_cmp_gt_f32_e64 s[0:1], s40, v133
	v_cmp_gt_f32_e64 s[10:11], s40, v134
	v_cmp_gt_f32_e64 s[12:13], s40, v135
	v_cndmask_b32_e32 v122, v132, v122, vcc
	v_cndmask_b32_e64 v132, v133, v156, s[0:1]
	v_cndmask_b32_e64 v133, v134, v157, s[10:11]
	v_cndmask_b32_e64 v134, v135, v158, s[12:13]
	v_rsq_f32_e32 v122, v122
	v_rsq_f32_e32 v132, v132
	v_rsq_f32_e32 v133, v133
	v_rsq_f32_e32 v134, v134
	v_mul_f32_e32 v135, 0x45800000, v122
	v_mul_f32_e32 v156, 0x45800000, v132
	v_mul_f32_e32 v157, 0x45800000, v133
	v_mul_f32_e32 v158, 0x45800000, v134
	v_cndmask_b32_e32 v122, v122, v135, vcc
	v_cndmask_b32_e64 v132, v132, v156, s[0:1]
	v_cndmask_b32_e64 v133, v133, v157, s[10:11]
	v_cndmask_b32_e64 v134, v134, v158, s[12:13]
	v_mul_f32_e32 v135, v148, v122
	v_mul_f32_e32 v148, v149, v132
	v_mul_f32_e32 v149, v150, v133
	v_mul_f32_e32 v150, v151, v134
	v_mul_f32_e32 v144, v144, v122
	v_mul_f32_e32 v140, v140, v122
	v_mul_f32_e32 v122, v128, v122
	v_mul_f32_e32 v151, v129, v132
	v_cvt_pk_bf16_f32 v128, v135, v148
	v_cvt_pk_bf16_f32 v129, v149, v150
	v_mul_f32_e32 v145, v145, v132
	v_mul_f32_e32 v146, v146, v133
	v_mul_f32_e32 v147, v147, v134
	v_mul_f32_e32 v141, v141, v132
	v_mul_f32_e32 v142, v142, v133
	v_mul_f32_e32 v143, v143, v134
	v_mul_f32_e32 v156, v130, v133
	v_mul_f32_e32 v157, v131, v134
	v_cvt_pk_bf16_f32 v130, v144, v145
	v_cvt_pk_bf16_f32 v131, v146, v147
	v_cvt_pk_bf16_f32 v132, v140, v141
	v_cvt_pk_bf16_f32 v133, v142, v143
	v_cvt_pk_bf16_f32 v134, v122, v151
	v_cvt_pk_bf16_f32 v135, v156, v157
	global_store_dwordx2 v[124:125], v[128:129], off
	global_store_dwordx2 v[124:125], v[130:131], off offset:2048
	global_store_dwordx2 v[138:139], v[132:133], off
	global_store_dwordx2 v[154:155], v[134:135], off
	global_load_dwordx4 v[128:131], v[136:137], off
	v_or_b32_e32 v132, 32, v120
	v_ashrrev_i32_e32 v133, 31, v132
	v_lshl_add_u64 v[134:135], v[126:127], 0, 32
	v_lshl_add_u64 v[132:133], v[132:133], 2, s[14:15]
	v_lshl_add_u64 v[136:137], v[134:135], 0, v[116:117]
	v_lshl_add_u64 v[134:135], v[134:135], 0, v[118:119]
	s_waitcnt vmcnt(0)
	v_pk_fma_f32 v[128:129], v[128:129], s[30:31], v[112:113] op_sel_hi:[1,0,0]
	v_pk_fma_f32 v[130:131], v[130:131], s[30:31], v[112:113] op_sel_hi:[1,0,0]
	v_mul_f32_e32 v122, 0x4b800000, v128
	v_mul_f32_e32 v138, 0x4b800000, v129
	v_mul_f32_e32 v139, 0x4b800000, v130
	v_mul_f32_e32 v140, 0x4b800000, v131
	v_cmp_gt_f32_e32 vcc, s40, v128
	v_cmp_gt_f32_e64 s[0:1], s40, v129
	v_cmp_gt_f32_e64 s[10:11], s40, v130
	v_cmp_gt_f32_e64 s[12:13], s40, v131
	v_cndmask_b32_e32 v122, v128, v122, vcc
	v_cndmask_b32_e64 v128, v129, v138, s[0:1]
	v_cndmask_b32_e64 v129, v130, v139, s[10:11]
	v_cndmask_b32_e64 v130, v131, v140, s[12:13]
	v_rsq_f32_e32 v122, v122
	v_rsq_f32_e32 v128, v128
	v_rsq_f32_e32 v129, v129
	v_rsq_f32_e32 v130, v130
	v_mul_f32_e32 v131, 0x45800000, v122
	v_mul_f32_e32 v138, 0x45800000, v128
	v_mul_f32_e32 v139, 0x45800000, v129
	v_mul_f32_e32 v140, 0x45800000, v130
	v_cndmask_b32_e32 v122, v122, v131, vcc
	v_cndmask_b32_e64 v128, v128, v138, s[0:1]
	v_cndmask_b32_e64 v129, v129, v139, s[10:11]
	v_cndmask_b32_e64 v130, v130, v140, s[12:13]
	v_mul_f32_e32 v108, v108, v122
	v_mul_f32_e32 v109, v109, v128
	v_mul_f32_e32 v110, v110, v129
	v_mul_f32_e32 v111, v111, v130
	v_mul_f32_e32 v104, v104, v122
	v_mul_f32_e32 v105, v105, v128
	v_mul_f32_e32 v100, v100, v122
	v_mul_f32_e32 v101, v101, v128
	v_mul_f32_e32 v102, v102, v129
	v_mul_f32_e32 v103, v103, v130
	v_mul_f32_e32 v122, v96, v122
	v_mul_f32_e32 v128, v97, v128
	v_cvt_pk_bf16_f32 v96, v108, v109
	v_cvt_pk_bf16_f32 v97, v110, v111
	v_mul_f32_e32 v106, v106, v129
	v_mul_f32_e32 v107, v107, v130
	v_mul_f32_e32 v129, v98, v129
	v_mul_f32_e32 v130, v99, v130
	v_cvt_pk_bf16_f32 v98, v104, v105
	v_cvt_pk_bf16_f32 v99, v106, v107
	v_cvt_pk_bf16_f32 v100, v100, v101
	v_cvt_pk_bf16_f32 v101, v102, v103
	v_cvt_pk_bf16_f32 v102, v122, v128
	v_cvt_pk_bf16_f32 v103, v129, v130
	global_store_dwordx2 v[124:125], v[96:97], off offset:32
	global_store_dwordx2 v[124:125], v[98:99], off offset:2080
	global_store_dwordx2 v[136:137], v[100:101], off
	global_store_dwordx2 v[134:135], v[102:103], off
	global_load_dwordx4 v[96:99], v[132:133], off
	v_or_b32_e32 v100, 48, v120
	v_ashrrev_i32_e32 v101, 31, v100
	v_lshl_add_u64 v[102:103], v[126:127], 0, 64
	v_lshl_add_u64 v[100:101], v[100:101], 2, s[14:15]
	v_lshl_add_u64 v[104:105], v[102:103], 0, v[116:117]
	v_lshl_add_u64 v[102:103], v[102:103], 0, v[118:119]
	s_waitcnt vmcnt(0)
	v_pk_fma_f32 v[96:97], v[96:97], s[30:31], v[112:113] op_sel_hi:[1,0,0]
	v_pk_fma_f32 v[98:99], v[98:99], s[30:31], v[112:113] op_sel_hi:[1,0,0]
	v_mul_f32_e32 v106, 0x4b800000, v96
	v_mul_f32_e32 v107, 0x4b800000, v97
	v_mul_f32_e32 v108, 0x4b800000, v98
	v_mul_f32_e32 v109, 0x4b800000, v99
	v_cmp_gt_f32_e32 vcc, s40, v96
	v_cmp_gt_f32_e64 s[0:1], s40, v97
	v_cmp_gt_f32_e64 s[10:11], s40, v98
	v_cmp_gt_f32_e64 s[12:13], s40, v99
	v_cndmask_b32_e32 v96, v96, v106, vcc
	v_cndmask_b32_e64 v97, v97, v107, s[0:1]
	v_cndmask_b32_e64 v98, v98, v108, s[10:11]
	v_cndmask_b32_e64 v99, v99, v109, s[12:13]
	v_rsq_f32_e32 v96, v96
	v_rsq_f32_e32 v97, v97
	v_rsq_f32_e32 v98, v98
	v_rsq_f32_e32 v99, v99
	v_mul_f32_e32 v106, 0x45800000, v96
	v_mul_f32_e32 v107, 0x45800000, v97
	v_mul_f32_e32 v108, 0x45800000, v98
	v_mul_f32_e32 v109, 0x45800000, v99
	v_cndmask_b32_e32 v96, v96, v106, vcc
	v_cndmask_b32_e64 v97, v97, v107, s[0:1]
	v_cndmask_b32_e64 v98, v98, v108, s[10:11]
	v_cndmask_b32_e64 v99, v99, v109, s[12:13]
	v_mul_f32_e32 v92, v92, v96
	v_mul_f32_e32 v93, v93, v97
	v_mul_f32_e32 v94, v94, v98
	v_mul_f32_e32 v95, v95, v99
	v_mul_f32_e32 v88, v88, v96
	v_mul_f32_e32 v89, v89, v97
	v_mul_f32_e32 v84, v84, v96
	v_mul_f32_e32 v85, v85, v97
	v_mul_f32_e32 v86, v86, v98
	v_mul_f32_e32 v87, v87, v99
	v_mul_f32_e32 v96, v80, v96
	v_mul_f32_e32 v97, v81, v97
	v_cvt_pk_bf16_f32 v80, v92, v93
	v_cvt_pk_bf16_f32 v81, v94, v95
	v_mul_f32_e32 v90, v90, v98
	v_mul_f32_e32 v91, v91, v99
	v_mul_f32_e32 v98, v82, v98
	v_mul_f32_e32 v99, v83, v99
	v_cvt_pk_bf16_f32 v82, v88, v89
	v_cvt_pk_bf16_f32 v83, v90, v91
	v_cvt_pk_bf16_f32 v84, v84, v85
	v_cvt_pk_bf16_f32 v85, v86, v87
	v_cvt_pk_bf16_f32 v86, v96, v97
	v_cvt_pk_bf16_f32 v87, v98, v99
	global_store_dwordx2 v[124:125], v[80:81], off offset:64
	global_store_dwordx2 v[124:125], v[82:83], off offset:2112
	global_store_dwordx2 v[104:105], v[84:85], off
	global_store_dwordx2 v[102:103], v[86:87], off
	global_load_dwordx4 v[80:83], v[100:101], off
	v_or_b32_e32 v84, 64, v120
	v_ashrrev_i32_e32 v85, 31, v84
	v_lshl_add_u64 v[86:87], v[84:85], 2, s[14:15]
	v_lshl_add_u64 v[88:89], v[126:127], 0, s[36:37]
	v_lshl_add_u64 v[90:91], v[88:89], 0, v[116:117]
	v_lshl_add_u64 v[88:89], v[88:89], 0, v[118:119]
	s_waitcnt vmcnt(0)
	v_pk_fma_f32 v[80:81], v[80:81], s[30:31], v[112:113] op_sel_hi:[1,0,0]
	v_pk_fma_f32 v[82:83], v[82:83], s[30:31], v[112:113] op_sel_hi:[1,0,0]
	v_mul_f32_e32 v85, 0x4b800000, v80
	v_mul_f32_e32 v92, 0x4b800000, v81
	v_mul_f32_e32 v93, 0x4b800000, v82
	v_mul_f32_e32 v94, 0x4b800000, v83
	v_cmp_gt_f32_e32 vcc, s40, v80
	v_cmp_gt_f32_e64 s[0:1], s40, v81
	v_cmp_gt_f32_e64 s[10:11], s40, v82
	v_cmp_gt_f32_e64 s[12:13], s40, v83
	v_cndmask_b32_e32 v80, v80, v85, vcc
	v_cndmask_b32_e64 v81, v81, v92, s[0:1]
	v_cndmask_b32_e64 v82, v82, v93, s[10:11]
	v_cndmask_b32_e64 v83, v83, v94, s[12:13]
	v_rsq_f32_e32 v80, v80
	v_rsq_f32_e32 v81, v81
	v_rsq_f32_e32 v82, v82
	v_rsq_f32_e32 v83, v83
	v_mul_f32_e32 v85, 0x45800000, v80
	v_mul_f32_e32 v92, 0x45800000, v81
	v_mul_f32_e32 v93, 0x45800000, v82
	v_mul_f32_e32 v94, 0x45800000, v83
	v_cndmask_b32_e32 v80, v80, v85, vcc
	v_cndmask_b32_e64 v81, v81, v92, s[0:1]
	v_cndmask_b32_e64 v82, v82, v93, s[10:11]
	v_cndmask_b32_e64 v83, v83, v94, s[12:13]
	v_mul_f32_e32 v76, v76, v80
	v_mul_f32_e32 v77, v77, v81
	v_mul_f32_e32 v78, v78, v82
	v_mul_f32_e32 v79, v79, v83
	v_mul_f32_e32 v72, v72, v80
	v_mul_f32_e32 v73, v73, v81
	v_mul_f32_e32 v68, v68, v80
	v_mul_f32_e32 v69, v69, v81
	v_mul_f32_e32 v70, v70, v82
	v_mul_f32_e32 v71, v71, v83
	v_mul_f32_e32 v80, v64, v80
	v_mul_f32_e32 v81, v65, v81
	v_cvt_pk_bf16_f32 v64, v76, v77
	v_cvt_pk_bf16_f32 v65, v78, v79
	v_mul_f32_e32 v74, v74, v82
	v_mul_f32_e32 v75, v75, v83
	v_mul_f32_e32 v82, v66, v82
	v_mul_f32_e32 v83, v67, v83
	v_cvt_pk_bf16_f32 v66, v72, v73
	v_cvt_pk_bf16_f32 v67, v74, v75
	v_cvt_pk_bf16_f32 v68, v68, v69
	v_cvt_pk_bf16_f32 v69, v70, v71
	v_cvt_pk_bf16_f32 v70, v80, v81
	v_cvt_pk_bf16_f32 v71, v82, v83
	global_store_dwordx2 v[124:125], v[64:65], off offset:96
	global_store_dwordx2 v[124:125], v[66:67], off offset:2144
	global_store_dwordx2 v[90:91], v[68:69], off
	global_store_dwordx2 v[88:89], v[70:71], off
	global_load_dwordx4 v[64:67], v[86:87], off
	v_or_b32_e32 v68, 0x50, v120
	v_ashrrev_i32_e32 v69, 31, v68
	v_lshl_add_u64 v[70:71], v[68:69], 2, s[14:15]
	v_lshrrev_b32_e32 v72, 6, v84
	v_and_or_b32 v122, v72, s50, v121
	v_lshlrev_b64 v[72:73], 14, v[122:123]
	v_lshl_add_u64 v[72:73], s[38:39], 0, v[72:73]
	v_lshl_add_u64 v[72:73], v[72:73], 0, v[152:153]
	v_lshl_add_u64 v[74:75], v[72:73], 0, v[114:115]
	v_lshl_add_u64 v[76:77], v[72:73], 0, v[116:117]
	v_lshl_add_u64 v[72:73], v[72:73], 0, v[118:119]
	s_waitcnt vmcnt(0)
	v_pk_fma_f32 v[64:65], v[64:65], s[30:31], v[112:113] op_sel_hi:[1,0,0]
	v_pk_fma_f32 v[66:67], v[66:67], s[30:31], v[112:113] op_sel_hi:[1,0,0]
	v_mul_f32_e32 v69, 0x4b800000, v64
	v_mul_f32_e32 v78, 0x4b800000, v65
	v_mul_f32_e32 v79, 0x4b800000, v66
	v_mul_f32_e32 v80, 0x4b800000, v67
	v_cmp_gt_f32_e32 vcc, s40, v64
	v_cmp_gt_f32_e64 s[0:1], s40, v65
	v_cmp_gt_f32_e64 s[10:11], s40, v66
	v_cmp_gt_f32_e64 s[12:13], s40, v67
	v_cndmask_b32_e32 v64, v64, v69, vcc
	v_cndmask_b32_e64 v65, v65, v78, s[0:1]
	v_cndmask_b32_e64 v66, v66, v79, s[10:11]
	v_cndmask_b32_e64 v67, v67, v80, s[12:13]
	v_rsq_f32_e32 v64, v64
	v_rsq_f32_e32 v65, v65
	v_rsq_f32_e32 v66, v66
	v_rsq_f32_e32 v67, v67
	v_mul_f32_e32 v69, 0x45800000, v64
	v_mul_f32_e32 v78, 0x45800000, v65
	v_mul_f32_e32 v79, 0x45800000, v66
	v_mul_f32_e32 v80, 0x45800000, v67
	v_cndmask_b32_e32 v64, v64, v69, vcc
	v_cndmask_b32_e64 v65, v65, v78, s[0:1]
	v_cndmask_b32_e64 v66, v66, v79, s[10:11]
	v_cndmask_b32_e64 v67, v67, v80, s[12:13]
	v_mul_f32_e32 v60, v60, v64
	v_mul_f32_e32 v61, v61, v65
	v_mul_f32_e32 v62, v62, v66
	v_mul_f32_e32 v63, v63, v67
	v_mul_f32_e32 v56, v56, v64
	v_mul_f32_e32 v57, v57, v65
	v_mul_f32_e32 v52, v52, v64
	v_mul_f32_e32 v53, v53, v65
	v_mul_f32_e32 v54, v54, v66
	v_mul_f32_e32 v55, v55, v67
	v_mul_f32_e32 v64, v48, v64
	v_mul_f32_e32 v65, v49, v65
	v_cvt_pk_bf16_f32 v48, v60, v61
	v_cvt_pk_bf16_f32 v49, v62, v63
	v_mul_f32_e32 v58, v58, v66
	v_mul_f32_e32 v59, v59, v67
	v_mul_f32_e32 v66, v50, v66
	v_mul_f32_e32 v67, v51, v67
	v_cvt_pk_bf16_f32 v50, v56, v57
	v_cvt_pk_bf16_f32 v51, v58, v59
	v_cvt_pk_bf16_f32 v52, v52, v53
	v_cvt_pk_bf16_f32 v53, v54, v55
	v_cvt_pk_bf16_f32 v54, v64, v65
	v_cvt_pk_bf16_f32 v55, v66, v67
	global_store_dwordx2 v[74:75], v[48:49], off
	global_store_dwordx2 v[74:75], v[50:51], off offset:2048
	global_store_dwordx2 v[76:77], v[52:53], off
	global_store_dwordx2 v[72:73], v[54:55], off
	global_load_dwordx4 v[48:51], v[70:71], off
	v_or_b32_e32 v52, 0x60, v120
	v_ashrrev_i32_e32 v53, 31, v52
	v_lshl_add_u64 v[54:55], v[52:53], 2, s[14:15]
	v_lshrrev_b32_e32 v56, 6, v68
	v_and_or_b32 v122, v56, s50, v121
	v_lshlrev_b64 v[56:57], 14, v[122:123]
	v_lshl_add_u64 v[56:57], s[38:39], 0, v[56:57]
	v_lshl_add_u64 v[56:57], v[56:57], 0, v[152:153]
	v_lshl_add_u64 v[58:59], v[56:57], 0, 32
	v_lshl_add_u64 v[56:57], v[56:57], 0, v[114:115]
	v_lshl_add_u64 v[60:61], v[58:59], 0, v[116:117]
	v_lshl_add_u64 v[58:59], v[58:59], 0, v[118:119]
	s_waitcnt vmcnt(0)
	v_pk_fma_f32 v[48:49], v[48:49], s[30:31], v[112:113] op_sel_hi:[1,0,0]
	v_pk_fma_f32 v[50:51], v[50:51], s[30:31], v[112:113] op_sel_hi:[1,0,0]
	v_mul_f32_e32 v53, 0x4b800000, v48
	v_mul_f32_e32 v62, 0x4b800000, v49
	v_mul_f32_e32 v63, 0x4b800000, v50
	v_mul_f32_e32 v64, 0x4b800000, v51
	v_cmp_gt_f32_e32 vcc, s40, v48
	v_cmp_gt_f32_e64 s[0:1], s40, v49
	v_cmp_gt_f32_e64 s[10:11], s40, v50
	v_cmp_gt_f32_e64 s[12:13], s40, v51
	v_cndmask_b32_e32 v48, v48, v53, vcc
	v_cndmask_b32_e64 v49, v49, v62, s[0:1]
	v_cndmask_b32_e64 v50, v50, v63, s[10:11]
	v_cndmask_b32_e64 v51, v51, v64, s[12:13]
	v_rsq_f32_e32 v48, v48
	v_rsq_f32_e32 v49, v49
	v_rsq_f32_e32 v50, v50
	v_rsq_f32_e32 v51, v51
	v_mul_f32_e32 v53, 0x45800000, v48
	v_mul_f32_e32 v62, 0x45800000, v49
	v_mul_f32_e32 v63, 0x45800000, v50
	v_mul_f32_e32 v64, 0x45800000, v51
	v_cndmask_b32_e32 v48, v48, v53, vcc
	v_cndmask_b32_e64 v49, v49, v62, s[0:1]
	v_cndmask_b32_e64 v50, v50, v63, s[10:11]
	v_cndmask_b32_e64 v51, v51, v64, s[12:13]
	v_mul_f32_e32 v44, v44, v48
	v_mul_f32_e32 v45, v45, v49
	v_mul_f32_e32 v46, v46, v50
	v_mul_f32_e32 v47, v47, v51
	v_mul_f32_e32 v40, v40, v48
	v_mul_f32_e32 v41, v41, v49
	v_mul_f32_e32 v36, v36, v48
	v_mul_f32_e32 v37, v37, v49
	v_mul_f32_e32 v38, v38, v50
	v_mul_f32_e32 v39, v39, v51
	v_mul_f32_e32 v48, v32, v48
	v_mul_f32_e32 v49, v33, v49
	v_cvt_pk_bf16_f32 v32, v44, v45
	v_cvt_pk_bf16_f32 v33, v46, v47
	v_mul_f32_e32 v42, v42, v50
	v_mul_f32_e32 v43, v43, v51
	v_mul_f32_e32 v50, v34, v50
	v_mul_f32_e32 v51, v35, v51
	v_cvt_pk_bf16_f32 v34, v40, v41
	v_cvt_pk_bf16_f32 v35, v42, v43
	v_cvt_pk_bf16_f32 v36, v36, v37
	v_cvt_pk_bf16_f32 v37, v38, v39
	v_cvt_pk_bf16_f32 v38, v48, v49
	v_cvt_pk_bf16_f32 v39, v50, v51
	global_store_dwordx2 v[56:57], v[32:33], off offset:32
	global_store_dwordx2 v[56:57], v[34:35], off offset:2080
	global_store_dwordx2 v[60:61], v[36:37], off
	global_store_dwordx2 v[58:59], v[38:39], off
	global_load_dwordx4 v[32:35], v[54:55], off
	v_or_b32_e32 v36, 0x70, v120
	v_ashrrev_i32_e32 v37, 31, v36
	v_lshl_add_u64 v[38:39], v[36:37], 2, s[14:15]
	v_lshrrev_b32_e32 v40, 6, v52
	v_and_or_b32 v122, v40, s50, v121
	v_lshlrev_b64 v[40:41], 14, v[122:123]
	v_lshl_add_u64 v[40:41], s[38:39], 0, v[40:41]
	v_lshl_add_u64 v[40:41], v[40:41], 0, v[152:153]
	v_lshl_add_u64 v[42:43], v[40:41], 0, 64
	v_lshl_add_u64 v[40:41], v[40:41], 0, v[114:115]
	v_lshl_add_u64 v[44:45], v[42:43], 0, v[116:117]
	v_lshl_add_u64 v[42:43], v[42:43], 0, v[118:119]
	s_waitcnt vmcnt(0)
	v_pk_fma_f32 v[32:33], v[32:33], s[30:31], v[112:113] op_sel_hi:[1,0,0]
	v_pk_fma_f32 v[34:35], v[34:35], s[30:31], v[112:113] op_sel_hi:[1,0,0]
	v_mul_f32_e32 v37, 0x4b800000, v32
	v_mul_f32_e32 v46, 0x4b800000, v33
	v_mul_f32_e32 v47, 0x4b800000, v34
	v_mul_f32_e32 v48, 0x4b800000, v35
	v_cmp_gt_f32_e32 vcc, s40, v32
	v_cmp_gt_f32_e64 s[0:1], s40, v33
	v_cmp_gt_f32_e64 s[10:11], s40, v34
	v_cmp_gt_f32_e64 s[12:13], s40, v35
	v_cndmask_b32_e32 v32, v32, v37, vcc
	v_cndmask_b32_e64 v33, v33, v46, s[0:1]
	v_cndmask_b32_e64 v34, v34, v47, s[10:11]
	v_cndmask_b32_e64 v35, v35, v48, s[12:13]
	v_rsq_f32_e32 v32, v32
	v_rsq_f32_e32 v33, v33
	v_rsq_f32_e32 v34, v34
	v_rsq_f32_e32 v35, v35
	v_mul_f32_e32 v37, 0x45800000, v32
	v_mul_f32_e32 v46, 0x45800000, v33
	v_mul_f32_e32 v47, 0x45800000, v34
	v_mul_f32_e32 v48, 0x45800000, v35
	v_cndmask_b32_e32 v32, v32, v37, vcc
	v_cndmask_b32_e64 v33, v33, v46, s[0:1]
	v_cndmask_b32_e64 v34, v34, v47, s[10:11]
	v_cndmask_b32_e64 v35, v35, v48, s[12:13]
	v_mul_f32_e32 v28, v28, v32
	v_mul_f32_e32 v29, v29, v33
	v_mul_f32_e32 v30, v30, v34
	v_mul_f32_e32 v31, v31, v35
	v_mul_f32_e32 v24, v24, v32
	v_mul_f32_e32 v25, v25, v33
	v_mul_f32_e32 v20, v20, v32
	v_mul_f32_e32 v21, v21, v33
	v_mul_f32_e32 v22, v22, v34
	v_mul_f32_e32 v23, v23, v35
	v_mul_f32_e32 v32, v16, v32
	v_mul_f32_e32 v33, v17, v33
	v_cvt_pk_bf16_f32 v16, v28, v29
	v_cvt_pk_bf16_f32 v17, v30, v31
	v_mul_f32_e32 v26, v26, v34
	v_mul_f32_e32 v27, v27, v35
	v_mul_f32_e32 v34, v18, v34
	v_mul_f32_e32 v35, v19, v35
	v_cvt_pk_bf16_f32 v18, v24, v25
	v_cvt_pk_bf16_f32 v19, v26, v27
	v_cvt_pk_bf16_f32 v20, v20, v21
	v_cvt_pk_bf16_f32 v21, v22, v23
	v_cvt_pk_bf16_f32 v22, v32, v33
	v_cvt_pk_bf16_f32 v23, v34, v35
	global_store_dwordx2 v[40:41], v[16:17], off offset:64
	global_store_dwordx2 v[40:41], v[18:19], off offset:2112
	global_store_dwordx2 v[44:45], v[20:21], off
	global_store_dwordx2 v[42:43], v[22:23], off
	global_load_dwordx4 v[16:19], v[38:39], off
	v_lshrrev_b32_e32 v20, 6, v36
	v_and_or_b32 v122, v20, s50, v121
	v_lshlrev_b64 v[20:21], 14, v[122:123]
	v_lshl_add_u64 v[20:21], s[38:39], 0, v[20:21]
	v_lshl_add_u64 v[20:21], v[20:21], 0, v[152:153]
	v_lshl_add_u64 v[22:23], v[20:21], 0, s[36:37]
	v_lshl_add_u64 v[20:21], v[20:21], 0, v[114:115]
	v_lshl_add_u64 v[24:25], v[22:23], 0, v[116:117]
	v_lshl_add_u64 v[22:23], v[22:23], 0, v[118:119]
	s_waitcnt vmcnt(0)
	v_pk_fma_f32 v[16:17], v[16:17], s[30:31], v[112:113] op_sel_hi:[1,0,0]
	v_pk_fma_f32 v[18:19], v[18:19], s[30:31], v[112:113] op_sel_hi:[1,0,0]
	v_mul_f32_e32 v26, 0x4b800000, v16
	v_mul_f32_e32 v27, 0x4b800000, v17
	v_mul_f32_e32 v28, 0x4b800000, v18
	v_mul_f32_e32 v29, 0x4b800000, v19
	v_cmp_gt_f32_e32 vcc, s40, v16
	v_cmp_gt_f32_e64 s[0:1], s40, v17
	v_cmp_gt_f32_e64 s[10:11], s40, v18
	v_cmp_gt_f32_e64 s[12:13], s40, v19
	v_cndmask_b32_e32 v16, v16, v26, vcc
	v_cndmask_b32_e64 v17, v17, v27, s[0:1]
	v_cndmask_b32_e64 v18, v18, v28, s[10:11]
	v_cndmask_b32_e64 v19, v19, v29, s[12:13]
	v_rsq_f32_e32 v16, v16
	v_rsq_f32_e32 v17, v17
	v_rsq_f32_e32 v18, v18
	v_rsq_f32_e32 v19, v19
	v_mul_f32_e32 v26, 0x45800000, v16
	v_mul_f32_e32 v27, 0x45800000, v17
	v_mul_f32_e32 v28, 0x45800000, v18
	v_mul_f32_e32 v29, 0x45800000, v19
	v_cndmask_b32_e32 v16, v16, v26, vcc
	v_cndmask_b32_e64 v17, v17, v27, s[0:1]
	v_cndmask_b32_e64 v18, v18, v28, s[10:11]
	v_cndmask_b32_e64 v19, v19, v29, s[12:13]
	v_mul_f32_e32 v12, v12, v16
	v_mul_f32_e32 v13, v13, v17
	v_mul_f32_e32 v14, v14, v18
	v_mul_f32_e32 v15, v15, v19
	v_mul_f32_e32 v8, v8, v16
	v_mul_f32_e32 v9, v9, v17
	v_mul_f32_e32 v4, v4, v16
	v_mul_f32_e32 v5, v5, v17
	v_mul_f32_e32 v6, v6, v18
	v_mul_f32_e32 v7, v7, v19
	v_mul_f32_e32 v16, v0, v16
	v_mul_f32_e32 v17, v1, v17
	v_cvt_pk_bf16_f32 v0, v12, v13
	v_cvt_pk_bf16_f32 v1, v14, v15
	v_mul_f32_e32 v10, v10, v18
	v_mul_f32_e32 v11, v11, v19
	v_mul_f32_e32 v18, v2, v18
	v_mul_f32_e32 v19, v3, v19
	v_cvt_pk_bf16_f32 v2, v8, v9
	v_cvt_pk_bf16_f32 v3, v10, v11
	v_cvt_pk_bf16_f32 v4, v4, v5
	v_cvt_pk_bf16_f32 v5, v6, v7
	v_cvt_pk_bf16_f32 v6, v16, v17
	v_cvt_pk_bf16_f32 v7, v18, v19
	global_store_dwordx2 v[20:21], v[0:1], off offset:96
	global_store_dwordx2 v[20:21], v[2:3], off offset:2144
	global_store_dwordx2 v[24:25], v[4:5], off
	global_store_dwordx2 v[22:23], v[6:7], off
	s_branch .LBB0_699

.LBB0_768:
	s_ashr_i32 s10, s4, 3
	s_mul_hi_i32 s11, s10, 0x78787879
	s_lshr_b32 s12, s11, 31
	s_ashr_i32 s11, s11, 3
	s_add_i32 s11, s11, s12
	s_mul_i32 s12, s11, 17
	s_sub_i32 s10, s10, s12
	s_lshl_b32 s12, s4, 8
	s_lshl_b32 s11, s11, 11
	s_and_b32 s12, s12, 0x700
	s_or_b32 s12, s11, s12
	s_ashr_i32 s13, s12, 31
	s_lshl_b32 s10, s10, 7
	s_lshl_b64 s[14:15], s[12:13], 11
	s_add_u32 s14, s6, s14
	s_addc_u32 s15, s7, s15
	s_ashr_i32 s11, s10, 31
	v_mov_b32_e32 v36, v220
	s_lshl_b64 s[16:17], s[10:11], 11
	s_add_u32 s16, s8, s16
	v_ashrrev_i32_e32 v26, 2, v36
	v_ashrrev_i32_e32 v27, 31, v26
	s_addc_u32 s17, s9, s17
	v_lshlrev_b64 v[0:1], 11, v[26:27]
	v_lshlrev_b32_e32 v4, 4, v36
	v_lshl_add_u64 v[2:3], s[16:17], 0, v[0:1]
	v_lshl_add_u64 v[0:1], s[14:15], 0, v[0:1]
	v_and_b32_e32 v152, 48, v4
	v_lshl_add_u64 v[154:155], v[0:1], 0, v[152:153]
	v_add_co_u32_e32 v28, vcc, s38, v154
	v_lshl_add_u64 v[156:157], v[2:3], 0, v[152:153]
	s_nop 0
	v_addc_co_u32_e32 v29, vcc, 0, v155, vcc
	v_add_co_u32_e32 v30, vcc, s39, v154
	global_load_dwordx4 v[2:5], v[154:155], off
	s_nop 0
	v_addc_co_u32_e32 v31, vcc, 0, v155, vcc
	v_add_co_u32_e32 v32, vcc, s40, v154
	global_load_dwordx4 v[6:9], v[28:29], off
	s_nop 0
	v_addc_co_u32_e32 v33, vcc, 0, v155, vcc
	v_add_co_u32_e32 v34, vcc, s38, v156
	global_load_dwordx4 v[10:13], v[30:31], off
	s_nop 0
	v_addc_co_u32_e32 v35, vcc, 0, v157, vcc
	global_load_dwordx4 v[14:17], v[32:33], off
	global_load_dwordx4 v[18:21], v[156:157], off
	global_load_dwordx4 v[22:25], v[34:35], off
	global_load_dwordx4 v[120:123], v[154:155], off offset:64
	global_load_dwordx4 v[128:131], v[28:29], off offset:64
	global_load_dwordx4 v[132:135], v[30:31], off offset:64
	global_load_dwordx4 v[136:139], v[32:33], off offset:64
	global_load_dwordx4 v[124:127], v[156:157], off offset:64
	global_load_dwordx4 v[140:143], v[34:35], off offset:64
	v_lshrrev_b32_e32 v1, 4, v36
	v_lshrrev_b32_e32 v27, 2, v36
	v_sub_u32_e32 v39, 0, v1
	v_sub_u32_e32 v27, 0, v27
	v_and_b32_e32 v37, 0x3ffff8f, v36
	v_lshlrev_b32_e32 v38, 6, v36
	v_xor_b32_e32 v36, v36, v39
	v_xor_b32_e32 v1, v1, v27
	v_lshlrev_b32_e32 v27, 4, v36
	v_lshlrev_b32_e32 v1, 4, v1
	v_and_b32_e32 v40, 0x1000, v38
	v_and_b32_e32 v27, 48, v27
	v_and_b32_e32 v1, 48, v1
	v_and_b32_e32 v41, 0x3c0, v38
	v_and_b32_e32 v38, 0xffffe3c0, v38
	v_lshl_add_u32 v37, v37, 6, v166
	v_lshl_or_b32 v152, v26, 6, v27
	v_or_b32_e32 v26, v1, v40
	s_mov_b32 s11, -2
	s_mov_b32 s13, s35
	v_mov_b32_e32 v0, 0
	v_or3_b32 v168, v40, v41, v1
	v_add_u32_e32 v169, v1, v38
	v_add_u32_e32 v170, v1, v37
	v_add_u32_e32 v171, v26, v41
	v_lshl_add_u64 v[158:159], v[154:155], 0, s[24:25]
	v_lshl_add_u64 v[160:161], v[154:155], 0, s[28:29]
	v_lshl_add_u64 v[162:163], v[154:155], 0, s[30:31]
	v_lshl_add_u64 v[164:165], v[156:157], 0, s[24:25]
	v_mov_b32_e32 v1, v153
	v_mov_b32_e32 v26, v153
	v_mov_b32_e32 v27, v153
	v_mov_b32_e32 v28, 0
	v_mov_b32_e32 v29, v153
	v_mov_b32_e32 v30, v153
	v_mov_b32_e32 v31, v153
	v_mov_b32_e32 v32, 0
	v_mov_b32_e32 v33, v153
	v_mov_b32_e32 v34, v153
	v_mov_b32_e32 v35, v153
	v_mov_b32_e32 v36, 0
	v_mov_b32_e32 v37, v153
	v_mov_b32_e32 v38, v153
	v_mov_b32_e32 v39, v153
	v_mov_b32_e32 v40, 0
	v_mov_b32_e32 v41, v153
	v_mov_b32_e32 v42, v153
	v_mov_b32_e32 v43, v153
	v_mov_b32_e32 v44, 0
	s_waitcnt vmcnt(11)
	ds_write_b128 v152, v[2:5]
	s_waitcnt vmcnt(10)
	ds_write_b128 v152, v[6:9] offset:4096
	s_waitcnt vmcnt(9)
	ds_write_b128 v152, v[10:13] offset:8192
	s_waitcnt vmcnt(8)
	ds_write_b128 v152, v[14:17] offset:12288
	s_waitcnt vmcnt(7)
	ds_write_b128 v152, v[18:21] offset:32768
	s_waitcnt vmcnt(6)
	ds_write_b128 v152, v[22:25] offset:36864
	v_mov_b32_e32 v2, v153
	v_mov_b32_e32 v3, v153
	v_mov_b32_e32 v4, 0
	v_mov_b32_e32 v5, v153
	v_mov_b32_e32 v6, v153
	v_mov_b32_e32 v7, v153
	v_mov_b32_e32 v8, 0
	v_mov_b32_e32 v9, v153
	v_mov_b32_e32 v10, v153
	v_mov_b32_e32 v11, v153
	v_mov_b32_e32 v12, 0
	v_mov_b32_e32 v13, v153
	v_mov_b32_e32 v14, v153
	v_mov_b32_e32 v15, v153
	v_mov_b32_e32 v16, 0
	v_mov_b32_e32 v17, v153
	v_mov_b32_e32 v18, v153
	v_mov_b32_e32 v19, v153
	v_mov_b32_e32 v20, 0
	v_mov_b32_e32 v21, v153
	v_mov_b32_e32 v22, v153
	v_mov_b32_e32 v23, v153
	v_mov_b32_e32 v24, 0
	v_mov_b32_e32 v25, v153
	v_mov_b32_e32 v45, v153
	v_mov_b32_e32 v46, v153
	v_mov_b32_e32 v47, v153
	v_mov_b32_e32 v48, 0
	v_mov_b32_e32 v49, v153
	v_mov_b32_e32 v50, v153
	v_mov_b32_e32 v51, v153
	v_mov_b32_e32 v52, 0
	v_mov_b32_e32 v53, v153
	v_mov_b32_e32 v54, v153
	v_mov_b32_e32 v55, v153
	v_mov_b32_e32 v56, 0
	v_mov_b32_e32 v57, v153
	v_mov_b32_e32 v58, v153
	v_mov_b32_e32 v59, v153
	v_mov_b32_e32 v60, 0
	v_mov_b32_e32 v61, v153
	v_mov_b32_e32 v62, v153
	v_mov_b32_e32 v63, v153
	v_mov_b32_e32 v64, 0
	v_mov_b32_e32 v65, v153
	v_mov_b32_e32 v66, v153
	v_mov_b32_e32 v67, v153
	v_mov_b32_e32 v68, 0
	v_mov_b32_e32 v69, v153
	v_mov_b32_e32 v70, v153
	v_mov_b32_e32 v71, v153
	v_mov_b32_e32 v72, 0
	v_mov_b32_e32 v73, v153
	v_mov_b32_e32 v74, v153
	v_mov_b32_e32 v75, v153
	v_mov_b32_e32 v76, 0
	v_mov_b32_e32 v77, v153
	v_mov_b32_e32 v78, v153
	v_mov_b32_e32 v79, v153
	v_mov_b32_e32 v80, 0
	v_mov_b32_e32 v81, v153
	v_mov_b32_e32 v82, v153
	v_mov_b32_e32 v83, v153
	v_mov_b32_e32 v84, 0
	v_mov_b32_e32 v85, v153
	v_mov_b32_e32 v86, v153
	v_mov_b32_e32 v87, v153
	v_mov_b32_e32 v88, 0
	v_mov_b32_e32 v89, v153
	v_mov_b32_e32 v90, v153
	v_mov_b32_e32 v91, v153
	v_mov_b32_e32 v92, 0
	v_mov_b32_e32 v93, v153
	v_mov_b32_e32 v94, v153
	v_mov_b32_e32 v95, v153
	v_mov_b32_e32 v96, 0
	v_mov_b32_e32 v97, v153
	v_mov_b32_e32 v98, v153
	v_mov_b32_e32 v99, v153
	v_mov_b32_e32 v100, 0
	v_mov_b32_e32 v101, v153
	v_mov_b32_e32 v102, v153
	v_mov_b32_e32 v103, v153
	v_mov_b32_e32 v104, 0
	v_mov_b32_e32 v105, v153
	v_mov_b32_e32 v106, v153
	v_mov_b32_e32 v107, v153
	v_mov_b32_e32 v108, 0
	v_mov_b32_e32 v109, v153
	v_mov_b32_e32 v110, v153
	v_mov_b32_e32 v111, v153
	v_mov_b32_e32 v112, 0
	v_mov_b32_e32 v113, v153
	v_mov_b32_e32 v114, v153
	v_mov_b32_e32 v115, v153
	v_mov_b32_e32 v116, 0
	v_mov_b32_e32 v117, v153
	v_mov_b32_e32 v118, v153
	v_mov_b32_e32 v119, v153
	v_mov_b32_e32 v144, 0
	v_mov_b32_e32 v145, v153
	v_mov_b32_e32 v146, v153
	v_mov_b32_e32 v147, v153
	v_mov_b32_e32 v148, 0
	v_mov_b32_e32 v149, v153
	v_mov_b32_e32 v150, v153
	v_mov_b32_e32 v151, v153
	s_waitcnt lgkmcnt(0)
	s_barrier
	global_load_dwordx4 v[172:175], v[154:155], off offset:128
	global_load_dwordx4 v[176:179], v[158:159], off offset:128
	global_load_dwordx4 v[180:183], v[160:161], off offset:128
	global_load_dwordx4 v[184:187], v[162:163], off offset:128
	global_load_dwordx4 v[188:191], v[156:157], off offset:128
	global_load_dwordx4 v[192:195], v[164:165], off offset:128
.LBB0_769:
	s_add_i32 s14, s13, 64
	s_add_i32 s34, s13, 96
	s_min_u32 s34, s34, 0x3e0
	s_lshl_b32 s34, s34, 1
	ds_read_b128 v[196:199], v171 offset:32768
	ds_read_b128 v[200:203], v171 offset:33792
	ds_read_b128 v[204:207], v171 offset:34816
	ds_read_b128 v[208:211], v171 offset:35840
	ds_read_b128 v[212:215], v169
	ds_read_b128 v[216:219], v169 offset:1024
	ds_read_b128 v[222:225], v169 offset:2048
	ds_read_b128 v[226:229], v169 offset:3072
	ds_read_b128 v[230:233], v169 offset:4096
	ds_read_b128 v[234:237], v169 offset:5120
	ds_read_b128 v[238:241], v169 offset:6144
	ds_read_b128 v[242:245], v169 offset:7168
	s_setprio 1
	s_waitcnt lgkmcnt(7)
	v_mfma_f32_16x16x32_bf16 v[148:151], v[196:199], v[212:215], v[148:151]
	v_mfma_f32_16x16x32_bf16 v[144:147], v[200:203], v[212:215], v[144:147]
	v_mfma_f32_16x16x32_bf16 v[116:119], v[204:207], v[212:215], v[116:119]
	v_mfma_f32_16x16x32_bf16 v[112:115], v[208:211], v[212:215], v[112:115]
	s_waitcnt vmcnt(11)
	ds_write_b128 v152, v[120:123] offset:16384
	s_waitcnt lgkmcnt(7)
	v_mfma_f32_16x16x32_bf16 v[108:111], v[196:199], v[216:219], v[108:111]
	v_mfma_f32_16x16x32_bf16 v[104:107], v[200:203], v[216:219], v[104:107]
	v_mfma_f32_16x16x32_bf16 v[100:103], v[204:207], v[216:219], v[100:103]
	v_mfma_f32_16x16x32_bf16 v[96:99], v[208:211], v[216:219], v[96:99]
	s_waitcnt vmcnt(10)
	ds_write_b128 v152, v[128:131] offset:20480
	v_lshl_add_u64 v[120:121], v[154:155], 0, s[34:35]
	global_load_dwordx4 v[120:123], v[120:121], off
	s_waitcnt lgkmcnt(7)
	v_mfma_f32_16x16x32_bf16 v[92:95], v[196:199], v[222:225], v[92:95]
	v_mfma_f32_16x16x32_bf16 v[88:91], v[200:203], v[222:225], v[88:91]
	v_mfma_f32_16x16x32_bf16 v[84:87], v[204:207], v[222:225], v[84:87]
	v_mfma_f32_16x16x32_bf16 v[80:83], v[208:211], v[222:225], v[80:83]
	s_waitcnt vmcnt(10)
	ds_write_b128 v152, v[132:135] offset:24576
	v_lshl_add_u64 v[128:129], v[158:159], 0, s[34:35]
	global_load_dwordx4 v[128:131], v[128:129], off
	s_waitcnt lgkmcnt(7)
	v_mfma_f32_16x16x32_bf16 v[76:79], v[196:199], v[226:229], v[76:79]
	v_mfma_f32_16x16x32_bf16 v[72:75], v[200:203], v[226:229], v[72:75]
	v_mfma_f32_16x16x32_bf16 v[68:71], v[204:207], v[226:229], v[68:71]
	v_mfma_f32_16x16x32_bf16 v[64:67], v[208:211], v[226:229], v[64:67]
	s_waitcnt vmcnt(10)
	ds_write_b128 v152, v[136:139] offset:28672
	v_lshl_add_u64 v[132:133], v[160:161], 0, s[34:35]
	global_load_dwordx4 v[132:135], v[132:133], off
	s_waitcnt lgkmcnt(7)
	v_mfma_f32_16x16x32_bf16 v[60:63], v[196:199], v[230:233], v[60:63]
	v_mfma_f32_16x16x32_bf16 v[56:59], v[200:203], v[230:233], v[56:59]
	v_mfma_f32_16x16x32_bf16 v[52:55], v[204:207], v[230:233], v[52:55]
	v_mfma_f32_16x16x32_bf16 v[48:51], v[208:211], v[230:233], v[48:51]
	s_waitcnt vmcnt(10)
	ds_write_b128 v152, v[124:127] offset:40960
	v_lshl_add_u64 v[136:137], v[162:163], 0, s[34:35]
	global_load_dwordx4 v[136:139], v[136:137], off
	s_waitcnt lgkmcnt(7)
	v_mfma_f32_16x16x32_bf16 v[44:47], v[196:199], v[234:237], v[44:47]
	v_mfma_f32_16x16x32_bf16 v[40:43], v[200:203], v[234:237], v[40:43]
	v_mfma_f32_16x16x32_bf16 v[36:39], v[204:207], v[234:237], v[36:39]
	v_mfma_f32_16x16x32_bf16 v[32:35], v[208:211], v[234:237], v[32:35]
	s_waitcnt vmcnt(10)
	ds_write_b128 v152, v[140:143] offset:45056
	v_lshl_add_u64 v[124:125], v[156:157], 0, s[34:35]
	global_load_dwordx4 v[124:127], v[124:125], off
	s_waitcnt lgkmcnt(7)
	v_mfma_f32_16x16x32_bf16 v[28:31], v[196:199], v[238:241], v[28:31]
	v_mfma_f32_16x16x32_bf16 v[24:27], v[200:203], v[238:241], v[24:27]
	v_mfma_f32_16x16x32_bf16 v[20:23], v[204:207], v[238:241], v[20:23]
	v_mfma_f32_16x16x32_bf16 v[16:19], v[208:211], v[238:241], v[16:19]
	v_lshl_add_u64 v[140:141], v[164:165], 0, s[34:35]
	global_load_dwordx4 v[140:143], v[140:141], off
	s_waitcnt lgkmcnt(6)
	v_mfma_f32_16x16x32_bf16 v[12:15], v[196:199], v[242:245], v[12:15]
	v_mfma_f32_16x16x32_bf16 v[8:11], v[200:203], v[242:245], v[8:11]
	v_mfma_f32_16x16x32_bf16 v[4:7], v[204:207], v[242:245], v[4:7]
	v_mfma_f32_16x16x32_bf16 v[0:3], v[208:211], v[242:245], v[0:3]
	s_setprio 0
	s_waitcnt lgkmcnt(0)
	s_barrier
	s_add_i32 s34, s13, 0x80
	s_min_u32 s34, s34, 0x3e0
	s_lshl_b32 s34, s34, 1
	ds_read_b128 v[196:199], v168 offset:40960
	ds_read_b128 v[200:203], v168 offset:41984
	ds_read_b128 v[204:207], v168 offset:43008
	ds_read_b128 v[208:211], v168 offset:44032
	ds_read_b128 v[212:215], v170
	ds_read_b128 v[216:219], v170 offset:1024
	ds_read_b128 v[222:225], v170 offset:2048
	ds_read_b128 v[226:229], v170 offset:3072
	ds_read_b128 v[230:233], v170 offset:4096
	ds_read_b128 v[234:237], v170 offset:5120
	ds_read_b128 v[238:241], v170 offset:6144
	ds_read_b128 v[242:245], v170 offset:7168
	s_setprio 1
	s_waitcnt lgkmcnt(7)
	v_mfma_f32_16x16x32_bf16 v[148:151], v[196:199], v[212:215], v[148:151]
	v_mfma_f32_16x16x32_bf16 v[144:147], v[200:203], v[212:215], v[144:147]
	v_mfma_f32_16x16x32_bf16 v[116:119], v[204:207], v[212:215], v[116:119]
	v_mfma_f32_16x16x32_bf16 v[112:115], v[208:211], v[212:215], v[112:115]
	s_waitcnt vmcnt(11)
	ds_write_b128 v152, v[172:175]
	s_waitcnt lgkmcnt(7)
	v_mfma_f32_16x16x32_bf16 v[108:111], v[196:199], v[216:219], v[108:111]
	v_mfma_f32_16x16x32_bf16 v[104:107], v[200:203], v[216:219], v[104:107]
	v_mfma_f32_16x16x32_bf16 v[100:103], v[204:207], v[216:219], v[100:103]
	v_mfma_f32_16x16x32_bf16 v[96:99], v[208:211], v[216:219], v[96:99]
	s_waitcnt vmcnt(10)
	ds_write_b128 v152, v[176:179] offset:4096
	v_lshl_add_u64 v[172:173], v[154:155], 0, s[34:35]
	global_load_dwordx4 v[172:175], v[172:173], off
	s_waitcnt lgkmcnt(7)
	v_mfma_f32_16x16x32_bf16 v[92:95], v[196:199], v[222:225], v[92:95]
	v_mfma_f32_16x16x32_bf16 v[88:91], v[200:203], v[222:225], v[88:91]
	v_mfma_f32_16x16x32_bf16 v[84:87], v[204:207], v[222:225], v[84:87]
	v_mfma_f32_16x16x32_bf16 v[80:83], v[208:211], v[222:225], v[80:83]
	s_waitcnt vmcnt(10)
	ds_write_b128 v152, v[180:183] offset:8192
	v_lshl_add_u64 v[176:177], v[158:159], 0, s[34:35]
	global_load_dwordx4 v[176:179], v[176:177], off
	s_waitcnt lgkmcnt(7)
	v_mfma_f32_16x16x32_bf16 v[76:79], v[196:199], v[226:229], v[76:79]
	v_mfma_f32_16x16x32_bf16 v[72:75], v[200:203], v[226:229], v[72:75]
	v_mfma_f32_16x16x32_bf16 v[68:71], v[204:207], v[226:229], v[68:71]
	v_mfma_f32_16x16x32_bf16 v[64:67], v[208:211], v[226:229], v[64:67]
	s_waitcnt vmcnt(10)
	ds_write_b128 v152, v[184:187] offset:12288
	v_lshl_add_u64 v[180:181], v[160:161], 0, s[34:35]
	global_load_dwordx4 v[180:183], v[180:181], off
	s_waitcnt lgkmcnt(7)
	v_mfma_f32_16x16x32_bf16 v[60:63], v[196:199], v[230:233], v[60:63]
	v_mfma_f32_16x16x32_bf16 v[56:59], v[200:203], v[230:233], v[56:59]
	v_mfma_f32_16x16x32_bf16 v[52:55], v[204:207], v[230:233], v[52:55]
	v_mfma_f32_16x16x32_bf16 v[48:51], v[208:211], v[230:233], v[48:51]
	s_waitcnt vmcnt(10)
	ds_write_b128 v152, v[188:191] offset:32768
	v_lshl_add_u64 v[184:185], v[162:163], 0, s[34:35]
	global_load_dwordx4 v[184:187], v[184:185], off
	s_waitcnt lgkmcnt(7)
	v_mfma_f32_16x16x32_bf16 v[44:47], v[196:199], v[234:237], v[44:47]
	v_mfma_f32_16x16x32_bf16 v[40:43], v[200:203], v[234:237], v[40:43]
	v_mfma_f32_16x16x32_bf16 v[36:39], v[204:207], v[234:237], v[36:39]
	v_mfma_f32_16x16x32_bf16 v[32:35], v[208:211], v[234:237], v[32:35]
	s_waitcnt vmcnt(10)
	ds_write_b128 v152, v[192:195] offset:36864
	v_lshl_add_u64 v[188:189], v[156:157], 0, s[34:35]
	global_load_dwordx4 v[188:191], v[188:189], off
	s_waitcnt lgkmcnt(7)
	v_mfma_f32_16x16x32_bf16 v[28:31], v[196:199], v[238:241], v[28:31]
	v_mfma_f32_16x16x32_bf16 v[24:27], v[200:203], v[238:241], v[24:27]
	v_mfma_f32_16x16x32_bf16 v[20:23], v[204:207], v[238:241], v[20:23]
	v_mfma_f32_16x16x32_bf16 v[16:19], v[208:211], v[238:241], v[16:19]
	v_lshl_add_u64 v[192:193], v[164:165], 0, s[34:35]
	global_load_dwordx4 v[192:195], v[192:193], off
	s_waitcnt lgkmcnt(6)
	v_mfma_f32_16x16x32_bf16 v[12:15], v[196:199], v[242:245], v[12:15]
	v_mfma_f32_16x16x32_bf16 v[8:11], v[200:203], v[242:245], v[8:11]
	v_mfma_f32_16x16x32_bf16 v[4:7], v[204:207], v[242:245], v[4:7]
	v_mfma_f32_16x16x32_bf16 v[0:3], v[208:211], v[242:245], v[0:3]
	s_setprio 0
	s_add_i32 s11, s11, 2
	s_cmp_lt_u32 s11, 30
	s_mov_b32 s13, s14
	s_waitcnt lgkmcnt(0)
	s_barrier
	s_cbranch_scc1 .LBB0_769
	s_waitcnt vmcnt(0)
	s_waitcnt vmcnt(4)
	v_mov_b32_e32 v126, v220
	v_mov_b64_e32 v[124:125], s[72:73]
	v_and_b32_e32 v120, 0xffffff80, v126
	v_add_u32_e32 v120, s12, v120
	v_and_or_b32 v122, v126, 15, v120
	v_ashrrev_i32_e32 v123, 31, v122
	v_lshl_add_u64 v[120:121], v[122:123], 2, s[0:1]
	global_load_dword v120, v[120:121], off
	v_and_b32_e32 v121, 64, v126
	v_lshrrev_b32_e32 v126, 2, v126
	v_and_b32_e32 v126, 12, v126
	s_waitcnt vmcnt(0)
	v_fmamk_f32 v120, v120, 0x3a800000, v167
	v_mul_f32_e32 v127, 0x4b800000, v120
	v_cmp_gt_f32_e32 vcc, s42, v120
	s_nop 1
	v_cndmask_b32_e32 v120, v120, v127, vcc
	v_rsq_f32_e32 v127, v120
	v_or3_b32 v120, v121, v126, s10
	v_mad_i64_i32 v[124:125], s[10:11], v122, s41, v[124:125]
	v_mul_f32_e32 v121, 0x45800000, v127
	v_cndmask_b32_e32 v129, v127, v121, vcc
	v_mul_f32_e32 v132, v148, v129
	v_mul_f32_e32 v131, v149, v129
	v_mul_f32_e32 v130, v150, v129
	v_mul_f32_e32 v128, v151, v129
	v_cmp_lt_i32_e64 s[10:11], s43, v120
	s_and_saveexec_b64 s[12:13], s[10:11]
	s_xor_b64 s[12:13], exec, s[12:13]
	s_cbranch_execz .LBB0_774
	v_cmp_gt_u32_e32 vcc, s44, v120
	s_and_saveexec_b64 s[14:15], vcc
	s_cbranch_execz .LBB0_773
	v_mul_f32_e32 v121, 0xbfb8aa3b, v132
	v_exp_f32_e32 v121, v121
	v_mul_f32_e32 v126, 0xbfb8aa3b, v131
	v_mul_f32_e32 v127, 0xbfb8aa3b, v128
	v_exp_f32_e32 v126, v126
	v_add_f32_e32 v121, 1.0, v121
	v_rcp_f32_e32 v132, v121
	v_mul_f32_e32 v121, 0xbfb8aa3b, v130
	v_exp_f32_e32 v121, v121
	v_exp_f32_e32 v127, v127
	v_add_f32_e32 v126, 1.0, v126
	v_rcp_f32_e32 v133, v126
	v_add_f32_e32 v121, 1.0, v121
	v_rcp_f32_e32 v134, v121
	v_add_f32_e32 v121, 1.0, v127
	v_rcp_f32_e32 v135, v121
	v_mov_b32_e32 v121, v153
	v_lshl_add_u64 v[126:127], v[120:121], 2, v[124:125]
	v_add_co_u32_e32 v126, vcc, 0x2ffe000, v126
	s_nop 1
	v_addc_co_u32_e32 v127, vcc, 0, v127, vcc
	global_store_dwordx4 v[126:127], v[132:135], off

.LBB0_1736:
	s_ashr_i32 s12, s23, 3
	s_lshr_b32 s20, s12, 28
	s_add_i32 s20, s12, s20
	s_and_b32 s21, s20, 0x1fffff0
	s_sub_i32 s12, s12, s21
	s_lshl_b32 s20, s20, 7
	s_lshl_b32 s21, s23, 8
	s_and_b32 s20, s20, 0xfffff800
	s_and_b32 s21, s21, 0x700
	s_or_b32 s20, s20, s21
	s_ashr_i32 s21, s20, 31
	s_lshl_b32 s24, s12, 7
	s_lshl_b64 s[26:27], s[20:21], 11
	s_add_u32 s26, s3, s26
	s_addc_u32 s27, s4, s27
	s_add_i32 s12, s24, 0x880
	v_mov_b32_e32 v36, v220
	s_lshl_b64 s[28:29], s[12:13], 11
	s_add_u32 s28, s5, s28
	v_ashrrev_i32_e32 v26, 2, v36
	v_ashrrev_i32_e32 v27, 31, v26
	s_addc_u32 s29, s6, s29
	v_lshlrev_b64 v[0:1], 11, v[26:27]
	v_lshlrev_b32_e32 v4, 4, v36
	v_lshl_add_u64 v[2:3], s[28:29], 0, v[0:1]
	v_lshl_add_u64 v[0:1], s[26:27], 0, v[0:1]
	v_and_b32_e32 v152, 48, v4
	v_lshl_add_u64 v[154:155], v[0:1], 0, v[152:153]
	v_add_co_u32_e32 v28, vcc, s7, v154
	v_lshl_add_u64 v[156:157], v[2:3], 0, v[152:153]
	s_nop 0
	v_addc_co_u32_e32 v29, vcc, 0, v155, vcc
	v_add_co_u32_e32 v30, vcc, s8, v154
	global_load_dwordx4 v[2:5], v[154:155], off
	s_nop 0
	v_addc_co_u32_e32 v31, vcc, 0, v155, vcc
	v_add_co_u32_e32 v32, vcc, s9, v154
	global_load_dwordx4 v[6:9], v[28:29], off
	s_nop 0
	v_addc_co_u32_e32 v33, vcc, 0, v155, vcc
	v_add_co_u32_e32 v34, vcc, s7, v156
	global_load_dwordx4 v[10:13], v[30:31], off
	s_nop 0
	v_addc_co_u32_e32 v35, vcc, 0, v157, vcc
	global_load_dwordx4 v[14:17], v[32:33], off
	global_load_dwordx4 v[18:21], v[156:157], off
	global_load_dwordx4 v[22:25], v[34:35], off
	global_load_dwordx4 v[120:123], v[154:155], off offset:64
	global_load_dwordx4 v[124:127], v[28:29], off offset:64
	global_load_dwordx4 v[128:131], v[30:31], off offset:64
	global_load_dwordx4 v[136:139], v[32:33], off offset:64
	global_load_dwordx4 v[132:135], v[156:157], off offset:64
	global_load_dwordx4 v[140:143], v[34:35], off offset:64
	v_lshrrev_b32_e32 v27, 4, v36
	v_lshrrev_b32_e32 v37, 2, v36
	v_sub_u32_e32 v40, 0, v27
	v_sub_u32_e32 v37, 0, v37
	v_and_b32_e32 v38, 0x3ffff8f, v36
	v_lshlrev_b32_e32 v39, 6, v36
	v_xor_b32_e32 v36, v36, v40
	v_xor_b32_e32 v27, v27, v37
	v_lshlrev_b32_e32 v36, 4, v36
	v_lshlrev_b32_e32 v27, 4, v27
	v_and_b32_e32 v41, 0x1000, v39
	v_and_b32_e32 v36, 48, v36
	v_and_b32_e32 v27, 48, v27
	v_and_b32_e32 v42, 0x3c0, v39
	v_and_b32_e32 v39, 0xffffe3c0, v39
	v_lshl_add_u32 v38, v38, 6, v166
	v_lshl_or_b32 v152, v26, 6, v36
	v_or_b32_e32 v26, v27, v41
	s_mov_b32 s21, -2
	s_mov_b32 s25, s13
	v_mov_b32_e32 v0, 0
	v_mov_b32_e32 v1, v153
	v_or3_b32 v168, v41, v42, v27
	v_add_u32_e32 v169, v27, v39
	v_add_u32_e32 v170, v27, v38
	v_add_u32_e32 v171, v26, v42
	v_lshl_add_u64 v[158:159], v[154:155], 0, s[14:15]
	v_lshl_add_u64 v[160:161], v[154:155], 0, s[16:17]
	v_lshl_add_u64 v[162:163], v[154:155], 0, s[18:19]
	v_lshl_add_u64 v[164:165], v[156:157], 0, s[14:15]
	v_mov_b32_e32 v26, v153
	v_mov_b32_e32 v27, v153
	v_mov_b32_e32 v28, 0
	v_mov_b32_e32 v29, v153
	v_mov_b32_e32 v30, v153
	v_mov_b32_e32 v31, v153
	v_mov_b32_e32 v32, 0
	v_mov_b32_e32 v33, v153
	v_mov_b32_e32 v34, v153
	v_mov_b32_e32 v35, v153
	v_mov_b32_e32 v36, 0
	v_mov_b32_e32 v37, v153
	v_mov_b32_e32 v38, v153
	v_mov_b32_e32 v39, v153
	v_mov_b32_e32 v40, 0
	v_mov_b32_e32 v41, v153
	v_mov_b32_e32 v42, v153
	v_mov_b32_e32 v43, v153
	v_mov_b32_e32 v44, 0
	s_waitcnt vmcnt(11)
	ds_write_b128 v152, v[2:5]
	s_waitcnt vmcnt(10)
	ds_write_b128 v152, v[6:9] offset:4096
	s_waitcnt vmcnt(9)
	ds_write_b128 v152, v[10:13] offset:8192
	s_waitcnt vmcnt(8)
	ds_write_b128 v152, v[14:17] offset:12288
	s_waitcnt vmcnt(7)
	ds_write_b128 v152, v[18:21] offset:32768
	s_waitcnt vmcnt(6)
	ds_write_b128 v152, v[22:25] offset:36864
	v_mov_b32_e32 v2, v153
	v_mov_b32_e32 v3, v153
	v_mov_b32_e32 v4, 0
	v_mov_b32_e32 v5, v153
	v_mov_b32_e32 v6, v153
	v_mov_b32_e32 v7, v153
	v_mov_b32_e32 v8, 0
	v_mov_b32_e32 v9, v153
	v_mov_b32_e32 v10, v153
	v_mov_b32_e32 v11, v153
	v_mov_b32_e32 v12, 0
	v_mov_b32_e32 v13, v153
	v_mov_b32_e32 v14, v153
	v_mov_b32_e32 v15, v153
	v_mov_b32_e32 v16, 0
	v_mov_b32_e32 v17, v153
	v_mov_b32_e32 v18, v153
	v_mov_b32_e32 v19, v153
	v_mov_b32_e32 v20, 0
	v_mov_b32_e32 v21, v153
	v_mov_b32_e32 v22, v153
	v_mov_b32_e32 v23, v153
	v_mov_b32_e32 v24, 0
	v_mov_b32_e32 v25, v153
	v_mov_b32_e32 v45, v153
	v_mov_b32_e32 v46, v153
	v_mov_b32_e32 v47, v153
	v_mov_b32_e32 v48, 0
	v_mov_b32_e32 v49, v153
	v_mov_b32_e32 v50, v153
	v_mov_b32_e32 v51, v153
	v_mov_b32_e32 v52, 0
	v_mov_b32_e32 v53, v153
	v_mov_b32_e32 v54, v153
	v_mov_b32_e32 v55, v153
	v_mov_b32_e32 v56, 0
	v_mov_b32_e32 v57, v153
	v_mov_b32_e32 v58, v153
	v_mov_b32_e32 v59, v153
	v_mov_b32_e32 v60, 0
	v_mov_b32_e32 v61, v153
	v_mov_b32_e32 v62, v153
	v_mov_b32_e32 v63, v153
	v_mov_b32_e32 v64, 0
	v_mov_b32_e32 v65, v153
	v_mov_b32_e32 v66, v153
	v_mov_b32_e32 v67, v153
	v_mov_b32_e32 v68, 0
	v_mov_b32_e32 v69, v153
	v_mov_b32_e32 v70, v153
	v_mov_b32_e32 v71, v153
	v_mov_b32_e32 v72, 0
	v_mov_b32_e32 v73, v153
	v_mov_b32_e32 v74, v153
	v_mov_b32_e32 v75, v153
	v_mov_b32_e32 v76, 0
	v_mov_b32_e32 v77, v153
	v_mov_b32_e32 v78, v153
	v_mov_b32_e32 v79, v153
	v_mov_b32_e32 v80, 0
	v_mov_b32_e32 v81, v153
	v_mov_b32_e32 v82, v153
	v_mov_b32_e32 v83, v153
	v_mov_b32_e32 v84, 0
	v_mov_b32_e32 v85, v153
	v_mov_b32_e32 v86, v153
	v_mov_b32_e32 v87, v153
	v_mov_b32_e32 v88, 0
	v_mov_b32_e32 v89, v153
	v_mov_b32_e32 v90, v153
	v_mov_b32_e32 v91, v153
	v_mov_b32_e32 v92, 0
	v_mov_b32_e32 v93, v153
	v_mov_b32_e32 v94, v153
	v_mov_b32_e32 v95, v153
	v_mov_b32_e32 v96, 0
	v_mov_b32_e32 v97, v153
	v_mov_b32_e32 v98, v153
	v_mov_b32_e32 v99, v153
	v_mov_b32_e32 v100, 0
	v_mov_b32_e32 v101, v153
	v_mov_b32_e32 v102, v153
	v_mov_b32_e32 v103, v153
	v_mov_b32_e32 v104, 0
	v_mov_b32_e32 v105, v153
	v_mov_b32_e32 v106, v153
	v_mov_b32_e32 v107, v153
	v_mov_b32_e32 v108, 0
	v_mov_b32_e32 v109, v153
	v_mov_b32_e32 v110, v153
	v_mov_b32_e32 v111, v153
	v_mov_b32_e32 v112, 0
	v_mov_b32_e32 v113, v153
	v_mov_b32_e32 v114, v153
	v_mov_b32_e32 v115, v153
	v_mov_b32_e32 v116, 0
	v_mov_b32_e32 v117, v153
	v_mov_b32_e32 v118, v153
	v_mov_b32_e32 v119, v153
	v_mov_b32_e32 v144, 0
	v_mov_b32_e32 v145, v153
	v_mov_b32_e32 v146, v153
	v_mov_b32_e32 v147, v153
	v_mov_b32_e32 v148, 0
	v_mov_b32_e32 v149, v153
	v_mov_b32_e32 v150, v153
	v_mov_b32_e32 v151, v153
	s_waitcnt lgkmcnt(0)
	s_barrier
	global_load_dwordx4 v[172:175], v[154:155], off offset:128
	global_load_dwordx4 v[176:179], v[158:159], off offset:128
	global_load_dwordx4 v[180:183], v[160:161], off offset:128
	global_load_dwordx4 v[184:187], v[162:163], off offset:128
	global_load_dwordx4 v[188:191], v[156:157], off offset:128
	global_load_dwordx4 v[192:195], v[164:165], off offset:128
.LBB0_1737:
	s_add_i32 s26, s25, 64
	s_add_i32 s12, s25, 96
	s_min_u32 s12, s12, 0x3e0
	s_lshl_b32 s12, s12, 1
	ds_read_b128 v[196:199], v171 offset:32768
	ds_read_b128 v[200:203], v171 offset:33792
	ds_read_b128 v[204:207], v171 offset:34816
	ds_read_b128 v[208:211], v171 offset:35840
	ds_read_b128 v[212:215], v169
	ds_read_b128 v[216:219], v169 offset:1024
	ds_read_b128 v[222:225], v169 offset:2048
	ds_read_b128 v[226:229], v169 offset:3072
	ds_read_b128 v[230:233], v169 offset:4096
	ds_read_b128 v[234:237], v169 offset:5120
	ds_read_b128 v[238:241], v169 offset:6144
	ds_read_b128 v[242:245], v169 offset:7168
	s_setprio 1
	s_waitcnt lgkmcnt(7)
	v_mfma_f32_16x16x32_bf16 v[148:151], v[196:199], v[212:215], v[148:151]
	v_mfma_f32_16x16x32_bf16 v[144:147], v[200:203], v[212:215], v[144:147]
	v_mfma_f32_16x16x32_bf16 v[116:119], v[204:207], v[212:215], v[116:119]
	v_mfma_f32_16x16x32_bf16 v[112:115], v[208:211], v[212:215], v[112:115]
	s_waitcnt vmcnt(11)
	ds_write_b128 v152, v[120:123] offset:16384
	s_waitcnt lgkmcnt(7)
	v_mfma_f32_16x16x32_bf16 v[108:111], v[196:199], v[216:219], v[108:111]
	v_mfma_f32_16x16x32_bf16 v[104:107], v[200:203], v[216:219], v[104:107]
	v_mfma_f32_16x16x32_bf16 v[100:103], v[204:207], v[216:219], v[100:103]
	v_mfma_f32_16x16x32_bf16 v[96:99], v[208:211], v[216:219], v[96:99]
	s_waitcnt vmcnt(10)
	ds_write_b128 v152, v[124:127] offset:20480
	v_lshl_add_u64 v[120:121], v[154:155], 0, s[12:13]
	global_load_dwordx4 v[120:123], v[120:121], off
	s_waitcnt lgkmcnt(7)
	v_mfma_f32_16x16x32_bf16 v[92:95], v[196:199], v[222:225], v[92:95]
	v_mfma_f32_16x16x32_bf16 v[88:91], v[200:203], v[222:225], v[88:91]
	v_mfma_f32_16x16x32_bf16 v[84:87], v[204:207], v[222:225], v[84:87]
	v_mfma_f32_16x16x32_bf16 v[80:83], v[208:211], v[222:225], v[80:83]
	s_waitcnt vmcnt(10)
	ds_write_b128 v152, v[128:131] offset:24576
	v_lshl_add_u64 v[124:125], v[158:159], 0, s[12:13]
	global_load_dwordx4 v[124:127], v[124:125], off
	s_waitcnt lgkmcnt(7)
	v_mfma_f32_16x16x32_bf16 v[76:79], v[196:199], v[226:229], v[76:79]
	v_mfma_f32_16x16x32_bf16 v[72:75], v[200:203], v[226:229], v[72:75]
	v_mfma_f32_16x16x32_bf16 v[68:71], v[204:207], v[226:229], v[68:71]
	v_mfma_f32_16x16x32_bf16 v[64:67], v[208:211], v[226:229], v[64:67]
	s_waitcnt vmcnt(10)
	ds_write_b128 v152, v[136:139] offset:28672
	v_lshl_add_u64 v[128:129], v[160:161], 0, s[12:13]
	global_load_dwordx4 v[128:131], v[128:129], off
	s_waitcnt lgkmcnt(7)
	v_mfma_f32_16x16x32_bf16 v[60:63], v[196:199], v[230:233], v[60:63]
	v_mfma_f32_16x16x32_bf16 v[56:59], v[200:203], v[230:233], v[56:59]
	v_mfma_f32_16x16x32_bf16 v[52:55], v[204:207], v[230:233], v[52:55]
	v_mfma_f32_16x16x32_bf16 v[48:51], v[208:211], v[230:233], v[48:51]
	s_waitcnt vmcnt(10)
	ds_write_b128 v152, v[132:135] offset:40960
	v_lshl_add_u64 v[136:137], v[162:163], 0, s[12:13]
	global_load_dwordx4 v[136:139], v[136:137], off
	s_waitcnt lgkmcnt(7)
	v_mfma_f32_16x16x32_bf16 v[44:47], v[196:199], v[234:237], v[44:47]
	v_mfma_f32_16x16x32_bf16 v[40:43], v[200:203], v[234:237], v[40:43]
	v_mfma_f32_16x16x32_bf16 v[36:39], v[204:207], v[234:237], v[36:39]
	v_mfma_f32_16x16x32_bf16 v[32:35], v[208:211], v[234:237], v[32:35]
	s_waitcnt vmcnt(10)
	ds_write_b128 v152, v[140:143] offset:45056
	v_lshl_add_u64 v[132:133], v[156:157], 0, s[12:13]
	global_load_dwordx4 v[132:135], v[132:133], off
	s_waitcnt lgkmcnt(7)
	v_mfma_f32_16x16x32_bf16 v[28:31], v[196:199], v[238:241], v[28:31]
	v_mfma_f32_16x16x32_bf16 v[24:27], v[200:203], v[238:241], v[24:27]
	v_mfma_f32_16x16x32_bf16 v[20:23], v[204:207], v[238:241], v[20:23]
	v_mfma_f32_16x16x32_bf16 v[16:19], v[208:211], v[238:241], v[16:19]
	v_lshl_add_u64 v[140:141], v[164:165], 0, s[12:13]
	global_load_dwordx4 v[140:143], v[140:141], off
	s_waitcnt lgkmcnt(6)
	v_mfma_f32_16x16x32_bf16 v[12:15], v[196:199], v[242:245], v[12:15]
	v_mfma_f32_16x16x32_bf16 v[8:11], v[200:203], v[242:245], v[8:11]
	v_mfma_f32_16x16x32_bf16 v[4:7], v[204:207], v[242:245], v[4:7]
	v_mfma_f32_16x16x32_bf16 v[0:3], v[208:211], v[242:245], v[0:3]
	s_setprio 0
	s_waitcnt lgkmcnt(0)
	s_barrier
	s_add_i32 s12, s25, 0x80
	s_min_u32 s12, s12, 0x3e0
	s_lshl_b32 s12, s12, 1
	ds_read_b128 v[196:199], v168 offset:40960
	ds_read_b128 v[200:203], v168 offset:41984
	ds_read_b128 v[204:207], v168 offset:43008
	ds_read_b128 v[208:211], v168 offset:44032
	ds_read_b128 v[212:215], v170
	ds_read_b128 v[216:219], v170 offset:1024
	ds_read_b128 v[222:225], v170 offset:2048
	ds_read_b128 v[226:229], v170 offset:3072
	ds_read_b128 v[230:233], v170 offset:4096
	ds_read_b128 v[234:237], v170 offset:5120
	ds_read_b128 v[238:241], v170 offset:6144
	ds_read_b128 v[242:245], v170 offset:7168
	s_setprio 1
	s_waitcnt lgkmcnt(7)
	v_mfma_f32_16x16x32_bf16 v[148:151], v[196:199], v[212:215], v[148:151]
	v_mfma_f32_16x16x32_bf16 v[144:147], v[200:203], v[212:215], v[144:147]
	v_mfma_f32_16x16x32_bf16 v[116:119], v[204:207], v[212:215], v[116:119]
	v_mfma_f32_16x16x32_bf16 v[112:115], v[208:211], v[212:215], v[112:115]
	s_waitcnt vmcnt(11)
	ds_write_b128 v152, v[172:175]
	s_waitcnt lgkmcnt(7)
	v_mfma_f32_16x16x32_bf16 v[108:111], v[196:199], v[216:219], v[108:111]
	v_mfma_f32_16x16x32_bf16 v[104:107], v[200:203], v[216:219], v[104:107]
	v_mfma_f32_16x16x32_bf16 v[100:103], v[204:207], v[216:219], v[100:103]
	v_mfma_f32_16x16x32_bf16 v[96:99], v[208:211], v[216:219], v[96:99]
	s_waitcnt vmcnt(10)
	ds_write_b128 v152, v[176:179] offset:4096
	v_lshl_add_u64 v[172:173], v[154:155], 0, s[12:13]
	global_load_dwordx4 v[172:175], v[172:173], off
	s_waitcnt lgkmcnt(7)
	v_mfma_f32_16x16x32_bf16 v[92:95], v[196:199], v[222:225], v[92:95]
	v_mfma_f32_16x16x32_bf16 v[88:91], v[200:203], v[222:225], v[88:91]
	v_mfma_f32_16x16x32_bf16 v[84:87], v[204:207], v[222:225], v[84:87]
	v_mfma_f32_16x16x32_bf16 v[80:83], v[208:211], v[222:225], v[80:83]
	s_waitcnt vmcnt(10)
	ds_write_b128 v152, v[180:183] offset:8192
	v_lshl_add_u64 v[176:177], v[158:159], 0, s[12:13]
	global_load_dwordx4 v[176:179], v[176:177], off
	s_waitcnt lgkmcnt(7)
	v_mfma_f32_16x16x32_bf16 v[76:79], v[196:199], v[226:229], v[76:79]
	v_mfma_f32_16x16x32_bf16 v[72:75], v[200:203], v[226:229], v[72:75]
	v_mfma_f32_16x16x32_bf16 v[68:71], v[204:207], v[226:229], v[68:71]
	v_mfma_f32_16x16x32_bf16 v[64:67], v[208:211], v[226:229], v[64:67]
	s_waitcnt vmcnt(10)
	ds_write_b128 v152, v[184:187] offset:12288
	v_lshl_add_u64 v[180:181], v[160:161], 0, s[12:13]
	global_load_dwordx4 v[180:183], v[180:181], off
	s_waitcnt lgkmcnt(7)
	v_mfma_f32_16x16x32_bf16 v[60:63], v[196:199], v[230:233], v[60:63]
	v_mfma_f32_16x16x32_bf16 v[56:59], v[200:203], v[230:233], v[56:59]
	v_mfma_f32_16x16x32_bf16 v[52:55], v[204:207], v[230:233], v[52:55]
	v_mfma_f32_16x16x32_bf16 v[48:51], v[208:211], v[230:233], v[48:51]
	s_waitcnt vmcnt(10)
	ds_write_b128 v152, v[188:191] offset:32768
	v_lshl_add_u64 v[184:185], v[162:163], 0, s[12:13]
	global_load_dwordx4 v[184:187], v[184:185], off
	s_waitcnt lgkmcnt(7)
	v_mfma_f32_16x16x32_bf16 v[44:47], v[196:199], v[234:237], v[44:47]
	v_mfma_f32_16x16x32_bf16 v[40:43], v[200:203], v[234:237], v[40:43]
	v_mfma_f32_16x16x32_bf16 v[36:39], v[204:207], v[234:237], v[36:39]
	v_mfma_f32_16x16x32_bf16 v[32:35], v[208:211], v[234:237], v[32:35]
	s_waitcnt vmcnt(10)
	ds_write_b128 v152, v[192:195] offset:36864
	v_lshl_add_u64 v[188:189], v[156:157], 0, s[12:13]
	global_load_dwordx4 v[188:191], v[188:189], off
	s_waitcnt lgkmcnt(7)
	v_mfma_f32_16x16x32_bf16 v[28:31], v[196:199], v[238:241], v[28:31]
	v_mfma_f32_16x16x32_bf16 v[24:27], v[200:203], v[238:241], v[24:27]
	v_mfma_f32_16x16x32_bf16 v[20:23], v[204:207], v[238:241], v[20:23]
	v_mfma_f32_16x16x32_bf16 v[16:19], v[208:211], v[238:241], v[16:19]
	v_lshl_add_u64 v[192:193], v[164:165], 0, s[12:13]
	global_load_dwordx4 v[192:195], v[192:193], off
	s_waitcnt lgkmcnt(6)
	v_mfma_f32_16x16x32_bf16 v[12:15], v[196:199], v[242:245], v[12:15]
	v_mfma_f32_16x16x32_bf16 v[8:11], v[200:203], v[242:245], v[8:11]
	v_mfma_f32_16x16x32_bf16 v[4:7], v[204:207], v[242:245], v[4:7]
	v_mfma_f32_16x16x32_bf16 v[0:3], v[208:211], v[242:245], v[0:3]
	s_setprio 0
	s_add_i32 s21, s21, 2
	s_cmp_lt_u32 s21, 30
	s_mov_b32 s25, s26
	s_waitcnt lgkmcnt(0)
	s_barrier
	s_cbranch_scc1 .LBB0_1737
	s_waitcnt vmcnt(0)
	s_waitcnt vmcnt(5)
	v_mov_b32_e32 v120, v220
	s_nop 0
	v_and_b32_e32 v122, 0xffffff80, v120
	v_add_u32_e32 v122, s20, v122
	v_and_b32_e32 v121, 64, v120
	v_and_or_b32 v122, v120, 15, v122
	v_lshrrev_b32_e32 v120, 2, v120
	v_and_b32_e32 v120, 12, v120
	v_or3_b32 v120, v121, v120, s24
	v_ashrrev_i32_e32 v121, 31, v120
	v_ashrrev_i32_e32 v123, 31, v122
	v_lshl_add_u64 v[120:121], v[120:121], 1, s[10:11]
	s_waitcnt vmcnt(3)
	v_lshl_add_u64 v[124:125], v[122:123], 2, s[0:1]
	v_lshlrev_b64 v[126:127], 12, v[122:123]
	v_lshl_add_u64 v[162:163], v[120:121], 0, v[126:127]
	global_load_dword v152, v[124:125], off
	global_load_dwordx2 v[168:169], v[162:163], off
	global_load_dwordx2 v[170:171], v[162:163], off offset:32
	global_load_dwordx2 v[172:173], v[162:163], off offset:64
	v_or_b32_e32 v124, 16, v122
	v_ashrrev_i32_e32 v125, 31, v124
	v_lshl_add_u64 v[126:127], v[124:125], 2, s[0:1]
	v_lshlrev_b64 v[124:125], 12, v[124:125]
	s_waitcnt vmcnt(4)
	v_lshl_add_u64 v[142:143], v[120:121], 0, v[124:125]
	v_or_b32_e32 v124, 32, v122
	v_ashrrev_i32_e32 v125, 31, v124
	global_load_dwordx2 v[174:175], v[162:163], off offset:96
	global_load_dword v176, v[126:127], off
	global_load_dwordx2 v[164:165], v[142:143], off
	global_load_dwordx2 v[160:161], v[142:143], off offset:32
	v_lshl_add_u64 v[126:127], v[124:125], 2, s[0:1]
	v_lshlrev_b64 v[124:125], 12, v[124:125]
	v_lshl_add_u64 v[132:133], v[120:121], 0, v[124:125]
	v_or_b32_e32 v124, 48, v122
	v_ashrrev_i32_e32 v125, 31, v124
	global_load_dwordx2 v[158:159], v[142:143], off offset:64
	global_load_dwordx2 v[156:157], v[142:143], off offset:96
	global_load_dword v177, v[126:127], off
	global_load_dwordx2 v[154:155], v[132:133], off
	v_lshl_add_u64 v[126:127], v[124:125], 2, s[0:1]
	v_lshlrev_b64 v[124:125], 12, v[124:125]
	v_lshl_add_u64 v[124:125], v[120:121], 0, v[124:125]
	global_load_dwordx2 v[140:141], v[132:133], off offset:32
	global_load_dwordx2 v[138:139], v[132:133], off offset:64
	global_load_dwordx2 v[136:137], v[132:133], off offset:96
	global_load_dword v123, v[126:127], off
	global_load_dwordx2 v[134:135], v[124:125], off
	global_load_dwordx2 v[130:131], v[124:125], off offset:32
	global_load_dwordx2 v[128:129], v[124:125], off offset:64
	s_nop 0
	global_load_dwordx2 v[126:127], v[124:125], off offset:96
	s_waitcnt vmcnt(19)
	v_fmamk_f32 v152, v152, 0x3a800000, v167
	v_mul_f32_e32 v178, 0x4b800000, v152
	v_cmp_gt_f32_e32 vcc, s22, v152
	s_nop 1
	v_cndmask_b32_e32 v152, v152, v178, vcc
	v_rsq_f32_e32 v152, v152
	s_waitcnt vmcnt(18)
	v_lshlrev_b32_e32 v178, 16, v168
	v_and_b32_e32 v168, 0xffff0000, v168
	v_mul_f32_e32 v179, 0x45800000, v152
	v_cndmask_b32_e32 v152, v152, v179, vcc
	v_mul_f32_e32 v148, v148, v152
	v_mul_f32_e32 v180, 0xbfb8aa3b, v148
	v_exp_f32_e32 v180, v180
	v_mul_f32_e32 v149, v149, v152
	v_mul_f32_e32 v181, 0xbfb8aa3b, v149
	v_exp_f32_e32 v181, v181
	v_add_f32_e32 v180, 1.0, v180
	v_rcp_f32_e32 v180, v180
	v_mul_f32_e32 v150, v150, v152
	v_mul_f32_e32 v151, v151, v152
	v_lshlrev_b32_e32 v179, 16, v169
	v_mul_f32_e32 v148, v148, v180
	v_mul_f32_e32 v148, v148, v178
	v_add_f32_e32 v178, 1.0, v181
	v_mul_f32_e32 v180, 0xbfb8aa3b, v150
	v_mul_f32_e32 v181, 0xbfb8aa3b, v151
	v_rcp_f32_e32 v178, v178
	v_exp_f32_e32 v180, v180
	v_exp_f32_e32 v181, v181
	v_and_b32_e32 v169, 0xffff0000, v169
	v_mul_f32_e32 v149, v149, v178
	v_add_f32_e32 v178, 1.0, v180
	v_add_f32_e32 v180, 1.0, v181
	v_rcp_f32_e32 v180, v180
	v_rcp_f32_e32 v178, v178
	v_mul_f32_e32 v149, v149, v168
	v_mul_f32_e32 v144, v144, v152
	v_mul_f32_e32 v151, v151, v180
	v_mul_f32_e32 v150, v150, v178
	v_mul_f32_e32 v151, v151, v169
	v_mul_f32_e32 v150, v150, v179
	v_cvt_pk_bf16_f32 v148, v148, v149
	v_cvt_pk_bf16_f32 v149, v150, v151
	v_mul_f32_e32 v151, 0xbfb8aa3b, v144
	v_exp_f32_e32 v151, v151
	v_mul_f32_e32 v145, v145, v152
	v_mul_f32_e32 v169, 0xbfb8aa3b, v145
	v_exp_f32_e32 v169, v169
	v_add_f32_e32 v151, 1.0, v151
	v_rcp_f32_e32 v151, v151
	global_store_dwordx2 v[162:163], v[148:149], off
	s_waitcnt vmcnt(18)
	v_lshlrev_b32_e32 v148, 16, v170
	v_mul_f32_e32 v146, v146, v152
	v_mul_f32_e32 v147, v147, v152
	v_mul_f32_e32 v144, v144, v151
	v_mul_f32_e32 v144, v144, v148
	v_add_f32_e32 v148, 1.0, v169
	v_mul_f32_e32 v151, 0xbfb8aa3b, v146
	v_mul_f32_e32 v169, 0xbfb8aa3b, v147
	v_rcp_f32_e32 v148, v148
	v_exp_f32_e32 v151, v151
	v_exp_f32_e32 v169, v169
	v_and_b32_e32 v149, 0xffff0000, v170
	v_mul_f32_e32 v145, v145, v148
	v_add_f32_e32 v148, 1.0, v151
	v_add_f32_e32 v151, 1.0, v169
	v_rcp_f32_e32 v151, v151
	v_rcp_f32_e32 v148, v148
	v_and_b32_e32 v168, 0xffff0000, v171
	v_lshlrev_b32_e32 v150, 16, v171
	v_mul_f32_e32 v147, v147, v151
	v_mul_f32_e32 v145, v145, v149
	v_mul_f32_e32 v146, v146, v148
	v_mul_f32_e32 v147, v147, v168
	v_mul_f32_e32 v116, v116, v152
	v_mul_f32_e32 v146, v146, v150
	v_cvt_pk_bf16_f32 v144, v144, v145
	v_cvt_pk_bf16_f32 v145, v146, v147
	v_mul_f32_e32 v147, 0xbfb8aa3b, v116
	v_exp_f32_e32 v147, v147
	v_mul_f32_e32 v117, v117, v152
	v_mul_f32_e32 v149, 0xbfb8aa3b, v117
	v_exp_f32_e32 v149, v149
	v_add_f32_e32 v147, 1.0, v147
	v_rcp_f32_e32 v147, v147
	global_store_dwordx2 v[162:163], v[144:145], off offset:32
	s_waitcnt vmcnt(18)
	v_lshlrev_b32_e32 v144, 16, v172
	v_mul_f32_e32 v118, v118, v152
	v_mul_f32_e32 v119, v119, v152
	v_mul_f32_e32 v116, v116, v147
	v_mul_f32_e32 v116, v116, v144
	v_add_f32_e32 v144, 1.0, v149
	v_mul_f32_e32 v147, 0xbfb8aa3b, v118
	v_mul_f32_e32 v149, 0xbfb8aa3b, v119
	v_rcp_f32_e32 v144, v144
	v_exp_f32_e32 v147, v147
	v_exp_f32_e32 v149, v149
	v_and_b32_e32 v145, 0xffff0000, v172
	v_mul_f32_e32 v117, v117, v144
	v_add_f32_e32 v144, 1.0, v147
	v_add_f32_e32 v147, 1.0, v149
	v_rcp_f32_e32 v147, v147
	v_rcp_f32_e32 v144, v144
	v_and_b32_e32 v148, 0xffff0000, v173
	v_lshlrev_b32_e32 v146, 16, v173
	v_mul_f32_e32 v119, v119, v147
	v_mul_f32_e32 v117, v117, v145
	v_mul_f32_e32 v118, v118, v144
	v_mul_f32_e32 v119, v119, v148
	v_mul_f32_e32 v112, v112, v152
	v_mul_f32_e32 v118, v118, v146
	v_cvt_pk_bf16_f32 v116, v116, v117
	v_cvt_pk_bf16_f32 v117, v118, v119
	v_mul_f32_e32 v119, 0xbfb8aa3b, v112
	v_exp_f32_e32 v119, v119
	v_mul_f32_e32 v113, v113, v152
	v_mul_f32_e32 v145, 0xbfb8aa3b, v113
	v_exp_f32_e32 v145, v145
	v_add_f32_e32 v119, 1.0, v119
	v_rcp_f32_e32 v119, v119
	global_store_dwordx2 v[162:163], v[116:117], off offset:64
	s_waitcnt vmcnt(18)
	v_lshlrev_b32_e32 v116, 16, v174
	v_mul_f32_e32 v114, v114, v152
	v_mul_f32_e32 v112, v112, v119
	v_mul_f32_e32 v112, v112, v116
	v_add_f32_e32 v116, 1.0, v145
	v_mul_f32_e32 v119, 0xbfb8aa3b, v114
	v_rcp_f32_e32 v116, v116
	v_exp_f32_e32 v119, v119
	v_mul_f32_e32 v115, v115, v152
	v_mul_f32_e32 v145, 0xbfb8aa3b, v115
	v_mul_f32_e32 v113, v113, v116
	v_add_f32_e32 v116, 1.0, v119
	v_rcp_f32_e32 v116, v116
	v_exp_f32_e32 v145, v145
	v_and_b32_e32 v117, 0xffff0000, v174
	v_mul_f32_e32 v113, v113, v117
	v_mul_f32_e32 v114, v114, v116
	s_waitcnt vmcnt(17)
	v_fmamk_f32 v116, v176, 0x3a800000, v167
	v_add_f32_e32 v119, 1.0, v145
	v_mul_f32_e32 v117, 0x4b800000, v116
	v_cmp_gt_f32_e32 vcc, s22, v116
	v_rcp_f32_e32 v119, v119
	v_lshlrev_b32_e32 v118, 16, v175
	v_cndmask_b32_e32 v116, v116, v117, vcc
	v_rsq_f32_e32 v116, v116
	v_and_b32_e32 v144, 0xffff0000, v175
	v_mul_f32_e32 v115, v115, v119
	v_cvt_pk_bf16_f32 v112, v112, v113
	v_mul_f32_e32 v114, v114, v118
	v_mul_f32_e32 v115, v115, v144
	v_cvt_pk_bf16_f32 v113, v114, v115
	global_store_dwordx2 v[162:163], v[112:113], off offset:96
	v_mul_f32_e32 v112, 0x45800000, v116
	v_cndmask_b32_e32 v112, v116, v112, vcc
	v_mul_f32_e32 v108, v108, v112
	v_mul_f32_e32 v116, 0xbfb8aa3b, v108
	v_exp_f32_e32 v116, v116
	v_mul_f32_e32 v109, v109, v112
	v_mul_f32_e32 v118, 0xbfb8aa3b, v109
	v_exp_f32_e32 v118, v118
	v_add_f32_e32 v116, 1.0, v116
	v_rcp_f32_e32 v116, v116
	s_waitcnt vmcnt(17)
	v_lshlrev_b32_e32 v113, 16, v164
	v_mul_f32_e32 v110, v110, v112
	v_mul_f32_e32 v111, v111, v112
	v_mul_f32_e32 v108, v108, v116
	v_mul_f32_e32 v108, v108, v113
	v_add_f32_e32 v113, 1.0, v118
	v_mul_f32_e32 v116, 0xbfb8aa3b, v110
	v_mul_f32_e32 v118, 0xbfb8aa3b, v111
	v_rcp_f32_e32 v113, v113
	v_exp_f32_e32 v116, v116
	v_exp_f32_e32 v118, v118
	v_and_b32_e32 v114, 0xffff0000, v164
	v_mul_f32_e32 v109, v109, v113
	v_add_f32_e32 v113, 1.0, v116
	v_add_f32_e32 v116, 1.0, v118
	v_rcp_f32_e32 v116, v116
	v_rcp_f32_e32 v113, v113
	v_and_b32_e32 v117, 0xffff0000, v165
	v_lshlrev_b32_e32 v115, 16, v165
	v_mul_f32_e32 v111, v111, v116
	v_mul_f32_e32 v109, v109, v114
	v_mul_f32_e32 v110, v110, v113
	v_mul_f32_e32 v111, v111, v117
	v_mul_f32_e32 v104, v104, v112
	v_mul_f32_e32 v110, v110, v115
	v_cvt_pk_bf16_f32 v108, v108, v109
	v_cvt_pk_bf16_f32 v109, v110, v111
	v_mul_f32_e32 v111, 0xbfb8aa3b, v104
	v_exp_f32_e32 v111, v111
	v_mul_f32_e32 v105, v105, v112
	v_mul_f32_e32 v114, 0xbfb8aa3b, v105
	v_exp_f32_e32 v114, v114
	v_add_f32_e32 v111, 1.0, v111
	v_rcp_f32_e32 v111, v111
	global_store_dwordx2 v[142:143], v[108:109], off
	s_waitcnt vmcnt(17)
	v_lshlrev_b32_e32 v108, 16, v160
	v_mul_f32_e32 v106, v106, v112
	v_mul_f32_e32 v107, v107, v112
	v_mul_f32_e32 v104, v104, v111
	v_mul_f32_e32 v104, v104, v108
	v_add_f32_e32 v108, 1.0, v114
	v_mul_f32_e32 v111, 0xbfb8aa3b, v106
	v_mul_f32_e32 v114, 0xbfb8aa3b, v107
	v_rcp_f32_e32 v108, v108
	v_exp_f32_e32 v111, v111
	v_exp_f32_e32 v114, v114
	v_and_b32_e32 v109, 0xffff0000, v160
	v_mul_f32_e32 v105, v105, v108
	v_add_f32_e32 v108, 1.0, v111
	v_add_f32_e32 v111, 1.0, v114
	v_rcp_f32_e32 v111, v111
	v_rcp_f32_e32 v108, v108
	v_and_b32_e32 v113, 0xffff0000, v161
	v_lshlrev_b32_e32 v110, 16, v161
	v_mul_f32_e32 v107, v107, v111
	v_mul_f32_e32 v105, v105, v109
	v_mul_f32_e32 v106, v106, v108
	v_mul_f32_e32 v107, v107, v113
	v_mul_f32_e32 v100, v100, v112
	v_mul_f32_e32 v106, v106, v110
	v_cvt_pk_bf16_f32 v104, v104, v105
	v_cvt_pk_bf16_f32 v105, v106, v107
	v_mul_f32_e32 v107, 0xbfb8aa3b, v100
	v_exp_f32_e32 v107, v107
	v_mul_f32_e32 v101, v101, v112
	v_mul_f32_e32 v109, 0xbfb8aa3b, v101
	v_exp_f32_e32 v109, v109
	v_add_f32_e32 v107, 1.0, v107
	v_rcp_f32_e32 v107, v107
	global_store_dwordx2 v[142:143], v[104:105], off offset:32
	s_waitcnt vmcnt(17)
	v_lshlrev_b32_e32 v104, 16, v158
	v_mul_f32_e32 v102, v102, v112
	v_mul_f32_e32 v103, v103, v112
	v_mul_f32_e32 v100, v100, v107
	v_mul_f32_e32 v100, v100, v104
	v_add_f32_e32 v104, 1.0, v109
	v_mul_f32_e32 v107, 0xbfb8aa3b, v102
	v_mul_f32_e32 v109, 0xbfb8aa3b, v103
	v_rcp_f32_e32 v104, v104
	v_exp_f32_e32 v107, v107
	v_exp_f32_e32 v109, v109
	v_and_b32_e32 v105, 0xffff0000, v158
	v_mul_f32_e32 v101, v101, v104
	v_add_f32_e32 v104, 1.0, v107
	v_add_f32_e32 v107, 1.0, v109
	v_rcp_f32_e32 v107, v107
	v_rcp_f32_e32 v104, v104
	v_and_b32_e32 v108, 0xffff0000, v159
	v_lshlrev_b32_e32 v106, 16, v159
	v_mul_f32_e32 v103, v103, v107
	v_mul_f32_e32 v101, v101, v105
	v_mul_f32_e32 v102, v102, v104
	v_mul_f32_e32 v103, v103, v108
	v_mul_f32_e32 v96, v96, v112
	v_mul_f32_e32 v102, v102, v106
	v_cvt_pk_bf16_f32 v100, v100, v101
	v_cvt_pk_bf16_f32 v101, v102, v103
	v_mul_f32_e32 v103, 0xbfb8aa3b, v96
	v_exp_f32_e32 v103, v103
	v_mul_f32_e32 v97, v97, v112
	v_mul_f32_e32 v105, 0xbfb8aa3b, v97
	v_exp_f32_e32 v105, v105
	v_add_f32_e32 v103, 1.0, v103
	v_rcp_f32_e32 v103, v103
	global_store_dwordx2 v[142:143], v[100:101], off offset:64
	s_waitcnt vmcnt(17)
	v_lshlrev_b32_e32 v100, 16, v156
	v_mul_f32_e32 v98, v98, v112
	v_mul_f32_e32 v96, v96, v103
	v_mul_f32_e32 v96, v96, v100
	v_add_f32_e32 v100, 1.0, v105
	v_mul_f32_e32 v103, 0xbfb8aa3b, v98
	v_rcp_f32_e32 v100, v100
	v_exp_f32_e32 v103, v103
	v_mul_f32_e32 v99, v99, v112
	v_mul_f32_e32 v105, 0xbfb8aa3b, v99
	v_mul_f32_e32 v97, v97, v100
	v_add_f32_e32 v100, 1.0, v103
	v_rcp_f32_e32 v100, v100
	v_exp_f32_e32 v105, v105
	v_and_b32_e32 v101, 0xffff0000, v156
	v_mul_f32_e32 v97, v97, v101
	v_mul_f32_e32 v98, v98, v100
	s_waitcnt vmcnt(16)
	v_fmamk_f32 v100, v177, 0x3a800000, v167
	v_add_f32_e32 v103, 1.0, v105
	v_mul_f32_e32 v101, 0x4b800000, v100
	v_cmp_gt_f32_e32 vcc, s22, v100
	v_rcp_f32_e32 v103, v103
	v_lshlrev_b32_e32 v102, 16, v157
	v_cndmask_b32_e32 v100, v100, v101, vcc
	v_rsq_f32_e32 v100, v100
	v_and_b32_e32 v104, 0xffff0000, v157
	v_mul_f32_e32 v99, v99, v103
	v_cvt_pk_bf16_f32 v96, v96, v97
	v_mul_f32_e32 v98, v98, v102
	v_mul_f32_e32 v99, v99, v104
	v_cvt_pk_bf16_f32 v97, v98, v99
	global_store_dwordx2 v[142:143], v[96:97], off offset:96
	v_mul_f32_e32 v96, 0x45800000, v100
	v_cndmask_b32_e32 v96, v100, v96, vcc
	v_mul_f32_e32 v92, v92, v96
	v_mul_f32_e32 v100, 0xbfb8aa3b, v92
	v_exp_f32_e32 v100, v100
	v_mul_f32_e32 v93, v93, v96
	v_mul_f32_e32 v102, 0xbfb8aa3b, v93
	v_exp_f32_e32 v102, v102
	v_add_f32_e32 v100, 1.0, v100
	v_rcp_f32_e32 v100, v100
	s_waitcnt vmcnt(16)
	v_lshlrev_b32_e32 v97, 16, v154
	v_mul_f32_e32 v94, v94, v96
	v_mul_f32_e32 v95, v95, v96
	v_mul_f32_e32 v92, v92, v100
	v_mul_f32_e32 v92, v92, v97
	v_add_f32_e32 v97, 1.0, v102
	v_mul_f32_e32 v100, 0xbfb8aa3b, v94
	v_mul_f32_e32 v102, 0xbfb8aa3b, v95
	v_rcp_f32_e32 v97, v97
	v_exp_f32_e32 v100, v100
	v_exp_f32_e32 v102, v102
	v_and_b32_e32 v98, 0xffff0000, v154
	v_mul_f32_e32 v93, v93, v97
	v_add_f32_e32 v97, 1.0, v100
	v_add_f32_e32 v100, 1.0, v102
	v_rcp_f32_e32 v100, v100
	v_rcp_f32_e32 v97, v97
	v_and_b32_e32 v101, 0xffff0000, v155
	v_lshlrev_b32_e32 v99, 16, v155
	v_mul_f32_e32 v95, v95, v100
	v_mul_f32_e32 v93, v93, v98
	v_mul_f32_e32 v94, v94, v97
	v_mul_f32_e32 v95, v95, v101
	v_mul_f32_e32 v88, v88, v96
	v_mul_f32_e32 v94, v94, v99
	v_cvt_pk_bf16_f32 v92, v92, v93
	v_cvt_pk_bf16_f32 v93, v94, v95
	v_mul_f32_e32 v95, 0xbfb8aa3b, v88
	v_exp_f32_e32 v95, v95
	v_mul_f32_e32 v89, v89, v96
	v_mul_f32_e32 v98, 0xbfb8aa3b, v89
	v_exp_f32_e32 v98, v98
	v_add_f32_e32 v95, 1.0, v95
	v_rcp_f32_e32 v95, v95
	global_store_dwordx2 v[132:133], v[92:93], off
	s_waitcnt vmcnt(16)
	v_lshlrev_b32_e32 v92, 16, v140
	v_mul_f32_e32 v90, v90, v96
	v_mul_f32_e32 v91, v91, v96
	v_mul_f32_e32 v88, v88, v95
	v_mul_f32_e32 v88, v88, v92
	v_add_f32_e32 v92, 1.0, v98
	v_mul_f32_e32 v95, 0xbfb8aa3b, v90
	v_mul_f32_e32 v98, 0xbfb8aa3b, v91
	v_rcp_f32_e32 v92, v92
	v_exp_f32_e32 v95, v95
	v_exp_f32_e32 v98, v98
	v_and_b32_e32 v93, 0xffff0000, v140
	v_mul_f32_e32 v89, v89, v92
	v_add_f32_e32 v92, 1.0, v95
	v_add_f32_e32 v95, 1.0, v98
	v_rcp_f32_e32 v95, v95
	v_rcp_f32_e32 v92, v92
	v_and_b32_e32 v97, 0xffff0000, v141
	v_lshlrev_b32_e32 v94, 16, v141
	v_mul_f32_e32 v91, v91, v95
	v_mul_f32_e32 v89, v89, v93
	v_mul_f32_e32 v90, v90, v92
	v_mul_f32_e32 v91, v91, v97
	v_mul_f32_e32 v84, v84, v96
	v_mul_f32_e32 v90, v90, v94
	v_cvt_pk_bf16_f32 v88, v88, v89
	v_cvt_pk_bf16_f32 v89, v90, v91
	v_mul_f32_e32 v91, 0xbfb8aa3b, v84
	v_exp_f32_e32 v91, v91
	v_mul_f32_e32 v85, v85, v96
	v_mul_f32_e32 v93, 0xbfb8aa3b, v85
	v_exp_f32_e32 v93, v93
	v_add_f32_e32 v91, 1.0, v91
	v_rcp_f32_e32 v91, v91
	global_store_dwordx2 v[132:133], v[88:89], off offset:32
	s_waitcnt vmcnt(16)
	v_lshlrev_b32_e32 v88, 16, v138
	v_mul_f32_e32 v86, v86, v96
	v_mul_f32_e32 v87, v87, v96
	v_mul_f32_e32 v84, v84, v91
	v_mul_f32_e32 v84, v84, v88
	v_add_f32_e32 v88, 1.0, v93
	v_mul_f32_e32 v91, 0xbfb8aa3b, v86
	v_mul_f32_e32 v93, 0xbfb8aa3b, v87
	v_rcp_f32_e32 v88, v88
	v_exp_f32_e32 v91, v91
	v_exp_f32_e32 v93, v93
	v_and_b32_e32 v89, 0xffff0000, v138
	v_mul_f32_e32 v85, v85, v88
	v_add_f32_e32 v88, 1.0, v91
	v_add_f32_e32 v91, 1.0, v93
	v_rcp_f32_e32 v91, v91
	v_rcp_f32_e32 v88, v88
	v_and_b32_e32 v92, 0xffff0000, v139
	v_lshlrev_b32_e32 v90, 16, v139
	v_mul_f32_e32 v87, v87, v91
	v_mul_f32_e32 v85, v85, v89
	v_mul_f32_e32 v86, v86, v88
	v_mul_f32_e32 v87, v87, v92
	v_mul_f32_e32 v80, v80, v96
	v_mul_f32_e32 v86, v86, v90
	v_cvt_pk_bf16_f32 v84, v84, v85
	v_cvt_pk_bf16_f32 v85, v86, v87
	v_mul_f32_e32 v87, 0xbfb8aa3b, v80
	v_exp_f32_e32 v87, v87
	v_mul_f32_e32 v81, v81, v96
	v_mul_f32_e32 v89, 0xbfb8aa3b, v81
	v_exp_f32_e32 v89, v89
	v_add_f32_e32 v87, 1.0, v87
	v_rcp_f32_e32 v87, v87
	global_store_dwordx2 v[132:133], v[84:85], off offset:64
	s_waitcnt vmcnt(16)
	v_lshlrev_b32_e32 v84, 16, v136
	v_mul_f32_e32 v82, v82, v96
	v_mul_f32_e32 v80, v80, v87
	v_mul_f32_e32 v80, v80, v84
	v_add_f32_e32 v84, 1.0, v89
	v_mul_f32_e32 v87, 0xbfb8aa3b, v82
	v_rcp_f32_e32 v84, v84
	v_exp_f32_e32 v87, v87
	v_mul_f32_e32 v83, v83, v96
	v_mul_f32_e32 v89, 0xbfb8aa3b, v83
	v_mul_f32_e32 v81, v81, v84
	v_add_f32_e32 v84, 1.0, v87
	v_rcp_f32_e32 v84, v84
	v_exp_f32_e32 v89, v89
	v_and_b32_e32 v85, 0xffff0000, v136
	v_mul_f32_e32 v81, v81, v85
	v_mul_f32_e32 v82, v82, v84
	s_waitcnt vmcnt(15)
	v_fmamk_f32 v84, v123, 0x3a800000, v167
	v_add_f32_e32 v87, 1.0, v89
	v_mul_f32_e32 v85, 0x4b800000, v84
	v_cmp_gt_f32_e32 vcc, s22, v84
	v_rcp_f32_e32 v87, v87
	v_lshlrev_b32_e32 v86, 16, v137
	v_cndmask_b32_e32 v84, v84, v85, vcc
	v_rsq_f32_e32 v84, v84
	v_and_b32_e32 v88, 0xffff0000, v137
	v_mul_f32_e32 v83, v83, v87
	v_cvt_pk_bf16_f32 v80, v80, v81
	v_mul_f32_e32 v82, v82, v86
	v_mul_f32_e32 v83, v83, v88
	v_cvt_pk_bf16_f32 v81, v82, v83
	global_store_dwordx2 v[132:133], v[80:81], off offset:96
	v_mul_f32_e32 v80, 0x45800000, v84
	v_cndmask_b32_e32 v80, v84, v80, vcc
	v_mul_f32_e32 v76, v76, v80
	v_mul_f32_e32 v84, 0xbfb8aa3b, v76
	v_exp_f32_e32 v84, v84
	v_mul_f32_e32 v77, v77, v80
	v_mul_f32_e32 v86, 0xbfb8aa3b, v77
	v_exp_f32_e32 v86, v86
	v_add_f32_e32 v84, 1.0, v84
	v_rcp_f32_e32 v84, v84
	s_waitcnt vmcnt(15)
	v_lshlrev_b32_e32 v81, 16, v134
	v_mul_f32_e32 v78, v78, v80
	v_mul_f32_e32 v79, v79, v80
	v_mul_f32_e32 v76, v76, v84
	v_mul_f32_e32 v76, v76, v81
	v_add_f32_e32 v81, 1.0, v86
	v_mul_f32_e32 v84, 0xbfb8aa3b, v78
	v_mul_f32_e32 v86, 0xbfb8aa3b, v79
	v_rcp_f32_e32 v81, v81
	v_exp_f32_e32 v84, v84
	v_exp_f32_e32 v86, v86
	v_and_b32_e32 v82, 0xffff0000, v134
	v_mul_f32_e32 v77, v77, v81
	v_add_f32_e32 v81, 1.0, v84
	v_add_f32_e32 v84, 1.0, v86
	v_rcp_f32_e32 v84, v84
	v_rcp_f32_e32 v81, v81
	v_and_b32_e32 v85, 0xffff0000, v135
	v_lshlrev_b32_e32 v83, 16, v135
	v_mul_f32_e32 v79, v79, v84
	v_mul_f32_e32 v77, v77, v82
	v_mul_f32_e32 v78, v78, v81
	v_mul_f32_e32 v79, v79, v85
	v_mul_f32_e32 v72, v72, v80
	v_mul_f32_e32 v78, v78, v83
	v_cvt_pk_bf16_f32 v76, v76, v77
	v_cvt_pk_bf16_f32 v77, v78, v79
	v_mul_f32_e32 v79, 0xbfb8aa3b, v72
	v_exp_f32_e32 v79, v79
	v_mul_f32_e32 v73, v73, v80
	v_mul_f32_e32 v82, 0xbfb8aa3b, v73
	v_exp_f32_e32 v82, v82
	v_add_f32_e32 v79, 1.0, v79
	v_rcp_f32_e32 v79, v79
	global_store_dwordx2 v[124:125], v[76:77], off
	s_waitcnt vmcnt(15)
	v_lshlrev_b32_e32 v76, 16, v130
	v_mul_f32_e32 v74, v74, v80
	v_mul_f32_e32 v75, v75, v80
	v_mul_f32_e32 v72, v72, v79
	v_mul_f32_e32 v72, v72, v76
	v_add_f32_e32 v76, 1.0, v82
	v_mul_f32_e32 v79, 0xbfb8aa3b, v74
	v_mul_f32_e32 v82, 0xbfb8aa3b, v75
	v_rcp_f32_e32 v76, v76
	v_exp_f32_e32 v79, v79
	v_exp_f32_e32 v82, v82
	v_and_b32_e32 v77, 0xffff0000, v130
	v_mul_f32_e32 v73, v73, v76
	v_add_f32_e32 v76, 1.0, v79
	v_add_f32_e32 v79, 1.0, v82
	v_rcp_f32_e32 v79, v79
	v_rcp_f32_e32 v76, v76
	v_and_b32_e32 v81, 0xffff0000, v131
	v_lshlrev_b32_e32 v78, 16, v131
	v_mul_f32_e32 v75, v75, v79
	v_mul_f32_e32 v73, v73, v77
	v_mul_f32_e32 v74, v74, v76
	v_mul_f32_e32 v75, v75, v81
	v_mul_f32_e32 v68, v68, v80
	v_mul_f32_e32 v74, v74, v78
	v_cvt_pk_bf16_f32 v72, v72, v73
	v_cvt_pk_bf16_f32 v73, v74, v75
	v_mul_f32_e32 v75, 0xbfb8aa3b, v68
	v_exp_f32_e32 v75, v75
	v_mul_f32_e32 v69, v69, v80
	v_mul_f32_e32 v77, 0xbfb8aa3b, v69
	v_exp_f32_e32 v77, v77
	v_add_f32_e32 v75, 1.0, v75
	v_rcp_f32_e32 v75, v75
	global_store_dwordx2 v[124:125], v[72:73], off offset:32
	s_waitcnt vmcnt(15)
	v_lshlrev_b32_e32 v72, 16, v128
	v_mul_f32_e32 v70, v70, v80
	v_mul_f32_e32 v71, v71, v80
	v_mul_f32_e32 v68, v68, v75
	v_mul_f32_e32 v68, v68, v72
	v_add_f32_e32 v72, 1.0, v77
	v_mul_f32_e32 v75, 0xbfb8aa3b, v70
	v_mul_f32_e32 v77, 0xbfb8aa3b, v71
	v_rcp_f32_e32 v72, v72
	v_exp_f32_e32 v75, v75
	v_exp_f32_e32 v77, v77
	v_and_b32_e32 v73, 0xffff0000, v128
	v_mul_f32_e32 v69, v69, v72
	v_add_f32_e32 v72, 1.0, v75
	v_add_f32_e32 v75, 1.0, v77
	v_rcp_f32_e32 v75, v75
	v_rcp_f32_e32 v72, v72
	v_and_b32_e32 v76, 0xffff0000, v129
	v_lshlrev_b32_e32 v74, 16, v129
	v_mul_f32_e32 v71, v71, v75
	v_mul_f32_e32 v69, v69, v73
	v_mul_f32_e32 v70, v70, v72
	v_mul_f32_e32 v71, v71, v76
	v_mul_f32_e32 v64, v64, v80
	v_mul_f32_e32 v70, v70, v74
	v_cvt_pk_bf16_f32 v68, v68, v69
	v_cvt_pk_bf16_f32 v69, v70, v71
	v_mul_f32_e32 v71, 0xbfb8aa3b, v64
	v_exp_f32_e32 v71, v71
	v_mul_f32_e32 v65, v65, v80
	v_mul_f32_e32 v73, 0xbfb8aa3b, v65
	v_exp_f32_e32 v73, v73
	v_add_f32_e32 v71, 1.0, v71
	v_rcp_f32_e32 v71, v71
	global_store_dwordx2 v[124:125], v[68:69], off offset:64
	s_waitcnt vmcnt(15)
	v_lshlrev_b32_e32 v68, 16, v126
	v_mul_f32_e32 v66, v66, v80
	v_mul_f32_e32 v67, v67, v80
	v_mul_f32_e32 v64, v64, v71
	v_mul_f32_e32 v64, v64, v68
	v_add_f32_e32 v68, 1.0, v73
	v_mul_f32_e32 v71, 0xbfb8aa3b, v66
	v_mul_f32_e32 v73, 0xbfb8aa3b, v67
	v_rcp_f32_e32 v68, v68
	v_exp_f32_e32 v71, v71
	v_exp_f32_e32 v73, v73
	v_and_b32_e32 v69, 0xffff0000, v126
	v_mul_f32_e32 v65, v65, v68
	v_add_f32_e32 v68, 1.0, v71
	v_add_f32_e32 v71, 1.0, v73
	v_rcp_f32_e32 v68, v68
	v_rcp_f32_e32 v71, v71
	v_lshlrev_b32_e32 v70, 16, v127
	v_and_b32_e32 v72, 0xffff0000, v127
	v_mul_f32_e32 v65, v65, v69
	v_mul_f32_e32 v66, v66, v68
	v_mul_f32_e32 v67, v67, v71
	v_mul_f32_e32 v66, v66, v70
	v_mul_f32_e32 v67, v67, v72
	v_cvt_pk_bf16_f32 v64, v64, v65
	v_cvt_pk_bf16_f32 v65, v66, v67
	global_store_dwordx2 v[124:125], v[64:65], off offset:96
	v_or_b32_e32 v64, 64, v122
	v_ashrrev_i32_e32 v65, 31, v64
	v_lshl_add_u64 v[66:67], v[64:65], 2, s[0:1]
	v_lshlrev_b64 v[64:65], 12, v[64:65]
	v_lshl_add_u64 v[92:93], v[120:121], 0, v[64:65]
	v_or_b32_e32 v64, 0x50, v122
	v_ashrrev_i32_e32 v65, 31, v64
	global_load_dword v97, v[66:67], off
	global_load_dwordx2 v[98:99], v[92:93], off
	global_load_dwordx2 v[100:101], v[92:93], off offset:32
	global_load_dwordx2 v[102:103], v[92:93], off offset:64
	v_lshl_add_u64 v[66:67], v[64:65], 2, s[0:1]
	v_lshlrev_b64 v[64:65], 12, v[64:65]
	v_lshl_add_u64 v[82:83], v[120:121], 0, v[64:65]
	v_or_b32_e32 v64, 0x60, v122
	v_ashrrev_i32_e32 v65, 31, v64
	global_load_dwordx2 v[104:105], v[92:93], off offset:96
	global_load_dword v106, v[66:67], off
	global_load_dwordx2 v[94:95], v[82:83], off
	global_load_dwordx2 v[90:91], v[82:83], off offset:32
	v_lshl_add_u64 v[66:67], v[64:65], 2, s[0:1]
	v_lshlrev_b64 v[64:65], 12, v[64:65]
	v_lshl_add_u64 v[72:73], v[120:121], 0, v[64:65]
	v_or_b32_e32 v64, 0x70, v122
	v_ashrrev_i32_e32 v65, 31, v64
	global_load_dwordx2 v[88:89], v[82:83], off offset:64
	global_load_dwordx2 v[86:87], v[82:83], off offset:96
	global_load_dword v107, v[66:67], off
	global_load_dwordx2 v[84:85], v[72:73], off
	v_lshl_add_u64 v[66:67], v[64:65], 2, s[0:1]
	v_lshlrev_b64 v[64:65], 12, v[64:65]
	v_lshl_add_u64 v[64:65], v[120:121], 0, v[64:65]
	global_load_dwordx2 v[80:81], v[72:73], off offset:32
	global_load_dwordx2 v[78:79], v[72:73], off offset:64
	global_load_dwordx2 v[76:77], v[72:73], off offset:96
	global_load_dword v96, v[66:67], off
	global_load_dwordx2 v[74:75], v[64:65], off
	global_load_dwordx2 v[70:71], v[64:65], off offset:32
	global_load_dwordx2 v[68:69], v[64:65], off offset:64
	s_nop 0
	global_load_dwordx2 v[66:67], v[64:65], off offset:96
	s_waitcnt vmcnt(19)
	v_fmamk_f32 v97, v97, 0x3a800000, v167
	v_mul_f32_e32 v108, 0x4b800000, v97
	v_cmp_gt_f32_e32 vcc, s22, v97
	s_nop 1
	v_cndmask_b32_e32 v97, v97, v108, vcc
	v_rsq_f32_e32 v97, v97
	s_waitcnt vmcnt(18)
	v_lshlrev_b32_e32 v108, 16, v98
	v_and_b32_e32 v98, 0xffff0000, v98
	v_mul_f32_e32 v109, 0x45800000, v97
	v_cndmask_b32_e32 v97, v97, v109, vcc
	v_mul_f32_e32 v60, v60, v97
	v_mul_f32_e32 v110, 0xbfb8aa3b, v60
	v_exp_f32_e32 v110, v110
	v_mul_f32_e32 v61, v61, v97
	v_mul_f32_e32 v111, 0xbfb8aa3b, v61
	v_exp_f32_e32 v111, v111
	v_add_f32_e32 v110, 1.0, v110
	v_rcp_f32_e32 v110, v110
	v_mul_f32_e32 v62, v62, v97
	v_mul_f32_e32 v63, v63, v97
	v_lshlrev_b32_e32 v109, 16, v99
	v_mul_f32_e32 v60, v60, v110
	v_mul_f32_e32 v60, v60, v108
	v_add_f32_e32 v108, 1.0, v111
	v_mul_f32_e32 v110, 0xbfb8aa3b, v62
	v_mul_f32_e32 v111, 0xbfb8aa3b, v63
	v_rcp_f32_e32 v108, v108
	v_exp_f32_e32 v110, v110
	v_exp_f32_e32 v111, v111
	v_and_b32_e32 v99, 0xffff0000, v99
	v_mul_f32_e32 v61, v61, v108
	v_add_f32_e32 v108, 1.0, v110
	v_add_f32_e32 v110, 1.0, v111
	v_rcp_f32_e32 v110, v110
	v_rcp_f32_e32 v108, v108
	v_mul_f32_e32 v61, v61, v98
	v_mul_f32_e32 v56, v56, v97
	v_mul_f32_e32 v63, v63, v110
	v_mul_f32_e32 v62, v62, v108
	v_mul_f32_e32 v63, v63, v99
	v_mul_f32_e32 v62, v62, v109
	v_cvt_pk_bf16_f32 v60, v60, v61
	v_cvt_pk_bf16_f32 v61, v62, v63
	v_mul_f32_e32 v63, 0xbfb8aa3b, v56
	v_exp_f32_e32 v63, v63
	v_mul_f32_e32 v57, v57, v97
	v_mul_f32_e32 v99, 0xbfb8aa3b, v57
	v_exp_f32_e32 v99, v99
	v_add_f32_e32 v63, 1.0, v63
	v_rcp_f32_e32 v63, v63
	global_store_dwordx2 v[92:93], v[60:61], off
	s_waitcnt vmcnt(18)
	v_lshlrev_b32_e32 v60, 16, v100
	v_mul_f32_e32 v58, v58, v97
	v_mul_f32_e32 v59, v59, v97
	v_mul_f32_e32 v56, v56, v63
	v_mul_f32_e32 v56, v56, v60
	v_add_f32_e32 v60, 1.0, v99
	v_mul_f32_e32 v63, 0xbfb8aa3b, v58
	v_mul_f32_e32 v99, 0xbfb8aa3b, v59
	v_rcp_f32_e32 v60, v60
	v_exp_f32_e32 v63, v63
	v_exp_f32_e32 v99, v99
	v_and_b32_e32 v61, 0xffff0000, v100
	v_mul_f32_e32 v57, v57, v60
	v_add_f32_e32 v60, 1.0, v63
	v_add_f32_e32 v63, 1.0, v99
	v_rcp_f32_e32 v63, v63
	v_rcp_f32_e32 v60, v60
	v_and_b32_e32 v98, 0xffff0000, v101
	v_lshlrev_b32_e32 v62, 16, v101
	v_mul_f32_e32 v59, v59, v63
	v_mul_f32_e32 v57, v57, v61
	v_mul_f32_e32 v58, v58, v60
	v_mul_f32_e32 v59, v59, v98
	v_mul_f32_e32 v52, v52, v97
	v_mul_f32_e32 v58, v58, v62
	v_cvt_pk_bf16_f32 v56, v56, v57
	v_cvt_pk_bf16_f32 v57, v58, v59
	v_mul_f32_e32 v59, 0xbfb8aa3b, v52
	v_exp_f32_e32 v59, v59
	v_mul_f32_e32 v53, v53, v97
	v_mul_f32_e32 v61, 0xbfb8aa3b, v53
	v_exp_f32_e32 v61, v61
	v_add_f32_e32 v59, 1.0, v59
	v_rcp_f32_e32 v59, v59
	global_store_dwordx2 v[92:93], v[56:57], off offset:32
	s_waitcnt vmcnt(18)
	v_lshlrev_b32_e32 v56, 16, v102
	v_mul_f32_e32 v54, v54, v97
	v_mul_f32_e32 v55, v55, v97
	v_mul_f32_e32 v52, v52, v59
	v_mul_f32_e32 v52, v52, v56
	v_add_f32_e32 v56, 1.0, v61
	v_mul_f32_e32 v59, 0xbfb8aa3b, v54
	v_mul_f32_e32 v61, 0xbfb8aa3b, v55
	v_rcp_f32_e32 v56, v56
	v_exp_f32_e32 v59, v59
	v_exp_f32_e32 v61, v61
	v_and_b32_e32 v57, 0xffff0000, v102
	v_mul_f32_e32 v53, v53, v56
	v_add_f32_e32 v56, 1.0, v59
	v_add_f32_e32 v59, 1.0, v61
	v_rcp_f32_e32 v59, v59
	v_rcp_f32_e32 v56, v56
	v_and_b32_e32 v60, 0xffff0000, v103
	v_lshlrev_b32_e32 v58, 16, v103
	v_mul_f32_e32 v55, v55, v59
	v_mul_f32_e32 v53, v53, v57
	v_mul_f32_e32 v54, v54, v56
	v_mul_f32_e32 v55, v55, v60
	v_mul_f32_e32 v48, v48, v97
	v_mul_f32_e32 v54, v54, v58
	v_cvt_pk_bf16_f32 v52, v52, v53
	v_cvt_pk_bf16_f32 v53, v54, v55
	v_mul_f32_e32 v55, 0xbfb8aa3b, v48
	v_exp_f32_e32 v55, v55
	v_mul_f32_e32 v49, v49, v97
	v_mul_f32_e32 v57, 0xbfb8aa3b, v49
	v_exp_f32_e32 v57, v57
	v_add_f32_e32 v55, 1.0, v55
	v_rcp_f32_e32 v55, v55
	global_store_dwordx2 v[92:93], v[52:53], off offset:64
	s_waitcnt vmcnt(18)
	v_lshlrev_b32_e32 v52, 16, v104
	v_mul_f32_e32 v50, v50, v97
	v_mul_f32_e32 v48, v48, v55
	v_mul_f32_e32 v48, v48, v52
	v_add_f32_e32 v52, 1.0, v57
	v_mul_f32_e32 v55, 0xbfb8aa3b, v50
	v_rcp_f32_e32 v52, v52
	v_exp_f32_e32 v55, v55
	v_mul_f32_e32 v51, v51, v97
	v_mul_f32_e32 v57, 0xbfb8aa3b, v51
	v_mul_f32_e32 v49, v49, v52
	v_add_f32_e32 v52, 1.0, v55
	v_rcp_f32_e32 v52, v52
	v_exp_f32_e32 v57, v57
	v_and_b32_e32 v53, 0xffff0000, v104
	v_mul_f32_e32 v49, v49, v53
	v_mul_f32_e32 v50, v50, v52
	s_waitcnt vmcnt(17)
	v_fmamk_f32 v52, v106, 0x3a800000, v167
	v_add_f32_e32 v55, 1.0, v57
	v_mul_f32_e32 v53, 0x4b800000, v52
	v_cmp_gt_f32_e32 vcc, s22, v52
	v_rcp_f32_e32 v55, v55
	v_lshlrev_b32_e32 v54, 16, v105
	v_cndmask_b32_e32 v52, v52, v53, vcc
	v_rsq_f32_e32 v52, v52
	v_and_b32_e32 v56, 0xffff0000, v105
	v_mul_f32_e32 v51, v51, v55
	v_cvt_pk_bf16_f32 v48, v48, v49
	v_mul_f32_e32 v50, v50, v54
	v_mul_f32_e32 v51, v51, v56
	v_cvt_pk_bf16_f32 v49, v50, v51
	global_store_dwordx2 v[92:93], v[48:49], off offset:96
	v_mul_f32_e32 v48, 0x45800000, v52
	v_cndmask_b32_e32 v48, v52, v48, vcc
	v_mul_f32_e32 v44, v44, v48
	v_mul_f32_e32 v52, 0xbfb8aa3b, v44
	v_exp_f32_e32 v52, v52
	v_mul_f32_e32 v45, v45, v48
	v_mul_f32_e32 v54, 0xbfb8aa3b, v45
	v_exp_f32_e32 v54, v54
	v_add_f32_e32 v52, 1.0, v52
	v_rcp_f32_e32 v52, v52
	s_waitcnt vmcnt(17)
	v_lshlrev_b32_e32 v49, 16, v94
	v_mul_f32_e32 v46, v46, v48
	v_mul_f32_e32 v47, v47, v48
	v_mul_f32_e32 v44, v44, v52
	v_mul_f32_e32 v44, v44, v49
	v_add_f32_e32 v49, 1.0, v54
	v_mul_f32_e32 v52, 0xbfb8aa3b, v46
	v_mul_f32_e32 v54, 0xbfb8aa3b, v47
	v_rcp_f32_e32 v49, v49
	v_exp_f32_e32 v52, v52
	v_exp_f32_e32 v54, v54
	v_and_b32_e32 v50, 0xffff0000, v94
	v_mul_f32_e32 v45, v45, v49
	v_add_f32_e32 v49, 1.0, v52
	v_add_f32_e32 v52, 1.0, v54
	v_rcp_f32_e32 v52, v52
	v_rcp_f32_e32 v49, v49
	v_and_b32_e32 v53, 0xffff0000, v95
	v_lshlrev_b32_e32 v51, 16, v95
	v_mul_f32_e32 v47, v47, v52
	v_mul_f32_e32 v45, v45, v50
	v_mul_f32_e32 v46, v46, v49
	v_mul_f32_e32 v47, v47, v53
	v_mul_f32_e32 v40, v40, v48
	v_mul_f32_e32 v46, v46, v51
	v_cvt_pk_bf16_f32 v44, v44, v45
	v_cvt_pk_bf16_f32 v45, v46, v47
	v_mul_f32_e32 v47, 0xbfb8aa3b, v40
	v_exp_f32_e32 v47, v47
	v_mul_f32_e32 v41, v41, v48
	v_mul_f32_e32 v50, 0xbfb8aa3b, v41
	v_exp_f32_e32 v50, v50
	v_add_f32_e32 v47, 1.0, v47
	v_rcp_f32_e32 v47, v47
	global_store_dwordx2 v[82:83], v[44:45], off
	s_waitcnt vmcnt(17)
	v_lshlrev_b32_e32 v44, 16, v90
	v_mul_f32_e32 v42, v42, v48
	v_mul_f32_e32 v43, v43, v48
	v_mul_f32_e32 v40, v40, v47
	v_mul_f32_e32 v40, v40, v44
	v_add_f32_e32 v44, 1.0, v50
	v_mul_f32_e32 v47, 0xbfb8aa3b, v42
	v_mul_f32_e32 v50, 0xbfb8aa3b, v43
	v_rcp_f32_e32 v44, v44
	v_exp_f32_e32 v47, v47
	v_exp_f32_e32 v50, v50
	v_and_b32_e32 v45, 0xffff0000, v90
	v_mul_f32_e32 v41, v41, v44
	v_add_f32_e32 v44, 1.0, v47
	v_add_f32_e32 v47, 1.0, v50
	v_rcp_f32_e32 v47, v47
	v_rcp_f32_e32 v44, v44
	v_and_b32_e32 v49, 0xffff0000, v91
	v_lshlrev_b32_e32 v46, 16, v91
	v_mul_f32_e32 v43, v43, v47
	v_mul_f32_e32 v41, v41, v45
	v_mul_f32_e32 v42, v42, v44
	v_mul_f32_e32 v43, v43, v49
	v_mul_f32_e32 v36, v36, v48
	v_mul_f32_e32 v42, v42, v46
	v_cvt_pk_bf16_f32 v40, v40, v41
	v_cvt_pk_bf16_f32 v41, v42, v43
	v_mul_f32_e32 v43, 0xbfb8aa3b, v36
	v_exp_f32_e32 v43, v43
	v_mul_f32_e32 v37, v37, v48
	v_mul_f32_e32 v45, 0xbfb8aa3b, v37
	v_exp_f32_e32 v45, v45
	v_add_f32_e32 v43, 1.0, v43
	v_rcp_f32_e32 v43, v43
	global_store_dwordx2 v[82:83], v[40:41], off offset:32
	s_waitcnt vmcnt(17)
	v_lshlrev_b32_e32 v40, 16, v88
	v_mul_f32_e32 v38, v38, v48
	v_mul_f32_e32 v39, v39, v48
	v_mul_f32_e32 v36, v36, v43
	v_mul_f32_e32 v36, v36, v40
	v_add_f32_e32 v40, 1.0, v45
	v_mul_f32_e32 v43, 0xbfb8aa3b, v38
	v_mul_f32_e32 v45, 0xbfb8aa3b, v39
	v_rcp_f32_e32 v40, v40
	v_exp_f32_e32 v43, v43
	v_exp_f32_e32 v45, v45
	v_and_b32_e32 v41, 0xffff0000, v88
	v_mul_f32_e32 v37, v37, v40
	v_add_f32_e32 v40, 1.0, v43
	v_add_f32_e32 v43, 1.0, v45
	v_rcp_f32_e32 v43, v43
	v_rcp_f32_e32 v40, v40
	v_and_b32_e32 v44, 0xffff0000, v89
	v_lshlrev_b32_e32 v42, 16, v89
	v_mul_f32_e32 v39, v39, v43
	v_mul_f32_e32 v37, v37, v41
	v_mul_f32_e32 v38, v38, v40
	v_mul_f32_e32 v39, v39, v44
	v_mul_f32_e32 v32, v32, v48
	v_mul_f32_e32 v38, v38, v42
	v_cvt_pk_bf16_f32 v36, v36, v37
	v_cvt_pk_bf16_f32 v37, v38, v39
	v_mul_f32_e32 v39, 0xbfb8aa3b, v32
	v_exp_f32_e32 v39, v39
	v_mul_f32_e32 v33, v33, v48
	v_mul_f32_e32 v41, 0xbfb8aa3b, v33
	v_exp_f32_e32 v41, v41
	v_add_f32_e32 v39, 1.0, v39
	v_rcp_f32_e32 v39, v39
	global_store_dwordx2 v[82:83], v[36:37], off offset:64
	s_waitcnt vmcnt(17)
	v_lshlrev_b32_e32 v36, 16, v86
	v_mul_f32_e32 v34, v34, v48
	v_mul_f32_e32 v32, v32, v39
	v_mul_f32_e32 v32, v32, v36
	v_add_f32_e32 v36, 1.0, v41
	v_mul_f32_e32 v39, 0xbfb8aa3b, v34
	v_rcp_f32_e32 v36, v36
	v_exp_f32_e32 v39, v39
	v_mul_f32_e32 v35, v35, v48
	v_mul_f32_e32 v41, 0xbfb8aa3b, v35
	v_mul_f32_e32 v33, v33, v36
	v_add_f32_e32 v36, 1.0, v39
	v_rcp_f32_e32 v36, v36
	v_exp_f32_e32 v41, v41
	v_and_b32_e32 v37, 0xffff0000, v86
	v_mul_f32_e32 v33, v33, v37
	v_mul_f32_e32 v34, v34, v36
	s_waitcnt vmcnt(16)
	v_fmamk_f32 v36, v107, 0x3a800000, v167
	v_add_f32_e32 v39, 1.0, v41
	v_mul_f32_e32 v37, 0x4b800000, v36
	v_cmp_gt_f32_e32 vcc, s22, v36
	v_rcp_f32_e32 v39, v39
	v_lshlrev_b32_e32 v38, 16, v87
	v_cndmask_b32_e32 v36, v36, v37, vcc
	v_rsq_f32_e32 v36, v36
	v_and_b32_e32 v40, 0xffff0000, v87
	v_mul_f32_e32 v35, v35, v39
	v_cvt_pk_bf16_f32 v32, v32, v33
	v_mul_f32_e32 v34, v34, v38
	v_mul_f32_e32 v35, v35, v40
	v_cvt_pk_bf16_f32 v33, v34, v35
	global_store_dwordx2 v[82:83], v[32:33], off offset:96
	v_mul_f32_e32 v32, 0x45800000, v36
	v_cndmask_b32_e32 v32, v36, v32, vcc
	v_mul_f32_e32 v28, v28, v32
	v_mul_f32_e32 v36, 0xbfb8aa3b, v28
	v_exp_f32_e32 v36, v36
	v_mul_f32_e32 v29, v29, v32
	v_mul_f32_e32 v38, 0xbfb8aa3b, v29
	v_exp_f32_e32 v38, v38
	v_add_f32_e32 v36, 1.0, v36
	v_rcp_f32_e32 v36, v36
	s_waitcnt vmcnt(16)
	v_lshlrev_b32_e32 v33, 16, v84
	v_mul_f32_e32 v30, v30, v32
	v_mul_f32_e32 v31, v31, v32
	v_mul_f32_e32 v28, v28, v36
	v_mul_f32_e32 v28, v28, v33
	v_add_f32_e32 v33, 1.0, v38
	v_mul_f32_e32 v36, 0xbfb8aa3b, v30
	v_mul_f32_e32 v38, 0xbfb8aa3b, v31
	v_rcp_f32_e32 v33, v33
	v_exp_f32_e32 v36, v36
	v_exp_f32_e32 v38, v38
	v_and_b32_e32 v34, 0xffff0000, v84
	v_mul_f32_e32 v29, v29, v33
	v_add_f32_e32 v33, 1.0, v36
	v_add_f32_e32 v36, 1.0, v38
	v_rcp_f32_e32 v36, v36
	v_rcp_f32_e32 v33, v33
	v_and_b32_e32 v37, 0xffff0000, v85
	v_lshlrev_b32_e32 v35, 16, v85
	v_mul_f32_e32 v31, v31, v36
	v_mul_f32_e32 v29, v29, v34
	v_mul_f32_e32 v30, v30, v33
	v_mul_f32_e32 v31, v31, v37
	v_mul_f32_e32 v24, v24, v32
	v_mul_f32_e32 v30, v30, v35
	v_cvt_pk_bf16_f32 v28, v28, v29
	v_cvt_pk_bf16_f32 v29, v30, v31
	v_mul_f32_e32 v31, 0xbfb8aa3b, v24
	v_exp_f32_e32 v31, v31
	v_mul_f32_e32 v25, v25, v32
	v_mul_f32_e32 v34, 0xbfb8aa3b, v25
	v_exp_f32_e32 v34, v34
	v_add_f32_e32 v31, 1.0, v31
	v_rcp_f32_e32 v31, v31
	global_store_dwordx2 v[72:73], v[28:29], off
	s_waitcnt vmcnt(16)
	v_lshlrev_b32_e32 v28, 16, v80
	v_mul_f32_e32 v26, v26, v32
	v_mul_f32_e32 v27, v27, v32
	v_mul_f32_e32 v24, v24, v31
	v_mul_f32_e32 v24, v24, v28
	v_add_f32_e32 v28, 1.0, v34
	v_mul_f32_e32 v31, 0xbfb8aa3b, v26
	v_mul_f32_e32 v34, 0xbfb8aa3b, v27
	v_rcp_f32_e32 v28, v28
	v_exp_f32_e32 v31, v31
	v_exp_f32_e32 v34, v34
	v_and_b32_e32 v29, 0xffff0000, v80
	v_mul_f32_e32 v25, v25, v28
	v_add_f32_e32 v28, 1.0, v31
	v_add_f32_e32 v31, 1.0, v34
	v_rcp_f32_e32 v31, v31
	v_rcp_f32_e32 v28, v28
	v_and_b32_e32 v33, 0xffff0000, v81
	v_lshlrev_b32_e32 v30, 16, v81
	v_mul_f32_e32 v27, v27, v31
	v_mul_f32_e32 v25, v25, v29
	v_mul_f32_e32 v26, v26, v28
	v_mul_f32_e32 v27, v27, v33
	v_mul_f32_e32 v20, v20, v32
	v_mul_f32_e32 v26, v26, v30
	v_cvt_pk_bf16_f32 v24, v24, v25
	v_cvt_pk_bf16_f32 v25, v26, v27
	v_mul_f32_e32 v27, 0xbfb8aa3b, v20
	v_exp_f32_e32 v27, v27
	v_mul_f32_e32 v21, v21, v32
	v_mul_f32_e32 v29, 0xbfb8aa3b, v21
	v_exp_f32_e32 v29, v29
	v_add_f32_e32 v27, 1.0, v27
	v_rcp_f32_e32 v27, v27
	global_store_dwordx2 v[72:73], v[24:25], off offset:32
	s_waitcnt vmcnt(16)
	v_lshlrev_b32_e32 v24, 16, v78
	v_mul_f32_e32 v22, v22, v32
	v_mul_f32_e32 v23, v23, v32
	v_mul_f32_e32 v20, v20, v27
	v_mul_f32_e32 v20, v20, v24
	v_add_f32_e32 v24, 1.0, v29
	v_mul_f32_e32 v27, 0xbfb8aa3b, v22
	v_mul_f32_e32 v29, 0xbfb8aa3b, v23
	v_rcp_f32_e32 v24, v24
	v_exp_f32_e32 v27, v27
	v_exp_f32_e32 v29, v29
	v_and_b32_e32 v25, 0xffff0000, v78
	v_mul_f32_e32 v21, v21, v24
	v_add_f32_e32 v24, 1.0, v27
	v_add_f32_e32 v27, 1.0, v29
	v_rcp_f32_e32 v27, v27
	v_rcp_f32_e32 v24, v24
	v_and_b32_e32 v28, 0xffff0000, v79
	v_lshlrev_b32_e32 v26, 16, v79
	v_mul_f32_e32 v23, v23, v27
	v_mul_f32_e32 v21, v21, v25
	v_mul_f32_e32 v22, v22, v24
	v_mul_f32_e32 v23, v23, v28
	v_mul_f32_e32 v16, v16, v32
	v_mul_f32_e32 v22, v22, v26
	v_cvt_pk_bf16_f32 v20, v20, v21
	v_cvt_pk_bf16_f32 v21, v22, v23
	v_mul_f32_e32 v23, 0xbfb8aa3b, v16
	v_exp_f32_e32 v23, v23
	v_mul_f32_e32 v17, v17, v32
	v_mul_f32_e32 v25, 0xbfb8aa3b, v17
	v_exp_f32_e32 v25, v25
	v_add_f32_e32 v23, 1.0, v23
	v_rcp_f32_e32 v23, v23
	global_store_dwordx2 v[72:73], v[20:21], off offset:64
	s_waitcnt vmcnt(16)
	v_lshlrev_b32_e32 v20, 16, v76
	v_mul_f32_e32 v18, v18, v32
	v_mul_f32_e32 v16, v16, v23
	v_mul_f32_e32 v16, v16, v20
	v_add_f32_e32 v20, 1.0, v25
	v_mul_f32_e32 v23, 0xbfb8aa3b, v18
	v_rcp_f32_e32 v20, v20
	v_exp_f32_e32 v23, v23
	v_mul_f32_e32 v19, v19, v32
	v_mul_f32_e32 v25, 0xbfb8aa3b, v19
	v_mul_f32_e32 v17, v17, v20
	v_add_f32_e32 v20, 1.0, v23
	v_rcp_f32_e32 v20, v20
	v_exp_f32_e32 v25, v25
	v_and_b32_e32 v21, 0xffff0000, v76
	v_mul_f32_e32 v17, v17, v21
	v_mul_f32_e32 v18, v18, v20
	s_waitcnt vmcnt(15)
	v_fmamk_f32 v20, v96, 0x3a800000, v167
	v_add_f32_e32 v23, 1.0, v25
	v_mul_f32_e32 v21, 0x4b800000, v20
	v_cmp_gt_f32_e32 vcc, s22, v20
	v_rcp_f32_e32 v23, v23
	v_lshlrev_b32_e32 v22, 16, v77
	v_cndmask_b32_e32 v20, v20, v21, vcc
	v_rsq_f32_e32 v20, v20
	v_and_b32_e32 v24, 0xffff0000, v77
	v_mul_f32_e32 v19, v19, v23
	v_cvt_pk_bf16_f32 v16, v16, v17
	v_mul_f32_e32 v18, v18, v22
	v_mul_f32_e32 v19, v19, v24
	v_cvt_pk_bf16_f32 v17, v18, v19
	global_store_dwordx2 v[72:73], v[16:17], off offset:96
	v_mul_f32_e32 v16, 0x45800000, v20
	v_cndmask_b32_e32 v16, v20, v16, vcc
	v_mul_f32_e32 v12, v12, v16
	v_mul_f32_e32 v20, 0xbfb8aa3b, v12
	v_exp_f32_e32 v20, v20
	v_mul_f32_e32 v13, v13, v16
	v_mul_f32_e32 v22, 0xbfb8aa3b, v13
	v_exp_f32_e32 v22, v22
	v_add_f32_e32 v20, 1.0, v20
	v_rcp_f32_e32 v20, v20
	s_waitcnt vmcnt(15)
	v_lshlrev_b32_e32 v17, 16, v74
	v_mul_f32_e32 v14, v14, v16
	v_mul_f32_e32 v15, v15, v16
	v_mul_f32_e32 v12, v12, v20
	v_mul_f32_e32 v12, v12, v17
	v_add_f32_e32 v17, 1.0, v22
	v_mul_f32_e32 v20, 0xbfb8aa3b, v14
	v_mul_f32_e32 v22, 0xbfb8aa3b, v15
	v_rcp_f32_e32 v17, v17
	v_exp_f32_e32 v20, v20
	v_exp_f32_e32 v22, v22
	v_and_b32_e32 v18, 0xffff0000, v74
	v_mul_f32_e32 v13, v13, v17
	v_add_f32_e32 v17, 1.0, v20
	v_add_f32_e32 v20, 1.0, v22
	v_rcp_f32_e32 v20, v20
	v_rcp_f32_e32 v17, v17
	v_and_b32_e32 v21, 0xffff0000, v75
	v_lshlrev_b32_e32 v19, 16, v75
	v_mul_f32_e32 v15, v15, v20
	v_mul_f32_e32 v13, v13, v18
	v_mul_f32_e32 v14, v14, v17
	v_mul_f32_e32 v15, v15, v21
	v_mul_f32_e32 v8, v8, v16
	v_mul_f32_e32 v14, v14, v19
	v_cvt_pk_bf16_f32 v12, v12, v13
	v_cvt_pk_bf16_f32 v13, v14, v15
	v_mul_f32_e32 v15, 0xbfb8aa3b, v8
	v_exp_f32_e32 v15, v15
	v_mul_f32_e32 v9, v9, v16
	v_mul_f32_e32 v18, 0xbfb8aa3b, v9
	v_exp_f32_e32 v18, v18
	v_add_f32_e32 v15, 1.0, v15
	v_rcp_f32_e32 v15, v15
	global_store_dwordx2 v[64:65], v[12:13], off
	s_waitcnt vmcnt(15)
	v_lshlrev_b32_e32 v12, 16, v70
	v_mul_f32_e32 v10, v10, v16
	v_mul_f32_e32 v11, v11, v16
	v_mul_f32_e32 v8, v8, v15
	v_mul_f32_e32 v8, v8, v12
	v_add_f32_e32 v12, 1.0, v18
	v_mul_f32_e32 v15, 0xbfb8aa3b, v10
	v_mul_f32_e32 v18, 0xbfb8aa3b, v11
	v_rcp_f32_e32 v12, v12
	v_exp_f32_e32 v15, v15
	v_exp_f32_e32 v18, v18
	v_and_b32_e32 v13, 0xffff0000, v70
	v_mul_f32_e32 v9, v9, v12
	v_add_f32_e32 v12, 1.0, v15
	v_add_f32_e32 v15, 1.0, v18
	v_rcp_f32_e32 v15, v15
	v_rcp_f32_e32 v12, v12
	v_and_b32_e32 v17, 0xffff0000, v71
	v_lshlrev_b32_e32 v14, 16, v71
	v_mul_f32_e32 v11, v11, v15
	v_mul_f32_e32 v9, v9, v13
	v_mul_f32_e32 v10, v10, v12
	v_mul_f32_e32 v11, v11, v17
	v_mul_f32_e32 v4, v4, v16
	v_mul_f32_e32 v10, v10, v14
	v_cvt_pk_bf16_f32 v8, v8, v9
	v_cvt_pk_bf16_f32 v9, v10, v11
	v_mul_f32_e32 v11, 0xbfb8aa3b, v4
	v_exp_f32_e32 v11, v11
	v_mul_f32_e32 v5, v5, v16
	v_mul_f32_e32 v13, 0xbfb8aa3b, v5
	v_exp_f32_e32 v13, v13
	v_add_f32_e32 v11, 1.0, v11
	v_rcp_f32_e32 v11, v11
	global_store_dwordx2 v[64:65], v[8:9], off offset:32
	s_waitcnt vmcnt(15)
	v_lshlrev_b32_e32 v8, 16, v68
	v_mul_f32_e32 v6, v6, v16
	v_mul_f32_e32 v7, v7, v16
	v_mul_f32_e32 v4, v4, v11
	v_mul_f32_e32 v4, v4, v8
	v_add_f32_e32 v8, 1.0, v13
	v_mul_f32_e32 v11, 0xbfb8aa3b, v6
	v_mul_f32_e32 v13, 0xbfb8aa3b, v7
	v_rcp_f32_e32 v8, v8
	v_exp_f32_e32 v11, v11
	v_exp_f32_e32 v13, v13
	v_and_b32_e32 v9, 0xffff0000, v68
	v_mul_f32_e32 v5, v5, v8
	v_add_f32_e32 v8, 1.0, v11
	v_add_f32_e32 v11, 1.0, v13
	v_rcp_f32_e32 v11, v11
	v_rcp_f32_e32 v8, v8
	v_and_b32_e32 v12, 0xffff0000, v69
	v_lshlrev_b32_e32 v10, 16, v69
	v_mul_f32_e32 v7, v7, v11
	v_mul_f32_e32 v5, v5, v9
	v_mul_f32_e32 v6, v6, v8
	v_mul_f32_e32 v7, v7, v12
	v_mul_f32_e32 v0, v0, v16
	v_mul_f32_e32 v6, v6, v10
	v_cvt_pk_bf16_f32 v4, v4, v5
	v_cvt_pk_bf16_f32 v5, v6, v7
	v_mul_f32_e32 v7, 0xbfb8aa3b, v0
	v_exp_f32_e32 v7, v7
	v_mul_f32_e32 v1, v1, v16
	v_mul_f32_e32 v9, 0xbfb8aa3b, v1
	v_exp_f32_e32 v9, v9
	v_add_f32_e32 v7, 1.0, v7
	v_rcp_f32_e32 v7, v7
	global_store_dwordx2 v[64:65], v[4:5], off offset:64
	s_waitcnt vmcnt(15)
	v_lshlrev_b32_e32 v4, 16, v66
	v_mul_f32_e32 v2, v2, v16
	v_mul_f32_e32 v3, v3, v16
	v_mul_f32_e32 v0, v0, v7
	v_mul_f32_e32 v0, v0, v4
	v_add_f32_e32 v4, 1.0, v9
	v_mul_f32_e32 v7, 0xbfb8aa3b, v2
	v_mul_f32_e32 v9, 0xbfb8aa3b, v3
	v_rcp_f32_e32 v4, v4
	v_exp_f32_e32 v7, v7
	v_exp_f32_e32 v9, v9
	v_and_b32_e32 v5, 0xffff0000, v66
	v_mul_f32_e32 v1, v1, v4
	v_add_f32_e32 v4, 1.0, v7
	v_add_f32_e32 v7, 1.0, v9
	v_rcp_f32_e32 v4, v4
	v_rcp_f32_e32 v7, v7
	v_lshlrev_b32_e32 v6, 16, v67
	v_and_b32_e32 v8, 0xffff0000, v67
	v_mul_f32_e32 v1, v1, v5
	v_mul_f32_e32 v2, v2, v4
	v_mul_f32_e32 v3, v3, v7
	v_mul_f32_e32 v2, v2, v6
	v_mul_f32_e32 v3, v3, v8
	v_cvt_pk_bf16_f32 v0, v0, v1
	v_cvt_pk_bf16_f32 v1, v2, v3
	global_store_dwordx2 v[64:65], v[0:1], off offset:96
	s_add_i32 s23, s23, s74
	s_cmpk_lt_i32 s23, 0x800
	s_cbranch_scc1 .LBB0_1736

.LBB0_1794:
	s_ashr_i32 s0, s25, 3
	s_lshr_b32 s1, s0, 29
	s_add_i32 s1, s0, s1
	s_and_b32 s18, s1, 0x1fffff8
	s_sub_i32 s0, s0, s18
	s_lshl_b32 s1, s1, 8
	s_lshl_b32 s18, s25, 8
	s_and_b32 s1, s1, 0xfffff800
	s_and_b32 s18, s18, 0x700
	s_or_b32 s20, s1, s18
	s_ashr_i32 s21, s20, 31
	s_lshl_b32 s0, s0, 7
	s_lshl_b64 s[26:27], s[20:21], 12
	s_add_u32 s26, s3, s26
	s_addc_u32 s27, s4, s27
	s_ashr_i32 s1, s0, 31
	v_mov_b32_e32 v36, v220
	s_lshl_b64 s[28:29], s[0:1], 12
	s_add_u32 s28, s5, s28
	v_ashrrev_i32_e32 v26, 2, v36
	v_ashrrev_i32_e32 v27, 31, v26
	s_addc_u32 s29, s6, s29
	v_lshlrev_b64 v[0:1], 12, v[26:27]
	v_lshlrev_b32_e32 v4, 4, v36
	v_lshl_add_u64 v[2:3], s[28:29], 0, v[0:1]
	v_lshl_add_u64 v[0:1], s[26:27], 0, v[0:1]
	v_and_b32_e32 v176, 48, v4
	s_waitcnt vmcnt(9)
	v_lshl_add_u64 v[152:153], v[0:1], 0, v[176:177]
	v_add_co_u32_e32 v28, vcc, s7, v152
	v_lshl_add_u64 v[154:155], v[2:3], 0, v[176:177]
	s_nop 0
	v_addc_co_u32_e32 v29, vcc, 0, v153, vcc
	v_add_co_u32_e32 v30, vcc, s22, v152
	global_load_dwordx4 v[2:5], v[152:153], off
	s_nop 0
	v_addc_co_u32_e32 v31, vcc, 0, v153, vcc
	v_add_co_u32_e32 v32, vcc, s23, v152
	global_load_dwordx4 v[6:9], v[28:29], off
	s_nop 0
	v_addc_co_u32_e32 v33, vcc, 0, v153, vcc
	v_add_co_u32_e32 v34, vcc, s7, v154
	global_load_dwordx4 v[10:13], v[30:31], off
	s_nop 0
	v_addc_co_u32_e32 v35, vcc, 0, v155, vcc
	global_load_dwordx4 v[14:17], v[32:33], off
	global_load_dwordx4 v[18:21], v[154:155], off
	global_load_dwordx4 v[22:25], v[34:35], off
	global_load_dwordx4 v[112:115], v[152:153], off offset:64
	global_load_dwordx4 v[120:123], v[28:29], off offset:64
	global_load_dwordx4 v[124:127], v[30:31], off offset:64
	global_load_dwordx4 v[132:135], v[32:33], off offset:64
	global_load_dwordx4 v[128:131], v[154:155], off offset:64
	global_load_dwordx4 v[136:139], v[34:35], off offset:64
	v_lshrrev_b32_e32 v27, 4, v36
	v_lshrrev_b32_e32 v37, 2, v36
	v_sub_u32_e32 v40, 0, v27
	v_sub_u32_e32 v37, 0, v37
	v_and_b32_e32 v38, 0x3ffff8f, v36
	v_lshlrev_b32_e32 v39, 6, v36
	v_xor_b32_e32 v36, v36, v40
	v_xor_b32_e32 v27, v27, v37
	v_lshlrev_b32_e32 v36, 4, v36
	v_lshlrev_b32_e32 v27, 4, v27
	v_and_b32_e32 v41, 0x1000, v39
	v_and_b32_e32 v36, 48, v36
	v_and_b32_e32 v27, 48, v27
	v_and_b32_e32 v42, 0x3c0, v39
	v_and_b32_e32 v39, 0xffffe3c0, v39
	v_lshl_add_u32 v38, v38, 6, v198
	v_lshl_or_b32 v164, v26, 6, v36
	v_or_b32_e32 v26, v27, v41
	s_mov_b32 s1, -2
	s_mov_b32 s21, s19
	v_mov_b32_e32 v0, 0
	v_mov_b32_e32 v1, v177
	v_or3_b32 v165, v41, v42, v27
	v_add_u32_e32 v166, v27, v39
	v_add_u32_e32 v167, v27, v38
	v_add_u32_e32 v168, v26, v42
	v_lshl_add_u64 v[156:157], v[152:153], 0, s[12:13]
	v_lshl_add_u64 v[158:159], v[152:153], 0, s[14:15]
	v_lshl_add_u64 v[160:161], v[152:153], 0, s[16:17]
	v_lshl_add_u64 v[162:163], v[154:155], 0, s[12:13]
	v_mov_b32_e32 v26, v177
	v_mov_b32_e32 v27, v177
	v_mov_b32_e32 v28, 0
	v_mov_b32_e32 v29, v177
	v_mov_b32_e32 v30, v177
	v_mov_b32_e32 v31, v177
	v_mov_b32_e32 v32, 0
	v_mov_b32_e32 v33, v177
	v_mov_b32_e32 v34, v177
	v_mov_b32_e32 v35, v177
	v_mov_b32_e32 v36, 0
	v_mov_b32_e32 v37, v177
	v_mov_b32_e32 v38, v177
	v_mov_b32_e32 v39, v177
	v_mov_b32_e32 v40, 0
	v_mov_b32_e32 v41, v177
	v_mov_b32_e32 v42, v177
	v_mov_b32_e32 v43, v177
	v_mov_b32_e32 v44, 0
	s_waitcnt vmcnt(11)
	ds_write_b128 v164, v[2:5]
	s_waitcnt vmcnt(10)
	ds_write_b128 v164, v[6:9] offset:4096
	s_waitcnt vmcnt(9)
	ds_write_b128 v164, v[10:13] offset:8192
	s_waitcnt vmcnt(8)
	ds_write_b128 v164, v[14:17] offset:12288
	s_waitcnt vmcnt(7)
	ds_write_b128 v164, v[18:21] offset:32768
	s_waitcnt vmcnt(6)
	ds_write_b128 v164, v[22:25] offset:36864
	v_mov_b32_e32 v2, v177
	v_mov_b32_e32 v3, v177
	v_mov_b32_e32 v4, 0
	v_mov_b32_e32 v5, v177
	v_mov_b32_e32 v6, v177
	v_mov_b32_e32 v7, v177
	v_mov_b32_e32 v8, 0
	v_mov_b32_e32 v9, v177
	v_mov_b32_e32 v10, v177
	v_mov_b32_e32 v11, v177
	v_mov_b32_e32 v12, 0
	v_mov_b32_e32 v13, v177
	v_mov_b32_e32 v14, v177
	v_mov_b32_e32 v15, v177
	v_mov_b32_e32 v16, 0
	v_mov_b32_e32 v17, v177
	v_mov_b32_e32 v18, v177
	v_mov_b32_e32 v19, v177
	v_mov_b32_e32 v20, 0
	v_mov_b32_e32 v21, v177
	v_mov_b32_e32 v22, v177
	v_mov_b32_e32 v23, v177
	v_mov_b32_e32 v24, 0
	v_mov_b32_e32 v25, v177
	v_mov_b32_e32 v45, v177
	v_mov_b32_e32 v46, v177
	v_mov_b32_e32 v47, v177
	v_mov_b32_e32 v48, 0
	v_mov_b32_e32 v49, v177
	v_mov_b32_e32 v50, v177
	v_mov_b32_e32 v51, v177
	v_mov_b32_e32 v52, 0
	v_mov_b32_e32 v53, v177
	v_mov_b32_e32 v54, v177
	v_mov_b32_e32 v55, v177
	v_mov_b32_e32 v56, 0
	v_mov_b32_e32 v57, v177
	v_mov_b32_e32 v58, v177
	v_mov_b32_e32 v59, v177
	v_mov_b32_e32 v60, 0
	v_mov_b32_e32 v61, v177
	v_mov_b32_e32 v62, v177
	v_mov_b32_e32 v63, v177
	v_mov_b32_e32 v64, 0
	v_mov_b32_e32 v65, v177
	v_mov_b32_e32 v66, v177
	v_mov_b32_e32 v67, v177
	v_mov_b32_e32 v68, 0
	v_mov_b32_e32 v69, v177
	v_mov_b32_e32 v70, v177
	v_mov_b32_e32 v71, v177
	v_mov_b32_e32 v72, 0
	v_mov_b32_e32 v73, v177
	v_mov_b32_e32 v74, v177
	v_mov_b32_e32 v75, v177
	v_mov_b32_e32 v76, 0
	v_mov_b32_e32 v77, v177
	v_mov_b32_e32 v78, v177
	v_mov_b32_e32 v79, v177
	v_mov_b32_e32 v80, 0
	v_mov_b32_e32 v81, v177
	v_mov_b32_e32 v82, v177
	v_mov_b32_e32 v83, v177
	v_mov_b32_e32 v84, 0
	v_mov_b32_e32 v85, v177
	v_mov_b32_e32 v86, v177
	v_mov_b32_e32 v87, v177
	v_mov_b32_e32 v88, 0
	v_mov_b32_e32 v89, v177
	v_mov_b32_e32 v90, v177
	v_mov_b32_e32 v91, v177
	v_mov_b32_e32 v92, 0
	v_mov_b32_e32 v93, v177
	v_mov_b32_e32 v94, v177
	v_mov_b32_e32 v95, v177
	v_mov_b32_e32 v96, 0
	v_mov_b32_e32 v97, v177
	v_mov_b32_e32 v98, v177
	v_mov_b32_e32 v99, v177
	v_mov_b32_e32 v100, 0
	v_mov_b32_e32 v101, v177
	v_mov_b32_e32 v102, v177
	v_mov_b32_e32 v103, v177
	v_mov_b32_e32 v104, 0
	v_mov_b32_e32 v105, v177
	v_mov_b32_e32 v106, v177
	v_mov_b32_e32 v107, v177
	v_mov_b32_e32 v108, 0
	v_mov_b32_e32 v109, v177
	v_mov_b32_e32 v110, v177
	v_mov_b32_e32 v111, v177
	v_mov_b32_e32 v116, 0
	v_mov_b32_e32 v117, v177
	v_mov_b32_e32 v118, v177
	v_mov_b32_e32 v119, v177
	v_mov_b32_e32 v140, 0
	v_mov_b32_e32 v141, v177
	v_mov_b32_e32 v142, v177
	v_mov_b32_e32 v143, v177
	v_mov_b32_e32 v144, 0
	v_mov_b32_e32 v145, v177
	v_mov_b32_e32 v146, v177
	v_mov_b32_e32 v147, v177
	v_mov_b32_e32 v148, 0
	v_mov_b32_e32 v149, v177
	v_mov_b32_e32 v150, v177
	v_mov_b32_e32 v151, v177
	s_waitcnt lgkmcnt(0)
	s_barrier
	global_load_dwordx4 v[170:173], v[152:153], off offset:128
	global_load_dwordx4 v[178:181], v[156:157], off offset:128
	global_load_dwordx4 v[182:185], v[158:159], off offset:128
	global_load_dwordx4 v[186:189], v[160:161], off offset:128
	global_load_dwordx4 v[190:193], v[154:155], off offset:128
	global_load_dwordx4 v[194:197], v[162:163], off offset:128
.LBB0_1795:
	s_add_i32 s26, s21, 64
	s_add_i32 s18, s21, 96
	s_min_u32 s18, s18, 0x7e0
	s_lshl_b32 s18, s18, 1
	ds_read_b128 v[200:203], v168 offset:32768
	ds_read_b128 v[204:207], v168 offset:33792
	ds_read_b128 v[208:211], v168 offset:34816
	ds_read_b128 v[212:215], v168 offset:35840
	ds_read_b128 v[216:219], v166
	ds_read_b128 v[222:225], v166 offset:1024
	ds_read_b128 v[226:229], v166 offset:2048
	ds_read_b128 v[230:233], v166 offset:3072
	ds_read_b128 v[234:237], v166 offset:4096
	ds_read_b128 v[238:241], v166 offset:5120
	ds_read_b128 v[242:245], v166 offset:6144
	ds_read_b128 v[246:249], v166 offset:7168
	s_setprio 1
	s_waitcnt lgkmcnt(7)
	v_mfma_f32_16x16x32_bf16 v[148:151], v[200:203], v[216:219], v[148:151]
	v_mfma_f32_16x16x32_bf16 v[144:147], v[204:207], v[216:219], v[144:147]
	v_mfma_f32_16x16x32_bf16 v[140:143], v[208:211], v[216:219], v[140:143]
	v_mfma_f32_16x16x32_bf16 v[116:119], v[212:215], v[216:219], v[116:119]
	s_waitcnt vmcnt(11)
	ds_write_b128 v164, v[112:115] offset:16384
	s_waitcnt lgkmcnt(7)
	v_mfma_f32_16x16x32_bf16 v[108:111], v[200:203], v[222:225], v[108:111]
	v_mfma_f32_16x16x32_bf16 v[104:107], v[204:207], v[222:225], v[104:107]
	v_mfma_f32_16x16x32_bf16 v[100:103], v[208:211], v[222:225], v[100:103]
	v_mfma_f32_16x16x32_bf16 v[96:99], v[212:215], v[222:225], v[96:99]
	s_waitcnt vmcnt(10)
	ds_write_b128 v164, v[120:123] offset:20480
	v_lshl_add_u64 v[112:113], v[152:153], 0, s[18:19]
	global_load_dwordx4 v[112:115], v[112:113], off
	s_waitcnt lgkmcnt(7)
	v_mfma_f32_16x16x32_bf16 v[92:95], v[200:203], v[226:229], v[92:95]
	v_mfma_f32_16x16x32_bf16 v[88:91], v[204:207], v[226:229], v[88:91]
	v_mfma_f32_16x16x32_bf16 v[84:87], v[208:211], v[226:229], v[84:87]
	v_mfma_f32_16x16x32_bf16 v[80:83], v[212:215], v[226:229], v[80:83]
	s_waitcnt vmcnt(10)
	ds_write_b128 v164, v[124:127] offset:24576
	v_lshl_add_u64 v[120:121], v[156:157], 0, s[18:19]
	global_load_dwordx4 v[120:123], v[120:121], off
	s_waitcnt lgkmcnt(7)
	v_mfma_f32_16x16x32_bf16 v[76:79], v[200:203], v[230:233], v[76:79]
	v_mfma_f32_16x16x32_bf16 v[72:75], v[204:207], v[230:233], v[72:75]
	v_mfma_f32_16x16x32_bf16 v[68:71], v[208:211], v[230:233], v[68:71]
	v_mfma_f32_16x16x32_bf16 v[64:67], v[212:215], v[230:233], v[64:67]
	s_waitcnt vmcnt(10)
	ds_write_b128 v164, v[132:135] offset:28672
	v_lshl_add_u64 v[124:125], v[158:159], 0, s[18:19]
	global_load_dwordx4 v[124:127], v[124:125], off
	s_waitcnt lgkmcnt(7)
	v_mfma_f32_16x16x32_bf16 v[60:63], v[200:203], v[234:237], v[60:63]
	v_mfma_f32_16x16x32_bf16 v[56:59], v[204:207], v[234:237], v[56:59]
	v_mfma_f32_16x16x32_bf16 v[52:55], v[208:211], v[234:237], v[52:55]
	v_mfma_f32_16x16x32_bf16 v[48:51], v[212:215], v[234:237], v[48:51]
	s_waitcnt vmcnt(10)
	ds_write_b128 v164, v[128:131] offset:40960
	v_lshl_add_u64 v[132:133], v[160:161], 0, s[18:19]
	global_load_dwordx4 v[132:135], v[132:133], off
	s_waitcnt lgkmcnt(7)
	v_mfma_f32_16x16x32_bf16 v[44:47], v[200:203], v[238:241], v[44:47]
	v_mfma_f32_16x16x32_bf16 v[40:43], v[204:207], v[238:241], v[40:43]
	v_mfma_f32_16x16x32_bf16 v[36:39], v[208:211], v[238:241], v[36:39]
	v_mfma_f32_16x16x32_bf16 v[32:35], v[212:215], v[238:241], v[32:35]
	s_waitcnt vmcnt(10)
	ds_write_b128 v164, v[136:139] offset:45056
	v_lshl_add_u64 v[128:129], v[154:155], 0, s[18:19]
	global_load_dwordx4 v[128:131], v[128:129], off
	s_waitcnt lgkmcnt(7)
	v_mfma_f32_16x16x32_bf16 v[28:31], v[200:203], v[242:245], v[28:31]
	v_mfma_f32_16x16x32_bf16 v[24:27], v[204:207], v[242:245], v[24:27]
	v_mfma_f32_16x16x32_bf16 v[20:23], v[208:211], v[242:245], v[20:23]
	v_mfma_f32_16x16x32_bf16 v[16:19], v[212:215], v[242:245], v[16:19]
	v_lshl_add_u64 v[136:137], v[162:163], 0, s[18:19]
	global_load_dwordx4 v[136:139], v[136:137], off
	s_waitcnt lgkmcnt(6)
	v_mfma_f32_16x16x32_bf16 v[12:15], v[200:203], v[246:249], v[12:15]
	v_mfma_f32_16x16x32_bf16 v[8:11], v[204:207], v[246:249], v[8:11]
	v_mfma_f32_16x16x32_bf16 v[4:7], v[208:211], v[246:249], v[4:7]
	v_mfma_f32_16x16x32_bf16 v[0:3], v[212:215], v[246:249], v[0:3]
	s_setprio 0
	s_waitcnt lgkmcnt(0)
	s_barrier
	s_add_i32 s18, s21, 0x80
	s_min_u32 s18, s18, 0x7e0
	s_lshl_b32 s18, s18, 1
	ds_read_b128 v[200:203], v165 offset:40960
	ds_read_b128 v[204:207], v165 offset:41984
	ds_read_b128 v[208:211], v165 offset:43008
	ds_read_b128 v[212:215], v165 offset:44032
	ds_read_b128 v[216:219], v167
	ds_read_b128 v[222:225], v167 offset:1024
	ds_read_b128 v[226:229], v167 offset:2048
	ds_read_b128 v[230:233], v167 offset:3072
	ds_read_b128 v[234:237], v167 offset:4096
	ds_read_b128 v[238:241], v167 offset:5120
	ds_read_b128 v[242:245], v167 offset:6144
	ds_read_b128 v[246:249], v167 offset:7168
	s_setprio 1
	s_waitcnt lgkmcnt(7)
	v_mfma_f32_16x16x32_bf16 v[148:151], v[200:203], v[216:219], v[148:151]
	v_mfma_f32_16x16x32_bf16 v[144:147], v[204:207], v[216:219], v[144:147]
	v_mfma_f32_16x16x32_bf16 v[140:143], v[208:211], v[216:219], v[140:143]
	v_mfma_f32_16x16x32_bf16 v[116:119], v[212:215], v[216:219], v[116:119]
	s_waitcnt vmcnt(11)
	ds_write_b128 v164, v[170:173]
	s_waitcnt lgkmcnt(7)
	v_mfma_f32_16x16x32_bf16 v[108:111], v[200:203], v[222:225], v[108:111]
	v_mfma_f32_16x16x32_bf16 v[104:107], v[204:207], v[222:225], v[104:107]
	v_mfma_f32_16x16x32_bf16 v[100:103], v[208:211], v[222:225], v[100:103]
	v_mfma_f32_16x16x32_bf16 v[96:99], v[212:215], v[222:225], v[96:99]
	s_waitcnt vmcnt(10)
	ds_write_b128 v164, v[178:181] offset:4096
	v_lshl_add_u64 v[170:171], v[152:153], 0, s[18:19]
	global_load_dwordx4 v[170:173], v[170:171], off
	s_waitcnt lgkmcnt(7)
	v_mfma_f32_16x16x32_bf16 v[92:95], v[200:203], v[226:229], v[92:95]
	v_mfma_f32_16x16x32_bf16 v[88:91], v[204:207], v[226:229], v[88:91]
	v_mfma_f32_16x16x32_bf16 v[84:87], v[208:211], v[226:229], v[84:87]
	v_mfma_f32_16x16x32_bf16 v[80:83], v[212:215], v[226:229], v[80:83]
	s_waitcnt vmcnt(10)
	ds_write_b128 v164, v[182:185] offset:8192
	v_lshl_add_u64 v[178:179], v[156:157], 0, s[18:19]
	global_load_dwordx4 v[178:181], v[178:179], off
	s_waitcnt lgkmcnt(7)
	v_mfma_f32_16x16x32_bf16 v[76:79], v[200:203], v[230:233], v[76:79]
	v_mfma_f32_16x16x32_bf16 v[72:75], v[204:207], v[230:233], v[72:75]
	v_mfma_f32_16x16x32_bf16 v[68:71], v[208:211], v[230:233], v[68:71]
	v_mfma_f32_16x16x32_bf16 v[64:67], v[212:215], v[230:233], v[64:67]
	s_waitcnt vmcnt(10)
	ds_write_b128 v164, v[186:189] offset:12288
	v_lshl_add_u64 v[182:183], v[158:159], 0, s[18:19]
	global_load_dwordx4 v[182:185], v[182:183], off
	s_waitcnt lgkmcnt(7)
	v_mfma_f32_16x16x32_bf16 v[60:63], v[200:203], v[234:237], v[60:63]
	v_mfma_f32_16x16x32_bf16 v[56:59], v[204:207], v[234:237], v[56:59]
	v_mfma_f32_16x16x32_bf16 v[52:55], v[208:211], v[234:237], v[52:55]
	v_mfma_f32_16x16x32_bf16 v[48:51], v[212:215], v[234:237], v[48:51]
	s_waitcnt vmcnt(10)
	ds_write_b128 v164, v[190:193] offset:32768
	v_lshl_add_u64 v[186:187], v[160:161], 0, s[18:19]
	global_load_dwordx4 v[186:189], v[186:187], off
	s_waitcnt lgkmcnt(7)
	v_mfma_f32_16x16x32_bf16 v[44:47], v[200:203], v[238:241], v[44:47]
	v_mfma_f32_16x16x32_bf16 v[40:43], v[204:207], v[238:241], v[40:43]
	v_mfma_f32_16x16x32_bf16 v[36:39], v[208:211], v[238:241], v[36:39]
	v_mfma_f32_16x16x32_bf16 v[32:35], v[212:215], v[238:241], v[32:35]
	s_waitcnt vmcnt(10)
	ds_write_b128 v164, v[194:197] offset:36864
	v_lshl_add_u64 v[190:191], v[154:155], 0, s[18:19]
	global_load_dwordx4 v[190:193], v[190:191], off
	s_waitcnt lgkmcnt(7)
	v_mfma_f32_16x16x32_bf16 v[28:31], v[200:203], v[242:245], v[28:31]
	v_mfma_f32_16x16x32_bf16 v[24:27], v[204:207], v[242:245], v[24:27]
	v_mfma_f32_16x16x32_bf16 v[20:23], v[208:211], v[242:245], v[20:23]
	v_mfma_f32_16x16x32_bf16 v[16:19], v[212:215], v[242:245], v[16:19]
	v_lshl_add_u64 v[194:195], v[162:163], 0, s[18:19]
	global_load_dwordx4 v[194:197], v[194:195], off
	s_waitcnt lgkmcnt(6)
	v_mfma_f32_16x16x32_bf16 v[12:15], v[200:203], v[246:249], v[12:15]
	v_mfma_f32_16x16x32_bf16 v[8:11], v[204:207], v[246:249], v[8:11]
	v_mfma_f32_16x16x32_bf16 v[4:7], v[208:211], v[246:249], v[4:7]
	v_mfma_f32_16x16x32_bf16 v[0:3], v[212:215], v[246:249], v[0:3]
	s_setprio 0
	s_add_i32 s1, s1, 2
	s_cmp_lt_u32 s1, 62
	s_mov_b32 s21, s26
	s_waitcnt lgkmcnt(0)
	s_barrier
	s_cbranch_scc1 .LBB0_1795
	s_waitcnt vmcnt(0)
	s_waitcnt vmcnt(5)
	v_mov_b32_e32 v112, v220
	s_nop 0
	v_and_b32_e32 v114, 0xffffff80, v112
	v_bfe_u32 v176, v112, 4, 2
	v_add_u32_e32 v114, s20, v114
	v_and_b32_e32 v113, 64, v112
	v_and_or_b32 v184, v112, 15, v114
	v_lshlrev_b32_e32 v112, 2, v176
	v_or3_b32 v178, v112, v113, s0
	v_ashrrev_i32_e32 v179, 31, v178
	v_lshlrev_b64 v[216:217], 2, v[178:179]
	v_ashrrev_i32_e32 v185, 31, v184
	v_or_b32_e32 v194, 16, v184
	v_lshl_add_u64 v[182:183], s[70:71], 0, v[216:217]
	v_lshlrev_b64 v[218:219], 12, v[184:185]
	v_ashrrev_i32_e32 v195, 31, v194
	v_or_b32_e32 v190, 32, v184
	v_lshl_add_u64 v[112:113], v[182:183], 0, v[218:219]
	v_lshlrev_b64 v[196:197], 12, v[194:195]
	v_ashrrev_i32_e32 v191, 31, v190
	v_or_b32_e32 v186, 48, v184
	global_load_dwordx4 v[200:203], v[112:113], off
	global_load_dwordx4 v[204:207], v[112:113], off offset:64
	global_load_dwordx4 v[208:211], v[112:113], off offset:128
	global_load_dwordx4 v[212:215], v[112:113], off offset:192
	v_lshl_add_u64 v[112:113], v[182:183], 0, v[196:197]
	v_lshlrev_b64 v[192:193], 12, v[190:191]
	v_ashrrev_i32_e32 v187, 31, v186
	global_load_dwordx4 v[172:175], v[112:113], off
	global_load_dwordx4 v[168:171], v[112:113], off offset:64
	global_load_dwordx4 v[164:167], v[112:113], off offset:128
	global_load_dwordx4 v[160:163], v[112:113], off offset:192
	v_lshl_add_u64 v[112:113], v[182:183], 0, v[192:193]
	v_lshlrev_b64 v[188:189], 12, v[186:187]
	global_load_dwordx4 v[156:159], v[112:113], off
	global_load_dwordx4 v[152:155], v[112:113], off offset:64
	global_load_dwordx4 v[136:139], v[112:113], off offset:128
	global_load_dwordx4 v[132:135], v[112:113], off offset:192
	v_lshl_add_u64 v[112:113], v[182:183], 0, v[188:189]
	global_load_dwordx4 v[128:131], v[112:113], off
	global_load_dwordx4 v[124:127], v[112:113], off offset:64
	global_load_dwordx4 v[120:123], v[112:113], off offset:128
	s_nop 0
	global_load_dwordx4 v[112:115], v[112:113], off offset:192
	v_cmp_eq_u32_e32 vcc, 0, v176
	v_lshlrev_b64 v[222:223], 11, v[184:185]
	v_lshlrev_b64 v[180:181], 1, v[178:179]
	v_lshl_add_u64 v[218:219], s[70:71], 0, v[218:219]
	v_lshl_add_u64 v[224:225], s[8:9], 0, v[222:223]
	v_lshl_add_u64 v[216:217], v[218:219], 0, v[216:217]
	v_lshl_add_u64 v[218:219], v[224:225], 0, v[180:181]
	v_lshl_add_u64 v[222:223], s[72:73], 0, v[222:223]
	v_lshl_add_u64 v[222:223], v[222:223], 0, v[180:181]
	s_waitcnt vmcnt(15)
	v_pk_add_f32 v[148:149], v[148:149], v[200:201]
	s_waitcnt vmcnt(14)
	v_pk_add_f32 v[144:145], v[144:145], v[204:205]
	v_pk_add_f32 v[146:147], v[146:147], v[206:207]
	s_waitcnt vmcnt(13)
	v_pk_add_f32 v[140:141], v[140:141], v[208:209]
	v_mul_f32_e32 v176, v149, v149
	v_mul_f32_e32 v206, v145, v145
	v_pk_add_f32 v[150:151], v[150:151], v[202:203]
	s_waitcnt vmcnt(12)
	v_pk_add_f32 v[116:117], v[116:117], v[212:213]
	v_mul_f32_e32 v212, v141, v141
	v_pk_fma_f32 v[226:227], v[148:149], v[148:149], v[176:177] op_sel_hi:[1,1,0]
	v_pk_fma_f32 v[206:207], v[144:145], v[144:145], v[206:207] op_sel_hi:[1,1,0]
	v_pk_add_f32 v[142:143], v[142:143], v[210:211]
	v_mul_f32_e32 v202, v151, v151
	v_mul_f32_e32 v208, v147, v147
	v_pk_fma_f32 v[212:213], v[140:141], v[140:141], v[212:213] op_sel_hi:[1,1,0]
	v_pk_fma_f32 v[226:227], v[150:151], v[150:151], v[226:227]
	v_pk_fma_f32 v[206:207], v[146:147], v[146:147], v[206:207]
	v_mul_f32_e32 v224, v143, v143
	v_pk_fma_f32 v[212:213], v[142:143], v[142:143], v[212:213]
	v_pk_add_f32 v[202:203], v[202:203], v[226:227] op_sel_hi:[0,1]
	v_pk_add_f32 v[206:207], v[208:209], v[206:207] op_sel_hi:[0,1]
	v_pk_add_f32 v[208:209], v[224:225], v[212:213] op_sel_hi:[0,1]
	v_pk_add_f32 v[202:203], v[202:203], v[206:207]
	v_cvt_pk_bf16_f32 v200, v148, v149
	v_cvt_pk_bf16_f32 v201, v150, v151
	v_cvt_pk_bf16_f32 v204, v144, v145
	v_cvt_pk_bf16_f32 v205, v146, v147
	v_cvt_pk_bf16_f32 v210, v140, v141
	v_cvt_pk_bf16_f32 v211, v142, v143
	s_nop 0
	v_pk_add_f32 v[202:203], v[202:203], v[208:209]
	v_pk_add_f32 v[118:119], v[118:119], v[214:215]
	global_store_dwordx4 v[216:217], v[148:151], off
	global_store_dwordx2 v[218:219], v[200:201], off
	global_store_dwordx4 v[216:217], v[144:147], off offset:64
	s_nop 1
	v_add_co_u32_e64 v144, s[0:1], s24, v222
	s_nop 1
	v_addc_co_u32_e64 v145, s[0:1], 0, v223, s[0:1]
	global_store_dwordx2 v[144:145], v[204:205], off offset:32
	global_store_dwordx4 v[216:217], v[140:143], off offset:128
	global_store_dwordx2 v[144:145], v[210:211], off offset:64
	global_store_dwordx4 v[216:217], v[116:119], off offset:192
	v_cvt_pk_bf16_f32 v140, v116, v117
	v_cvt_pk_bf16_f32 v141, v118, v119
	global_store_dwordx2 v[144:145], v[140:141], off offset:96
	v_mul_f32_e32 v140, v117, v117
	v_pk_fma_f32 v[116:117], v[116:117], v[116:117], v[140:141] op_sel_hi:[1,1,0]
	s_nop 0
	v_pk_fma_f32 v[116:117], v[118:119], v[118:119], v[116:117]
	v_mul_f32_e32 v118, v119, v119
	v_pk_add_f32 v[116:117], v[118:119], v[116:117] op_sel_hi:[0,1]
	v_pk_add_f32 v[116:117], v[202:203], v[116:117]
	s_nop 0
	v_mov_b32_e32 v117, v116
	s_nop 1
	v_permlane32_swap_b32_e32 v116, v117
	v_add_f32_e32 v116, v116, v117
	v_mov_b32_e32 v117, v116
	s_nop 1
	v_permlane16_swap_b32_e32 v116, v117
	s_and_saveexec_b64 s[0:1], vcc
	s_cbranch_execz .LBB0_1798
	v_lshl_add_u64 v[118:119], v[184:185], 2, s[10:11]
	v_add_f32_e32 v116, v116, v117
	global_atomic_add_f32 v[118:119], v116, off
